# GEMM K-loop MFMA runs padded to 8-byte alignment (one s_nop in the preceding load segment where needed)
# speedup vs baseline: 1.0019x; 1.0002x over previous
; #define PG8_STAGE(bufoff, gbase, voff) do { _Pragma("unroll") for (int _i = 0; _i < 2; ++_i) \
;         __builtin_amdgcn_global_load_lds((const unsigned*)((const char*)(gbase) + (voff)[_i]), (PG8_LAS unsigned*)(lds + (bufoff) + ldsw + _i * 8192), 16, 0, 0); } while (0)
; #define PG8_LDA(dst, b, h) do { _Pragma("unroll") for (int m = 0; m < 4; ++m) _Pragma("unroll") for (int k = 0; k < 2; ++k) dst[m][k] = *(const PG8_LAS bf16x8*)(lds + PG8_SA(b, h) + aoff + m * 2048 + k * 1024); } while (0)
; #define PG8_LDB(dst, b, h) do { _Pragma("unroll") for (int n = 0; n < 2; ++n) _Pragma("unroll") for (int k = 0; k < 2; ++k) dst[n][k] = *(const PG8_LAS bf16x8*)(lds + PG8_SB(b, h) + boff + n * 2048 + k * 1024); } while (0)
; #define PG8_WAIT_V(n) asm volatile("s_waitcnt vmcnt(" #n ")" ::: "memory")
; #define PG8_WAIT_L(n) asm volatile("s_waitcnt lgkmcnt(" #n ")" ::: "memory")
; #define PG8_BAR __builtin_amdgcn_s_barrier()
; #define PG8_SCHED __builtin_amdgcn_sched_barrier(0)
; template <class Epi, class Sched, bool ALIGN_EPI = false, bool SP2 = false>
; __device__ __forceinline__ void gemm_phase(PG8_LAS unsigned char* lds, const Gemm g, const Sched& S, const Epi& E) {
;     ...
;         const char* nA = has_next ? (const char*)g.A + (size_t)nxt.pm * tstep : cA; const char* nB = has_next ? (const char*)g.Bt + (size_t)nxt.pn * tstep : cB;
;         for (int t = 0; t < nt; t += 2) {
;             const bool last = (t == nt - 2);
;             const char* a1 = cA + (size_t)(t + 1) * kstep;
;             const char* a2 = last ? nA : cA + (size_t)(t + 2) * kstep; const char* b2 = last ? nB : cB + (size_t)(t + 2) * kstep;
;             const char* a3 = a2 + kstep; const char* b3 = b2 + kstep;
;             if (last && has_next) S.a_ready(nxt);
;             if constexpr (SP2) {
;             PG8_LDB(B0, 0, 0); PG8_LDB(B1, 0, 1); PG8_SCHED; PG8_LDA(At, 0, 0); PG8_STAGE(PG8_SA(1, 1), a1 + hstep, voffA);
;             PG8_WAIT_V(8); PG8_WAIT_L(0); PG8_BAR; PG8_MMA(0, 0, At, B0); PG8_MMA(0, 1, At, B1); PG8_BAR; PG8_SCHED;
;             PG8_LDA(At, 0, 1); PG8_STAGE(PG8_SB(0, 0), b2, voffB); PG8_STAGE(PG8_SB(0, 1), b2 + hstep, voffB); PG8_STAGE(PG8_SA(0, 0), a2, voffA);
;             PG8_WAIT_V(8); PG8_WAIT_L(0); PG8_BAR; PG8_MMA(1, 0, At, B0); PG8_MMA(1, 1, At, B1); PG8_BAR; PG8_SCHED;
.LBB0_223:
	s_ashr_i32 s15, s14, 31
	s_lshl_b64 s[16:17], s[14:15], 19
	s_add_u32 s16, s36, s16
	s_addc_u32 s17, s37, s17
	s_and_b64 s[18:19], s[4:5], exec
	s_cselect_b32 s15, s17, s21
	s_cselect_b32 s68, s16, s20
	s_ashr_i32 s13, s12, 31
	s_lshl_b64 s[18:19], s[12:13], 19
	s_add_u32 s18, s53, s18
	s_addc_u32 s19, s54, s19
	s_and_b64 s[46:47], s[4:5], exec
	s_cselect_b32 s13, s19, s43
	s_cselect_b32 s69, s18, s42
	s_add_u32 s20, s20, 0x40080
	s_addc_u32 s21, s21, 0
	s_add_u32 s70, s42, 0x100
	s_addc_u32 s71, s43, 0
	s_mov_b32 s72, -2
	ds_read_b128 v[154:157], v150
	ds_read_b128 v[158:161], v150 offset:1024
	ds_read_b128 v[162:165], v150 offset:2048
	ds_read_b128 v[166:169], v150 offset:3072
	ds_read_b128 v[170:173], v151
	ds_read_b128 v[174:177], v151 offset:1024
	ds_read_b128 v[178:181], v151 offset:2048
	ds_read_b128 v[182:185], v151 offset:3072
	s_add_u32 s42, s20, 0xfffc0080
	s_addc_u32 s43, s21, -1
	s_cmp_eq_u32 s72, 12
	s_cselect_b32 s47, s15, s43
	s_cselect_b32 s46, s68, s42
	s_cselect_b32 s43, s13, s71
	s_cselect_b32 s42, s69, s70
	s_add_i32 m0, s35, 0xc000
	ds_read_b128 v[186:189], v152
	ds_read_b128 v[190:193], v152 offset:1024
	ds_read_b128 v[198:201], v152 offset:2048
	ds_read_b128 v[202:205], v152 offset:3072
	ds_read_b128 v[206:209], v152 offset:4096
	ds_read_b128 v[210:213], v152 offset:5120
	ds_read_b128 v[214:217], v152 offset:6144
	ds_read_b128 v[218:221], v152 offset:7168
	global_load_lds_dwordx4 v136, s[20:21]
	s_add_i32 m0, s35, 0xe000
	s_nop 0
	global_load_lds_dwordx4 v138, s[20:21]
	s_nop 0
	s_waitcnt vmcnt(8)
	s_waitcnt lgkmcnt(0)
	s_barrier
	v_mfma_f32_16x16x32_bf16 v[124:127], v[154:157], v[186:189], 0
	v_mfma_f32_16x16x32_bf16 v[116:119], v[162:165], v[186:189], 0
	v_mfma_f32_16x16x32_bf16 v[108:111], v[154:157], v[198:201], 0
	v_mfma_f32_16x16x32_bf16 v[100:103], v[162:165], v[198:201], 0
	v_mfma_f32_16x16x32_bf16 v[92:95], v[154:157], v[206:209], 0
	v_mfma_f32_16x16x32_bf16 v[84:87], v[162:165], v[206:209], 0
	v_mfma_f32_16x16x32_bf16 v[76:79], v[154:157], v[214:217], 0
	v_mfma_f32_16x16x32_bf16 v[68:71], v[162:165], v[214:217], 0
	v_mfma_f32_16x16x32_bf16 v[124:127], v[158:161], v[190:193], v[124:127]
	v_mfma_f32_16x16x32_bf16 v[116:119], v[166:169], v[190:193], v[116:119]
	v_mfma_f32_16x16x32_bf16 v[108:111], v[158:161], v[202:205], v[108:111]
	v_mfma_f32_16x16x32_bf16 v[100:103], v[166:169], v[202:205], v[100:103]
	v_mfma_f32_16x16x32_bf16 v[92:95], v[158:161], v[210:213], v[92:95]
	v_mfma_f32_16x16x32_bf16 v[84:87], v[166:169], v[210:213], v[84:87]
	v_mfma_f32_16x16x32_bf16 v[76:79], v[158:161], v[218:221], v[76:79]
	v_mfma_f32_16x16x32_bf16 v[68:71], v[166:169], v[218:221], v[68:71]
	v_mfma_f32_16x16x32_bf16 v[120:123], v[170:173], v[186:189], 0
	v_mfma_f32_16x16x32_bf16 v[112:115], v[178:181], v[186:189], 0
	v_mfma_f32_16x16x32_bf16 v[104:107], v[170:173], v[198:201], 0
	v_mfma_f32_16x16x32_bf16 v[96:99], v[178:181], v[198:201], 0
	v_mfma_f32_16x16x32_bf16 v[88:91], v[170:173], v[206:209], 0
	v_mfma_f32_16x16x32_bf16 v[80:83], v[178:181], v[206:209], 0
	v_mfma_f32_16x16x32_bf16 v[72:75], v[170:173], v[214:217], 0
	v_mfma_f32_16x16x32_bf16 v[64:67], v[178:181], v[214:217], 0
	v_mfma_f32_16x16x32_bf16 v[120:123], v[174:177], v[190:193], v[120:123]
	v_mfma_f32_16x16x32_bf16 v[112:115], v[182:185], v[190:193], v[112:115]
	v_mfma_f32_16x16x32_bf16 v[104:107], v[174:177], v[202:205], v[104:107]
	v_mfma_f32_16x16x32_bf16 v[96:99], v[182:185], v[202:205], v[96:99]
	v_mfma_f32_16x16x32_bf16 v[88:91], v[174:177], v[210:213], v[88:91]
	v_mfma_f32_16x16x32_bf16 v[80:83], v[182:185], v[210:213], v[80:83]
	v_mfma_f32_16x16x32_bf16 v[72:75], v[174:177], v[218:221], v[72:75]
	v_mfma_f32_16x16x32_bf16 v[64:67], v[182:185], v[218:221], v[64:67]
	s_barrier
	s_add_i32 s73, s63, s55
	s_add_u32 s98, s42, s8
	s_addc_u32 s99, s43, s9
	s_add_u32 s100, s46, s8
	s_addc_u32 s101, s47, s9
	s_mov_b32 m0, s73
	ds_read_b128 v[186:189], v152 offset:16384
	ds_read_b128 v[190:193], v152 offset:17408
	ds_read_b128 v[198:201], v152 offset:18432
	ds_read_b128 v[202:205], v152 offset:19456
	ds_read_b128 v[206:209], v152 offset:20480
	ds_read_b128 v[210:213], v152 offset:21504
	ds_read_b128 v[214:217], v152 offset:22528
	ds_read_b128 v[218:221], v152 offset:23552
	global_load_lds_dwordx4 v132, s[42:43]
	s_add_i32 m0, s73, 0x2000
	s_add_u32 s74, s42, 0x40000
	s_addc_u32 s75, s43, 0
	s_add_i32 s73, s64, s55
	global_load_lds_dwordx4 v128, s[42:43]
	s_mov_b32 m0, s73
	s_nop 0
	global_load_lds_dwordx4 v132, s[74:75]
	s_add_i32 m0, s73, 0x2000
	s_nop 0
	global_load_lds_dwordx4 v128, s[74:75]
	s_mov_b32 m0, s35
	s_nop 0
	global_load_lds_dwordx4 v134, s[46:47]
	s_mov_b32 m0, s57
	s_nop 0
	global_load_lds_dwordx4 v130, s[46:47]
	s_nop 0
	s_waitcnt vmcnt(8)
	s_waitcnt lgkmcnt(0)
	s_barrier
; #define PG8_STAGE(bufoff, gbase, voff) do { _Pragma("unroll") for (int _i = 0; _i < 2; ++_i) \
;         __builtin_amdgcn_global_load_lds((const unsigned*)((const char*)(gbase) + (voff)[_i]), (PG8_LAS unsigned*)(lds + (bufoff) + ldsw + _i * 8192), 16, 0, 0); } while (0)
; #define PG8_LDA(dst, b, h) do { _Pragma("unroll") for (int m = 0; m < 4; ++m) _Pragma("unroll") for (int k = 0; k < 2; ++k) dst[m][k] = *(const PG8_LAS bf16x8*)(lds + PG8_SA(b, h) + aoff + m * 2048 + k * 1024); } while (0)
; #define PG8_LDB(dst, b, h) do { _Pragma("unroll") for (int n = 0; n < 2; ++n) _Pragma("unroll") for (int k = 0; k < 2; ++k) dst[n][k] = *(const PG8_LAS bf16x8*)(lds + PG8_SB(b, h) + boff + n * 2048 + k * 1024); } while (0)
; #define PG8_MMA(ai, bj, At, Bt) do { __builtin_amdgcn_s_setprio(1); _Pragma("unroll") for (int m = 0; m < 4; ++m) _Pragma("unroll") for (int n = 0; n < 2; ++n) _Pragma("unroll") for (int k = 0; k < 2; ++k) \
;         acc[ai][bj][m][n] = __builtin_amdgcn_mfma_f32_16x16x32_bf16(Bt[n][k], At[m][k], acc[ai][bj][m][n], 0, 0, 0); __builtin_amdgcn_s_setprio(0); } while (0)
; #define PG8_WAIT_V(n) asm volatile("s_waitcnt vmcnt(" #n ")" ::: "memory")
; #define PG8_WAIT_L(n) asm volatile("s_waitcnt lgkmcnt(" #n ")" ::: "memory")
; #define PG8_BAR __builtin_amdgcn_s_barrier()
; #define PG8_SCHED __builtin_amdgcn_sched_barrier(0)
; template <class Epi, class Sched, bool ALIGN_EPI = false, bool SP2 = false>
; __device__ __forceinline__ void gemm_phase(PG8_LAS unsigned char* lds, const Gemm g, const Sched& S, const Epi& E) {
;     ...
;             PG8_WAIT_V(8); PG8_WAIT_L(0); PG8_BAR; PG8_MMA(1, 0, At, B0); PG8_MMA(1, 1, At, B1); PG8_BAR; PG8_SCHED;
;             PG8_LDB(B0, 1, 0); PG8_LDB(B1, 1, 1); PG8_SCHED; PG8_LDA(At, 1, 0); PG8_STAGE(PG8_SA(0, 1), a2 + hstep, voffA);
;             PG8_WAIT_V(8); PG8_WAIT_L(0); PG8_BAR; PG8_MMA(0, 0, At, B0); PG8_MMA(0, 1, At, B1); PG8_BAR; PG8_SCHED;
	v_mfma_f32_16x16x32_bf16 v[60:63], v[154:157], v[186:189], 0
	v_mfma_f32_16x16x32_bf16 v[52:55], v[162:165], v[186:189], 0
	v_mfma_f32_16x16x32_bf16 v[44:47], v[154:157], v[198:201], 0
	v_mfma_f32_16x16x32_bf16 v[36:39], v[162:165], v[198:201], 0
	v_mfma_f32_16x16x32_bf16 v[28:31], v[154:157], v[206:209], 0
	v_mfma_f32_16x16x32_bf16 v[20:23], v[162:165], v[206:209], 0
	v_mfma_f32_16x16x32_bf16 v[12:15], v[154:157], v[214:217], 0
	v_mfma_f32_16x16x32_bf16 v[4:7], v[162:165], v[214:217], 0
	v_mfma_f32_16x16x32_bf16 v[60:63], v[158:161], v[190:193], v[60:63]
	v_mfma_f32_16x16x32_bf16 v[52:55], v[166:169], v[190:193], v[52:55]
	v_mfma_f32_16x16x32_bf16 v[44:47], v[158:161], v[202:205], v[44:47]
	v_mfma_f32_16x16x32_bf16 v[36:39], v[166:169], v[202:205], v[36:39]
	v_mfma_f32_16x16x32_bf16 v[28:31], v[158:161], v[210:213], v[28:31]
	v_mfma_f32_16x16x32_bf16 v[20:23], v[166:169], v[210:213], v[20:23]
	v_mfma_f32_16x16x32_bf16 v[12:15], v[158:161], v[218:221], v[12:15]
	v_mfma_f32_16x16x32_bf16 v[4:7], v[166:169], v[218:221], v[4:7]
	v_mfma_f32_16x16x32_bf16 v[56:59], v[170:173], v[186:189], 0
	v_mfma_f32_16x16x32_bf16 v[48:51], v[178:181], v[186:189], 0
	v_mfma_f32_16x16x32_bf16 v[40:43], v[170:173], v[198:201], 0
	v_mfma_f32_16x16x32_bf16 v[32:35], v[178:181], v[198:201], 0
	v_mfma_f32_16x16x32_bf16 v[24:27], v[170:173], v[206:209], 0
	v_mfma_f32_16x16x32_bf16 v[16:19], v[178:181], v[206:209], 0
	v_mfma_f32_16x16x32_bf16 v[8:11], v[170:173], v[214:217], 0
	v_mfma_f32_16x16x32_bf16 v[0:3], v[178:181], v[214:217], 0
	v_mfma_f32_16x16x32_bf16 v[56:59], v[174:177], v[190:193], v[56:59]
	v_mfma_f32_16x16x32_bf16 v[48:51], v[182:185], v[190:193], v[48:51]
	v_mfma_f32_16x16x32_bf16 v[40:43], v[174:177], v[202:205], v[40:43]
	v_mfma_f32_16x16x32_bf16 v[32:35], v[182:185], v[202:205], v[32:35]
	v_mfma_f32_16x16x32_bf16 v[24:27], v[174:177], v[210:213], v[24:27]
	v_mfma_f32_16x16x32_bf16 v[16:19], v[182:185], v[210:213], v[16:19]
	v_mfma_f32_16x16x32_bf16 v[8:11], v[174:177], v[218:221], v[8:11]
	v_mfma_f32_16x16x32_bf16 v[0:3], v[182:185], v[218:221], v[0:3]
	s_barrier
	s_add_i32 s73, 0, 0x18000
	v_add_u32_e32 v153, s73, v147
	s_add_i32 s74, 0, 0x1c000
	ds_read_b128 v[154:157], v153
	ds_read_b128 v[158:161], v153 offset:1024
	ds_read_b128 v[162:165], v153 offset:2048
	ds_read_b128 v[166:169], v153 offset:3072
	v_add_u32_e32 v153, s74, v147
	ds_read_b128 v[170:173], v153
	ds_read_b128 v[174:177], v153 offset:1024
	ds_read_b128 v[178:181], v153 offset:2048
	ds_read_b128 v[182:185], v153 offset:3072
	s_add_u32 s46, s46, 0x40000
	s_addc_u32 s47, s47, 0
	s_mov_b32 m0, s58
	ds_read_b128 v[186:189], v152 offset:32768
	ds_read_b128 v[190:193], v152 offset:33792
	ds_read_b128 v[198:201], v152 offset:34816
	ds_read_b128 v[202:205], v152 offset:35840
	ds_read_b128 v[206:209], v152 offset:36864
	ds_read_b128 v[210:213], v152 offset:37888
	ds_read_b128 v[214:217], v152 offset:38912
	ds_read_b128 v[218:221], v152 offset:39936
	global_load_lds_dwordx4 v134, s[46:47]
	s_mov_b32 m0, s59
	s_nop 0
	global_load_lds_dwordx4 v130, s[46:47]
	s_waitcnt vmcnt(8)
	s_waitcnt lgkmcnt(0)
	s_barrier
	v_mfma_f32_16x16x32_bf16 v[124:127], v[154:157], v[186:189], v[124:127]
	v_mfma_f32_16x16x32_bf16 v[116:119], v[162:165], v[186:189], v[116:119]
	v_mfma_f32_16x16x32_bf16 v[108:111], v[154:157], v[198:201], v[108:111]
	v_mfma_f32_16x16x32_bf16 v[100:103], v[162:165], v[198:201], v[100:103]
	v_mfma_f32_16x16x32_bf16 v[92:95], v[154:157], v[206:209], v[92:95]
	v_mfma_f32_16x16x32_bf16 v[84:87], v[162:165], v[206:209], v[84:87]
	v_mfma_f32_16x16x32_bf16 v[76:79], v[154:157], v[214:217], v[76:79]
	v_mfma_f32_16x16x32_bf16 v[68:71], v[162:165], v[214:217], v[68:71]
	v_mfma_f32_16x16x32_bf16 v[124:127], v[158:161], v[190:193], v[124:127]
	v_mfma_f32_16x16x32_bf16 v[116:119], v[166:169], v[190:193], v[116:119]
	v_mfma_f32_16x16x32_bf16 v[108:111], v[158:161], v[202:205], v[108:111]
	v_mfma_f32_16x16x32_bf16 v[100:103], v[166:169], v[202:205], v[100:103]
	v_mfma_f32_16x16x32_bf16 v[92:95], v[158:161], v[210:213], v[92:95]
	v_mfma_f32_16x16x32_bf16 v[84:87], v[166:169], v[210:213], v[84:87]
	v_mfma_f32_16x16x32_bf16 v[76:79], v[158:161], v[218:221], v[76:79]
	v_mfma_f32_16x16x32_bf16 v[68:71], v[166:169], v[218:221], v[68:71]
	v_mfma_f32_16x16x32_bf16 v[120:123], v[170:173], v[186:189], v[120:123]
	v_mfma_f32_16x16x32_bf16 v[112:115], v[178:181], v[186:189], v[112:115]
	v_mfma_f32_16x16x32_bf16 v[104:107], v[170:173], v[198:201], v[104:107]
	v_mfma_f32_16x16x32_bf16 v[96:99], v[178:181], v[198:201], v[96:99]
	v_mfma_f32_16x16x32_bf16 v[88:91], v[170:173], v[206:209], v[88:91]
	v_mfma_f32_16x16x32_bf16 v[80:83], v[178:181], v[206:209], v[80:83]
	v_mfma_f32_16x16x32_bf16 v[72:75], v[170:173], v[214:217], v[72:75]
	v_mfma_f32_16x16x32_bf16 v[64:67], v[178:181], v[214:217], v[64:67]
	v_mfma_f32_16x16x32_bf16 v[120:123], v[174:177], v[190:193], v[120:123]
	v_mfma_f32_16x16x32_bf16 v[112:115], v[182:185], v[190:193], v[112:115]
	v_mfma_f32_16x16x32_bf16 v[104:107], v[174:177], v[202:205], v[104:107]
	v_mfma_f32_16x16x32_bf16 v[96:99], v[182:185], v[202:205], v[96:99]
	v_mfma_f32_16x16x32_bf16 v[88:91], v[174:177], v[210:213], v[88:91]
	v_mfma_f32_16x16x32_bf16 v[80:83], v[182:185], v[210:213], v[80:83]
	v_mfma_f32_16x16x32_bf16 v[72:75], v[174:177], v[218:221], v[72:75]
	v_mfma_f32_16x16x32_bf16 v[64:67], v[182:185], v[218:221], v[64:67]
	s_barrier
; #define PG8_STAGE(bufoff, gbase, voff) do { _Pragma("unroll") for (int _i = 0; _i < 2; ++_i) \
;         __builtin_amdgcn_global_load_lds((const unsigned*)((const char*)(gbase) + (voff)[_i]), (PG8_LAS unsigned*)(lds + (bufoff) + ldsw + _i * 8192), 16, 0, 0); } while (0)
; #define PG8_LDA(dst, b, h) do { _Pragma("unroll") for (int m = 0; m < 4; ++m) _Pragma("unroll") for (int k = 0; k < 2; ++k) dst[m][k] = *(const PG8_LAS bf16x8*)(lds + PG8_SA(b, h) + aoff + m * 2048 + k * 1024); } while (0)
; #define PG8_LDB(dst, b, h) do { _Pragma("unroll") for (int n = 0; n < 2; ++n) _Pragma("unroll") for (int k = 0; k < 2; ++k) dst[n][k] = *(const PG8_LAS bf16x8*)(lds + PG8_SB(b, h) + boff + n * 2048 + k * 1024); } while (0)
; #define PG8_MMA(ai, bj, At, Bt) do { __builtin_amdgcn_s_setprio(1); _Pragma("unroll") for (int m = 0; m < 4; ++m) _Pragma("unroll") for (int n = 0; n < 2; ++n) _Pragma("unroll") for (int k = 0; k < 2; ++k) \
;         acc[ai][bj][m][n] = __builtin_amdgcn_mfma_f32_16x16x32_bf16(Bt[n][k], At[m][k], acc[ai][bj][m][n], 0, 0, 0); __builtin_amdgcn_s_setprio(0); } while (0)
; #define PG8_WAIT_V(n) asm volatile("s_waitcnt vmcnt(" #n ")" ::: "memory")
; template <class Epi, class Sched, bool ALIGN_EPI = false, bool SP2 = false>
; __device__ __forceinline__ void gemm_phase(PG8_LAS unsigned char* lds, const Gemm g, const Sched& S, const Epi& E) {
;     ...
;             PG8_LDB(B0, 0, 0); PG8_LDB(B1, 0, 1); PG8_SCHED; PG8_LDA(At, 0, 0); PG8_STAGE(PG8_SA(1, 1), a1 + hstep, voffA);
;             PG8_WAIT_V(8); PG8_WAIT_L(0); PG8_BAR; PG8_MMA(0, 0, At, B0); PG8_MMA(0, 1, At, B1); PG8_BAR; PG8_SCHED;
;             PG8_LDA(At, 0, 1); PG8_STAGE(PG8_SB(0, 0), b2, voffB); PG8_STAGE(PG8_SB(0, 1), b2 + hstep, voffB); PG8_STAGE(PG8_SA(0, 0), a2, voffA);
;             PG8_WAIT_V(8); PG8_WAIT_L(0); PG8_BAR; PG8_MMA(1, 0, At, B0); PG8_MMA(1, 1, At, B1); PG8_BAR; PG8_SCHED;
;             PG8_LDB(B0, 1, 0); PG8_LDB(B1, 1, 1); PG8_SCHED; PG8_LDA(At, 1, 0); PG8_STAGE(PG8_SA(0, 1), a2 + hstep, voffA);
;             PG8_WAIT_V(8); PG8_WAIT_L(0); PG8_BAR; PG8_MMA(0, 0, At, B0); PG8_MMA(0, 1, At, B1); PG8_BAR; PG8_SCHED;
;             PG8_LDA(At, 1, 1); PG8_STAGE(PG8_SB(1, 0), b3, voffB); PG8_STAGE(PG8_SB(1, 1), b3 + hstep, voffB); PG8_STAGE(PG8_SA(1, 0), a3, voffA);
;             PG8_WAIT_V(8); PG8_WAIT_L(0); PG8_BAR; PG8_MMA(1, 0, At, B0); PG8_MMA(1, 1, At, B1); PG8_BAR; PG8_SCHED;
	s_add_i32 s46, s73, s55
	s_mov_b32 m0, s46
	ds_read_b128 v[186:189], v152 offset:49152
	ds_read_b128 v[190:193], v152 offset:50176
	ds_read_b128 v[198:201], v152 offset:51200
	ds_read_b128 v[202:205], v152 offset:52224
	ds_read_b128 v[206:209], v152 offset:53248
	ds_read_b128 v[210:213], v152 offset:54272
	ds_read_b128 v[214:217], v152 offset:55296
	ds_read_b128 v[218:221], v152 offset:56320
	global_load_lds_dwordx4 v132, s[98:99]
	s_add_i32 m0, s46, 0x2000
	s_add_u32 s42, s42, 0x40080
	s_addc_u32 s43, s43, 0
	s_add_i32 s46, s74, s55
	global_load_lds_dwordx4 v128, s[98:99]
	s_mov_b32 m0, s46
	s_nop 0
	global_load_lds_dwordx4 v132, s[42:43]
	s_add_i32 m0, s46, 0x2000
	s_nop 0
	global_load_lds_dwordx4 v128, s[42:43]
	s_mov_b32 m0, s61
	s_nop 0
	global_load_lds_dwordx4 v134, s[100:101]
	s_mov_b32 m0, s62
	s_nop 0
	global_load_lds_dwordx4 v130, s[100:101]
	s_nop 0
	s_waitcnt vmcnt(8)
	s_waitcnt lgkmcnt(0)
	s_barrier
	v_mfma_f32_16x16x32_bf16 v[60:63], v[154:157], v[186:189], v[60:63]
	v_mfma_f32_16x16x32_bf16 v[52:55], v[162:165], v[186:189], v[52:55]
	v_mfma_f32_16x16x32_bf16 v[44:47], v[154:157], v[198:201], v[44:47]
	v_mfma_f32_16x16x32_bf16 v[36:39], v[162:165], v[198:201], v[36:39]
	v_mfma_f32_16x16x32_bf16 v[28:31], v[154:157], v[206:209], v[28:31]
	v_mfma_f32_16x16x32_bf16 v[20:23], v[162:165], v[206:209], v[20:23]
	v_mfma_f32_16x16x32_bf16 v[12:15], v[154:157], v[214:217], v[12:15]
	v_mfma_f32_16x16x32_bf16 v[4:7], v[162:165], v[214:217], v[4:7]
	v_mfma_f32_16x16x32_bf16 v[60:63], v[158:161], v[190:193], v[60:63]
	v_mfma_f32_16x16x32_bf16 v[52:55], v[166:169], v[190:193], v[52:55]
	v_mfma_f32_16x16x32_bf16 v[44:47], v[158:161], v[202:205], v[44:47]
	v_mfma_f32_16x16x32_bf16 v[36:39], v[166:169], v[202:205], v[36:39]
	v_mfma_f32_16x16x32_bf16 v[28:31], v[158:161], v[210:213], v[28:31]
	v_mfma_f32_16x16x32_bf16 v[20:23], v[166:169], v[210:213], v[20:23]
	v_mfma_f32_16x16x32_bf16 v[12:15], v[158:161], v[218:221], v[12:15]
	v_mfma_f32_16x16x32_bf16 v[4:7], v[166:169], v[218:221], v[4:7]
	v_mfma_f32_16x16x32_bf16 v[56:59], v[170:173], v[186:189], v[56:59]
	v_mfma_f32_16x16x32_bf16 v[48:51], v[178:181], v[186:189], v[48:51]
	v_mfma_f32_16x16x32_bf16 v[40:43], v[170:173], v[198:201], v[40:43]
	v_mfma_f32_16x16x32_bf16 v[32:35], v[178:181], v[198:201], v[32:35]
	v_mfma_f32_16x16x32_bf16 v[24:27], v[170:173], v[206:209], v[24:27]
	v_mfma_f32_16x16x32_bf16 v[16:19], v[178:181], v[206:209], v[16:19]
	v_mfma_f32_16x16x32_bf16 v[8:11], v[170:173], v[214:217], v[8:11]
	v_mfma_f32_16x16x32_bf16 v[0:3], v[178:181], v[214:217], v[0:3]
	v_mfma_f32_16x16x32_bf16 v[56:59], v[174:177], v[190:193], v[56:59]
	v_mfma_f32_16x16x32_bf16 v[48:51], v[182:185], v[190:193], v[48:51]
	v_mfma_f32_16x16x32_bf16 v[40:43], v[174:177], v[202:205], v[40:43]
	v_mfma_f32_16x16x32_bf16 v[32:35], v[182:185], v[202:205], v[32:35]
	v_mfma_f32_16x16x32_bf16 v[24:27], v[174:177], v[210:213], v[24:27]
	v_mfma_f32_16x16x32_bf16 v[16:19], v[182:185], v[210:213], v[16:19]
	v_mfma_f32_16x16x32_bf16 v[8:11], v[174:177], v[218:221], v[8:11]
	v_mfma_f32_16x16x32_bf16 v[0:3], v[182:185], v[218:221], v[0:3]
	s_barrier
	s_add_i32 s72, s72, 2
	s_add_u32 s20, s20, 0x100
	s_addc_u32 s21, s21, 0
	s_add_u32 s70, s70, 0x100
	s_addc_u32 s71, s71, 0
	s_cmp_gt_u32 s72, 13
.LBB0_224:
	ds_read_b128 v[154:157], v150
	ds_read_b128 v[158:161], v150 offset:1024
	ds_read_b128 v[162:165], v150 offset:2048
	ds_read_b128 v[166:169], v150 offset:3072
	ds_read_b128 v[170:173], v151
	ds_read_b128 v[174:177], v151 offset:1024
	ds_read_b128 v[178:181], v151 offset:2048
	ds_read_b128 v[182:185], v151 offset:3072
	s_add_u32 s42, s20, 0xfffc0080
	s_addc_u32 s43, s21, -1
	s_cmp_eq_u32 s72, 12
	s_cselect_b32 s47, s15, s43
	s_cselect_b32 s46, s68, s42
	s_cselect_b32 s43, s13, s71
	s_cselect_b32 s42, s69, s70
	s_add_i32 m0, s35, 0xc000
	ds_read_b128 v[186:189], v152
	ds_read_b128 v[190:193], v152 offset:1024
	ds_read_b128 v[198:201], v152 offset:2048
	ds_read_b128 v[202:205], v152 offset:3072
	ds_read_b128 v[206:209], v152 offset:4096
	ds_read_b128 v[210:213], v152 offset:5120
	ds_read_b128 v[214:217], v152 offset:6144
	ds_read_b128 v[218:221], v152 offset:7168
	global_load_lds_dwordx4 v136, s[20:21]
	s_add_i32 m0, s35, 0xe000
	s_nop 0
	global_load_lds_dwordx4 v138, s[20:21]
	s_nop 0
	s_waitcnt vmcnt(8)
	s_waitcnt lgkmcnt(0)
	s_barrier
	v_mfma_f32_16x16x32_bf16 v[124:127], v[154:157], v[186:189], v[124:127]
	v_mfma_f32_16x16x32_bf16 v[116:119], v[162:165], v[186:189], v[116:119]
	v_mfma_f32_16x16x32_bf16 v[108:111], v[154:157], v[198:201], v[108:111]
	v_mfma_f32_16x16x32_bf16 v[100:103], v[162:165], v[198:201], v[100:103]
	v_mfma_f32_16x16x32_bf16 v[92:95], v[154:157], v[206:209], v[92:95]
	v_mfma_f32_16x16x32_bf16 v[84:87], v[162:165], v[206:209], v[84:87]
	v_mfma_f32_16x16x32_bf16 v[76:79], v[154:157], v[214:217], v[76:79]
	v_mfma_f32_16x16x32_bf16 v[68:71], v[162:165], v[214:217], v[68:71]
	v_mfma_f32_16x16x32_bf16 v[124:127], v[158:161], v[190:193], v[124:127]
	v_mfma_f32_16x16x32_bf16 v[116:119], v[166:169], v[190:193], v[116:119]
	v_mfma_f32_16x16x32_bf16 v[108:111], v[158:161], v[202:205], v[108:111]
	v_mfma_f32_16x16x32_bf16 v[100:103], v[166:169], v[202:205], v[100:103]
	v_mfma_f32_16x16x32_bf16 v[92:95], v[158:161], v[210:213], v[92:95]
	v_mfma_f32_16x16x32_bf16 v[84:87], v[166:169], v[210:213], v[84:87]
	v_mfma_f32_16x16x32_bf16 v[76:79], v[158:161], v[218:221], v[76:79]
	v_mfma_f32_16x16x32_bf16 v[68:71], v[166:169], v[218:221], v[68:71]
	v_mfma_f32_16x16x32_bf16 v[120:123], v[170:173], v[186:189], v[120:123]
	v_mfma_f32_16x16x32_bf16 v[112:115], v[178:181], v[186:189], v[112:115]
	v_mfma_f32_16x16x32_bf16 v[104:107], v[170:173], v[198:201], v[104:107]
	v_mfma_f32_16x16x32_bf16 v[96:99], v[178:181], v[198:201], v[96:99]
	v_mfma_f32_16x16x32_bf16 v[88:91], v[170:173], v[206:209], v[88:91]
	v_mfma_f32_16x16x32_bf16 v[80:83], v[178:181], v[206:209], v[80:83]
	v_mfma_f32_16x16x32_bf16 v[72:75], v[170:173], v[214:217], v[72:75]
	v_mfma_f32_16x16x32_bf16 v[64:67], v[178:181], v[214:217], v[64:67]
	v_mfma_f32_16x16x32_bf16 v[120:123], v[174:177], v[190:193], v[120:123]
	v_mfma_f32_16x16x32_bf16 v[112:115], v[182:185], v[190:193], v[112:115]
	v_mfma_f32_16x16x32_bf16 v[104:107], v[174:177], v[202:205], v[104:107]
	v_mfma_f32_16x16x32_bf16 v[96:99], v[182:185], v[202:205], v[96:99]
	v_mfma_f32_16x16x32_bf16 v[88:91], v[174:177], v[210:213], v[88:91]
	v_mfma_f32_16x16x32_bf16 v[80:83], v[182:185], v[210:213], v[80:83]
	v_mfma_f32_16x16x32_bf16 v[72:75], v[174:177], v[218:221], v[72:75]
	v_mfma_f32_16x16x32_bf16 v[64:67], v[182:185], v[218:221], v[64:67]
	s_barrier
; #define PG8_STAGE(bufoff, gbase, voff) do { _Pragma("unroll") for (int _i = 0; _i < 2; ++_i) \
;         __builtin_amdgcn_global_load_lds((const unsigned*)((const char*)(gbase) + (voff)[_i]), (PG8_LAS unsigned*)(lds + (bufoff) + ldsw + _i * 8192), 16, 0, 0); } while (0)
; #define PG8_LDA(dst, b, h) do { _Pragma("unroll") for (int m = 0; m < 4; ++m) _Pragma("unroll") for (int k = 0; k < 2; ++k) dst[m][k] = *(const PG8_LAS bf16x8*)(lds + PG8_SA(b, h) + aoff + m * 2048 + k * 1024); } while (0)
; #define PG8_LDB(dst, b, h) do { _Pragma("unroll") for (int n = 0; n < 2; ++n) _Pragma("unroll") for (int k = 0; k < 2; ++k) dst[n][k] = *(const PG8_LAS bf16x8*)(lds + PG8_SB(b, h) + boff + n * 2048 + k * 1024); } while (0)
; #define PG8_MMA(ai, bj, At, Bt) do { __builtin_amdgcn_s_setprio(1); _Pragma("unroll") for (int m = 0; m < 4; ++m) _Pragma("unroll") for (int n = 0; n < 2; ++n) _Pragma("unroll") for (int k = 0; k < 2; ++k) \
;         acc[ai][bj][m][n] = __builtin_amdgcn_mfma_f32_16x16x32_bf16(Bt[n][k], At[m][k], acc[ai][bj][m][n], 0, 0, 0); __builtin_amdgcn_s_setprio(0); } while (0)
; #define PG8_WAIT_V(n) asm volatile("s_waitcnt vmcnt(" #n ")" ::: "memory")
; #define PG8_WAIT_L(n) asm volatile("s_waitcnt lgkmcnt(" #n ")" ::: "memory")
; #define PG8_BAR __builtin_amdgcn_s_barrier()
; #define PG8_SCHED __builtin_amdgcn_sched_barrier(0)
; template <class Epi, class Sched, bool ALIGN_EPI = false, bool SP2 = false>
; __device__ __forceinline__ void gemm_phase(PG8_LAS unsigned char* lds, const Gemm g, const Sched& S, const Epi& E) {
;     ...
;             PG8_LDA(At, 0, 1); PG8_STAGE(PG8_SB(0, 0), b2, voffB); PG8_STAGE(PG8_SB(0, 1), b2 + hstep, voffB); PG8_STAGE(PG8_SA(0, 0), a2, voffA);
;             PG8_WAIT_V(8); PG8_WAIT_L(0); PG8_BAR; PG8_MMA(1, 0, At, B0); PG8_MMA(1, 1, At, B1); PG8_BAR; PG8_SCHED;
;             PG8_LDB(B0, 1, 0); PG8_LDB(B1, 1, 1); PG8_SCHED; PG8_LDA(At, 1, 0); PG8_STAGE(PG8_SA(0, 1), a2 + hstep, voffA);
;             PG8_WAIT_V(8); PG8_WAIT_L(0); PG8_BAR; PG8_MMA(0, 0, At, B0); PG8_MMA(0, 1, At, B1); PG8_BAR; PG8_SCHED;
	s_add_i32 s73, s63, s55
	s_add_u32 s98, s42, s8
	s_addc_u32 s99, s43, s9
	s_add_u32 s100, s46, s8
	s_addc_u32 s101, s47, s9
	s_mov_b32 m0, s73
	ds_read_b128 v[186:189], v152 offset:16384
	ds_read_b128 v[190:193], v152 offset:17408
	ds_read_b128 v[198:201], v152 offset:18432
	ds_read_b128 v[202:205], v152 offset:19456
	ds_read_b128 v[206:209], v152 offset:20480
	ds_read_b128 v[210:213], v152 offset:21504
	ds_read_b128 v[214:217], v152 offset:22528
	ds_read_b128 v[218:221], v152 offset:23552
	global_load_lds_dwordx4 v132, s[42:43]
	s_add_i32 m0, s73, 0x2000
	s_add_u32 s74, s42, 0x40000
	s_addc_u32 s75, s43, 0
	s_add_i32 s73, s64, s55
	global_load_lds_dwordx4 v128, s[42:43]
	s_mov_b32 m0, s73
	s_nop 0
	global_load_lds_dwordx4 v132, s[74:75]
	s_add_i32 m0, s73, 0x2000
	s_nop 0
	global_load_lds_dwordx4 v128, s[74:75]
	s_mov_b32 m0, s35
	s_nop 0
	global_load_lds_dwordx4 v134, s[46:47]
	s_mov_b32 m0, s57
	s_nop 0
	global_load_lds_dwordx4 v130, s[46:47]
	s_nop 0
	s_waitcnt vmcnt(8)
	s_waitcnt lgkmcnt(0)
	s_barrier
	v_mfma_f32_16x16x32_bf16 v[60:63], v[154:157], v[186:189], v[60:63]
	v_mfma_f32_16x16x32_bf16 v[52:55], v[162:165], v[186:189], v[52:55]
	v_mfma_f32_16x16x32_bf16 v[44:47], v[154:157], v[198:201], v[44:47]
	v_mfma_f32_16x16x32_bf16 v[36:39], v[162:165], v[198:201], v[36:39]
	v_mfma_f32_16x16x32_bf16 v[28:31], v[154:157], v[206:209], v[28:31]
	v_mfma_f32_16x16x32_bf16 v[20:23], v[162:165], v[206:209], v[20:23]
	v_mfma_f32_16x16x32_bf16 v[12:15], v[154:157], v[214:217], v[12:15]
	v_mfma_f32_16x16x32_bf16 v[4:7], v[162:165], v[214:217], v[4:7]
	v_mfma_f32_16x16x32_bf16 v[60:63], v[158:161], v[190:193], v[60:63]
	v_mfma_f32_16x16x32_bf16 v[52:55], v[166:169], v[190:193], v[52:55]
	v_mfma_f32_16x16x32_bf16 v[44:47], v[158:161], v[202:205], v[44:47]
	v_mfma_f32_16x16x32_bf16 v[36:39], v[166:169], v[202:205], v[36:39]
	v_mfma_f32_16x16x32_bf16 v[28:31], v[158:161], v[210:213], v[28:31]
	v_mfma_f32_16x16x32_bf16 v[20:23], v[166:169], v[210:213], v[20:23]
	v_mfma_f32_16x16x32_bf16 v[12:15], v[158:161], v[218:221], v[12:15]
	v_mfma_f32_16x16x32_bf16 v[4:7], v[166:169], v[218:221], v[4:7]
	v_mfma_f32_16x16x32_bf16 v[56:59], v[170:173], v[186:189], v[56:59]
	v_mfma_f32_16x16x32_bf16 v[48:51], v[178:181], v[186:189], v[48:51]
	v_mfma_f32_16x16x32_bf16 v[40:43], v[170:173], v[198:201], v[40:43]
	v_mfma_f32_16x16x32_bf16 v[32:35], v[178:181], v[198:201], v[32:35]
	v_mfma_f32_16x16x32_bf16 v[24:27], v[170:173], v[206:209], v[24:27]
	v_mfma_f32_16x16x32_bf16 v[16:19], v[178:181], v[206:209], v[16:19]
	v_mfma_f32_16x16x32_bf16 v[8:11], v[170:173], v[214:217], v[8:11]
	v_mfma_f32_16x16x32_bf16 v[0:3], v[178:181], v[214:217], v[0:3]
	v_mfma_f32_16x16x32_bf16 v[56:59], v[174:177], v[190:193], v[56:59]
	v_mfma_f32_16x16x32_bf16 v[48:51], v[182:185], v[190:193], v[48:51]
	v_mfma_f32_16x16x32_bf16 v[40:43], v[174:177], v[202:205], v[40:43]
	v_mfma_f32_16x16x32_bf16 v[32:35], v[182:185], v[202:205], v[32:35]
	v_mfma_f32_16x16x32_bf16 v[24:27], v[174:177], v[210:213], v[24:27]
	v_mfma_f32_16x16x32_bf16 v[16:19], v[182:185], v[210:213], v[16:19]
	v_mfma_f32_16x16x32_bf16 v[8:11], v[174:177], v[218:221], v[8:11]
	v_mfma_f32_16x16x32_bf16 v[0:3], v[182:185], v[218:221], v[0:3]
	s_barrier
	s_add_i32 s73, 0, 0x18000
	v_add_u32_e32 v153, s73, v147
	s_add_i32 s74, 0, 0x1c000
	ds_read_b128 v[154:157], v153
	ds_read_b128 v[158:161], v153 offset:1024
	ds_read_b128 v[162:165], v153 offset:2048
	ds_read_b128 v[166:169], v153 offset:3072
	v_add_u32_e32 v153, s74, v147
	ds_read_b128 v[170:173], v153
	ds_read_b128 v[174:177], v153 offset:1024
	ds_read_b128 v[178:181], v153 offset:2048
	ds_read_b128 v[182:185], v153 offset:3072
	s_add_u32 s46, s46, 0x40000
	s_addc_u32 s47, s47, 0
	s_mov_b32 m0, s58
	ds_read_b128 v[186:189], v152 offset:32768
	ds_read_b128 v[190:193], v152 offset:33792
	ds_read_b128 v[198:201], v152 offset:34816
	ds_read_b128 v[202:205], v152 offset:35840
	ds_read_b128 v[206:209], v152 offset:36864
	ds_read_b128 v[210:213], v152 offset:37888
	ds_read_b128 v[214:217], v152 offset:38912
	ds_read_b128 v[218:221], v152 offset:39936
	global_load_lds_dwordx4 v134, s[46:47]
	s_mov_b32 m0, s59
	s_nop 0
	global_load_lds_dwordx4 v130, s[46:47]
	s_waitcnt vmcnt(8)
	s_waitcnt lgkmcnt(0)
	s_barrier
; #define PG8_STAGE(bufoff, gbase, voff) do { _Pragma("unroll") for (int _i = 0; _i < 2; ++_i) \
;         __builtin_amdgcn_global_load_lds((const unsigned*)((const char*)(gbase) + (voff)[_i]), (PG8_LAS unsigned*)(lds + (bufoff) + ldsw + _i * 8192), 16, 0, 0); } while (0)
; #define PG8_LDA(dst, b, h) do { _Pragma("unroll") for (int m = 0; m < 4; ++m) _Pragma("unroll") for (int k = 0; k < 2; ++k) dst[m][k] = *(const PG8_LAS bf16x8*)(lds + PG8_SA(b, h) + aoff + m * 2048 + k * 1024); } while (0)
; #define PG8_MMA(ai, bj, At, Bt) do { __builtin_amdgcn_s_setprio(1); _Pragma("unroll") for (int m = 0; m < 4; ++m) _Pragma("unroll") for (int n = 0; n < 2; ++n) _Pragma("unroll") for (int k = 0; k < 2; ++k) \
;         acc[ai][bj][m][n] = __builtin_amdgcn_mfma_f32_16x16x32_bf16(Bt[n][k], At[m][k], acc[ai][bj][m][n], 0, 0, 0); __builtin_amdgcn_s_setprio(0); } while (0)
; #define PG8_WAIT_V(n) asm volatile("s_waitcnt vmcnt(" #n ")" ::: "memory")
; #define PG8_WAIT_L(n) asm volatile("s_waitcnt lgkmcnt(" #n ")" ::: "memory")
; #define PG8_BAR __builtin_amdgcn_s_barrier()
; #define PG8_SCHED __builtin_amdgcn_sched_barrier(0)
; template <class Epi, class Sched, bool ALIGN_EPI = false, bool SP2 = false>
; __device__ __forceinline__ void gemm_phase(PG8_LAS unsigned char* lds, const Gemm g, const Sched& S, const Epi& E) {
;     ...
;             PG8_WAIT_V(8); PG8_WAIT_L(0); PG8_BAR; PG8_MMA(0, 0, At, B0); PG8_MMA(0, 1, At, B1); PG8_BAR; PG8_SCHED;
;             PG8_LDA(At, 1, 1); PG8_STAGE(PG8_SB(1, 0), b3, voffB); PG8_STAGE(PG8_SB(1, 1), b3 + hstep, voffB); PG8_STAGE(PG8_SA(1, 0), a3, voffA);
;             PG8_WAIT_V(8); PG8_WAIT_L(0); PG8_BAR; PG8_MMA(1, 0, At, B0); PG8_MMA(1, 1, At, B1); PG8_BAR; PG8_SCHED;
;     ...
;         if constexpr (ALIGN_EPI) { if (wr == 0) PG8_BAR; }
	v_mfma_f32_16x16x32_bf16 v[124:127], v[154:157], v[186:189], v[124:127]
	v_mfma_f32_16x16x32_bf16 v[116:119], v[162:165], v[186:189], v[116:119]
	v_mfma_f32_16x16x32_bf16 v[108:111], v[154:157], v[198:201], v[108:111]
	v_mfma_f32_16x16x32_bf16 v[100:103], v[162:165], v[198:201], v[100:103]
	v_mfma_f32_16x16x32_bf16 v[92:95], v[154:157], v[206:209], v[92:95]
	v_mfma_f32_16x16x32_bf16 v[84:87], v[162:165], v[206:209], v[84:87]
	v_mfma_f32_16x16x32_bf16 v[76:79], v[154:157], v[214:217], v[76:79]
	v_mfma_f32_16x16x32_bf16 v[68:71], v[162:165], v[214:217], v[68:71]
	v_mfma_f32_16x16x32_bf16 v[124:127], v[158:161], v[190:193], v[124:127]
	v_mfma_f32_16x16x32_bf16 v[116:119], v[166:169], v[190:193], v[116:119]
	v_mfma_f32_16x16x32_bf16 v[108:111], v[158:161], v[202:205], v[108:111]
	v_mfma_f32_16x16x32_bf16 v[100:103], v[166:169], v[202:205], v[100:103]
	v_mfma_f32_16x16x32_bf16 v[92:95], v[158:161], v[210:213], v[92:95]
	v_mfma_f32_16x16x32_bf16 v[84:87], v[166:169], v[210:213], v[84:87]
	v_mfma_f32_16x16x32_bf16 v[76:79], v[158:161], v[218:221], v[76:79]
	v_mfma_f32_16x16x32_bf16 v[68:71], v[166:169], v[218:221], v[68:71]
	v_mfma_f32_16x16x32_bf16 v[120:123], v[170:173], v[186:189], v[120:123]
	v_mfma_f32_16x16x32_bf16 v[112:115], v[178:181], v[186:189], v[112:115]
	v_mfma_f32_16x16x32_bf16 v[104:107], v[170:173], v[198:201], v[104:107]
	v_mfma_f32_16x16x32_bf16 v[96:99], v[178:181], v[198:201], v[96:99]
	v_mfma_f32_16x16x32_bf16 v[88:91], v[170:173], v[206:209], v[88:91]
	v_mfma_f32_16x16x32_bf16 v[80:83], v[178:181], v[206:209], v[80:83]
	v_mfma_f32_16x16x32_bf16 v[72:75], v[170:173], v[214:217], v[72:75]
	v_mfma_f32_16x16x32_bf16 v[64:67], v[178:181], v[214:217], v[64:67]
	v_mfma_f32_16x16x32_bf16 v[120:123], v[174:177], v[190:193], v[120:123]
	v_mfma_f32_16x16x32_bf16 v[112:115], v[182:185], v[190:193], v[112:115]
	v_mfma_f32_16x16x32_bf16 v[104:107], v[174:177], v[202:205], v[104:107]
	v_mfma_f32_16x16x32_bf16 v[96:99], v[182:185], v[202:205], v[96:99]
	v_mfma_f32_16x16x32_bf16 v[88:91], v[174:177], v[210:213], v[88:91]
	v_mfma_f32_16x16x32_bf16 v[80:83], v[182:185], v[210:213], v[80:83]
	v_mfma_f32_16x16x32_bf16 v[72:75], v[174:177], v[218:221], v[72:75]
	v_mfma_f32_16x16x32_bf16 v[64:67], v[182:185], v[218:221], v[64:67]
	s_barrier
	s_add_i32 s46, s73, s55
	s_mov_b32 m0, s46
	ds_read_b128 v[186:189], v152 offset:49152
	ds_read_b128 v[190:193], v152 offset:50176
	ds_read_b128 v[198:201], v152 offset:51200
	ds_read_b128 v[202:205], v152 offset:52224
	ds_read_b128 v[206:209], v152 offset:53248
	ds_read_b128 v[210:213], v152 offset:54272
	ds_read_b128 v[214:217], v152 offset:55296
	ds_read_b128 v[218:221], v152 offset:56320
	global_load_lds_dwordx4 v132, s[98:99]
	s_add_i32 m0, s46, 0x2000
	s_add_u32 s42, s42, 0x40080
	s_addc_u32 s43, s43, 0
	s_add_i32 s46, s74, s55
	global_load_lds_dwordx4 v128, s[98:99]
	s_mov_b32 m0, s46
	s_nop 0
	global_load_lds_dwordx4 v132, s[42:43]
	s_add_i32 m0, s46, 0x2000
	s_nop 0
	global_load_lds_dwordx4 v128, s[42:43]
	s_mov_b32 m0, s61
	s_nop 0
	global_load_lds_dwordx4 v134, s[100:101]
	s_mov_b32 m0, s62
	s_nop 0
	global_load_lds_dwordx4 v130, s[100:101]
	s_nop 0
	s_waitcnt vmcnt(8)
	s_waitcnt lgkmcnt(0)
	s_barrier
	v_mfma_f32_16x16x32_bf16 v[60:63], v[154:157], v[186:189], v[60:63]
	v_mfma_f32_16x16x32_bf16 v[52:55], v[162:165], v[186:189], v[52:55]
	v_mfma_f32_16x16x32_bf16 v[44:47], v[154:157], v[198:201], v[44:47]
	v_mfma_f32_16x16x32_bf16 v[36:39], v[162:165], v[198:201], v[36:39]
	v_mfma_f32_16x16x32_bf16 v[28:31], v[154:157], v[206:209], v[28:31]
	v_mfma_f32_16x16x32_bf16 v[20:23], v[162:165], v[206:209], v[20:23]
	v_mfma_f32_16x16x32_bf16 v[12:15], v[154:157], v[214:217], v[12:15]
	v_mfma_f32_16x16x32_bf16 v[4:7], v[162:165], v[214:217], v[4:7]
	v_mfma_f32_16x16x32_bf16 v[60:63], v[158:161], v[190:193], v[60:63]
	v_mfma_f32_16x16x32_bf16 v[52:55], v[166:169], v[190:193], v[52:55]
	v_mfma_f32_16x16x32_bf16 v[44:47], v[158:161], v[202:205], v[44:47]
	v_mfma_f32_16x16x32_bf16 v[36:39], v[166:169], v[202:205], v[36:39]
	v_mfma_f32_16x16x32_bf16 v[28:31], v[158:161], v[210:213], v[28:31]
	v_mfma_f32_16x16x32_bf16 v[20:23], v[166:169], v[210:213], v[20:23]
	v_mfma_f32_16x16x32_bf16 v[12:15], v[158:161], v[218:221], v[12:15]
	v_mfma_f32_16x16x32_bf16 v[4:7], v[166:169], v[218:221], v[4:7]
	v_mfma_f32_16x16x32_bf16 v[56:59], v[170:173], v[186:189], v[56:59]
	v_mfma_f32_16x16x32_bf16 v[48:51], v[178:181], v[186:189], v[48:51]
	v_mfma_f32_16x16x32_bf16 v[40:43], v[170:173], v[198:201], v[40:43]
	v_mfma_f32_16x16x32_bf16 v[32:35], v[178:181], v[198:201], v[32:35]
	v_mfma_f32_16x16x32_bf16 v[24:27], v[170:173], v[206:209], v[24:27]
	v_mfma_f32_16x16x32_bf16 v[16:19], v[178:181], v[206:209], v[16:19]
	v_mfma_f32_16x16x32_bf16 v[8:11], v[170:173], v[214:217], v[8:11]
	v_mfma_f32_16x16x32_bf16 v[0:3], v[178:181], v[214:217], v[0:3]
	v_mfma_f32_16x16x32_bf16 v[56:59], v[174:177], v[190:193], v[56:59]
	v_mfma_f32_16x16x32_bf16 v[48:51], v[182:185], v[190:193], v[48:51]
	v_mfma_f32_16x16x32_bf16 v[40:43], v[174:177], v[202:205], v[40:43]
	v_mfma_f32_16x16x32_bf16 v[32:35], v[182:185], v[202:205], v[32:35]
	v_mfma_f32_16x16x32_bf16 v[24:27], v[174:177], v[210:213], v[24:27]
	v_mfma_f32_16x16x32_bf16 v[16:19], v[182:185], v[210:213], v[16:19]
	v_mfma_f32_16x16x32_bf16 v[8:11], v[174:177], v[218:221], v[8:11]
	v_mfma_f32_16x16x32_bf16 v[0:3], v[182:185], v[218:221], v[0:3]
	s_barrier
	s_add_i32 s72, s72, 2
	s_add_u32 s20, s20, 0x100
	s_addc_u32 s21, s21, 0
	s_add_u32 s70, s70, 0x100
	s_addc_u32 s71, s71, 0
	s_cmp_gt_u32 s72, 13
	s_cbranch_scc0 .LBB0_224
	s_and_b64 vcc, exec, s[10:11]
	s_cbranch_vccz .LBB0_227
	s_barrier

; #define PG8_STAGE(bufoff, gbase, voff) do { _Pragma("unroll") for (int _i = 0; _i < 2; ++_i) \
;         __builtin_amdgcn_global_load_lds((const unsigned*)((const char*)(gbase) + (voff)[_i]), (PG8_LAS unsigned*)(lds + (bufoff) + ldsw + _i * 8192), 16, 0, 0); } while (0)
; #define PG8_LDA(dst, b, h) do { _Pragma("unroll") for (int m = 0; m < 4; ++m) _Pragma("unroll") for (int k = 0; k < 2; ++k) dst[m][k] = *(const PG8_LAS bf16x8*)(lds + PG8_SA(b, h) + aoff + m * 2048 + k * 1024); } while (0)
; #define PG8_LDB(dst, b, h) do { _Pragma("unroll") for (int n = 0; n < 2; ++n) _Pragma("unroll") for (int k = 0; k < 2; ++k) dst[n][k] = *(const PG8_LAS bf16x8*)(lds + PG8_SB(b, h) + boff + n * 2048 + k * 1024); } while (0)
; #define PG8_MMA(ai, bj, At, Bt) do { __builtin_amdgcn_s_setprio(1); _Pragma("unroll") for (int m = 0; m < 4; ++m) _Pragma("unroll") for (int n = 0; n < 2; ++n) _Pragma("unroll") for (int k = 0; k < 2; ++k) \
;         acc[ai][bj][m][n] = __builtin_amdgcn_mfma_f32_16x16x32_bf16(Bt[n][k], At[m][k], acc[ai][bj][m][n], 0, 0, 0); __builtin_amdgcn_s_setprio(0); } while (0)
; #define PG8_WAIT_V(n) asm volatile("s_waitcnt vmcnt(" #n ")" ::: "memory")
; #define PG8_WAIT_L(n) asm volatile("s_waitcnt lgkmcnt(" #n ")" ::: "memory")
; #define PG8_BAR __builtin_amdgcn_s_barrier()
; template <class Epi, class Sched, bool ALIGN_EPI = false, bool SP2 = false>
; __device__ __forceinline__ void gemm_phase(PG8_LAS unsigned char* lds, const Gemm g, const Sched& S, const Epi& E) {
;     ...
;             const char* a1 = cA + (size_t)(t + 1) * kstep;
;             const char* a2 = last ? nA : cA + (size_t)(t + 2) * kstep; const char* b2 = last ? nB : cB + (size_t)(t + 2) * kstep;
;             const char* a3 = a2 + kstep; const char* b3 = b2 + kstep;
;             if (last && has_next) S.a_ready(nxt);
;             if constexpr (SP2) {
;             PG8_LDB(B0, 0, 0); PG8_LDB(B1, 0, 1); PG8_SCHED; PG8_LDA(At, 0, 0); PG8_STAGE(PG8_SA(1, 1), a1 + hstep, voffA);
;             PG8_WAIT_V(8); PG8_WAIT_L(0); PG8_BAR; PG8_MMA(0, 0, At, B0); PG8_MMA(0, 1, At, B1); PG8_BAR; PG8_SCHED;
;             PG8_LDA(At, 0, 1); PG8_STAGE(PG8_SB(0, 0), b2, voffB); PG8_STAGE(PG8_SB(0, 1), b2 + hstep, voffB); PG8_STAGE(PG8_SA(0, 0), a2, voffA);
;             PG8_WAIT_V(8); PG8_WAIT_L(0); PG8_BAR; PG8_MMA(1, 0, At, B0); PG8_MMA(1, 1, At, B1); PG8_BAR; PG8_SCHED;
.LBB0_308:
	s_add_u32 s20, s20, 0xb0080
	s_addc_u32 s21, s21, 0
	s_add_u32 s73, s34, 0x100
	s_addc_u32 s74, s35, 0
	s_mov_b32 s75, -2
	s_waitcnt lgkmcnt(0)
	s_waitcnt lgkmcnt(0)
	ds_read_b128 v[96:99], v223
	ds_read_b128 v[108:111], v223 offset:1024
	ds_read_b128 v[120:123], v223 offset:2048
	ds_read_b128 v[128:131], v223 offset:3072
	ds_read_b128 v[144:147], v224
	ds_read_b128 v[148:151], v224 offset:1024
	ds_read_b128 v[152:155], v224 offset:2048
	ds_read_b128 v[156:159], v224 offset:3072
	s_add_u32 s34, s20, 0xfff50080
	s_addc_u32 s35, s21, -1
	s_cmp_eq_u32 s75, 40
	s_cselect_b32 s51, s1, s35
	s_cselect_b32 s50, s0, s34
	s_cselect_b32 s35, s49, s74
	s_cselect_b32 s34, s48, s73
	s_add_i32 m0, s54, 0xc000
	ds_read_b128 v[160:163], v225
	ds_read_b128 v[164:167], v225 offset:1024
	ds_read_b128 v[168:171], v225 offset:2048
	ds_read_b128 v[172:175], v225 offset:3072
	ds_read_b128 v[176:179], v225 offset:4096
	ds_read_b128 v[180:183], v225 offset:5120
	ds_read_b128 v[202:205], v225 offset:6144
	ds_read_b128 v[206:209], v225 offset:7168
	global_load_lds_dwordx4 v192, s[20:21]
	s_add_i32 m0, s54, 0xe000
	s_nop 0
	global_load_lds_dwordx4 v194, s[20:21]
	s_nop 0
	s_waitcnt vmcnt(8)
	s_waitcnt lgkmcnt(0)
	s_barrier
	v_mfma_f32_16x16x32_bf16 v[140:143], v[96:99], v[160:163], 0
	v_mfma_f32_16x16x32_bf16 v[136:139], v[120:123], v[160:163], 0
	v_mfma_f32_16x16x32_bf16 v[116:119], v[96:99], v[168:171], 0
	v_mfma_f32_16x16x32_bf16 v[112:115], v[120:123], v[168:171], 0
	v_mfma_f32_16x16x32_bf16 v[92:95], v[96:99], v[176:179], 0
	v_mfma_f32_16x16x32_bf16 v[88:91], v[120:123], v[176:179], 0
	v_mfma_f32_16x16x32_bf16 v[76:79], v[96:99], v[202:205], 0
	v_mfma_f32_16x16x32_bf16 v[72:75], v[120:123], v[202:205], 0
	v_mfma_f32_16x16x32_bf16 v[140:143], v[108:111], v[164:167], v[140:143]
	v_mfma_f32_16x16x32_bf16 v[136:139], v[128:131], v[164:167], v[136:139]
	v_mfma_f32_16x16x32_bf16 v[116:119], v[108:111], v[172:175], v[116:119]
	v_mfma_f32_16x16x32_bf16 v[112:115], v[128:131], v[172:175], v[112:115]
	v_mfma_f32_16x16x32_bf16 v[92:95], v[108:111], v[180:183], v[92:95]
	v_mfma_f32_16x16x32_bf16 v[88:91], v[128:131], v[180:183], v[88:91]
	v_mfma_f32_16x16x32_bf16 v[76:79], v[108:111], v[206:209], v[76:79]
	v_mfma_f32_16x16x32_bf16 v[72:75], v[128:131], v[206:209], v[72:75]
	v_mfma_f32_16x16x32_bf16 v[132:135], v[144:147], v[160:163], 0
	v_mfma_f32_16x16x32_bf16 v[124:127], v[152:155], v[160:163], 0
	v_mfma_f32_16x16x32_bf16 v[104:107], v[144:147], v[168:171], 0
	v_mfma_f32_16x16x32_bf16 v[100:103], v[152:155], v[168:171], 0
	v_mfma_f32_16x16x32_bf16 v[84:87], v[144:147], v[176:179], 0
	v_mfma_f32_16x16x32_bf16 v[80:83], v[152:155], v[176:179], 0
	v_mfma_f32_16x16x32_bf16 v[68:71], v[144:147], v[202:205], 0
	v_mfma_f32_16x16x32_bf16 v[64:67], v[152:155], v[202:205], 0
	v_mfma_f32_16x16x32_bf16 v[132:135], v[148:151], v[164:167], v[132:135]
	v_mfma_f32_16x16x32_bf16 v[124:127], v[156:159], v[164:167], v[124:127]
	v_mfma_f32_16x16x32_bf16 v[104:107], v[148:151], v[172:175], v[104:107]
	v_mfma_f32_16x16x32_bf16 v[100:103], v[156:159], v[172:175], v[100:103]
	v_mfma_f32_16x16x32_bf16 v[84:87], v[148:151], v[180:183], v[84:87]
	v_mfma_f32_16x16x32_bf16 v[80:83], v[156:159], v[180:183], v[80:83]
	v_mfma_f32_16x16x32_bf16 v[68:71], v[148:151], v[206:209], v[68:71]
	v_mfma_f32_16x16x32_bf16 v[64:67], v[156:159], v[206:209], v[64:67]
	s_barrier
	s_add_i32 s76, s67, s53
	s_add_u32 s98, s34, s12
	s_addc_u32 s99, s35, s13
	s_add_u32 s100, s50, s12
	s_addc_u32 s101, s51, s13
	s_mov_b32 m0, s76
	ds_read_b128 v[160:163], v225 offset:16384
	ds_read_b128 v[164:167], v225 offset:17408
	ds_read_b128 v[168:171], v225 offset:18432
	ds_read_b128 v[172:175], v225 offset:19456
	ds_read_b128 v[176:179], v225 offset:20480
	ds_read_b128 v[180:183], v225 offset:21504
	ds_read_b128 v[202:205], v225 offset:22528
	ds_read_b128 v[206:209], v225 offset:23552
	global_load_lds_dwordx4 v186, s[34:35]
	s_add_i32 m0, s76, 0x2000
	s_add_u32 s76, s34, 0xb0000
	s_addc_u32 s77, s35, 0
	s_add_i32 s78, s68, s53
	global_load_lds_dwordx4 v190, s[34:35]
	s_mov_b32 m0, s78
	s_nop 0
	global_load_lds_dwordx4 v186, s[76:77]
	s_add_i32 m0, s78, 0x2000
	s_nop 0
	global_load_lds_dwordx4 v190, s[76:77]
	s_mov_b32 m0, s54
	s_nop 0
	global_load_lds_dwordx4 v184, s[50:51]
	s_mov_b32 m0, s55
	s_nop 0
	global_load_lds_dwordx4 v188, s[50:51]
	s_nop 0
	s_waitcnt vmcnt(8)
	s_waitcnt lgkmcnt(0)
	s_barrier
	v_mfma_f32_16x16x32_bf16 v[60:63], v[96:99], v[160:163], 0
	v_mfma_f32_16x16x32_bf16 v[56:59], v[120:123], v[160:163], 0
	v_mfma_f32_16x16x32_bf16 v[44:47], v[96:99], v[168:171], 0
	v_mfma_f32_16x16x32_bf16 v[40:43], v[120:123], v[168:171], 0
	v_mfma_f32_16x16x32_bf16 v[28:31], v[96:99], v[176:179], 0
	v_mfma_f32_16x16x32_bf16 v[24:27], v[120:123], v[176:179], 0
	v_mfma_f32_16x16x32_bf16 v[12:15], v[96:99], v[202:205], 0
	v_mfma_f32_16x16x32_bf16 v[8:11], v[120:123], v[202:205], 0
	v_mfma_f32_16x16x32_bf16 v[60:63], v[108:111], v[164:167], v[60:63]
	v_mfma_f32_16x16x32_bf16 v[56:59], v[128:131], v[164:167], v[56:59]
	v_mfma_f32_16x16x32_bf16 v[44:47], v[108:111], v[172:175], v[44:47]
	v_mfma_f32_16x16x32_bf16 v[40:43], v[128:131], v[172:175], v[40:43]
	v_mfma_f32_16x16x32_bf16 v[28:31], v[108:111], v[180:183], v[28:31]
	v_mfma_f32_16x16x32_bf16 v[24:27], v[128:131], v[180:183], v[24:27]
	v_mfma_f32_16x16x32_bf16 v[12:15], v[108:111], v[206:209], v[12:15]
	v_mfma_f32_16x16x32_bf16 v[8:11], v[128:131], v[206:209], v[8:11]
	v_mfma_f32_16x16x32_bf16 v[52:55], v[144:147], v[160:163], 0
	v_mfma_f32_16x16x32_bf16 v[48:51], v[152:155], v[160:163], 0
	v_mfma_f32_16x16x32_bf16 v[36:39], v[144:147], v[168:171], 0
	v_mfma_f32_16x16x32_bf16 v[32:35], v[152:155], v[168:171], 0
	v_mfma_f32_16x16x32_bf16 v[20:23], v[144:147], v[176:179], 0
	v_mfma_f32_16x16x32_bf16 v[16:19], v[152:155], v[176:179], 0
	v_mfma_f32_16x16x32_bf16 v[4:7], v[144:147], v[202:205], 0
	v_mfma_f32_16x16x32_bf16 v[0:3], v[152:155], v[202:205], 0
	v_mfma_f32_16x16x32_bf16 v[52:55], v[148:151], v[164:167], v[52:55]
	v_mfma_f32_16x16x32_bf16 v[48:51], v[156:159], v[164:167], v[48:51]
	v_mfma_f32_16x16x32_bf16 v[36:39], v[148:151], v[172:175], v[36:39]
	v_mfma_f32_16x16x32_bf16 v[32:35], v[156:159], v[172:175], v[32:35]
	v_mfma_f32_16x16x32_bf16 v[20:23], v[148:151], v[180:183], v[20:23]
	v_mfma_f32_16x16x32_bf16 v[16:19], v[156:159], v[180:183], v[16:19]
	v_mfma_f32_16x16x32_bf16 v[4:7], v[148:151], v[206:209], v[4:7]
	v_mfma_f32_16x16x32_bf16 v[0:3], v[156:159], v[206:209], v[0:3]
	s_barrier
; #define PG8_STAGE(bufoff, gbase, voff) do { _Pragma("unroll") for (int _i = 0; _i < 2; ++_i) \
;         __builtin_amdgcn_global_load_lds((const unsigned*)((const char*)(gbase) + (voff)[_i]), (PG8_LAS unsigned*)(lds + (bufoff) + ldsw + _i * 8192), 16, 0, 0); } while (0)
; #define PG8_LDA(dst, b, h) do { _Pragma("unroll") for (int m = 0; m < 4; ++m) _Pragma("unroll") for (int k = 0; k < 2; ++k) dst[m][k] = *(const PG8_LAS bf16x8*)(lds + PG8_SA(b, h) + aoff + m * 2048 + k * 1024); } while (0)
; #define PG8_LDB(dst, b, h) do { _Pragma("unroll") for (int n = 0; n < 2; ++n) _Pragma("unroll") for (int k = 0; k < 2; ++k) dst[n][k] = *(const PG8_LAS bf16x8*)(lds + PG8_SB(b, h) + boff + n * 2048 + k * 1024); } while (0)
; #define PG8_MMA(ai, bj, At, Bt) do { __builtin_amdgcn_s_setprio(1); _Pragma("unroll") for (int m = 0; m < 4; ++m) _Pragma("unroll") for (int n = 0; n < 2; ++n) _Pragma("unroll") for (int k = 0; k < 2; ++k) \
;         acc[ai][bj][m][n] = __builtin_amdgcn_mfma_f32_16x16x32_bf16(Bt[n][k], At[m][k], acc[ai][bj][m][n], 0, 0, 0); __builtin_amdgcn_s_setprio(0); } while (0)
; #define PG8_WAIT_V(n) asm volatile("s_waitcnt vmcnt(" #n ")" ::: "memory")
; #define PG8_WAIT_L(n) asm volatile("s_waitcnt lgkmcnt(" #n ")" ::: "memory")
; #define PG8_BAR __builtin_amdgcn_s_barrier()
; #define PG8_SCHED __builtin_amdgcn_sched_barrier(0)
; template <class Epi, class Sched, bool ALIGN_EPI = false, bool SP2 = false>
; __device__ __forceinline__ void gemm_phase(PG8_LAS unsigned char* lds, const Gemm g, const Sched& S, const Epi& E) {
;     ...
;             PG8_LDB(B0, 1, 0); PG8_LDB(B1, 1, 1); PG8_SCHED; PG8_LDA(At, 1, 0); PG8_STAGE(PG8_SA(0, 1), a2 + hstep, voffA);
;             PG8_WAIT_V(8); PG8_WAIT_L(0); PG8_BAR; PG8_MMA(0, 0, At, B0); PG8_MMA(0, 1, At, B1); PG8_BAR; PG8_SCHED;
;             PG8_LDA(At, 1, 1); PG8_STAGE(PG8_SB(1, 0), b3, voffB); PG8_STAGE(PG8_SB(1, 1), b3 + hstep, voffB); PG8_STAGE(PG8_SA(1, 0), a3, voffA);
;             PG8_WAIT_V(8); PG8_WAIT_L(0); PG8_BAR; PG8_MMA(1, 0, At, B0); PG8_MMA(1, 1, At, B1); PG8_BAR; PG8_SCHED;
	s_add_i32 s76, 0, 0x18000
	s_add_i32 s77, 0, 0x1c000
	v_add_u32_e32 v128, s76, v221
	v_add_u32_e32 v156, s77, v221
	ds_read_b128 v[96:99], v128
	ds_read_b128 v[108:111], v128 offset:1024
	ds_read_b128 v[120:123], v128 offset:2048
	ds_read_b128 v[128:131], v128 offset:3072
	ds_read_b128 v[144:147], v156
	ds_read_b128 v[148:151], v156 offset:1024
	ds_read_b128 v[152:155], v156 offset:2048
	ds_read_b128 v[156:159], v156 offset:3072
	s_add_u32 s50, s50, 0xb0000
	s_addc_u32 s51, s51, 0
	s_mov_b32 m0, s56
	ds_read_b128 v[160:163], v225 offset:32768
	ds_read_b128 v[164:167], v225 offset:33792
	ds_read_b128 v[168:171], v225 offset:34816
	ds_read_b128 v[172:175], v225 offset:35840
	ds_read_b128 v[176:179], v225 offset:36864
	ds_read_b128 v[180:183], v225 offset:37888
	ds_read_b128 v[202:205], v225 offset:38912
	ds_read_b128 v[206:209], v225 offset:39936
	global_load_lds_dwordx4 v184, s[50:51]
	s_mov_b32 m0, s57
	s_nop 0
	global_load_lds_dwordx4 v188, s[50:51]
	s_waitcnt vmcnt(8)
	s_waitcnt lgkmcnt(0)
	s_barrier
	v_mfma_f32_16x16x32_bf16 v[140:143], v[96:99], v[160:163], v[140:143]
	v_mfma_f32_16x16x32_bf16 v[136:139], v[120:123], v[160:163], v[136:139]
	v_mfma_f32_16x16x32_bf16 v[116:119], v[96:99], v[168:171], v[116:119]
	v_mfma_f32_16x16x32_bf16 v[112:115], v[120:123], v[168:171], v[112:115]
	v_mfma_f32_16x16x32_bf16 v[92:95], v[96:99], v[176:179], v[92:95]
	v_mfma_f32_16x16x32_bf16 v[88:91], v[120:123], v[176:179], v[88:91]
	v_mfma_f32_16x16x32_bf16 v[76:79], v[96:99], v[202:205], v[76:79]
	v_mfma_f32_16x16x32_bf16 v[72:75], v[120:123], v[202:205], v[72:75]
	v_mfma_f32_16x16x32_bf16 v[140:143], v[108:111], v[164:167], v[140:143]
	v_mfma_f32_16x16x32_bf16 v[136:139], v[128:131], v[164:167], v[136:139]
	v_mfma_f32_16x16x32_bf16 v[116:119], v[108:111], v[172:175], v[116:119]
	v_mfma_f32_16x16x32_bf16 v[112:115], v[128:131], v[172:175], v[112:115]
	v_mfma_f32_16x16x32_bf16 v[92:95], v[108:111], v[180:183], v[92:95]
	v_mfma_f32_16x16x32_bf16 v[88:91], v[128:131], v[180:183], v[88:91]
	v_mfma_f32_16x16x32_bf16 v[76:79], v[108:111], v[206:209], v[76:79]
	v_mfma_f32_16x16x32_bf16 v[72:75], v[128:131], v[206:209], v[72:75]
	v_mfma_f32_16x16x32_bf16 v[132:135], v[144:147], v[160:163], v[132:135]
	v_mfma_f32_16x16x32_bf16 v[124:127], v[152:155], v[160:163], v[124:127]
	v_mfma_f32_16x16x32_bf16 v[104:107], v[144:147], v[168:171], v[104:107]
	v_mfma_f32_16x16x32_bf16 v[100:103], v[152:155], v[168:171], v[100:103]
	v_mfma_f32_16x16x32_bf16 v[84:87], v[144:147], v[176:179], v[84:87]
	v_mfma_f32_16x16x32_bf16 v[80:83], v[152:155], v[176:179], v[80:83]
	v_mfma_f32_16x16x32_bf16 v[68:71], v[144:147], v[202:205], v[68:71]
	v_mfma_f32_16x16x32_bf16 v[64:67], v[152:155], v[202:205], v[64:67]
	v_mfma_f32_16x16x32_bf16 v[132:135], v[148:151], v[164:167], v[132:135]
	v_mfma_f32_16x16x32_bf16 v[124:127], v[156:159], v[164:167], v[124:127]
	v_mfma_f32_16x16x32_bf16 v[104:107], v[148:151], v[172:175], v[104:107]
	v_mfma_f32_16x16x32_bf16 v[100:103], v[156:159], v[172:175], v[100:103]
	v_mfma_f32_16x16x32_bf16 v[84:87], v[148:151], v[180:183], v[84:87]
	v_mfma_f32_16x16x32_bf16 v[80:83], v[156:159], v[180:183], v[80:83]
	v_mfma_f32_16x16x32_bf16 v[68:71], v[148:151], v[206:209], v[68:71]
	v_mfma_f32_16x16x32_bf16 v[64:67], v[156:159], v[206:209], v[64:67]
	s_barrier
	s_add_i32 s50, s76, s53
	s_mov_b32 m0, s50
	ds_read_b128 v[160:163], v225 offset:49152
	ds_read_b128 v[164:167], v225 offset:50176
	ds_read_b128 v[168:171], v225 offset:51200
	ds_read_b128 v[172:175], v225 offset:52224
	ds_read_b128 v[176:179], v225 offset:53248
	ds_read_b128 v[180:183], v225 offset:54272
	ds_read_b128 v[202:205], v225 offset:55296
	ds_read_b128 v[206:209], v225 offset:56320
	global_load_lds_dwordx4 v186, s[98:99]
	s_add_i32 m0, s50, 0x2000
	s_add_u32 s34, s34, 0xb0080
	s_addc_u32 s35, s35, 0
	s_add_i32 s50, s77, s53
	global_load_lds_dwordx4 v190, s[98:99]
	s_mov_b32 m0, s50
	s_nop 0
	global_load_lds_dwordx4 v186, s[34:35]
	s_add_i32 m0, s50, 0x2000
	s_nop 0
	global_load_lds_dwordx4 v190, s[34:35]
	s_mov_b32 m0, s62
	s_nop 0
	global_load_lds_dwordx4 v184, s[100:101]
	s_mov_b32 m0, s63
	s_nop 0
	global_load_lds_dwordx4 v188, s[100:101]
	s_nop 0
	s_waitcnt vmcnt(8)
	s_waitcnt lgkmcnt(0)
	s_barrier
	v_mfma_f32_16x16x32_bf16 v[60:63], v[96:99], v[160:163], v[60:63]
	v_mfma_f32_16x16x32_bf16 v[56:59], v[120:123], v[160:163], v[56:59]
	v_mfma_f32_16x16x32_bf16 v[44:47], v[96:99], v[168:171], v[44:47]
	v_mfma_f32_16x16x32_bf16 v[40:43], v[120:123], v[168:171], v[40:43]
	v_mfma_f32_16x16x32_bf16 v[28:31], v[96:99], v[176:179], v[28:31]
	v_mfma_f32_16x16x32_bf16 v[24:27], v[120:123], v[176:179], v[24:27]
	v_mfma_f32_16x16x32_bf16 v[12:15], v[96:99], v[202:205], v[12:15]
	v_mfma_f32_16x16x32_bf16 v[8:11], v[120:123], v[202:205], v[8:11]
	v_mfma_f32_16x16x32_bf16 v[60:63], v[108:111], v[164:167], v[60:63]
	v_mfma_f32_16x16x32_bf16 v[56:59], v[128:131], v[164:167], v[56:59]
	v_mfma_f32_16x16x32_bf16 v[44:47], v[108:111], v[172:175], v[44:47]
	v_mfma_f32_16x16x32_bf16 v[40:43], v[128:131], v[172:175], v[40:43]
	v_mfma_f32_16x16x32_bf16 v[28:31], v[108:111], v[180:183], v[28:31]
	v_mfma_f32_16x16x32_bf16 v[24:27], v[128:131], v[180:183], v[24:27]
	v_mfma_f32_16x16x32_bf16 v[12:15], v[108:111], v[206:209], v[12:15]
	v_mfma_f32_16x16x32_bf16 v[8:11], v[128:131], v[206:209], v[8:11]
	v_mfma_f32_16x16x32_bf16 v[52:55], v[144:147], v[160:163], v[52:55]
	v_mfma_f32_16x16x32_bf16 v[48:51], v[152:155], v[160:163], v[48:51]
	v_mfma_f32_16x16x32_bf16 v[36:39], v[144:147], v[168:171], v[36:39]
	v_mfma_f32_16x16x32_bf16 v[32:35], v[152:155], v[168:171], v[32:35]
	v_mfma_f32_16x16x32_bf16 v[20:23], v[144:147], v[176:179], v[20:23]
	v_mfma_f32_16x16x32_bf16 v[16:19], v[152:155], v[176:179], v[16:19]
	v_mfma_f32_16x16x32_bf16 v[4:7], v[144:147], v[202:205], v[4:7]
	v_mfma_f32_16x16x32_bf16 v[0:3], v[152:155], v[202:205], v[0:3]
	v_mfma_f32_16x16x32_bf16 v[52:55], v[148:151], v[164:167], v[52:55]
	v_mfma_f32_16x16x32_bf16 v[48:51], v[156:159], v[164:167], v[48:51]
	v_mfma_f32_16x16x32_bf16 v[36:39], v[148:151], v[172:175], v[36:39]
	v_mfma_f32_16x16x32_bf16 v[32:35], v[156:159], v[172:175], v[32:35]
	v_mfma_f32_16x16x32_bf16 v[20:23], v[148:151], v[180:183], v[20:23]
	v_mfma_f32_16x16x32_bf16 v[16:19], v[156:159], v[180:183], v[16:19]
	v_mfma_f32_16x16x32_bf16 v[4:7], v[148:151], v[206:209], v[4:7]
	v_mfma_f32_16x16x32_bf16 v[0:3], v[156:159], v[206:209], v[0:3]
	s_barrier
	s_add_i32 s75, s75, 2
	s_add_u32 s20, s20, 0x100
	s_addc_u32 s21, s21, 0
	s_add_u32 s73, s73, 0x100
	s_addc_u32 s74, s74, 0
	s_cmp_gt_u32 s75, 41
; #define PG8_STAGE(bufoff, gbase, voff) do { _Pragma("unroll") for (int _i = 0; _i < 2; ++_i) \
;         __builtin_amdgcn_global_load_lds((const unsigned*)((const char*)(gbase) + (voff)[_i]), (PG8_LAS unsigned*)(lds + (bufoff) + ldsw + _i * 8192), 16, 0, 0); } while (0)
; #define PG8_LDA(dst, b, h) do { _Pragma("unroll") for (int m = 0; m < 4; ++m) _Pragma("unroll") for (int k = 0; k < 2; ++k) dst[m][k] = *(const PG8_LAS bf16x8*)(lds + PG8_SA(b, h) + aoff + m * 2048 + k * 1024); } while (0)
; #define PG8_LDB(dst, b, h) do { _Pragma("unroll") for (int n = 0; n < 2; ++n) _Pragma("unroll") for (int k = 0; k < 2; ++k) dst[n][k] = *(const PG8_LAS bf16x8*)(lds + PG8_SB(b, h) + boff + n * 2048 + k * 1024); } while (0)
; #define PG8_MMA(ai, bj, At, Bt) do { __builtin_amdgcn_s_setprio(1); _Pragma("unroll") for (int m = 0; m < 4; ++m) _Pragma("unroll") for (int n = 0; n < 2; ++n) _Pragma("unroll") for (int k = 0; k < 2; ++k) \
;         acc[ai][bj][m][n] = __builtin_amdgcn_mfma_f32_16x16x32_bf16(Bt[n][k], At[m][k], acc[ai][bj][m][n], 0, 0, 0); __builtin_amdgcn_s_setprio(0); } while (0)
; #define PG8_WAIT_V(n) asm volatile("s_waitcnt vmcnt(" #n ")" ::: "memory")
; #define PG8_WAIT_L(n) asm volatile("s_waitcnt lgkmcnt(" #n ")" ::: "memory")
; #define PG8_BAR __builtin_amdgcn_s_barrier()
; #define PG8_SCHED __builtin_amdgcn_sched_barrier(0)
; template <class Epi, class Sched, bool ALIGN_EPI = false, bool SP2 = false>
; __device__ __forceinline__ void gemm_phase(PG8_LAS unsigned char* lds, const Gemm g, const Sched& S, const Epi& E) {
;     ...
;             PG8_LDB(B0, 0, 0); PG8_LDB(B1, 0, 1); PG8_SCHED; PG8_LDA(At, 0, 0); PG8_STAGE(PG8_SA(1, 1), a1 + hstep, voffA);
;             PG8_WAIT_V(8); PG8_WAIT_L(0); PG8_BAR; PG8_MMA(0, 0, At, B0); PG8_MMA(0, 1, At, B1); PG8_BAR; PG8_SCHED;
;             PG8_LDA(At, 0, 1); PG8_STAGE(PG8_SB(0, 0), b2, voffB); PG8_STAGE(PG8_SB(0, 1), b2 + hstep, voffB); PG8_STAGE(PG8_SA(0, 0), a2, voffA);
;             PG8_WAIT_V(8); PG8_WAIT_L(0); PG8_BAR; PG8_MMA(1, 0, At, B0); PG8_MMA(1, 1, At, B1); PG8_BAR; PG8_SCHED;
.LBB0_309:
	ds_read_b128 v[96:99], v223
	ds_read_b128 v[108:111], v223 offset:1024
	ds_read_b128 v[120:123], v223 offset:2048
	ds_read_b128 v[128:131], v223 offset:3072
	ds_read_b128 v[144:147], v224
	ds_read_b128 v[148:151], v224 offset:1024
	ds_read_b128 v[152:155], v224 offset:2048
	ds_read_b128 v[156:159], v224 offset:3072
	s_add_u32 s34, s20, 0xfff50080
	s_addc_u32 s35, s21, -1
	s_cmp_eq_u32 s75, 40
	s_cselect_b32 s51, s1, s35
	s_cselect_b32 s50, s0, s34
	s_cselect_b32 s35, s49, s74
	s_cselect_b32 s34, s48, s73
	s_add_i32 m0, s54, 0xc000
	ds_read_b128 v[160:163], v225
	ds_read_b128 v[164:167], v225 offset:1024
	ds_read_b128 v[168:171], v225 offset:2048
	ds_read_b128 v[172:175], v225 offset:3072
	ds_read_b128 v[176:179], v225 offset:4096
	ds_read_b128 v[180:183], v225 offset:5120
	ds_read_b128 v[202:205], v225 offset:6144
	ds_read_b128 v[206:209], v225 offset:7168
	global_load_lds_dwordx4 v192, s[20:21]
	s_add_i32 m0, s54, 0xe000
	s_nop 0
	global_load_lds_dwordx4 v194, s[20:21]
	s_nop 0
	s_waitcnt vmcnt(8)
	s_waitcnt lgkmcnt(0)
	s_barrier
	v_mfma_f32_16x16x32_bf16 v[140:143], v[96:99], v[160:163], v[140:143]
	v_mfma_f32_16x16x32_bf16 v[136:139], v[120:123], v[160:163], v[136:139]
	v_mfma_f32_16x16x32_bf16 v[116:119], v[96:99], v[168:171], v[116:119]
	v_mfma_f32_16x16x32_bf16 v[112:115], v[120:123], v[168:171], v[112:115]
	v_mfma_f32_16x16x32_bf16 v[92:95], v[96:99], v[176:179], v[92:95]
	v_mfma_f32_16x16x32_bf16 v[88:91], v[120:123], v[176:179], v[88:91]
	v_mfma_f32_16x16x32_bf16 v[76:79], v[96:99], v[202:205], v[76:79]
	v_mfma_f32_16x16x32_bf16 v[72:75], v[120:123], v[202:205], v[72:75]
	v_mfma_f32_16x16x32_bf16 v[140:143], v[108:111], v[164:167], v[140:143]
	v_mfma_f32_16x16x32_bf16 v[136:139], v[128:131], v[164:167], v[136:139]
	v_mfma_f32_16x16x32_bf16 v[116:119], v[108:111], v[172:175], v[116:119]
	v_mfma_f32_16x16x32_bf16 v[112:115], v[128:131], v[172:175], v[112:115]
	v_mfma_f32_16x16x32_bf16 v[92:95], v[108:111], v[180:183], v[92:95]
	v_mfma_f32_16x16x32_bf16 v[88:91], v[128:131], v[180:183], v[88:91]
	v_mfma_f32_16x16x32_bf16 v[76:79], v[108:111], v[206:209], v[76:79]
	v_mfma_f32_16x16x32_bf16 v[72:75], v[128:131], v[206:209], v[72:75]
	v_mfma_f32_16x16x32_bf16 v[132:135], v[144:147], v[160:163], v[132:135]
	v_mfma_f32_16x16x32_bf16 v[124:127], v[152:155], v[160:163], v[124:127]
	v_mfma_f32_16x16x32_bf16 v[104:107], v[144:147], v[168:171], v[104:107]
	v_mfma_f32_16x16x32_bf16 v[100:103], v[152:155], v[168:171], v[100:103]
	v_mfma_f32_16x16x32_bf16 v[84:87], v[144:147], v[176:179], v[84:87]
	v_mfma_f32_16x16x32_bf16 v[80:83], v[152:155], v[176:179], v[80:83]
	v_mfma_f32_16x16x32_bf16 v[68:71], v[144:147], v[202:205], v[68:71]
	v_mfma_f32_16x16x32_bf16 v[64:67], v[152:155], v[202:205], v[64:67]
	v_mfma_f32_16x16x32_bf16 v[132:135], v[148:151], v[164:167], v[132:135]
	v_mfma_f32_16x16x32_bf16 v[124:127], v[156:159], v[164:167], v[124:127]
	v_mfma_f32_16x16x32_bf16 v[104:107], v[148:151], v[172:175], v[104:107]
	v_mfma_f32_16x16x32_bf16 v[100:103], v[156:159], v[172:175], v[100:103]
	v_mfma_f32_16x16x32_bf16 v[84:87], v[148:151], v[180:183], v[84:87]
	v_mfma_f32_16x16x32_bf16 v[80:83], v[156:159], v[180:183], v[80:83]
	v_mfma_f32_16x16x32_bf16 v[68:71], v[148:151], v[206:209], v[68:71]
	v_mfma_f32_16x16x32_bf16 v[64:67], v[156:159], v[206:209], v[64:67]
	s_barrier
	s_add_i32 s76, s67, s53
	s_add_u32 s98, s34, s12
	s_addc_u32 s99, s35, s13
	s_add_u32 s100, s50, s12
	s_addc_u32 s101, s51, s13
	s_mov_b32 m0, s76
	ds_read_b128 v[160:163], v225 offset:16384
	ds_read_b128 v[164:167], v225 offset:17408
	ds_read_b128 v[168:171], v225 offset:18432
	ds_read_b128 v[172:175], v225 offset:19456
	ds_read_b128 v[176:179], v225 offset:20480
	ds_read_b128 v[180:183], v225 offset:21504
	ds_read_b128 v[202:205], v225 offset:22528
	ds_read_b128 v[206:209], v225 offset:23552
	global_load_lds_dwordx4 v186, s[34:35]
	s_add_i32 m0, s76, 0x2000
	s_add_u32 s76, s34, 0xb0000
	s_addc_u32 s77, s35, 0
	s_add_i32 s78, s68, s53
	global_load_lds_dwordx4 v190, s[34:35]
	s_mov_b32 m0, s78
	s_nop 0
	global_load_lds_dwordx4 v186, s[76:77]
	s_add_i32 m0, s78, 0x2000
	s_nop 0
	global_load_lds_dwordx4 v190, s[76:77]
	s_mov_b32 m0, s54
	s_nop 0
	global_load_lds_dwordx4 v184, s[50:51]
	s_mov_b32 m0, s55
	s_nop 0
	global_load_lds_dwordx4 v188, s[50:51]
	s_nop 0
	s_waitcnt vmcnt(8)
	s_waitcnt lgkmcnt(0)
	s_barrier
	v_mfma_f32_16x16x32_bf16 v[60:63], v[96:99], v[160:163], v[60:63]
	v_mfma_f32_16x16x32_bf16 v[56:59], v[120:123], v[160:163], v[56:59]
	v_mfma_f32_16x16x32_bf16 v[44:47], v[96:99], v[168:171], v[44:47]
	v_mfma_f32_16x16x32_bf16 v[40:43], v[120:123], v[168:171], v[40:43]
	v_mfma_f32_16x16x32_bf16 v[28:31], v[96:99], v[176:179], v[28:31]
	v_mfma_f32_16x16x32_bf16 v[24:27], v[120:123], v[176:179], v[24:27]
	v_mfma_f32_16x16x32_bf16 v[12:15], v[96:99], v[202:205], v[12:15]
	v_mfma_f32_16x16x32_bf16 v[8:11], v[120:123], v[202:205], v[8:11]
	v_mfma_f32_16x16x32_bf16 v[60:63], v[108:111], v[164:167], v[60:63]
	v_mfma_f32_16x16x32_bf16 v[56:59], v[128:131], v[164:167], v[56:59]
	v_mfma_f32_16x16x32_bf16 v[44:47], v[108:111], v[172:175], v[44:47]
	v_mfma_f32_16x16x32_bf16 v[40:43], v[128:131], v[172:175], v[40:43]
	v_mfma_f32_16x16x32_bf16 v[28:31], v[108:111], v[180:183], v[28:31]
	v_mfma_f32_16x16x32_bf16 v[24:27], v[128:131], v[180:183], v[24:27]
	v_mfma_f32_16x16x32_bf16 v[12:15], v[108:111], v[206:209], v[12:15]
	v_mfma_f32_16x16x32_bf16 v[8:11], v[128:131], v[206:209], v[8:11]
	v_mfma_f32_16x16x32_bf16 v[52:55], v[144:147], v[160:163], v[52:55]
	v_mfma_f32_16x16x32_bf16 v[48:51], v[152:155], v[160:163], v[48:51]
	v_mfma_f32_16x16x32_bf16 v[36:39], v[144:147], v[168:171], v[36:39]
	v_mfma_f32_16x16x32_bf16 v[32:35], v[152:155], v[168:171], v[32:35]
	v_mfma_f32_16x16x32_bf16 v[20:23], v[144:147], v[176:179], v[20:23]
	v_mfma_f32_16x16x32_bf16 v[16:19], v[152:155], v[176:179], v[16:19]
	v_mfma_f32_16x16x32_bf16 v[4:7], v[144:147], v[202:205], v[4:7]
	v_mfma_f32_16x16x32_bf16 v[0:3], v[152:155], v[202:205], v[0:3]
	v_mfma_f32_16x16x32_bf16 v[52:55], v[148:151], v[164:167], v[52:55]
	v_mfma_f32_16x16x32_bf16 v[48:51], v[156:159], v[164:167], v[48:51]
	v_mfma_f32_16x16x32_bf16 v[36:39], v[148:151], v[172:175], v[36:39]
	v_mfma_f32_16x16x32_bf16 v[32:35], v[156:159], v[172:175], v[32:35]
	v_mfma_f32_16x16x32_bf16 v[20:23], v[148:151], v[180:183], v[20:23]
	v_mfma_f32_16x16x32_bf16 v[16:19], v[156:159], v[180:183], v[16:19]
	v_mfma_f32_16x16x32_bf16 v[4:7], v[148:151], v[206:209], v[4:7]
	v_mfma_f32_16x16x32_bf16 v[0:3], v[156:159], v[206:209], v[0:3]
	s_barrier
; #define PG8_STAGE(bufoff, gbase, voff) do { _Pragma("unroll") for (int _i = 0; _i < 2; ++_i) \
;         __builtin_amdgcn_global_load_lds((const unsigned*)((const char*)(gbase) + (voff)[_i]), (PG8_LAS unsigned*)(lds + (bufoff) + ldsw + _i * 8192), 16, 0, 0); } while (0)
; #define PG8_LDA(dst, b, h) do { _Pragma("unroll") for (int m = 0; m < 4; ++m) _Pragma("unroll") for (int k = 0; k < 2; ++k) dst[m][k] = *(const PG8_LAS bf16x8*)(lds + PG8_SA(b, h) + aoff + m * 2048 + k * 1024); } while (0)
; #define PG8_LDB(dst, b, h) do { _Pragma("unroll") for (int n = 0; n < 2; ++n) _Pragma("unroll") for (int k = 0; k < 2; ++k) dst[n][k] = *(const PG8_LAS bf16x8*)(lds + PG8_SB(b, h) + boff + n * 2048 + k * 1024); } while (0)
; #define PG8_MMA(ai, bj, At, Bt) do { __builtin_amdgcn_s_setprio(1); _Pragma("unroll") for (int m = 0; m < 4; ++m) _Pragma("unroll") for (int n = 0; n < 2; ++n) _Pragma("unroll") for (int k = 0; k < 2; ++k) \
;         acc[ai][bj][m][n] = __builtin_amdgcn_mfma_f32_16x16x32_bf16(Bt[n][k], At[m][k], acc[ai][bj][m][n], 0, 0, 0); __builtin_amdgcn_s_setprio(0); } while (0)
; #define PG8_WAIT_V(n) asm volatile("s_waitcnt vmcnt(" #n ")" ::: "memory")
; #define PG8_WAIT_L(n) asm volatile("s_waitcnt lgkmcnt(" #n ")" ::: "memory")
; #define PG8_BAR __builtin_amdgcn_s_barrier()
; #define PG8_SCHED __builtin_amdgcn_sched_barrier(0)
; template <class Epi, class Sched, bool ALIGN_EPI = false, bool SP2 = false>
; __device__ __forceinline__ void gemm_phase(PG8_LAS unsigned char* lds, const Gemm g, const Sched& S, const Epi& E) {
;     ...
;             PG8_LDB(B0, 1, 0); PG8_LDB(B1, 1, 1); PG8_SCHED; PG8_LDA(At, 1, 0); PG8_STAGE(PG8_SA(0, 1), a2 + hstep, voffA);
;             PG8_WAIT_V(8); PG8_WAIT_L(0); PG8_BAR; PG8_MMA(0, 0, At, B0); PG8_MMA(0, 1, At, B1); PG8_BAR; PG8_SCHED;
;             PG8_LDA(At, 1, 1); PG8_STAGE(PG8_SB(1, 0), b3, voffB); PG8_STAGE(PG8_SB(1, 1), b3 + hstep, voffB); PG8_STAGE(PG8_SA(1, 0), a3, voffA);
;             PG8_WAIT_V(8); PG8_WAIT_L(0); PG8_BAR; PG8_MMA(1, 0, At, B0); PG8_MMA(1, 1, At, B1); PG8_BAR; PG8_SCHED;
;     ...
;         if constexpr (ALIGN_EPI) { if (wr == 0) PG8_BAR; }
	s_add_i32 s76, 0, 0x18000
	s_add_i32 s77, 0, 0x1c000
	v_add_u32_e32 v128, s76, v221
	v_add_u32_e32 v156, s77, v221
	ds_read_b128 v[96:99], v128
	ds_read_b128 v[108:111], v128 offset:1024
	ds_read_b128 v[120:123], v128 offset:2048
	ds_read_b128 v[128:131], v128 offset:3072
	ds_read_b128 v[144:147], v156
	ds_read_b128 v[148:151], v156 offset:1024
	ds_read_b128 v[152:155], v156 offset:2048
	ds_read_b128 v[156:159], v156 offset:3072
	s_add_u32 s50, s50, 0xb0000
	s_addc_u32 s51, s51, 0
	s_mov_b32 m0, s56
	ds_read_b128 v[160:163], v225 offset:32768
	ds_read_b128 v[164:167], v225 offset:33792
	ds_read_b128 v[168:171], v225 offset:34816
	ds_read_b128 v[172:175], v225 offset:35840
	ds_read_b128 v[176:179], v225 offset:36864
	ds_read_b128 v[180:183], v225 offset:37888
	ds_read_b128 v[202:205], v225 offset:38912
	ds_read_b128 v[206:209], v225 offset:39936
	global_load_lds_dwordx4 v184, s[50:51]
	s_mov_b32 m0, s57
	s_nop 0
	global_load_lds_dwordx4 v188, s[50:51]
	s_waitcnt vmcnt(8)
	s_waitcnt lgkmcnt(0)
	s_barrier
	v_mfma_f32_16x16x32_bf16 v[140:143], v[96:99], v[160:163], v[140:143]
	v_mfma_f32_16x16x32_bf16 v[136:139], v[120:123], v[160:163], v[136:139]
	v_mfma_f32_16x16x32_bf16 v[116:119], v[96:99], v[168:171], v[116:119]
	v_mfma_f32_16x16x32_bf16 v[112:115], v[120:123], v[168:171], v[112:115]
	v_mfma_f32_16x16x32_bf16 v[92:95], v[96:99], v[176:179], v[92:95]
	v_mfma_f32_16x16x32_bf16 v[88:91], v[120:123], v[176:179], v[88:91]
	v_mfma_f32_16x16x32_bf16 v[76:79], v[96:99], v[202:205], v[76:79]
	v_mfma_f32_16x16x32_bf16 v[72:75], v[120:123], v[202:205], v[72:75]
	v_mfma_f32_16x16x32_bf16 v[140:143], v[108:111], v[164:167], v[140:143]
	v_mfma_f32_16x16x32_bf16 v[136:139], v[128:131], v[164:167], v[136:139]
	v_mfma_f32_16x16x32_bf16 v[116:119], v[108:111], v[172:175], v[116:119]
	v_mfma_f32_16x16x32_bf16 v[112:115], v[128:131], v[172:175], v[112:115]
	v_mfma_f32_16x16x32_bf16 v[92:95], v[108:111], v[180:183], v[92:95]
	v_mfma_f32_16x16x32_bf16 v[88:91], v[128:131], v[180:183], v[88:91]
	v_mfma_f32_16x16x32_bf16 v[76:79], v[108:111], v[206:209], v[76:79]
	v_mfma_f32_16x16x32_bf16 v[72:75], v[128:131], v[206:209], v[72:75]
	v_mfma_f32_16x16x32_bf16 v[132:135], v[144:147], v[160:163], v[132:135]
	v_mfma_f32_16x16x32_bf16 v[124:127], v[152:155], v[160:163], v[124:127]
	v_mfma_f32_16x16x32_bf16 v[104:107], v[144:147], v[168:171], v[104:107]
	v_mfma_f32_16x16x32_bf16 v[100:103], v[152:155], v[168:171], v[100:103]
	v_mfma_f32_16x16x32_bf16 v[84:87], v[144:147], v[176:179], v[84:87]
	v_mfma_f32_16x16x32_bf16 v[80:83], v[152:155], v[176:179], v[80:83]
	v_mfma_f32_16x16x32_bf16 v[68:71], v[144:147], v[202:205], v[68:71]
	v_mfma_f32_16x16x32_bf16 v[64:67], v[152:155], v[202:205], v[64:67]
	v_mfma_f32_16x16x32_bf16 v[132:135], v[148:151], v[164:167], v[132:135]
	v_mfma_f32_16x16x32_bf16 v[124:127], v[156:159], v[164:167], v[124:127]
	v_mfma_f32_16x16x32_bf16 v[104:107], v[148:151], v[172:175], v[104:107]
	v_mfma_f32_16x16x32_bf16 v[100:103], v[156:159], v[172:175], v[100:103]
	v_mfma_f32_16x16x32_bf16 v[84:87], v[148:151], v[180:183], v[84:87]
	v_mfma_f32_16x16x32_bf16 v[80:83], v[156:159], v[180:183], v[80:83]
	v_mfma_f32_16x16x32_bf16 v[68:71], v[148:151], v[206:209], v[68:71]
	v_mfma_f32_16x16x32_bf16 v[64:67], v[156:159], v[206:209], v[64:67]
	s_barrier
	s_add_i32 s50, s76, s53
	s_mov_b32 m0, s50
	ds_read_b128 v[160:163], v225 offset:49152
	ds_read_b128 v[164:167], v225 offset:50176
	ds_read_b128 v[168:171], v225 offset:51200
	ds_read_b128 v[172:175], v225 offset:52224
	ds_read_b128 v[176:179], v225 offset:53248
	ds_read_b128 v[180:183], v225 offset:54272
	ds_read_b128 v[202:205], v225 offset:55296
	ds_read_b128 v[206:209], v225 offset:56320
	global_load_lds_dwordx4 v186, s[98:99]
	s_add_i32 m0, s50, 0x2000
	s_add_u32 s34, s34, 0xb0080
	s_addc_u32 s35, s35, 0
	s_add_i32 s50, s77, s53
	global_load_lds_dwordx4 v190, s[98:99]
	s_mov_b32 m0, s50
	s_nop 0
	global_load_lds_dwordx4 v186, s[34:35]
	s_add_i32 m0, s50, 0x2000
	s_nop 0
	global_load_lds_dwordx4 v190, s[34:35]
	s_mov_b32 m0, s62
	s_nop 0
	global_load_lds_dwordx4 v184, s[100:101]
	s_mov_b32 m0, s63
	s_nop 0
	global_load_lds_dwordx4 v188, s[100:101]
	s_nop 0
	s_waitcnt vmcnt(8)
	s_waitcnt lgkmcnt(0)
	s_barrier
	v_mfma_f32_16x16x32_bf16 v[60:63], v[96:99], v[160:163], v[60:63]
	v_mfma_f32_16x16x32_bf16 v[56:59], v[120:123], v[160:163], v[56:59]
	v_mfma_f32_16x16x32_bf16 v[44:47], v[96:99], v[168:171], v[44:47]
	v_mfma_f32_16x16x32_bf16 v[40:43], v[120:123], v[168:171], v[40:43]
	v_mfma_f32_16x16x32_bf16 v[28:31], v[96:99], v[176:179], v[28:31]
	v_mfma_f32_16x16x32_bf16 v[24:27], v[120:123], v[176:179], v[24:27]
	v_mfma_f32_16x16x32_bf16 v[12:15], v[96:99], v[202:205], v[12:15]
	v_mfma_f32_16x16x32_bf16 v[8:11], v[120:123], v[202:205], v[8:11]
	v_mfma_f32_16x16x32_bf16 v[60:63], v[108:111], v[164:167], v[60:63]
	v_mfma_f32_16x16x32_bf16 v[56:59], v[128:131], v[164:167], v[56:59]
	v_mfma_f32_16x16x32_bf16 v[44:47], v[108:111], v[172:175], v[44:47]
	v_mfma_f32_16x16x32_bf16 v[40:43], v[128:131], v[172:175], v[40:43]
	v_mfma_f32_16x16x32_bf16 v[28:31], v[108:111], v[180:183], v[28:31]
	v_mfma_f32_16x16x32_bf16 v[24:27], v[128:131], v[180:183], v[24:27]
	v_mfma_f32_16x16x32_bf16 v[12:15], v[108:111], v[206:209], v[12:15]
	v_mfma_f32_16x16x32_bf16 v[8:11], v[128:131], v[206:209], v[8:11]
	v_mfma_f32_16x16x32_bf16 v[52:55], v[144:147], v[160:163], v[52:55]
	v_mfma_f32_16x16x32_bf16 v[48:51], v[152:155], v[160:163], v[48:51]
	v_mfma_f32_16x16x32_bf16 v[36:39], v[144:147], v[168:171], v[36:39]
	v_mfma_f32_16x16x32_bf16 v[32:35], v[152:155], v[168:171], v[32:35]
	v_mfma_f32_16x16x32_bf16 v[20:23], v[144:147], v[176:179], v[20:23]
	v_mfma_f32_16x16x32_bf16 v[16:19], v[152:155], v[176:179], v[16:19]
	v_mfma_f32_16x16x32_bf16 v[4:7], v[144:147], v[202:205], v[4:7]
	v_mfma_f32_16x16x32_bf16 v[0:3], v[152:155], v[202:205], v[0:3]
	v_mfma_f32_16x16x32_bf16 v[52:55], v[148:151], v[164:167], v[52:55]
	v_mfma_f32_16x16x32_bf16 v[48:51], v[156:159], v[164:167], v[48:51]
	v_mfma_f32_16x16x32_bf16 v[36:39], v[148:151], v[172:175], v[36:39]
	v_mfma_f32_16x16x32_bf16 v[32:35], v[156:159], v[172:175], v[32:35]
	v_mfma_f32_16x16x32_bf16 v[20:23], v[148:151], v[180:183], v[20:23]
	v_mfma_f32_16x16x32_bf16 v[16:19], v[156:159], v[180:183], v[16:19]
	v_mfma_f32_16x16x32_bf16 v[4:7], v[148:151], v[206:209], v[4:7]
	v_mfma_f32_16x16x32_bf16 v[0:3], v[156:159], v[206:209], v[0:3]
	s_barrier
	s_add_i32 s75, s75, 2
	s_add_u32 s20, s20, 0x100
	s_addc_u32 s21, s21, 0
	s_add_u32 s73, s73, 0x100
	s_addc_u32 s74, s74, 0
	s_cmp_gt_u32 s75, 41
	s_cbranch_scc0 .LBB0_309
	s_and_b64 vcc, exec, s[14:15]
	s_cbranch_vccz .LBB0_312
	s_barrier

; #define PG8_STAGE(bufoff, gbase, voff) do { _Pragma("unroll") for (int _i = 0; _i < 2; ++_i) \
;         __builtin_amdgcn_global_load_lds((const unsigned*)((const char*)(gbase) + (voff)[_i]), (PG8_LAS unsigned*)(lds + (bufoff) + ldsw + _i * 8192), 16, 0, 0); } while (0)
; #define PG8_LDA(dst, b, h) do { _Pragma("unroll") for (int m = 0; m < 4; ++m) _Pragma("unroll") for (int k = 0; k < 2; ++k) dst[m][k] = *(const PG8_LAS bf16x8*)(lds + PG8_SA(b, h) + aoff + m * 2048 + k * 1024); } while (0)
; #define PG8_LDB(dst, b, h) do { _Pragma("unroll") for (int n = 0; n < 2; ++n) _Pragma("unroll") for (int k = 0; k < 2; ++k) dst[n][k] = *(const PG8_LAS bf16x8*)(lds + PG8_SB(b, h) + boff + n * 2048 + k * 1024); } while (0)
; #define PG8_WAIT_V(n) asm volatile("s_waitcnt vmcnt(" #n ")" ::: "memory")
; #define PG8_WAIT_L(n) asm volatile("s_waitcnt lgkmcnt(" #n ")" ::: "memory")
; #define PG8_BAR __builtin_amdgcn_s_barrier()
; #define PG8_SCHED __builtin_amdgcn_sched_barrier(0)
; template <class Epi, class Sched, bool ALIGN_EPI = false, bool SP2 = false>
; __device__ __forceinline__ void gemm_phase(PG8_LAS unsigned char* lds, const Gemm g, const Sched& S, const Epi& E) {
;     ...
;         const char* nA = has_next ? (const char*)g.A + (size_t)nxt.pm * tstep : cA; const char* nB = has_next ? (const char*)g.Bt + (size_t)nxt.pn * tstep : cB;
;         for (int t = 0; t < nt; t += 2) {
;             const bool last = (t == nt - 2);
;             const char* a1 = cA + (size_t)(t + 1) * kstep;
;             const char* a2 = last ? nA : cA + (size_t)(t + 2) * kstep; const char* b2 = last ? nB : cB + (size_t)(t + 2) * kstep;
;             const char* a3 = a2 + kstep; const char* b3 = b2 + kstep;
;             if (last && has_next) S.a_ready(nxt);
;             if constexpr (SP2) {
;             PG8_LDB(B0, 0, 0); PG8_LDB(B1, 0, 1); PG8_SCHED; PG8_LDA(At, 0, 0); PG8_STAGE(PG8_SA(1, 1), a1 + hstep, voffA);
;             PG8_WAIT_V(8); PG8_WAIT_L(0); PG8_BAR; PG8_MMA(0, 0, At, B0); PG8_MMA(0, 1, At, B1); PG8_BAR; PG8_SCHED;
;             PG8_LDA(At, 0, 1); PG8_STAGE(PG8_SB(0, 0), b2, voffB); PG8_STAGE(PG8_SB(0, 1), b2 + hstep, voffB); PG8_STAGE(PG8_SA(0, 0), a2, voffA);
;             PG8_WAIT_V(8); PG8_WAIT_L(0); PG8_BAR; PG8_MMA(1, 0, At, B0); PG8_MMA(1, 1, At, B1); PG8_BAR; PG8_SCHED;
.LBB0_413:
	s_ashr_i32 s43, s42, 31
	s_lshl_b64 s[48:49], s[42:43], 19
	s_add_u32 s48, s36, s48
	s_addc_u32 s49, s37, s49
	s_and_b64 s[50:51], s[4:5], exec
	s_cselect_b32 s43, s49, s21
	s_cselect_b32 s78, s48, s20
	s_ashr_i32 s19, s18, 31
	s_lshl_b64 s[50:51], s[18:19], 19
	s_add_u32 s50, s61, s50
	s_addc_u32 s51, s62, s51
	s_and_b64 s[54:55], s[4:5], exec
	s_cselect_b32 s19, s51, s53
	s_cselect_b32 s79, s50, s52
	s_add_u32 s20, s20, 0x40080
	s_addc_u32 s21, s21, 0
	s_add_u32 s80, s52, 0x100
	s_addc_u32 s81, s53, 0
	s_mov_b32 s84, -2
	ds_read_b128 v[146:149], v165
	ds_read_b128 v[150:153], v165 offset:1024
	ds_read_b128 v[154:157], v165 offset:2048
	ds_read_b128 v[168:171], v165 offset:3072
	ds_read_b128 v[172:175], v166
	ds_read_b128 v[176:179], v166 offset:1024
	ds_read_b128 v[180:183], v166 offset:2048
	ds_read_b128 v[184:187], v166 offset:3072
	s_add_u32 s52, s20, 0xfffc0080
	s_addc_u32 s53, s21, -1
	s_cmp_eq_u32 s84, 12
	s_cselect_b32 s55, s43, s53
	s_cselect_b32 s54, s78, s52
	s_cselect_b32 s53, s19, s81
	s_cselect_b32 s52, s79, s80
	s_add_i32 m0, s35, 0xc000
	ds_read_b128 v[188:191], v167
	ds_read_b128 v[192:195], v167 offset:1024
	ds_read_b128 v[198:201], v167 offset:2048
	ds_read_b128 v[202:205], v167 offset:3072
	ds_read_b128 v[206:209], v167 offset:4096
	ds_read_b128 v[210:213], v167 offset:5120
	ds_read_b128 v[214:217], v167 offset:6144
	ds_read_b128 v[218:221], v167 offset:7168
	global_load_lds_dwordx4 v138, s[20:21]
	s_add_i32 m0, s35, 0xe000
	s_nop 0
	global_load_lds_dwordx4 v140, s[20:21]
	s_waitcnt vmcnt(8)
	s_waitcnt lgkmcnt(0)
	s_barrier
	v_mfma_f32_16x16x32_bf16 v[124:127], v[146:149], v[188:191], 0
	v_mfma_f32_16x16x32_bf16 v[120:123], v[154:157], v[188:191], 0
	v_mfma_f32_16x16x32_bf16 v[108:111], v[146:149], v[198:201], 0
	v_mfma_f32_16x16x32_bf16 v[104:107], v[154:157], v[198:201], 0
	v_mfma_f32_16x16x32_bf16 v[92:95], v[146:149], v[206:209], 0
	v_mfma_f32_16x16x32_bf16 v[88:91], v[154:157], v[206:209], 0
	v_mfma_f32_16x16x32_bf16 v[76:79], v[146:149], v[214:217], 0
	v_mfma_f32_16x16x32_bf16 v[72:75], v[154:157], v[214:217], 0
	v_mfma_f32_16x16x32_bf16 v[124:127], v[150:153], v[192:195], v[124:127]
	v_mfma_f32_16x16x32_bf16 v[120:123], v[168:171], v[192:195], v[120:123]
	v_mfma_f32_16x16x32_bf16 v[108:111], v[150:153], v[202:205], v[108:111]
	v_mfma_f32_16x16x32_bf16 v[104:107], v[168:171], v[202:205], v[104:107]
	v_mfma_f32_16x16x32_bf16 v[92:95], v[150:153], v[210:213], v[92:95]
	v_mfma_f32_16x16x32_bf16 v[88:91], v[168:171], v[210:213], v[88:91]
	v_mfma_f32_16x16x32_bf16 v[76:79], v[150:153], v[218:221], v[76:79]
	v_mfma_f32_16x16x32_bf16 v[72:75], v[168:171], v[218:221], v[72:75]
	v_mfma_f32_16x16x32_bf16 v[116:119], v[172:175], v[188:191], 0
	v_mfma_f32_16x16x32_bf16 v[112:115], v[180:183], v[188:191], 0
	v_mfma_f32_16x16x32_bf16 v[100:103], v[172:175], v[198:201], 0
	v_mfma_f32_16x16x32_bf16 v[96:99], v[180:183], v[198:201], 0
	v_mfma_f32_16x16x32_bf16 v[84:87], v[172:175], v[206:209], 0
	v_mfma_f32_16x16x32_bf16 v[80:83], v[180:183], v[206:209], 0
	v_mfma_f32_16x16x32_bf16 v[68:71], v[172:175], v[214:217], 0
	v_mfma_f32_16x16x32_bf16 v[64:67], v[180:183], v[214:217], 0
	v_mfma_f32_16x16x32_bf16 v[116:119], v[176:179], v[192:195], v[116:119]
	v_mfma_f32_16x16x32_bf16 v[112:115], v[184:187], v[192:195], v[112:115]
	v_mfma_f32_16x16x32_bf16 v[100:103], v[176:179], v[202:205], v[100:103]
	v_mfma_f32_16x16x32_bf16 v[96:99], v[184:187], v[202:205], v[96:99]
	v_mfma_f32_16x16x32_bf16 v[84:87], v[176:179], v[210:213], v[84:87]
	v_mfma_f32_16x16x32_bf16 v[80:83], v[184:187], v[210:213], v[80:83]
	v_mfma_f32_16x16x32_bf16 v[68:71], v[176:179], v[218:221], v[68:71]
	v_mfma_f32_16x16x32_bf16 v[64:67], v[184:187], v[218:221], v[64:67]
	s_barrier
	s_add_i32 s85, s72, s63
	s_add_u32 s98, s52, s8
	s_addc_u32 s99, s53, s9
	s_add_u32 s100, s54, s8
	s_addc_u32 s101, s55, s9
	s_mov_b32 m0, s85
	ds_read_b128 v[188:191], v167 offset:16384
	ds_read_b128 v[192:195], v167 offset:17408
	ds_read_b128 v[198:201], v167 offset:18432
	ds_read_b128 v[202:205], v167 offset:19456
	ds_read_b128 v[206:209], v167 offset:20480
	ds_read_b128 v[210:213], v167 offset:21504
	ds_read_b128 v[214:217], v167 offset:22528
	ds_read_b128 v[218:221], v167 offset:23552
	global_load_lds_dwordx4 v132, s[52:53]
	s_add_i32 m0, s85, 0x2000
	s_add_u32 s86, s52, 0x40000
	s_addc_u32 s87, s53, 0
	s_add_i32 s85, s73, s63
	global_load_lds_dwordx4 v128, s[52:53]
	s_mov_b32 m0, s85
	s_nop 0
	global_load_lds_dwordx4 v132, s[86:87]
	s_add_i32 m0, s85, 0x2000
	s_nop 0
	global_load_lds_dwordx4 v128, s[86:87]
	s_mov_b32 m0, s35
	s_nop 0
	global_load_lds_dwordx4 v134, s[54:55]
	s_mov_b32 m0, s65
	s_nop 0
	global_load_lds_dwordx4 v130, s[54:55]
	s_nop 0
	s_waitcnt vmcnt(8)
	s_waitcnt lgkmcnt(0)
	s_barrier
; #define PG8_STAGE(bufoff, gbase, voff) do { _Pragma("unroll") for (int _i = 0; _i < 2; ++_i) \
;         __builtin_amdgcn_global_load_lds((const unsigned*)((const char*)(gbase) + (voff)[_i]), (PG8_LAS unsigned*)(lds + (bufoff) + ldsw + _i * 8192), 16, 0, 0); } while (0)
; #define PG8_LDA(dst, b, h) do { _Pragma("unroll") for (int m = 0; m < 4; ++m) _Pragma("unroll") for (int k = 0; k < 2; ++k) dst[m][k] = *(const PG8_LAS bf16x8*)(lds + PG8_SA(b, h) + aoff + m * 2048 + k * 1024); } while (0)
; #define PG8_LDB(dst, b, h) do { _Pragma("unroll") for (int n = 0; n < 2; ++n) _Pragma("unroll") for (int k = 0; k < 2; ++k) dst[n][k] = *(const PG8_LAS bf16x8*)(lds + PG8_SB(b, h) + boff + n * 2048 + k * 1024); } while (0)
; #define PG8_MMA(ai, bj, At, Bt) do { __builtin_amdgcn_s_setprio(1); _Pragma("unroll") for (int m = 0; m < 4; ++m) _Pragma("unroll") for (int n = 0; n < 2; ++n) _Pragma("unroll") for (int k = 0; k < 2; ++k) \
;         acc[ai][bj][m][n] = __builtin_amdgcn_mfma_f32_16x16x32_bf16(Bt[n][k], At[m][k], acc[ai][bj][m][n], 0, 0, 0); __builtin_amdgcn_s_setprio(0); } while (0)
; #define PG8_WAIT_V(n) asm volatile("s_waitcnt vmcnt(" #n ")" ::: "memory")
; #define PG8_WAIT_L(n) asm volatile("s_waitcnt lgkmcnt(" #n ")" ::: "memory")
; #define PG8_BAR __builtin_amdgcn_s_barrier()
; #define PG8_SCHED __builtin_amdgcn_sched_barrier(0)
; template <class Epi, class Sched, bool ALIGN_EPI = false, bool SP2 = false>
; __device__ __forceinline__ void gemm_phase(PG8_LAS unsigned char* lds, const Gemm g, const Sched& S, const Epi& E) {
;     ...
;             PG8_WAIT_V(8); PG8_WAIT_L(0); PG8_BAR; PG8_MMA(1, 0, At, B0); PG8_MMA(1, 1, At, B1); PG8_BAR; PG8_SCHED;
;             PG8_LDB(B0, 1, 0); PG8_LDB(B1, 1, 1); PG8_SCHED; PG8_LDA(At, 1, 0); PG8_STAGE(PG8_SA(0, 1), a2 + hstep, voffA);
;             PG8_WAIT_V(8); PG8_WAIT_L(0); PG8_BAR; PG8_MMA(0, 0, At, B0); PG8_MMA(0, 1, At, B1); PG8_BAR; PG8_SCHED;
	v_mfma_f32_16x16x32_bf16 v[60:63], v[146:149], v[188:191], 0
	v_mfma_f32_16x16x32_bf16 v[56:59], v[154:157], v[188:191], 0
	v_mfma_f32_16x16x32_bf16 v[44:47], v[146:149], v[198:201], 0
	v_mfma_f32_16x16x32_bf16 v[40:43], v[154:157], v[198:201], 0
	v_mfma_f32_16x16x32_bf16 v[28:31], v[146:149], v[206:209], 0
	v_mfma_f32_16x16x32_bf16 v[24:27], v[154:157], v[206:209], 0
	v_mfma_f32_16x16x32_bf16 v[12:15], v[146:149], v[214:217], 0
	v_mfma_f32_16x16x32_bf16 v[8:11], v[154:157], v[214:217], 0
	v_mfma_f32_16x16x32_bf16 v[60:63], v[150:153], v[192:195], v[60:63]
	v_mfma_f32_16x16x32_bf16 v[56:59], v[168:171], v[192:195], v[56:59]
	v_mfma_f32_16x16x32_bf16 v[44:47], v[150:153], v[202:205], v[44:47]
	v_mfma_f32_16x16x32_bf16 v[40:43], v[168:171], v[202:205], v[40:43]
	v_mfma_f32_16x16x32_bf16 v[28:31], v[150:153], v[210:213], v[28:31]
	v_mfma_f32_16x16x32_bf16 v[24:27], v[168:171], v[210:213], v[24:27]
	v_mfma_f32_16x16x32_bf16 v[12:15], v[150:153], v[218:221], v[12:15]
	v_mfma_f32_16x16x32_bf16 v[8:11], v[168:171], v[218:221], v[8:11]
	v_mfma_f32_16x16x32_bf16 v[52:55], v[172:175], v[188:191], 0
	v_mfma_f32_16x16x32_bf16 v[48:51], v[180:183], v[188:191], 0
	v_mfma_f32_16x16x32_bf16 v[36:39], v[172:175], v[198:201], 0
	v_mfma_f32_16x16x32_bf16 v[32:35], v[180:183], v[198:201], 0
	v_mfma_f32_16x16x32_bf16 v[20:23], v[172:175], v[206:209], 0
	v_mfma_f32_16x16x32_bf16 v[16:19], v[180:183], v[206:209], 0
	v_mfma_f32_16x16x32_bf16 v[4:7], v[172:175], v[214:217], 0
	v_mfma_f32_16x16x32_bf16 v[0:3], v[180:183], v[214:217], 0
	v_mfma_f32_16x16x32_bf16 v[52:55], v[176:179], v[192:195], v[52:55]
	v_mfma_f32_16x16x32_bf16 v[48:51], v[184:187], v[192:195], v[48:51]
	v_mfma_f32_16x16x32_bf16 v[36:39], v[176:179], v[202:205], v[36:39]
	v_mfma_f32_16x16x32_bf16 v[32:35], v[184:187], v[202:205], v[32:35]
	v_mfma_f32_16x16x32_bf16 v[20:23], v[176:179], v[210:213], v[20:23]
	v_mfma_f32_16x16x32_bf16 v[16:19], v[184:187], v[210:213], v[16:19]
	v_mfma_f32_16x16x32_bf16 v[4:7], v[176:179], v[218:221], v[4:7]
	v_mfma_f32_16x16x32_bf16 v[0:3], v[184:187], v[218:221], v[0:3]
	s_barrier
	s_add_i32 s85, 0, 0x18000
	v_add_u32_e32 v136, s85, v161
	s_add_i32 s86, 0, 0x1c000
	ds_read_b128 v[146:149], v136
	ds_read_b128 v[150:153], v136 offset:1024
	ds_read_b128 v[154:157], v136 offset:2048
	ds_read_b128 v[168:171], v136 offset:3072
	v_add_u32_e32 v136, s86, v161
	ds_read_b128 v[172:175], v136
	ds_read_b128 v[176:179], v136 offset:1024
	ds_read_b128 v[180:183], v136 offset:2048
	ds_read_b128 v[184:187], v136 offset:3072
	s_add_u32 s54, s54, 0x40000
	s_addc_u32 s55, s55, 0
	s_mov_b32 m0, s66
	ds_read_b128 v[188:191], v167 offset:32768
	ds_read_b128 v[192:195], v167 offset:33792
	ds_read_b128 v[198:201], v167 offset:34816
	ds_read_b128 v[202:205], v167 offset:35840
	ds_read_b128 v[206:209], v167 offset:36864
	ds_read_b128 v[210:213], v167 offset:37888
	ds_read_b128 v[214:217], v167 offset:38912
	ds_read_b128 v[218:221], v167 offset:39936
	global_load_lds_dwordx4 v134, s[54:55]
	s_mov_b32 m0, s67
	s_nop 0
	global_load_lds_dwordx4 v130, s[54:55]
	s_waitcnt vmcnt(8)
	s_waitcnt lgkmcnt(0)
	s_barrier
	v_mfma_f32_16x16x32_bf16 v[124:127], v[146:149], v[188:191], v[124:127]
	v_mfma_f32_16x16x32_bf16 v[120:123], v[154:157], v[188:191], v[120:123]
	v_mfma_f32_16x16x32_bf16 v[108:111], v[146:149], v[198:201], v[108:111]
	v_mfma_f32_16x16x32_bf16 v[104:107], v[154:157], v[198:201], v[104:107]
	v_mfma_f32_16x16x32_bf16 v[92:95], v[146:149], v[206:209], v[92:95]
	v_mfma_f32_16x16x32_bf16 v[88:91], v[154:157], v[206:209], v[88:91]
	v_mfma_f32_16x16x32_bf16 v[76:79], v[146:149], v[214:217], v[76:79]
	v_mfma_f32_16x16x32_bf16 v[72:75], v[154:157], v[214:217], v[72:75]
	v_mfma_f32_16x16x32_bf16 v[124:127], v[150:153], v[192:195], v[124:127]
	v_mfma_f32_16x16x32_bf16 v[120:123], v[168:171], v[192:195], v[120:123]
	v_mfma_f32_16x16x32_bf16 v[108:111], v[150:153], v[202:205], v[108:111]
	v_mfma_f32_16x16x32_bf16 v[104:107], v[168:171], v[202:205], v[104:107]
	v_mfma_f32_16x16x32_bf16 v[92:95], v[150:153], v[210:213], v[92:95]
	v_mfma_f32_16x16x32_bf16 v[88:91], v[168:171], v[210:213], v[88:91]
	v_mfma_f32_16x16x32_bf16 v[76:79], v[150:153], v[218:221], v[76:79]
	v_mfma_f32_16x16x32_bf16 v[72:75], v[168:171], v[218:221], v[72:75]
	v_mfma_f32_16x16x32_bf16 v[116:119], v[172:175], v[188:191], v[116:119]
	v_mfma_f32_16x16x32_bf16 v[112:115], v[180:183], v[188:191], v[112:115]
	v_mfma_f32_16x16x32_bf16 v[100:103], v[172:175], v[198:201], v[100:103]
	v_mfma_f32_16x16x32_bf16 v[96:99], v[180:183], v[198:201], v[96:99]
	v_mfma_f32_16x16x32_bf16 v[84:87], v[172:175], v[206:209], v[84:87]
	v_mfma_f32_16x16x32_bf16 v[80:83], v[180:183], v[206:209], v[80:83]
	v_mfma_f32_16x16x32_bf16 v[68:71], v[172:175], v[214:217], v[68:71]
	v_mfma_f32_16x16x32_bf16 v[64:67], v[180:183], v[214:217], v[64:67]
	v_mfma_f32_16x16x32_bf16 v[116:119], v[176:179], v[192:195], v[116:119]
	v_mfma_f32_16x16x32_bf16 v[112:115], v[184:187], v[192:195], v[112:115]
	v_mfma_f32_16x16x32_bf16 v[100:103], v[176:179], v[202:205], v[100:103]
	v_mfma_f32_16x16x32_bf16 v[96:99], v[184:187], v[202:205], v[96:99]
	v_mfma_f32_16x16x32_bf16 v[84:87], v[176:179], v[210:213], v[84:87]
	v_mfma_f32_16x16x32_bf16 v[80:83], v[184:187], v[210:213], v[80:83]
	v_mfma_f32_16x16x32_bf16 v[68:71], v[176:179], v[218:221], v[68:71]
	v_mfma_f32_16x16x32_bf16 v[64:67], v[184:187], v[218:221], v[64:67]
	s_barrier
; #define PG8_STAGE(bufoff, gbase, voff) do { _Pragma("unroll") for (int _i = 0; _i < 2; ++_i) \
;         __builtin_amdgcn_global_load_lds((const unsigned*)((const char*)(gbase) + (voff)[_i]), (PG8_LAS unsigned*)(lds + (bufoff) + ldsw + _i * 8192), 16, 0, 0); } while (0)
; #define PG8_LDA(dst, b, h) do { _Pragma("unroll") for (int m = 0; m < 4; ++m) _Pragma("unroll") for (int k = 0; k < 2; ++k) dst[m][k] = *(const PG8_LAS bf16x8*)(lds + PG8_SA(b, h) + aoff + m * 2048 + k * 1024); } while (0)
; #define PG8_LDB(dst, b, h) do { _Pragma("unroll") for (int n = 0; n < 2; ++n) _Pragma("unroll") for (int k = 0; k < 2; ++k) dst[n][k] = *(const PG8_LAS bf16x8*)(lds + PG8_SB(b, h) + boff + n * 2048 + k * 1024); } while (0)
; #define PG8_MMA(ai, bj, At, Bt) do { __builtin_amdgcn_s_setprio(1); _Pragma("unroll") for (int m = 0; m < 4; ++m) _Pragma("unroll") for (int n = 0; n < 2; ++n) _Pragma("unroll") for (int k = 0; k < 2; ++k) \
;         acc[ai][bj][m][n] = __builtin_amdgcn_mfma_f32_16x16x32_bf16(Bt[n][k], At[m][k], acc[ai][bj][m][n], 0, 0, 0); __builtin_amdgcn_s_setprio(0); } while (0)
; #define PG8_WAIT_V(n) asm volatile("s_waitcnt vmcnt(" #n ")" ::: "memory")
; template <class Epi, class Sched, bool ALIGN_EPI = false, bool SP2 = false>
; __device__ __forceinline__ void gemm_phase(PG8_LAS unsigned char* lds, const Gemm g, const Sched& S, const Epi& E) {
;     ...
;             PG8_LDB(B0, 0, 0); PG8_LDB(B1, 0, 1); PG8_SCHED; PG8_LDA(At, 0, 0); PG8_STAGE(PG8_SA(1, 1), a1 + hstep, voffA);
;             PG8_WAIT_V(8); PG8_WAIT_L(0); PG8_BAR; PG8_MMA(0, 0, At, B0); PG8_MMA(0, 1, At, B1); PG8_BAR; PG8_SCHED;
;             PG8_LDA(At, 0, 1); PG8_STAGE(PG8_SB(0, 0), b2, voffB); PG8_STAGE(PG8_SB(0, 1), b2 + hstep, voffB); PG8_STAGE(PG8_SA(0, 0), a2, voffA);
;             PG8_WAIT_V(8); PG8_WAIT_L(0); PG8_BAR; PG8_MMA(1, 0, At, B0); PG8_MMA(1, 1, At, B1); PG8_BAR; PG8_SCHED;
;             PG8_LDB(B0, 1, 0); PG8_LDB(B1, 1, 1); PG8_SCHED; PG8_LDA(At, 1, 0); PG8_STAGE(PG8_SA(0, 1), a2 + hstep, voffA);
;             PG8_WAIT_V(8); PG8_WAIT_L(0); PG8_BAR; PG8_MMA(0, 0, At, B0); PG8_MMA(0, 1, At, B1); PG8_BAR; PG8_SCHED;
;             PG8_LDA(At, 1, 1); PG8_STAGE(PG8_SB(1, 0), b3, voffB); PG8_STAGE(PG8_SB(1, 1), b3 + hstep, voffB); PG8_STAGE(PG8_SA(1, 0), a3, voffA);
;             PG8_WAIT_V(8); PG8_WAIT_L(0); PG8_BAR; PG8_MMA(1, 0, At, B0); PG8_MMA(1, 1, At, B1); PG8_BAR; PG8_SCHED;
	s_add_i32 s54, s85, s63
	s_mov_b32 m0, s54
	ds_read_b128 v[188:191], v167 offset:49152
	ds_read_b128 v[192:195], v167 offset:50176
	ds_read_b128 v[198:201], v167 offset:51200
	ds_read_b128 v[202:205], v167 offset:52224
	ds_read_b128 v[206:209], v167 offset:53248
	ds_read_b128 v[210:213], v167 offset:54272
	ds_read_b128 v[214:217], v167 offset:55296
	ds_read_b128 v[218:221], v167 offset:56320
	global_load_lds_dwordx4 v132, s[98:99]
	s_add_i32 m0, s54, 0x2000
	s_add_u32 s52, s52, 0x40080
	s_addc_u32 s53, s53, 0
	s_add_i32 s54, s86, s63
	global_load_lds_dwordx4 v128, s[98:99]
	s_mov_b32 m0, s54
	s_nop 0
	global_load_lds_dwordx4 v132, s[52:53]
	s_add_i32 m0, s54, 0x2000
	s_nop 0
	global_load_lds_dwordx4 v128, s[52:53]
	s_mov_b32 m0, s69
	s_nop 0
	global_load_lds_dwordx4 v134, s[100:101]
	s_mov_b32 m0, s70
	s_nop 0
	global_load_lds_dwordx4 v130, s[100:101]
	s_nop 0
	s_waitcnt vmcnt(8)
	s_waitcnt lgkmcnt(0)
	s_barrier
	v_mfma_f32_16x16x32_bf16 v[60:63], v[146:149], v[188:191], v[60:63]
	v_mfma_f32_16x16x32_bf16 v[56:59], v[154:157], v[188:191], v[56:59]
	v_mfma_f32_16x16x32_bf16 v[44:47], v[146:149], v[198:201], v[44:47]
	v_mfma_f32_16x16x32_bf16 v[40:43], v[154:157], v[198:201], v[40:43]
	v_mfma_f32_16x16x32_bf16 v[28:31], v[146:149], v[206:209], v[28:31]
	v_mfma_f32_16x16x32_bf16 v[24:27], v[154:157], v[206:209], v[24:27]
	v_mfma_f32_16x16x32_bf16 v[12:15], v[146:149], v[214:217], v[12:15]
	v_mfma_f32_16x16x32_bf16 v[8:11], v[154:157], v[214:217], v[8:11]
	v_mfma_f32_16x16x32_bf16 v[60:63], v[150:153], v[192:195], v[60:63]
	v_mfma_f32_16x16x32_bf16 v[56:59], v[168:171], v[192:195], v[56:59]
	v_mfma_f32_16x16x32_bf16 v[44:47], v[150:153], v[202:205], v[44:47]
	v_mfma_f32_16x16x32_bf16 v[40:43], v[168:171], v[202:205], v[40:43]
	v_mfma_f32_16x16x32_bf16 v[28:31], v[150:153], v[210:213], v[28:31]
	v_mfma_f32_16x16x32_bf16 v[24:27], v[168:171], v[210:213], v[24:27]
	v_mfma_f32_16x16x32_bf16 v[12:15], v[150:153], v[218:221], v[12:15]
	v_mfma_f32_16x16x32_bf16 v[8:11], v[168:171], v[218:221], v[8:11]
	v_mfma_f32_16x16x32_bf16 v[52:55], v[172:175], v[188:191], v[52:55]
	v_mfma_f32_16x16x32_bf16 v[48:51], v[180:183], v[188:191], v[48:51]
	v_mfma_f32_16x16x32_bf16 v[36:39], v[172:175], v[198:201], v[36:39]
	v_mfma_f32_16x16x32_bf16 v[32:35], v[180:183], v[198:201], v[32:35]
	v_mfma_f32_16x16x32_bf16 v[20:23], v[172:175], v[206:209], v[20:23]
	v_mfma_f32_16x16x32_bf16 v[16:19], v[180:183], v[206:209], v[16:19]
	v_mfma_f32_16x16x32_bf16 v[4:7], v[172:175], v[214:217], v[4:7]
	v_mfma_f32_16x16x32_bf16 v[0:3], v[180:183], v[214:217], v[0:3]
	v_mfma_f32_16x16x32_bf16 v[52:55], v[176:179], v[192:195], v[52:55]
	v_mfma_f32_16x16x32_bf16 v[48:51], v[184:187], v[192:195], v[48:51]
	v_mfma_f32_16x16x32_bf16 v[36:39], v[176:179], v[202:205], v[36:39]
	v_mfma_f32_16x16x32_bf16 v[32:35], v[184:187], v[202:205], v[32:35]
	v_mfma_f32_16x16x32_bf16 v[20:23], v[176:179], v[210:213], v[20:23]
	v_mfma_f32_16x16x32_bf16 v[16:19], v[184:187], v[210:213], v[16:19]
	v_mfma_f32_16x16x32_bf16 v[4:7], v[176:179], v[218:221], v[4:7]
	v_mfma_f32_16x16x32_bf16 v[0:3], v[184:187], v[218:221], v[0:3]
	s_barrier
	s_add_i32 s84, s84, 2
	s_add_u32 s20, s20, 0x100
	s_addc_u32 s21, s21, 0
	s_add_u32 s80, s80, 0x100
	s_addc_u32 s81, s81, 0
	s_cmp_gt_u32 s84, 13
.LBB0_414:
	ds_read_b128 v[146:149], v165
	ds_read_b128 v[150:153], v165 offset:1024
	ds_read_b128 v[154:157], v165 offset:2048
	ds_read_b128 v[168:171], v165 offset:3072
	ds_read_b128 v[172:175], v166
	ds_read_b128 v[176:179], v166 offset:1024
	ds_read_b128 v[180:183], v166 offset:2048
	ds_read_b128 v[184:187], v166 offset:3072
	s_add_u32 s52, s20, 0xfffc0080
	s_addc_u32 s53, s21, -1
	s_cmp_eq_u32 s84, 12
	s_cselect_b32 s55, s43, s53
	s_cselect_b32 s54, s78, s52
	s_cselect_b32 s53, s19, s81
	s_cselect_b32 s52, s79, s80
	s_add_i32 m0, s35, 0xc000
	ds_read_b128 v[188:191], v167
	ds_read_b128 v[192:195], v167 offset:1024
	ds_read_b128 v[198:201], v167 offset:2048
	ds_read_b128 v[202:205], v167 offset:3072
	ds_read_b128 v[206:209], v167 offset:4096
	ds_read_b128 v[210:213], v167 offset:5120
	ds_read_b128 v[214:217], v167 offset:6144
	ds_read_b128 v[218:221], v167 offset:7168
	global_load_lds_dwordx4 v138, s[20:21]
	s_add_i32 m0, s35, 0xe000
	s_nop 0
	global_load_lds_dwordx4 v140, s[20:21]
	s_nop 0
	s_waitcnt vmcnt(8)
	s_waitcnt lgkmcnt(0)
	s_barrier
	v_mfma_f32_16x16x32_bf16 v[124:127], v[146:149], v[188:191], v[124:127]
	v_mfma_f32_16x16x32_bf16 v[120:123], v[154:157], v[188:191], v[120:123]
	v_mfma_f32_16x16x32_bf16 v[108:111], v[146:149], v[198:201], v[108:111]
	v_mfma_f32_16x16x32_bf16 v[104:107], v[154:157], v[198:201], v[104:107]
	v_mfma_f32_16x16x32_bf16 v[92:95], v[146:149], v[206:209], v[92:95]
	v_mfma_f32_16x16x32_bf16 v[88:91], v[154:157], v[206:209], v[88:91]
	v_mfma_f32_16x16x32_bf16 v[76:79], v[146:149], v[214:217], v[76:79]
	v_mfma_f32_16x16x32_bf16 v[72:75], v[154:157], v[214:217], v[72:75]
	v_mfma_f32_16x16x32_bf16 v[124:127], v[150:153], v[192:195], v[124:127]
	v_mfma_f32_16x16x32_bf16 v[120:123], v[168:171], v[192:195], v[120:123]
	v_mfma_f32_16x16x32_bf16 v[108:111], v[150:153], v[202:205], v[108:111]
	v_mfma_f32_16x16x32_bf16 v[104:107], v[168:171], v[202:205], v[104:107]
	v_mfma_f32_16x16x32_bf16 v[92:95], v[150:153], v[210:213], v[92:95]
	v_mfma_f32_16x16x32_bf16 v[88:91], v[168:171], v[210:213], v[88:91]
	v_mfma_f32_16x16x32_bf16 v[76:79], v[150:153], v[218:221], v[76:79]
	v_mfma_f32_16x16x32_bf16 v[72:75], v[168:171], v[218:221], v[72:75]
	v_mfma_f32_16x16x32_bf16 v[116:119], v[172:175], v[188:191], v[116:119]
	v_mfma_f32_16x16x32_bf16 v[112:115], v[180:183], v[188:191], v[112:115]
	v_mfma_f32_16x16x32_bf16 v[100:103], v[172:175], v[198:201], v[100:103]
	v_mfma_f32_16x16x32_bf16 v[96:99], v[180:183], v[198:201], v[96:99]
	v_mfma_f32_16x16x32_bf16 v[84:87], v[172:175], v[206:209], v[84:87]
	v_mfma_f32_16x16x32_bf16 v[80:83], v[180:183], v[206:209], v[80:83]
	v_mfma_f32_16x16x32_bf16 v[68:71], v[172:175], v[214:217], v[68:71]
	v_mfma_f32_16x16x32_bf16 v[64:67], v[180:183], v[214:217], v[64:67]
	v_mfma_f32_16x16x32_bf16 v[116:119], v[176:179], v[192:195], v[116:119]
	v_mfma_f32_16x16x32_bf16 v[112:115], v[184:187], v[192:195], v[112:115]
	v_mfma_f32_16x16x32_bf16 v[100:103], v[176:179], v[202:205], v[100:103]
	v_mfma_f32_16x16x32_bf16 v[96:99], v[184:187], v[202:205], v[96:99]
	v_mfma_f32_16x16x32_bf16 v[84:87], v[176:179], v[210:213], v[84:87]
	v_mfma_f32_16x16x32_bf16 v[80:83], v[184:187], v[210:213], v[80:83]
	v_mfma_f32_16x16x32_bf16 v[68:71], v[176:179], v[218:221], v[68:71]
	v_mfma_f32_16x16x32_bf16 v[64:67], v[184:187], v[218:221], v[64:67]
	s_barrier
; #define PG8_STAGE(bufoff, gbase, voff) do { _Pragma("unroll") for (int _i = 0; _i < 2; ++_i) \
;         __builtin_amdgcn_global_load_lds((const unsigned*)((const char*)(gbase) + (voff)[_i]), (PG8_LAS unsigned*)(lds + (bufoff) + ldsw + _i * 8192), 16, 0, 0); } while (0)
; #define PG8_LDA(dst, b, h) do { _Pragma("unroll") for (int m = 0; m < 4; ++m) _Pragma("unroll") for (int k = 0; k < 2; ++k) dst[m][k] = *(const PG8_LAS bf16x8*)(lds + PG8_SA(b, h) + aoff + m * 2048 + k * 1024); } while (0)
; #define PG8_LDB(dst, b, h) do { _Pragma("unroll") for (int n = 0; n < 2; ++n) _Pragma("unroll") for (int k = 0; k < 2; ++k) dst[n][k] = *(const PG8_LAS bf16x8*)(lds + PG8_SB(b, h) + boff + n * 2048 + k * 1024); } while (0)
; #define PG8_MMA(ai, bj, At, Bt) do { __builtin_amdgcn_s_setprio(1); _Pragma("unroll") for (int m = 0; m < 4; ++m) _Pragma("unroll") for (int n = 0; n < 2; ++n) _Pragma("unroll") for (int k = 0; k < 2; ++k) \
;         acc[ai][bj][m][n] = __builtin_amdgcn_mfma_f32_16x16x32_bf16(Bt[n][k], At[m][k], acc[ai][bj][m][n], 0, 0, 0); __builtin_amdgcn_s_setprio(0); } while (0)
; #define PG8_WAIT_V(n) asm volatile("s_waitcnt vmcnt(" #n ")" ::: "memory")
; #define PG8_WAIT_L(n) asm volatile("s_waitcnt lgkmcnt(" #n ")" ::: "memory")
; #define PG8_BAR __builtin_amdgcn_s_barrier()
; #define PG8_SCHED __builtin_amdgcn_sched_barrier(0)
; template <class Epi, class Sched, bool ALIGN_EPI = false, bool SP2 = false>
; __device__ __forceinline__ void gemm_phase(PG8_LAS unsigned char* lds, const Gemm g, const Sched& S, const Epi& E) {
;     ...
;             PG8_LDA(At, 0, 1); PG8_STAGE(PG8_SB(0, 0), b2, voffB); PG8_STAGE(PG8_SB(0, 1), b2 + hstep, voffB); PG8_STAGE(PG8_SA(0, 0), a2, voffA);
;             PG8_WAIT_V(8); PG8_WAIT_L(0); PG8_BAR; PG8_MMA(1, 0, At, B0); PG8_MMA(1, 1, At, B1); PG8_BAR; PG8_SCHED;
;             PG8_LDB(B0, 1, 0); PG8_LDB(B1, 1, 1); PG8_SCHED; PG8_LDA(At, 1, 0); PG8_STAGE(PG8_SA(0, 1), a2 + hstep, voffA);
;             PG8_WAIT_V(8); PG8_WAIT_L(0); PG8_BAR; PG8_MMA(0, 0, At, B0); PG8_MMA(0, 1, At, B1); PG8_BAR; PG8_SCHED;
	s_add_i32 s85, s72, s63
	s_add_u32 s98, s52, s8
	s_addc_u32 s99, s53, s9
	s_add_u32 s100, s54, s8
	s_addc_u32 s101, s55, s9
	s_mov_b32 m0, s85
	ds_read_b128 v[188:191], v167 offset:16384
	ds_read_b128 v[192:195], v167 offset:17408
	ds_read_b128 v[198:201], v167 offset:18432
	ds_read_b128 v[202:205], v167 offset:19456
	ds_read_b128 v[206:209], v167 offset:20480
	ds_read_b128 v[210:213], v167 offset:21504
	ds_read_b128 v[214:217], v167 offset:22528
	ds_read_b128 v[218:221], v167 offset:23552
	global_load_lds_dwordx4 v132, s[52:53]
	s_add_i32 m0, s85, 0x2000
	s_add_u32 s86, s52, 0x40000
	s_addc_u32 s87, s53, 0
	s_add_i32 s85, s73, s63
	global_load_lds_dwordx4 v128, s[52:53]
	s_mov_b32 m0, s85
	s_nop 0
	global_load_lds_dwordx4 v132, s[86:87]
	s_add_i32 m0, s85, 0x2000
	s_nop 0
	global_load_lds_dwordx4 v128, s[86:87]
	s_mov_b32 m0, s35
	s_nop 0
	global_load_lds_dwordx4 v134, s[54:55]
	s_mov_b32 m0, s65
	s_nop 0
	global_load_lds_dwordx4 v130, s[54:55]
	s_nop 0
	s_waitcnt vmcnt(8)
	s_waitcnt lgkmcnt(0)
	s_barrier
	v_mfma_f32_16x16x32_bf16 v[60:63], v[146:149], v[188:191], v[60:63]
	v_mfma_f32_16x16x32_bf16 v[56:59], v[154:157], v[188:191], v[56:59]
	v_mfma_f32_16x16x32_bf16 v[44:47], v[146:149], v[198:201], v[44:47]
	v_mfma_f32_16x16x32_bf16 v[40:43], v[154:157], v[198:201], v[40:43]
	v_mfma_f32_16x16x32_bf16 v[28:31], v[146:149], v[206:209], v[28:31]
	v_mfma_f32_16x16x32_bf16 v[24:27], v[154:157], v[206:209], v[24:27]
	v_mfma_f32_16x16x32_bf16 v[12:15], v[146:149], v[214:217], v[12:15]
	v_mfma_f32_16x16x32_bf16 v[8:11], v[154:157], v[214:217], v[8:11]
	v_mfma_f32_16x16x32_bf16 v[60:63], v[150:153], v[192:195], v[60:63]
	v_mfma_f32_16x16x32_bf16 v[56:59], v[168:171], v[192:195], v[56:59]
	v_mfma_f32_16x16x32_bf16 v[44:47], v[150:153], v[202:205], v[44:47]
	v_mfma_f32_16x16x32_bf16 v[40:43], v[168:171], v[202:205], v[40:43]
	v_mfma_f32_16x16x32_bf16 v[28:31], v[150:153], v[210:213], v[28:31]
	v_mfma_f32_16x16x32_bf16 v[24:27], v[168:171], v[210:213], v[24:27]
	v_mfma_f32_16x16x32_bf16 v[12:15], v[150:153], v[218:221], v[12:15]
	v_mfma_f32_16x16x32_bf16 v[8:11], v[168:171], v[218:221], v[8:11]
	v_mfma_f32_16x16x32_bf16 v[52:55], v[172:175], v[188:191], v[52:55]
	v_mfma_f32_16x16x32_bf16 v[48:51], v[180:183], v[188:191], v[48:51]
	v_mfma_f32_16x16x32_bf16 v[36:39], v[172:175], v[198:201], v[36:39]
	v_mfma_f32_16x16x32_bf16 v[32:35], v[180:183], v[198:201], v[32:35]
	v_mfma_f32_16x16x32_bf16 v[20:23], v[172:175], v[206:209], v[20:23]
	v_mfma_f32_16x16x32_bf16 v[16:19], v[180:183], v[206:209], v[16:19]
	v_mfma_f32_16x16x32_bf16 v[4:7], v[172:175], v[214:217], v[4:7]
	v_mfma_f32_16x16x32_bf16 v[0:3], v[180:183], v[214:217], v[0:3]
	v_mfma_f32_16x16x32_bf16 v[52:55], v[176:179], v[192:195], v[52:55]
	v_mfma_f32_16x16x32_bf16 v[48:51], v[184:187], v[192:195], v[48:51]
	v_mfma_f32_16x16x32_bf16 v[36:39], v[176:179], v[202:205], v[36:39]
	v_mfma_f32_16x16x32_bf16 v[32:35], v[184:187], v[202:205], v[32:35]
	v_mfma_f32_16x16x32_bf16 v[20:23], v[176:179], v[210:213], v[20:23]
	v_mfma_f32_16x16x32_bf16 v[16:19], v[184:187], v[210:213], v[16:19]
	v_mfma_f32_16x16x32_bf16 v[4:7], v[176:179], v[218:221], v[4:7]
	v_mfma_f32_16x16x32_bf16 v[0:3], v[184:187], v[218:221], v[0:3]
	s_barrier
	s_add_i32 s85, 0, 0x18000
	v_add_u32_e32 v136, s85, v161
	s_add_i32 s86, 0, 0x1c000
	ds_read_b128 v[146:149], v136
	ds_read_b128 v[150:153], v136 offset:1024
	ds_read_b128 v[154:157], v136 offset:2048
	ds_read_b128 v[168:171], v136 offset:3072
	v_add_u32_e32 v136, s86, v161
	ds_read_b128 v[172:175], v136
	ds_read_b128 v[176:179], v136 offset:1024
	ds_read_b128 v[180:183], v136 offset:2048
	ds_read_b128 v[184:187], v136 offset:3072
	s_add_u32 s54, s54, 0x40000
	s_addc_u32 s55, s55, 0
	s_mov_b32 m0, s66
	ds_read_b128 v[188:191], v167 offset:32768
	ds_read_b128 v[192:195], v167 offset:33792
	ds_read_b128 v[198:201], v167 offset:34816
	ds_read_b128 v[202:205], v167 offset:35840
	ds_read_b128 v[206:209], v167 offset:36864
	ds_read_b128 v[210:213], v167 offset:37888
	ds_read_b128 v[214:217], v167 offset:38912
	ds_read_b128 v[218:221], v167 offset:39936
	global_load_lds_dwordx4 v134, s[54:55]
	s_mov_b32 m0, s67
	s_nop 0
	global_load_lds_dwordx4 v130, s[54:55]
	s_waitcnt vmcnt(8)
	s_waitcnt lgkmcnt(0)
	s_barrier
; #define PG8_STAGE(bufoff, gbase, voff) do { _Pragma("unroll") for (int _i = 0; _i < 2; ++_i) \
;         __builtin_amdgcn_global_load_lds((const unsigned*)((const char*)(gbase) + (voff)[_i]), (PG8_LAS unsigned*)(lds + (bufoff) + ldsw + _i * 8192), 16, 0, 0); } while (0)
; #define PG8_LDA(dst, b, h) do { _Pragma("unroll") for (int m = 0; m < 4; ++m) _Pragma("unroll") for (int k = 0; k < 2; ++k) dst[m][k] = *(const PG8_LAS bf16x8*)(lds + PG8_SA(b, h) + aoff + m * 2048 + k * 1024); } while (0)
; #define PG8_MMA(ai, bj, At, Bt) do { __builtin_amdgcn_s_setprio(1); _Pragma("unroll") for (int m = 0; m < 4; ++m) _Pragma("unroll") for (int n = 0; n < 2; ++n) _Pragma("unroll") for (int k = 0; k < 2; ++k) \
;         acc[ai][bj][m][n] = __builtin_amdgcn_mfma_f32_16x16x32_bf16(Bt[n][k], At[m][k], acc[ai][bj][m][n], 0, 0, 0); __builtin_amdgcn_s_setprio(0); } while (0)
; #define PG8_WAIT_V(n) asm volatile("s_waitcnt vmcnt(" #n ")" ::: "memory")
; #define PG8_WAIT_L(n) asm volatile("s_waitcnt lgkmcnt(" #n ")" ::: "memory")
; #define PG8_BAR __builtin_amdgcn_s_barrier()
; #define PG8_SCHED __builtin_amdgcn_sched_barrier(0)
; template <class Epi, class Sched, bool ALIGN_EPI = false, bool SP2 = false>
; __device__ __forceinline__ void gemm_phase(PG8_LAS unsigned char* lds, const Gemm g, const Sched& S, const Epi& E) {
;     ...
;             PG8_WAIT_V(8); PG8_WAIT_L(0); PG8_BAR; PG8_MMA(0, 0, At, B0); PG8_MMA(0, 1, At, B1); PG8_BAR; PG8_SCHED;
;             PG8_LDA(At, 1, 1); PG8_STAGE(PG8_SB(1, 0), b3, voffB); PG8_STAGE(PG8_SB(1, 1), b3 + hstep, voffB); PG8_STAGE(PG8_SA(1, 0), a3, voffA);
;             PG8_WAIT_V(8); PG8_WAIT_L(0); PG8_BAR; PG8_MMA(1, 0, At, B0); PG8_MMA(1, 1, At, B1); PG8_BAR; PG8_SCHED;
;     ...
;         if constexpr (ALIGN_EPI) { if (wr == 0) PG8_BAR; }
	v_mfma_f32_16x16x32_bf16 v[124:127], v[146:149], v[188:191], v[124:127]
	v_mfma_f32_16x16x32_bf16 v[120:123], v[154:157], v[188:191], v[120:123]
	v_mfma_f32_16x16x32_bf16 v[108:111], v[146:149], v[198:201], v[108:111]
	v_mfma_f32_16x16x32_bf16 v[104:107], v[154:157], v[198:201], v[104:107]
	v_mfma_f32_16x16x32_bf16 v[92:95], v[146:149], v[206:209], v[92:95]
	v_mfma_f32_16x16x32_bf16 v[88:91], v[154:157], v[206:209], v[88:91]
	v_mfma_f32_16x16x32_bf16 v[76:79], v[146:149], v[214:217], v[76:79]
	v_mfma_f32_16x16x32_bf16 v[72:75], v[154:157], v[214:217], v[72:75]
	v_mfma_f32_16x16x32_bf16 v[124:127], v[150:153], v[192:195], v[124:127]
	v_mfma_f32_16x16x32_bf16 v[120:123], v[168:171], v[192:195], v[120:123]
	v_mfma_f32_16x16x32_bf16 v[108:111], v[150:153], v[202:205], v[108:111]
	v_mfma_f32_16x16x32_bf16 v[104:107], v[168:171], v[202:205], v[104:107]
	v_mfma_f32_16x16x32_bf16 v[92:95], v[150:153], v[210:213], v[92:95]
	v_mfma_f32_16x16x32_bf16 v[88:91], v[168:171], v[210:213], v[88:91]
	v_mfma_f32_16x16x32_bf16 v[76:79], v[150:153], v[218:221], v[76:79]
	v_mfma_f32_16x16x32_bf16 v[72:75], v[168:171], v[218:221], v[72:75]
	v_mfma_f32_16x16x32_bf16 v[116:119], v[172:175], v[188:191], v[116:119]
	v_mfma_f32_16x16x32_bf16 v[112:115], v[180:183], v[188:191], v[112:115]
	v_mfma_f32_16x16x32_bf16 v[100:103], v[172:175], v[198:201], v[100:103]
	v_mfma_f32_16x16x32_bf16 v[96:99], v[180:183], v[198:201], v[96:99]
	v_mfma_f32_16x16x32_bf16 v[84:87], v[172:175], v[206:209], v[84:87]
	v_mfma_f32_16x16x32_bf16 v[80:83], v[180:183], v[206:209], v[80:83]
	v_mfma_f32_16x16x32_bf16 v[68:71], v[172:175], v[214:217], v[68:71]
	v_mfma_f32_16x16x32_bf16 v[64:67], v[180:183], v[214:217], v[64:67]
	v_mfma_f32_16x16x32_bf16 v[116:119], v[176:179], v[192:195], v[116:119]
	v_mfma_f32_16x16x32_bf16 v[112:115], v[184:187], v[192:195], v[112:115]
	v_mfma_f32_16x16x32_bf16 v[100:103], v[176:179], v[202:205], v[100:103]
	v_mfma_f32_16x16x32_bf16 v[96:99], v[184:187], v[202:205], v[96:99]
	v_mfma_f32_16x16x32_bf16 v[84:87], v[176:179], v[210:213], v[84:87]
	v_mfma_f32_16x16x32_bf16 v[80:83], v[184:187], v[210:213], v[80:83]
	v_mfma_f32_16x16x32_bf16 v[68:71], v[176:179], v[218:221], v[68:71]
	v_mfma_f32_16x16x32_bf16 v[64:67], v[184:187], v[218:221], v[64:67]
	s_barrier
	s_add_i32 s54, s85, s63
	s_mov_b32 m0, s54
	ds_read_b128 v[188:191], v167 offset:49152
	ds_read_b128 v[192:195], v167 offset:50176
	ds_read_b128 v[198:201], v167 offset:51200
	ds_read_b128 v[202:205], v167 offset:52224
	ds_read_b128 v[206:209], v167 offset:53248
	ds_read_b128 v[210:213], v167 offset:54272
	ds_read_b128 v[214:217], v167 offset:55296
	ds_read_b128 v[218:221], v167 offset:56320
	global_load_lds_dwordx4 v132, s[98:99]
	s_add_i32 m0, s54, 0x2000
	s_add_u32 s52, s52, 0x40080
	s_addc_u32 s53, s53, 0
	s_add_i32 s54, s86, s63
	global_load_lds_dwordx4 v128, s[98:99]
	s_mov_b32 m0, s54
	s_nop 0
	global_load_lds_dwordx4 v132, s[52:53]
	s_add_i32 m0, s54, 0x2000
	s_nop 0
	global_load_lds_dwordx4 v128, s[52:53]
	s_mov_b32 m0, s69
	s_nop 0
	global_load_lds_dwordx4 v134, s[100:101]
	s_mov_b32 m0, s70
	s_nop 0
	global_load_lds_dwordx4 v130, s[100:101]
	s_nop 0
	s_waitcnt vmcnt(8)
	s_waitcnt lgkmcnt(0)
	s_barrier
	v_mfma_f32_16x16x32_bf16 v[60:63], v[146:149], v[188:191], v[60:63]
	v_mfma_f32_16x16x32_bf16 v[56:59], v[154:157], v[188:191], v[56:59]
	v_mfma_f32_16x16x32_bf16 v[44:47], v[146:149], v[198:201], v[44:47]
	v_mfma_f32_16x16x32_bf16 v[40:43], v[154:157], v[198:201], v[40:43]
	v_mfma_f32_16x16x32_bf16 v[28:31], v[146:149], v[206:209], v[28:31]
	v_mfma_f32_16x16x32_bf16 v[24:27], v[154:157], v[206:209], v[24:27]
	v_mfma_f32_16x16x32_bf16 v[12:15], v[146:149], v[214:217], v[12:15]
	v_mfma_f32_16x16x32_bf16 v[8:11], v[154:157], v[214:217], v[8:11]
	v_mfma_f32_16x16x32_bf16 v[60:63], v[150:153], v[192:195], v[60:63]
	v_mfma_f32_16x16x32_bf16 v[56:59], v[168:171], v[192:195], v[56:59]
	v_mfma_f32_16x16x32_bf16 v[44:47], v[150:153], v[202:205], v[44:47]
	v_mfma_f32_16x16x32_bf16 v[40:43], v[168:171], v[202:205], v[40:43]
	v_mfma_f32_16x16x32_bf16 v[28:31], v[150:153], v[210:213], v[28:31]
	v_mfma_f32_16x16x32_bf16 v[24:27], v[168:171], v[210:213], v[24:27]
	v_mfma_f32_16x16x32_bf16 v[12:15], v[150:153], v[218:221], v[12:15]
	v_mfma_f32_16x16x32_bf16 v[8:11], v[168:171], v[218:221], v[8:11]
	v_mfma_f32_16x16x32_bf16 v[52:55], v[172:175], v[188:191], v[52:55]
	v_mfma_f32_16x16x32_bf16 v[48:51], v[180:183], v[188:191], v[48:51]
	v_mfma_f32_16x16x32_bf16 v[36:39], v[172:175], v[198:201], v[36:39]
	v_mfma_f32_16x16x32_bf16 v[32:35], v[180:183], v[198:201], v[32:35]
	v_mfma_f32_16x16x32_bf16 v[20:23], v[172:175], v[206:209], v[20:23]
	v_mfma_f32_16x16x32_bf16 v[16:19], v[180:183], v[206:209], v[16:19]
	v_mfma_f32_16x16x32_bf16 v[4:7], v[172:175], v[214:217], v[4:7]
	v_mfma_f32_16x16x32_bf16 v[0:3], v[180:183], v[214:217], v[0:3]
	v_mfma_f32_16x16x32_bf16 v[52:55], v[176:179], v[192:195], v[52:55]
	v_mfma_f32_16x16x32_bf16 v[48:51], v[184:187], v[192:195], v[48:51]
	v_mfma_f32_16x16x32_bf16 v[36:39], v[176:179], v[202:205], v[36:39]
	v_mfma_f32_16x16x32_bf16 v[32:35], v[184:187], v[202:205], v[32:35]
	v_mfma_f32_16x16x32_bf16 v[20:23], v[176:179], v[210:213], v[20:23]
	v_mfma_f32_16x16x32_bf16 v[16:19], v[184:187], v[210:213], v[16:19]
	v_mfma_f32_16x16x32_bf16 v[4:7], v[176:179], v[218:221], v[4:7]
	v_mfma_f32_16x16x32_bf16 v[0:3], v[184:187], v[218:221], v[0:3]
	s_barrier
	s_add_i32 s84, s84, 2
	s_add_u32 s20, s20, 0x100
	s_addc_u32 s21, s21, 0
	s_add_u32 s80, s80, 0x100
	s_addc_u32 s81, s81, 0
	s_cmp_gt_u32 s84, 13
	s_cbranch_scc0 .LBB0_414
	s_and_b64 vcc, exec, s[10:11]
	s_cbranch_vccz .LBB0_417
	s_barrier

; #define PG8_STAGE(bufoff, gbase, voff) do { _Pragma("unroll") for (int _i = 0; _i < 2; ++_i) \
;         __builtin_amdgcn_global_load_lds((const unsigned*)((const char*)(gbase) + (voff)[_i]), (PG8_LAS unsigned*)(lds + (bufoff) + ldsw + _i * 8192), 16, 0, 0); } while (0)
; #define PG8_LDA(dst, b, h) do { _Pragma("unroll") for (int m = 0; m < 4; ++m) _Pragma("unroll") for (int k = 0; k < 2; ++k) dst[m][k] = *(const PG8_LAS bf16x8*)(lds + PG8_SA(b, h) + aoff + m * 2048 + k * 1024); } while (0)
; #define PG8_LDB(dst, b, h) do { _Pragma("unroll") for (int n = 0; n < 2; ++n) _Pragma("unroll") for (int k = 0; k < 2; ++k) dst[n][k] = *(const PG8_LAS bf16x8*)(lds + PG8_SB(b, h) + boff + n * 2048 + k * 1024); } while (0)
; #define PG8_WAIT_V(n) asm volatile("s_waitcnt vmcnt(" #n ")" ::: "memory")
; #define PG8_WAIT_L(n) asm volatile("s_waitcnt lgkmcnt(" #n ")" ::: "memory")
; #define PG8_BAR __builtin_amdgcn_s_barrier()
; #define PG8_SCHED __builtin_amdgcn_sched_barrier(0)
; template <class Epi, class Sched, bool ALIGN_EPI = false, bool SP2 = false>
; __device__ __forceinline__ void gemm_phase(PG8_LAS unsigned char* lds, const Gemm g, const Sched& S, const Epi& E) {
;     ...
;         const char* nA = has_next ? (const char*)g.A + (size_t)nxt.pm * tstep : cA; const char* nB = has_next ? (const char*)g.Bt + (size_t)nxt.pn * tstep : cB;
;         for (int t = 0; t < nt; t += 2) {
;             const bool last = (t == nt - 2);
;             const char* a1 = cA + (size_t)(t + 1) * kstep;
;             const char* a2 = last ? nA : cA + (size_t)(t + 2) * kstep; const char* b2 = last ? nB : cB + (size_t)(t + 2) * kstep;
;             const char* a3 = a2 + kstep; const char* b3 = b2 + kstep;
;             if (last && has_next) S.a_ready(nxt);
;             if constexpr (SP2) {
;             PG8_LDB(B0, 0, 0); PG8_LDB(B1, 0, 1); PG8_SCHED; PG8_LDA(At, 0, 0); PG8_STAGE(PG8_SA(1, 1), a1 + hstep, voffA);
;             PG8_WAIT_V(8); PG8_WAIT_L(0); PG8_BAR; PG8_MMA(0, 0, At, B0); PG8_MMA(0, 1, At, B1); PG8_BAR; PG8_SCHED;
;             PG8_LDA(At, 0, 1); PG8_STAGE(PG8_SB(0, 0), b2, voffB); PG8_STAGE(PG8_SB(0, 1), b2 + hstep, voffB); PG8_STAGE(PG8_SA(0, 0), a2, voffA);
;             PG8_WAIT_V(8); PG8_WAIT_L(0); PG8_BAR; PG8_MMA(1, 0, At, B0); PG8_MMA(1, 1, At, B1); PG8_BAR; PG8_SCHED;
.LBB0_623:
	s_ashr_i32 s17, s16, 31
	s_lshl_b64 s[18:19], s[16:17], 18
	s_add_u32 s18, s0, s18
	s_addc_u32 s19, s1, s19
	s_and_b64 s[38:39], s[4:5], exec
	s_cselect_b32 s17, s19, s21
	s_cselect_b32 s63, s18, s20
	s_ashr_i32 s15, s14, 31
	s_lshl_b64 s[38:39], s[14:15], 18
	s_add_u32 s38, s33, s38
	s_addc_u32 s39, s50, s39
	s_and_b64 s[48:49], s[4:5], exec
	s_cselect_b32 s15, s39, s47
	s_cselect_b32 s64, s38, s46
	s_add_u32 s20, s20, 0x20080
	s_addc_u32 s21, s21, 0
	s_add_u32 s65, s46, 0x100
	s_addc_u32 s66, s47, 0
	s_mov_b32 s67, -2
	ds_read_b128 v[112:115], v167
	ds_read_b128 v[116:119], v167 offset:1024
	ds_read_b128 v[152:155], v167 offset:2048
	ds_read_b128 v[156:159], v167 offset:3072
	ds_read_b128 v[160:163], v168
	ds_read_b128 v[170:173], v168 offset:1024
	ds_read_b128 v[174:177], v168 offset:2048
	ds_read_b128 v[178:181], v168 offset:3072
	s_add_u32 s46, s20, 0xfffe0080
	s_addc_u32 s47, s21, -1
	s_cmp_eq_u32 s67, 4
	s_cselect_b32 s49, s17, s47
	s_cselect_b32 s48, s63, s46
	s_cselect_b32 s47, s15, s66
	s_cselect_b32 s46, s64, s65
	s_add_i32 m0, s35, 0xc000
	ds_read_b128 v[182:185], v169
	ds_read_b128 v[186:189], v169 offset:1024
	ds_read_b128 v[190:193], v169 offset:2048
	ds_read_b128 v[198:201], v169 offset:3072
	ds_read_b128 v[202:205], v169 offset:4096
	ds_read_b128 v[206:209], v169 offset:5120
	ds_read_b128 v[210:213], v169 offset:6144
	ds_read_b128 v[214:217], v169 offset:7168
	global_load_lds_dwordx4 v144, s[20:21]
	s_add_i32 m0, s35, 0xe000
	s_nop 0
	global_load_lds_dwordx4 v146, s[20:21]
	s_nop 0
	s_waitcnt vmcnt(8)
	s_waitcnt lgkmcnt(0)
	s_barrier
	v_mfma_f32_16x16x32_bf16 v[132:135], v[112:115], v[182:185], 0
	v_mfma_f32_16x16x32_bf16 v[128:131], v[152:155], v[182:185], 0
	v_mfma_f32_16x16x32_bf16 v[124:127], v[112:115], v[190:193], 0
	v_mfma_f32_16x16x32_bf16 v[120:123], v[152:155], v[190:193], 0
	v_mfma_f32_16x16x32_bf16 v[108:111], v[112:115], v[202:205], 0
	v_mfma_f32_16x16x32_bf16 v[104:107], v[152:155], v[202:205], 0
	v_mfma_f32_16x16x32_bf16 v[100:103], v[112:115], v[210:213], 0
	v_mfma_f32_16x16x32_bf16 v[96:99], v[152:155], v[210:213], 0
	v_mfma_f32_16x16x32_bf16 v[132:135], v[116:119], v[186:189], v[132:135]
	v_mfma_f32_16x16x32_bf16 v[128:131], v[156:159], v[186:189], v[128:131]
	v_mfma_f32_16x16x32_bf16 v[124:127], v[116:119], v[198:201], v[124:127]
	v_mfma_f32_16x16x32_bf16 v[120:123], v[156:159], v[198:201], v[120:123]
	v_mfma_f32_16x16x32_bf16 v[108:111], v[116:119], v[206:209], v[108:111]
	v_mfma_f32_16x16x32_bf16 v[104:107], v[156:159], v[206:209], v[104:107]
	v_mfma_f32_16x16x32_bf16 v[100:103], v[116:119], v[214:217], v[100:103]
	v_mfma_f32_16x16x32_bf16 v[96:99], v[156:159], v[214:217], v[96:99]
	v_mfma_f32_16x16x32_bf16 v[60:63], v[160:163], v[182:185], 0
	v_mfma_f32_16x16x32_bf16 v[56:59], v[174:177], v[182:185], 0
	v_mfma_f32_16x16x32_bf16 v[52:55], v[160:163], v[190:193], 0
	v_mfma_f32_16x16x32_bf16 v[48:51], v[174:177], v[190:193], 0
	v_mfma_f32_16x16x32_bf16 v[44:47], v[160:163], v[202:205], 0
	v_mfma_f32_16x16x32_bf16 v[40:43], v[174:177], v[202:205], 0
	v_mfma_f32_16x16x32_bf16 v[36:39], v[160:163], v[210:213], 0
	v_mfma_f32_16x16x32_bf16 v[32:35], v[174:177], v[210:213], 0
	v_mfma_f32_16x16x32_bf16 v[60:63], v[170:173], v[186:189], v[60:63]
	v_mfma_f32_16x16x32_bf16 v[56:59], v[178:181], v[186:189], v[56:59]
	v_mfma_f32_16x16x32_bf16 v[52:55], v[170:173], v[198:201], v[52:55]
	v_mfma_f32_16x16x32_bf16 v[48:51], v[178:181], v[198:201], v[48:51]
	v_mfma_f32_16x16x32_bf16 v[44:47], v[170:173], v[206:209], v[44:47]
	v_mfma_f32_16x16x32_bf16 v[40:43], v[178:181], v[206:209], v[40:43]
	v_mfma_f32_16x16x32_bf16 v[36:39], v[170:173], v[214:217], v[36:39]
	v_mfma_f32_16x16x32_bf16 v[32:35], v[178:181], v[214:217], v[32:35]
	s_barrier
	s_add_i32 s68, s60, s51
	s_add_u32 s98, s46, s10
	s_addc_u32 s99, s47, s11
	s_add_u32 s100, s48, s10
	s_addc_u32 s101, s49, s11
	s_mov_b32 m0, s68
	ds_read_b128 v[182:185], v169 offset:16384
	ds_read_b128 v[186:189], v169 offset:17408
	ds_read_b128 v[190:193], v169 offset:18432
	ds_read_b128 v[198:201], v169 offset:19456
	ds_read_b128 v[202:205], v169 offset:20480
	ds_read_b128 v[206:209], v169 offset:21504
	ds_read_b128 v[210:213], v169 offset:22528
	ds_read_b128 v[214:217], v169 offset:23552
	global_load_lds_dwordx4 v138, s[46:47]
	s_add_i32 m0, s68, 0x2000
	s_add_u32 s68, s46, 0x20000
	s_addc_u32 s69, s47, 0
	s_add_i32 s70, s61, s51
	global_load_lds_dwordx4 v142, s[46:47]
	s_mov_b32 m0, s70
	s_nop 0
	global_load_lds_dwordx4 v138, s[68:69]
	s_add_i32 m0, s70, 0x2000
	s_nop 0
	global_load_lds_dwordx4 v142, s[68:69]
	s_mov_b32 m0, s35
	s_nop 0
	global_load_lds_dwordx4 v136, s[48:49]
	s_mov_b32 m0, s52
	s_nop 0
	global_load_lds_dwordx4 v140, s[48:49]
	s_nop 0
	s_waitcnt vmcnt(8)
	s_waitcnt lgkmcnt(0)
	s_barrier
; #define PG8_STAGE(bufoff, gbase, voff) do { _Pragma("unroll") for (int _i = 0; _i < 2; ++_i) \
;         __builtin_amdgcn_global_load_lds((const unsigned*)((const char*)(gbase) + (voff)[_i]), (PG8_LAS unsigned*)(lds + (bufoff) + ldsw + _i * 8192), 16, 0, 0); } while (0)
; #define PG8_LDA(dst, b, h) do { _Pragma("unroll") for (int m = 0; m < 4; ++m) _Pragma("unroll") for (int k = 0; k < 2; ++k) dst[m][k] = *(const PG8_LAS bf16x8*)(lds + PG8_SA(b, h) + aoff + m * 2048 + k * 1024); } while (0)
; #define PG8_LDB(dst, b, h) do { _Pragma("unroll") for (int n = 0; n < 2; ++n) _Pragma("unroll") for (int k = 0; k < 2; ++k) dst[n][k] = *(const PG8_LAS bf16x8*)(lds + PG8_SB(b, h) + boff + n * 2048 + k * 1024); } while (0)
; #define PG8_MMA(ai, bj, At, Bt) do { __builtin_amdgcn_s_setprio(1); _Pragma("unroll") for (int m = 0; m < 4; ++m) _Pragma("unroll") for (int n = 0; n < 2; ++n) _Pragma("unroll") for (int k = 0; k < 2; ++k) \
;         acc[ai][bj][m][n] = __builtin_amdgcn_mfma_f32_16x16x32_bf16(Bt[n][k], At[m][k], acc[ai][bj][m][n], 0, 0, 0); __builtin_amdgcn_s_setprio(0); } while (0)
; #define PG8_WAIT_V(n) asm volatile("s_waitcnt vmcnt(" #n ")" ::: "memory")
; #define PG8_WAIT_L(n) asm volatile("s_waitcnt lgkmcnt(" #n ")" ::: "memory")
; #define PG8_BAR __builtin_amdgcn_s_barrier()
; #define PG8_SCHED __builtin_amdgcn_sched_barrier(0)
; template <class Epi, class Sched, bool ALIGN_EPI = false, bool SP2 = false>
; __device__ __forceinline__ void gemm_phase(PG8_LAS unsigned char* lds, const Gemm g, const Sched& S, const Epi& E) {
;     ...
;             PG8_WAIT_V(8); PG8_WAIT_L(0); PG8_BAR; PG8_MMA(1, 0, At, B0); PG8_MMA(1, 1, At, B1); PG8_BAR; PG8_SCHED;
;             PG8_LDB(B0, 1, 0); PG8_LDB(B1, 1, 1); PG8_SCHED; PG8_LDA(At, 1, 0); PG8_STAGE(PG8_SA(0, 1), a2 + hstep, voffA);
;             PG8_WAIT_V(8); PG8_WAIT_L(0); PG8_BAR; PG8_MMA(0, 0, At, B0); PG8_MMA(0, 1, At, B1); PG8_BAR; PG8_SCHED;
	v_mfma_f32_16x16x32_bf16 v[92:95], v[112:115], v[182:185], 0
	v_mfma_f32_16x16x32_bf16 v[88:91], v[152:155], v[182:185], 0
	v_mfma_f32_16x16x32_bf16 v[84:87], v[112:115], v[190:193], 0
	v_mfma_f32_16x16x32_bf16 v[80:83], v[152:155], v[190:193], 0
	v_mfma_f32_16x16x32_bf16 v[76:79], v[112:115], v[202:205], 0
	v_mfma_f32_16x16x32_bf16 v[72:75], v[152:155], v[202:205], 0
	v_mfma_f32_16x16x32_bf16 v[68:71], v[112:115], v[210:213], 0
	v_mfma_f32_16x16x32_bf16 v[64:67], v[152:155], v[210:213], 0
	v_mfma_f32_16x16x32_bf16 v[92:95], v[116:119], v[186:189], v[92:95]
	v_mfma_f32_16x16x32_bf16 v[88:91], v[156:159], v[186:189], v[88:91]
	v_mfma_f32_16x16x32_bf16 v[84:87], v[116:119], v[198:201], v[84:87]
	v_mfma_f32_16x16x32_bf16 v[80:83], v[156:159], v[198:201], v[80:83]
	v_mfma_f32_16x16x32_bf16 v[76:79], v[116:119], v[206:209], v[76:79]
	v_mfma_f32_16x16x32_bf16 v[72:75], v[156:159], v[206:209], v[72:75]
	v_mfma_f32_16x16x32_bf16 v[68:71], v[116:119], v[214:217], v[68:71]
	v_mfma_f32_16x16x32_bf16 v[64:67], v[156:159], v[214:217], v[64:67]
	v_mfma_f32_16x16x32_bf16 v[28:31], v[160:163], v[182:185], 0
	v_mfma_f32_16x16x32_bf16 v[24:27], v[174:177], v[182:185], 0
	v_mfma_f32_16x16x32_bf16 v[20:23], v[160:163], v[190:193], 0
	v_mfma_f32_16x16x32_bf16 v[16:19], v[174:177], v[190:193], 0
	v_mfma_f32_16x16x32_bf16 v[12:15], v[160:163], v[202:205], 0
	v_mfma_f32_16x16x32_bf16 v[8:11], v[174:177], v[202:205], 0
	v_mfma_f32_16x16x32_bf16 v[4:7], v[160:163], v[210:213], 0
	v_mfma_f32_16x16x32_bf16 v[0:3], v[174:177], v[210:213], 0
	v_mfma_f32_16x16x32_bf16 v[28:31], v[170:173], v[186:189], v[28:31]
	v_mfma_f32_16x16x32_bf16 v[24:27], v[178:181], v[186:189], v[24:27]
	v_mfma_f32_16x16x32_bf16 v[20:23], v[170:173], v[198:201], v[20:23]
	v_mfma_f32_16x16x32_bf16 v[16:19], v[178:181], v[198:201], v[16:19]
	v_mfma_f32_16x16x32_bf16 v[12:15], v[170:173], v[206:209], v[12:15]
	v_mfma_f32_16x16x32_bf16 v[8:11], v[178:181], v[206:209], v[8:11]
	v_mfma_f32_16x16x32_bf16 v[4:7], v[170:173], v[214:217], v[4:7]
	v_mfma_f32_16x16x32_bf16 v[0:3], v[178:181], v[214:217], v[0:3]
	s_barrier
	s_add_i32 s68, 0, 0x18000
	s_add_i32 s69, 0, 0x1c000
	v_add_u32_e32 v156, s68, v165
	v_add_u32_e32 v178, s69, v165
	ds_read_b128 v[112:115], v156
	ds_read_b128 v[116:119], v156 offset:1024
	ds_read_b128 v[152:155], v156 offset:2048
	ds_read_b128 v[156:159], v156 offset:3072
	ds_read_b128 v[160:163], v178
	ds_read_b128 v[170:173], v178 offset:1024
	ds_read_b128 v[174:177], v178 offset:2048
	ds_read_b128 v[178:181], v178 offset:3072
	s_add_u32 s48, s48, 0x20000
	s_addc_u32 s49, s49, 0
	s_mov_b32 m0, s53
	ds_read_b128 v[182:185], v169 offset:32768
	ds_read_b128 v[186:189], v169 offset:33792
	ds_read_b128 v[190:193], v169 offset:34816
	ds_read_b128 v[198:201], v169 offset:35840
	ds_read_b128 v[202:205], v169 offset:36864
	ds_read_b128 v[206:209], v169 offset:37888
	ds_read_b128 v[210:213], v169 offset:38912
	ds_read_b128 v[214:217], v169 offset:39936
	global_load_lds_dwordx4 v136, s[48:49]
	s_mov_b32 m0, s54
	s_nop 0
	global_load_lds_dwordx4 v140, s[48:49]
	s_waitcnt vmcnt(8)
	s_waitcnt lgkmcnt(0)
	s_barrier
	v_mfma_f32_16x16x32_bf16 v[132:135], v[112:115], v[182:185], v[132:135]
	v_mfma_f32_16x16x32_bf16 v[128:131], v[152:155], v[182:185], v[128:131]
	v_mfma_f32_16x16x32_bf16 v[124:127], v[112:115], v[190:193], v[124:127]
	v_mfma_f32_16x16x32_bf16 v[120:123], v[152:155], v[190:193], v[120:123]
	v_mfma_f32_16x16x32_bf16 v[108:111], v[112:115], v[202:205], v[108:111]
	v_mfma_f32_16x16x32_bf16 v[104:107], v[152:155], v[202:205], v[104:107]
	v_mfma_f32_16x16x32_bf16 v[100:103], v[112:115], v[210:213], v[100:103]
	v_mfma_f32_16x16x32_bf16 v[96:99], v[152:155], v[210:213], v[96:99]
	v_mfma_f32_16x16x32_bf16 v[132:135], v[116:119], v[186:189], v[132:135]
	v_mfma_f32_16x16x32_bf16 v[128:131], v[156:159], v[186:189], v[128:131]
	v_mfma_f32_16x16x32_bf16 v[124:127], v[116:119], v[198:201], v[124:127]
	v_mfma_f32_16x16x32_bf16 v[120:123], v[156:159], v[198:201], v[120:123]
	v_mfma_f32_16x16x32_bf16 v[108:111], v[116:119], v[206:209], v[108:111]
	v_mfma_f32_16x16x32_bf16 v[104:107], v[156:159], v[206:209], v[104:107]
	v_mfma_f32_16x16x32_bf16 v[100:103], v[116:119], v[214:217], v[100:103]
	v_mfma_f32_16x16x32_bf16 v[96:99], v[156:159], v[214:217], v[96:99]
	v_mfma_f32_16x16x32_bf16 v[60:63], v[160:163], v[182:185], v[60:63]
	v_mfma_f32_16x16x32_bf16 v[56:59], v[174:177], v[182:185], v[56:59]
	v_mfma_f32_16x16x32_bf16 v[52:55], v[160:163], v[190:193], v[52:55]
	v_mfma_f32_16x16x32_bf16 v[48:51], v[174:177], v[190:193], v[48:51]
	v_mfma_f32_16x16x32_bf16 v[44:47], v[160:163], v[202:205], v[44:47]
	v_mfma_f32_16x16x32_bf16 v[40:43], v[174:177], v[202:205], v[40:43]
	v_mfma_f32_16x16x32_bf16 v[36:39], v[160:163], v[210:213], v[36:39]
	v_mfma_f32_16x16x32_bf16 v[32:35], v[174:177], v[210:213], v[32:35]
	v_mfma_f32_16x16x32_bf16 v[60:63], v[170:173], v[186:189], v[60:63]
	v_mfma_f32_16x16x32_bf16 v[56:59], v[178:181], v[186:189], v[56:59]
	v_mfma_f32_16x16x32_bf16 v[52:55], v[170:173], v[198:201], v[52:55]
	v_mfma_f32_16x16x32_bf16 v[48:51], v[178:181], v[198:201], v[48:51]
	v_mfma_f32_16x16x32_bf16 v[44:47], v[170:173], v[206:209], v[44:47]
	v_mfma_f32_16x16x32_bf16 v[40:43], v[178:181], v[206:209], v[40:43]
	v_mfma_f32_16x16x32_bf16 v[36:39], v[170:173], v[214:217], v[36:39]
	v_mfma_f32_16x16x32_bf16 v[32:35], v[178:181], v[214:217], v[32:35]
	s_barrier
; #define PG8_STAGE(bufoff, gbase, voff) do { _Pragma("unroll") for (int _i = 0; _i < 2; ++_i) \
;         __builtin_amdgcn_global_load_lds((const unsigned*)((const char*)(gbase) + (voff)[_i]), (PG8_LAS unsigned*)(lds + (bufoff) + ldsw + _i * 8192), 16, 0, 0); } while (0)
; #define PG8_LDA(dst, b, h) do { _Pragma("unroll") for (int m = 0; m < 4; ++m) _Pragma("unroll") for (int k = 0; k < 2; ++k) dst[m][k] = *(const PG8_LAS bf16x8*)(lds + PG8_SA(b, h) + aoff + m * 2048 + k * 1024); } while (0)
; #define PG8_LDB(dst, b, h) do { _Pragma("unroll") for (int n = 0; n < 2; ++n) _Pragma("unroll") for (int k = 0; k < 2; ++k) dst[n][k] = *(const PG8_LAS bf16x8*)(lds + PG8_SB(b, h) + boff + n * 2048 + k * 1024); } while (0)
; #define PG8_MMA(ai, bj, At, Bt) do { __builtin_amdgcn_s_setprio(1); _Pragma("unroll") for (int m = 0; m < 4; ++m) _Pragma("unroll") for (int n = 0; n < 2; ++n) _Pragma("unroll") for (int k = 0; k < 2; ++k) \
;         acc[ai][bj][m][n] = __builtin_amdgcn_mfma_f32_16x16x32_bf16(Bt[n][k], At[m][k], acc[ai][bj][m][n], 0, 0, 0); __builtin_amdgcn_s_setprio(0); } while (0)
; #define PG8_WAIT_V(n) asm volatile("s_waitcnt vmcnt(" #n ")" ::: "memory")
; template <class Epi, class Sched, bool ALIGN_EPI = false, bool SP2 = false>
; __device__ __forceinline__ void gemm_phase(PG8_LAS unsigned char* lds, const Gemm g, const Sched& S, const Epi& E) {
;     ...
;             PG8_LDB(B0, 0, 0); PG8_LDB(B1, 0, 1); PG8_SCHED; PG8_LDA(At, 0, 0); PG8_STAGE(PG8_SA(1, 1), a1 + hstep, voffA);
;             PG8_WAIT_V(8); PG8_WAIT_L(0); PG8_BAR; PG8_MMA(0, 0, At, B0); PG8_MMA(0, 1, At, B1); PG8_BAR; PG8_SCHED;
;             PG8_LDA(At, 0, 1); PG8_STAGE(PG8_SB(0, 0), b2, voffB); PG8_STAGE(PG8_SB(0, 1), b2 + hstep, voffB); PG8_STAGE(PG8_SA(0, 0), a2, voffA);
;             PG8_WAIT_V(8); PG8_WAIT_L(0); PG8_BAR; PG8_MMA(1, 0, At, B0); PG8_MMA(1, 1, At, B1); PG8_BAR; PG8_SCHED;
;             PG8_LDB(B0, 1, 0); PG8_LDB(B1, 1, 1); PG8_SCHED; PG8_LDA(At, 1, 0); PG8_STAGE(PG8_SA(0, 1), a2 + hstep, voffA);
;             PG8_WAIT_V(8); PG8_WAIT_L(0); PG8_BAR; PG8_MMA(0, 0, At, B0); PG8_MMA(0, 1, At, B1); PG8_BAR; PG8_SCHED;
;             PG8_LDA(At, 1, 1); PG8_STAGE(PG8_SB(1, 0), b3, voffB); PG8_STAGE(PG8_SB(1, 1), b3 + hstep, voffB); PG8_STAGE(PG8_SA(1, 0), a3, voffA);
;             PG8_WAIT_V(8); PG8_WAIT_L(0); PG8_BAR; PG8_MMA(1, 0, At, B0); PG8_MMA(1, 1, At, B1); PG8_BAR; PG8_SCHED;
	s_add_i32 s48, s68, s51
	s_mov_b32 m0, s48
	ds_read_b128 v[182:185], v169 offset:49152
	ds_read_b128 v[186:189], v169 offset:50176
	ds_read_b128 v[190:193], v169 offset:51200
	ds_read_b128 v[198:201], v169 offset:52224
	ds_read_b128 v[202:205], v169 offset:53248
	ds_read_b128 v[206:209], v169 offset:54272
	ds_read_b128 v[210:213], v169 offset:55296
	ds_read_b128 v[214:217], v169 offset:56320
	global_load_lds_dwordx4 v138, s[98:99]
	s_add_i32 m0, s48, 0x2000
	s_add_u32 s46, s46, 0x20080
	s_addc_u32 s47, s47, 0
	s_add_i32 s48, s69, s51
	global_load_lds_dwordx4 v142, s[98:99]
	s_mov_b32 m0, s48
	s_nop 0
	global_load_lds_dwordx4 v138, s[46:47]
	s_add_i32 m0, s48, 0x2000
	s_nop 0
	global_load_lds_dwordx4 v142, s[46:47]
	s_mov_b32 m0, s56
	s_nop 0
	global_load_lds_dwordx4 v136, s[100:101]
	s_mov_b32 m0, s57
	s_nop 0
	global_load_lds_dwordx4 v140, s[100:101]
	s_nop 0
	s_waitcnt vmcnt(8)
	s_waitcnt lgkmcnt(0)
	s_barrier
	v_mfma_f32_16x16x32_bf16 v[92:95], v[112:115], v[182:185], v[92:95]
	v_mfma_f32_16x16x32_bf16 v[88:91], v[152:155], v[182:185], v[88:91]
	v_mfma_f32_16x16x32_bf16 v[84:87], v[112:115], v[190:193], v[84:87]
	v_mfma_f32_16x16x32_bf16 v[80:83], v[152:155], v[190:193], v[80:83]
	v_mfma_f32_16x16x32_bf16 v[76:79], v[112:115], v[202:205], v[76:79]
	v_mfma_f32_16x16x32_bf16 v[72:75], v[152:155], v[202:205], v[72:75]
	v_mfma_f32_16x16x32_bf16 v[68:71], v[112:115], v[210:213], v[68:71]
	v_mfma_f32_16x16x32_bf16 v[64:67], v[152:155], v[210:213], v[64:67]
	v_mfma_f32_16x16x32_bf16 v[92:95], v[116:119], v[186:189], v[92:95]
	v_mfma_f32_16x16x32_bf16 v[88:91], v[156:159], v[186:189], v[88:91]
	v_mfma_f32_16x16x32_bf16 v[84:87], v[116:119], v[198:201], v[84:87]
	v_mfma_f32_16x16x32_bf16 v[80:83], v[156:159], v[198:201], v[80:83]
	v_mfma_f32_16x16x32_bf16 v[76:79], v[116:119], v[206:209], v[76:79]
	v_mfma_f32_16x16x32_bf16 v[72:75], v[156:159], v[206:209], v[72:75]
	v_mfma_f32_16x16x32_bf16 v[68:71], v[116:119], v[214:217], v[68:71]
	v_mfma_f32_16x16x32_bf16 v[64:67], v[156:159], v[214:217], v[64:67]
	v_mfma_f32_16x16x32_bf16 v[28:31], v[160:163], v[182:185], v[28:31]
	v_mfma_f32_16x16x32_bf16 v[24:27], v[174:177], v[182:185], v[24:27]
	v_mfma_f32_16x16x32_bf16 v[20:23], v[160:163], v[190:193], v[20:23]
	v_mfma_f32_16x16x32_bf16 v[16:19], v[174:177], v[190:193], v[16:19]
	v_mfma_f32_16x16x32_bf16 v[12:15], v[160:163], v[202:205], v[12:15]
	v_mfma_f32_16x16x32_bf16 v[8:11], v[174:177], v[202:205], v[8:11]
	v_mfma_f32_16x16x32_bf16 v[4:7], v[160:163], v[210:213], v[4:7]
	v_mfma_f32_16x16x32_bf16 v[0:3], v[174:177], v[210:213], v[0:3]
	v_mfma_f32_16x16x32_bf16 v[28:31], v[170:173], v[186:189], v[28:31]
	v_mfma_f32_16x16x32_bf16 v[24:27], v[178:181], v[186:189], v[24:27]
	v_mfma_f32_16x16x32_bf16 v[20:23], v[170:173], v[198:201], v[20:23]
	v_mfma_f32_16x16x32_bf16 v[16:19], v[178:181], v[198:201], v[16:19]
	v_mfma_f32_16x16x32_bf16 v[12:15], v[170:173], v[206:209], v[12:15]
	v_mfma_f32_16x16x32_bf16 v[8:11], v[178:181], v[206:209], v[8:11]
	v_mfma_f32_16x16x32_bf16 v[4:7], v[170:173], v[214:217], v[4:7]
	v_mfma_f32_16x16x32_bf16 v[0:3], v[178:181], v[214:217], v[0:3]
	s_barrier
	s_add_i32 s67, s67, 2
	s_add_u32 s20, s20, 0x100
	s_addc_u32 s21, s21, 0
	s_add_u32 s65, s65, 0x100
	s_addc_u32 s66, s66, 0
	s_cmp_gt_u32 s67, 5
.LBB0_624:
	ds_read_b128 v[112:115], v167
	ds_read_b128 v[116:119], v167 offset:1024
	ds_read_b128 v[152:155], v167 offset:2048
	ds_read_b128 v[156:159], v167 offset:3072
	ds_read_b128 v[160:163], v168
	ds_read_b128 v[170:173], v168 offset:1024
	ds_read_b128 v[174:177], v168 offset:2048
	ds_read_b128 v[178:181], v168 offset:3072
	s_add_u32 s46, s20, 0xfffe0080
	s_addc_u32 s47, s21, -1
	s_cmp_eq_u32 s67, 4
	s_cselect_b32 s49, s17, s47
	s_cselect_b32 s48, s63, s46
	s_cselect_b32 s47, s15, s66
	s_cselect_b32 s46, s64, s65
	s_add_i32 m0, s35, 0xc000
	ds_read_b128 v[182:185], v169
	ds_read_b128 v[186:189], v169 offset:1024
	ds_read_b128 v[190:193], v169 offset:2048
	ds_read_b128 v[198:201], v169 offset:3072
	ds_read_b128 v[202:205], v169 offset:4096
	ds_read_b128 v[206:209], v169 offset:5120
	ds_read_b128 v[210:213], v169 offset:6144
	ds_read_b128 v[214:217], v169 offset:7168
	global_load_lds_dwordx4 v144, s[20:21]
	s_add_i32 m0, s35, 0xe000
	s_nop 0
	global_load_lds_dwordx4 v146, s[20:21]
	s_nop 0
	s_waitcnt vmcnt(8)
	s_waitcnt lgkmcnt(0)
	s_barrier
	v_mfma_f32_16x16x32_bf16 v[132:135], v[112:115], v[182:185], v[132:135]
	v_mfma_f32_16x16x32_bf16 v[128:131], v[152:155], v[182:185], v[128:131]
	v_mfma_f32_16x16x32_bf16 v[124:127], v[112:115], v[190:193], v[124:127]
	v_mfma_f32_16x16x32_bf16 v[120:123], v[152:155], v[190:193], v[120:123]
	v_mfma_f32_16x16x32_bf16 v[108:111], v[112:115], v[202:205], v[108:111]
	v_mfma_f32_16x16x32_bf16 v[104:107], v[152:155], v[202:205], v[104:107]
	v_mfma_f32_16x16x32_bf16 v[100:103], v[112:115], v[210:213], v[100:103]
	v_mfma_f32_16x16x32_bf16 v[96:99], v[152:155], v[210:213], v[96:99]
	v_mfma_f32_16x16x32_bf16 v[132:135], v[116:119], v[186:189], v[132:135]
	v_mfma_f32_16x16x32_bf16 v[128:131], v[156:159], v[186:189], v[128:131]
	v_mfma_f32_16x16x32_bf16 v[124:127], v[116:119], v[198:201], v[124:127]
	v_mfma_f32_16x16x32_bf16 v[120:123], v[156:159], v[198:201], v[120:123]
	v_mfma_f32_16x16x32_bf16 v[108:111], v[116:119], v[206:209], v[108:111]
	v_mfma_f32_16x16x32_bf16 v[104:107], v[156:159], v[206:209], v[104:107]
	v_mfma_f32_16x16x32_bf16 v[100:103], v[116:119], v[214:217], v[100:103]
	v_mfma_f32_16x16x32_bf16 v[96:99], v[156:159], v[214:217], v[96:99]
	v_mfma_f32_16x16x32_bf16 v[60:63], v[160:163], v[182:185], v[60:63]
	v_mfma_f32_16x16x32_bf16 v[56:59], v[174:177], v[182:185], v[56:59]
	v_mfma_f32_16x16x32_bf16 v[52:55], v[160:163], v[190:193], v[52:55]
	v_mfma_f32_16x16x32_bf16 v[48:51], v[174:177], v[190:193], v[48:51]
	v_mfma_f32_16x16x32_bf16 v[44:47], v[160:163], v[202:205], v[44:47]
	v_mfma_f32_16x16x32_bf16 v[40:43], v[174:177], v[202:205], v[40:43]
	v_mfma_f32_16x16x32_bf16 v[36:39], v[160:163], v[210:213], v[36:39]
	v_mfma_f32_16x16x32_bf16 v[32:35], v[174:177], v[210:213], v[32:35]
	v_mfma_f32_16x16x32_bf16 v[60:63], v[170:173], v[186:189], v[60:63]
	v_mfma_f32_16x16x32_bf16 v[56:59], v[178:181], v[186:189], v[56:59]
	v_mfma_f32_16x16x32_bf16 v[52:55], v[170:173], v[198:201], v[52:55]
	v_mfma_f32_16x16x32_bf16 v[48:51], v[178:181], v[198:201], v[48:51]
	v_mfma_f32_16x16x32_bf16 v[44:47], v[170:173], v[206:209], v[44:47]
	v_mfma_f32_16x16x32_bf16 v[40:43], v[178:181], v[206:209], v[40:43]
	v_mfma_f32_16x16x32_bf16 v[36:39], v[170:173], v[214:217], v[36:39]
	v_mfma_f32_16x16x32_bf16 v[32:35], v[178:181], v[214:217], v[32:35]
	s_barrier
; #define PG8_STAGE(bufoff, gbase, voff) do { _Pragma("unroll") for (int _i = 0; _i < 2; ++_i) \
;         __builtin_amdgcn_global_load_lds((const unsigned*)((const char*)(gbase) + (voff)[_i]), (PG8_LAS unsigned*)(lds + (bufoff) + ldsw + _i * 8192), 16, 0, 0); } while (0)
; #define PG8_LDA(dst, b, h) do { _Pragma("unroll") for (int m = 0; m < 4; ++m) _Pragma("unroll") for (int k = 0; k < 2; ++k) dst[m][k] = *(const PG8_LAS bf16x8*)(lds + PG8_SA(b, h) + aoff + m * 2048 + k * 1024); } while (0)
; #define PG8_LDB(dst, b, h) do { _Pragma("unroll") for (int n = 0; n < 2; ++n) _Pragma("unroll") for (int k = 0; k < 2; ++k) dst[n][k] = *(const PG8_LAS bf16x8*)(lds + PG8_SB(b, h) + boff + n * 2048 + k * 1024); } while (0)
; #define PG8_MMA(ai, bj, At, Bt) do { __builtin_amdgcn_s_setprio(1); _Pragma("unroll") for (int m = 0; m < 4; ++m) _Pragma("unroll") for (int n = 0; n < 2; ++n) _Pragma("unroll") for (int k = 0; k < 2; ++k) \
;         acc[ai][bj][m][n] = __builtin_amdgcn_mfma_f32_16x16x32_bf16(Bt[n][k], At[m][k], acc[ai][bj][m][n], 0, 0, 0); __builtin_amdgcn_s_setprio(0); } while (0)
; #define PG8_WAIT_V(n) asm volatile("s_waitcnt vmcnt(" #n ")" ::: "memory")
; #define PG8_WAIT_L(n) asm volatile("s_waitcnt lgkmcnt(" #n ")" ::: "memory")
; #define PG8_BAR __builtin_amdgcn_s_barrier()
; #define PG8_SCHED __builtin_amdgcn_sched_barrier(0)
; template <class Epi, class Sched, bool ALIGN_EPI = false, bool SP2 = false>
; __device__ __forceinline__ void gemm_phase(PG8_LAS unsigned char* lds, const Gemm g, const Sched& S, const Epi& E) {
;     ...
;             PG8_LDA(At, 0, 1); PG8_STAGE(PG8_SB(0, 0), b2, voffB); PG8_STAGE(PG8_SB(0, 1), b2 + hstep, voffB); PG8_STAGE(PG8_SA(0, 0), a2, voffA);
;             PG8_WAIT_V(8); PG8_WAIT_L(0); PG8_BAR; PG8_MMA(1, 0, At, B0); PG8_MMA(1, 1, At, B1); PG8_BAR; PG8_SCHED;
;             PG8_LDB(B0, 1, 0); PG8_LDB(B1, 1, 1); PG8_SCHED; PG8_LDA(At, 1, 0); PG8_STAGE(PG8_SA(0, 1), a2 + hstep, voffA);
;             PG8_WAIT_V(8); PG8_WAIT_L(0); PG8_BAR; PG8_MMA(0, 0, At, B0); PG8_MMA(0, 1, At, B1); PG8_BAR; PG8_SCHED;
	s_add_i32 s68, s60, s51
	s_add_u32 s98, s46, s10
	s_addc_u32 s99, s47, s11
	s_add_u32 s100, s48, s10
	s_addc_u32 s101, s49, s11
	s_mov_b32 m0, s68
	ds_read_b128 v[182:185], v169 offset:16384
	ds_read_b128 v[186:189], v169 offset:17408
	ds_read_b128 v[190:193], v169 offset:18432
	ds_read_b128 v[198:201], v169 offset:19456
	ds_read_b128 v[202:205], v169 offset:20480
	ds_read_b128 v[206:209], v169 offset:21504
	ds_read_b128 v[210:213], v169 offset:22528
	ds_read_b128 v[214:217], v169 offset:23552
	global_load_lds_dwordx4 v138, s[46:47]
	s_add_i32 m0, s68, 0x2000
	s_add_u32 s68, s46, 0x20000
	s_addc_u32 s69, s47, 0
	s_add_i32 s70, s61, s51
	global_load_lds_dwordx4 v142, s[46:47]
	s_mov_b32 m0, s70
	s_nop 0
	global_load_lds_dwordx4 v138, s[68:69]
	s_add_i32 m0, s70, 0x2000
	s_nop 0
	global_load_lds_dwordx4 v142, s[68:69]
	s_mov_b32 m0, s35
	s_nop 0
	global_load_lds_dwordx4 v136, s[48:49]
	s_mov_b32 m0, s52
	s_nop 0
	global_load_lds_dwordx4 v140, s[48:49]
	s_nop 0
	s_waitcnt vmcnt(8)
	s_waitcnt lgkmcnt(0)
	s_barrier
	v_mfma_f32_16x16x32_bf16 v[92:95], v[112:115], v[182:185], v[92:95]
	v_mfma_f32_16x16x32_bf16 v[88:91], v[152:155], v[182:185], v[88:91]
	v_mfma_f32_16x16x32_bf16 v[84:87], v[112:115], v[190:193], v[84:87]
	v_mfma_f32_16x16x32_bf16 v[80:83], v[152:155], v[190:193], v[80:83]
	v_mfma_f32_16x16x32_bf16 v[76:79], v[112:115], v[202:205], v[76:79]
	v_mfma_f32_16x16x32_bf16 v[72:75], v[152:155], v[202:205], v[72:75]
	v_mfma_f32_16x16x32_bf16 v[68:71], v[112:115], v[210:213], v[68:71]
	v_mfma_f32_16x16x32_bf16 v[64:67], v[152:155], v[210:213], v[64:67]
	v_mfma_f32_16x16x32_bf16 v[92:95], v[116:119], v[186:189], v[92:95]
	v_mfma_f32_16x16x32_bf16 v[88:91], v[156:159], v[186:189], v[88:91]
	v_mfma_f32_16x16x32_bf16 v[84:87], v[116:119], v[198:201], v[84:87]
	v_mfma_f32_16x16x32_bf16 v[80:83], v[156:159], v[198:201], v[80:83]
	v_mfma_f32_16x16x32_bf16 v[76:79], v[116:119], v[206:209], v[76:79]
	v_mfma_f32_16x16x32_bf16 v[72:75], v[156:159], v[206:209], v[72:75]
	v_mfma_f32_16x16x32_bf16 v[68:71], v[116:119], v[214:217], v[68:71]
	v_mfma_f32_16x16x32_bf16 v[64:67], v[156:159], v[214:217], v[64:67]
	v_mfma_f32_16x16x32_bf16 v[28:31], v[160:163], v[182:185], v[28:31]
	v_mfma_f32_16x16x32_bf16 v[24:27], v[174:177], v[182:185], v[24:27]
	v_mfma_f32_16x16x32_bf16 v[20:23], v[160:163], v[190:193], v[20:23]
	v_mfma_f32_16x16x32_bf16 v[16:19], v[174:177], v[190:193], v[16:19]
	v_mfma_f32_16x16x32_bf16 v[12:15], v[160:163], v[202:205], v[12:15]
	v_mfma_f32_16x16x32_bf16 v[8:11], v[174:177], v[202:205], v[8:11]
	v_mfma_f32_16x16x32_bf16 v[4:7], v[160:163], v[210:213], v[4:7]
	v_mfma_f32_16x16x32_bf16 v[0:3], v[174:177], v[210:213], v[0:3]
	v_mfma_f32_16x16x32_bf16 v[28:31], v[170:173], v[186:189], v[28:31]
	v_mfma_f32_16x16x32_bf16 v[24:27], v[178:181], v[186:189], v[24:27]
	v_mfma_f32_16x16x32_bf16 v[20:23], v[170:173], v[198:201], v[20:23]
	v_mfma_f32_16x16x32_bf16 v[16:19], v[178:181], v[198:201], v[16:19]
	v_mfma_f32_16x16x32_bf16 v[12:15], v[170:173], v[206:209], v[12:15]
	v_mfma_f32_16x16x32_bf16 v[8:11], v[178:181], v[206:209], v[8:11]
	v_mfma_f32_16x16x32_bf16 v[4:7], v[170:173], v[214:217], v[4:7]
	v_mfma_f32_16x16x32_bf16 v[0:3], v[178:181], v[214:217], v[0:3]
	s_barrier
	s_add_i32 s68, 0, 0x18000
	s_add_i32 s69, 0, 0x1c000
	v_add_u32_e32 v156, s68, v165
	v_add_u32_e32 v178, s69, v165
	ds_read_b128 v[112:115], v156
	ds_read_b128 v[116:119], v156 offset:1024
	ds_read_b128 v[152:155], v156 offset:2048
	ds_read_b128 v[156:159], v156 offset:3072
	ds_read_b128 v[160:163], v178
	ds_read_b128 v[170:173], v178 offset:1024
	ds_read_b128 v[174:177], v178 offset:2048
	ds_read_b128 v[178:181], v178 offset:3072
	s_add_u32 s48, s48, 0x20000
	s_addc_u32 s49, s49, 0
	s_mov_b32 m0, s53
	ds_read_b128 v[182:185], v169 offset:32768
	ds_read_b128 v[186:189], v169 offset:33792
	ds_read_b128 v[190:193], v169 offset:34816
	ds_read_b128 v[198:201], v169 offset:35840
	ds_read_b128 v[202:205], v169 offset:36864
	ds_read_b128 v[206:209], v169 offset:37888
	ds_read_b128 v[210:213], v169 offset:38912
	ds_read_b128 v[214:217], v169 offset:39936
	global_load_lds_dwordx4 v136, s[48:49]
	s_mov_b32 m0, s54
	s_nop 0
	global_load_lds_dwordx4 v140, s[48:49]
	s_waitcnt vmcnt(8)
	s_waitcnt lgkmcnt(0)
	s_barrier
; #define PG8_STAGE(bufoff, gbase, voff) do { _Pragma("unroll") for (int _i = 0; _i < 2; ++_i) \
;         __builtin_amdgcn_global_load_lds((const unsigned*)((const char*)(gbase) + (voff)[_i]), (PG8_LAS unsigned*)(lds + (bufoff) + ldsw + _i * 8192), 16, 0, 0); } while (0)
; #define PG8_LDA(dst, b, h) do { _Pragma("unroll") for (int m = 0; m < 4; ++m) _Pragma("unroll") for (int k = 0; k < 2; ++k) dst[m][k] = *(const PG8_LAS bf16x8*)(lds + PG8_SA(b, h) + aoff + m * 2048 + k * 1024); } while (0)
; #define PG8_MMA(ai, bj, At, Bt) do { __builtin_amdgcn_s_setprio(1); _Pragma("unroll") for (int m = 0; m < 4; ++m) _Pragma("unroll") for (int n = 0; n < 2; ++n) _Pragma("unroll") for (int k = 0; k < 2; ++k) \
;         acc[ai][bj][m][n] = __builtin_amdgcn_mfma_f32_16x16x32_bf16(Bt[n][k], At[m][k], acc[ai][bj][m][n], 0, 0, 0); __builtin_amdgcn_s_setprio(0); } while (0)
; #define PG8_WAIT_V(n) asm volatile("s_waitcnt vmcnt(" #n ")" ::: "memory")
; #define PG8_WAIT_L(n) asm volatile("s_waitcnt lgkmcnt(" #n ")" ::: "memory")
; #define PG8_BAR __builtin_amdgcn_s_barrier()
; #define PG8_SCHED __builtin_amdgcn_sched_barrier(0)
; template <class Epi, class Sched, bool ALIGN_EPI = false, bool SP2 = false>
; __device__ __forceinline__ void gemm_phase(PG8_LAS unsigned char* lds, const Gemm g, const Sched& S, const Epi& E) {
;     ...
;             PG8_WAIT_V(8); PG8_WAIT_L(0); PG8_BAR; PG8_MMA(0, 0, At, B0); PG8_MMA(0, 1, At, B1); PG8_BAR; PG8_SCHED;
;             PG8_LDA(At, 1, 1); PG8_STAGE(PG8_SB(1, 0), b3, voffB); PG8_STAGE(PG8_SB(1, 1), b3 + hstep, voffB); PG8_STAGE(PG8_SA(1, 0), a3, voffA);
;             PG8_WAIT_V(8); PG8_WAIT_L(0); PG8_BAR; PG8_MMA(1, 0, At, B0); PG8_MMA(1, 1, At, B1); PG8_BAR; PG8_SCHED;
;     ...
;         if constexpr (ALIGN_EPI) { if (wr == 0) PG8_BAR; }
	v_mfma_f32_16x16x32_bf16 v[132:135], v[112:115], v[182:185], v[132:135]
	v_mfma_f32_16x16x32_bf16 v[128:131], v[152:155], v[182:185], v[128:131]
	v_mfma_f32_16x16x32_bf16 v[124:127], v[112:115], v[190:193], v[124:127]
	v_mfma_f32_16x16x32_bf16 v[120:123], v[152:155], v[190:193], v[120:123]
	v_mfma_f32_16x16x32_bf16 v[108:111], v[112:115], v[202:205], v[108:111]
	v_mfma_f32_16x16x32_bf16 v[104:107], v[152:155], v[202:205], v[104:107]
	v_mfma_f32_16x16x32_bf16 v[100:103], v[112:115], v[210:213], v[100:103]
	v_mfma_f32_16x16x32_bf16 v[96:99], v[152:155], v[210:213], v[96:99]
	v_mfma_f32_16x16x32_bf16 v[132:135], v[116:119], v[186:189], v[132:135]
	v_mfma_f32_16x16x32_bf16 v[128:131], v[156:159], v[186:189], v[128:131]
	v_mfma_f32_16x16x32_bf16 v[124:127], v[116:119], v[198:201], v[124:127]
	v_mfma_f32_16x16x32_bf16 v[120:123], v[156:159], v[198:201], v[120:123]
	v_mfma_f32_16x16x32_bf16 v[108:111], v[116:119], v[206:209], v[108:111]
	v_mfma_f32_16x16x32_bf16 v[104:107], v[156:159], v[206:209], v[104:107]
	v_mfma_f32_16x16x32_bf16 v[100:103], v[116:119], v[214:217], v[100:103]
	v_mfma_f32_16x16x32_bf16 v[96:99], v[156:159], v[214:217], v[96:99]
	v_mfma_f32_16x16x32_bf16 v[60:63], v[160:163], v[182:185], v[60:63]
	v_mfma_f32_16x16x32_bf16 v[56:59], v[174:177], v[182:185], v[56:59]
	v_mfma_f32_16x16x32_bf16 v[52:55], v[160:163], v[190:193], v[52:55]
	v_mfma_f32_16x16x32_bf16 v[48:51], v[174:177], v[190:193], v[48:51]
	v_mfma_f32_16x16x32_bf16 v[44:47], v[160:163], v[202:205], v[44:47]
	v_mfma_f32_16x16x32_bf16 v[40:43], v[174:177], v[202:205], v[40:43]
	v_mfma_f32_16x16x32_bf16 v[36:39], v[160:163], v[210:213], v[36:39]
	v_mfma_f32_16x16x32_bf16 v[32:35], v[174:177], v[210:213], v[32:35]
	v_mfma_f32_16x16x32_bf16 v[60:63], v[170:173], v[186:189], v[60:63]
	v_mfma_f32_16x16x32_bf16 v[56:59], v[178:181], v[186:189], v[56:59]
	v_mfma_f32_16x16x32_bf16 v[52:55], v[170:173], v[198:201], v[52:55]
	v_mfma_f32_16x16x32_bf16 v[48:51], v[178:181], v[198:201], v[48:51]
	v_mfma_f32_16x16x32_bf16 v[44:47], v[170:173], v[206:209], v[44:47]
	v_mfma_f32_16x16x32_bf16 v[40:43], v[178:181], v[206:209], v[40:43]
	v_mfma_f32_16x16x32_bf16 v[36:39], v[170:173], v[214:217], v[36:39]
	v_mfma_f32_16x16x32_bf16 v[32:35], v[178:181], v[214:217], v[32:35]
	s_barrier
	s_add_i32 s48, s68, s51
	s_mov_b32 m0, s48
	ds_read_b128 v[182:185], v169 offset:49152
	ds_read_b128 v[186:189], v169 offset:50176
	ds_read_b128 v[190:193], v169 offset:51200
	ds_read_b128 v[198:201], v169 offset:52224
	ds_read_b128 v[202:205], v169 offset:53248
	ds_read_b128 v[206:209], v169 offset:54272
	ds_read_b128 v[210:213], v169 offset:55296
	ds_read_b128 v[214:217], v169 offset:56320
	global_load_lds_dwordx4 v138, s[98:99]
	s_add_i32 m0, s48, 0x2000
	s_add_u32 s46, s46, 0x20080
	s_addc_u32 s47, s47, 0
	s_add_i32 s48, s69, s51
	global_load_lds_dwordx4 v142, s[98:99]
	s_mov_b32 m0, s48
	s_nop 0
	global_load_lds_dwordx4 v138, s[46:47]
	s_add_i32 m0, s48, 0x2000
	s_nop 0
	global_load_lds_dwordx4 v142, s[46:47]
	s_mov_b32 m0, s56
	s_nop 0
	global_load_lds_dwordx4 v136, s[100:101]
	s_mov_b32 m0, s57
	s_nop 0
	global_load_lds_dwordx4 v140, s[100:101]
	s_nop 0
	s_waitcnt vmcnt(8)
	s_waitcnt lgkmcnt(0)
	s_barrier
	v_mfma_f32_16x16x32_bf16 v[92:95], v[112:115], v[182:185], v[92:95]
	v_mfma_f32_16x16x32_bf16 v[88:91], v[152:155], v[182:185], v[88:91]
	v_mfma_f32_16x16x32_bf16 v[84:87], v[112:115], v[190:193], v[84:87]
	v_mfma_f32_16x16x32_bf16 v[80:83], v[152:155], v[190:193], v[80:83]
	v_mfma_f32_16x16x32_bf16 v[76:79], v[112:115], v[202:205], v[76:79]
	v_mfma_f32_16x16x32_bf16 v[72:75], v[152:155], v[202:205], v[72:75]
	v_mfma_f32_16x16x32_bf16 v[68:71], v[112:115], v[210:213], v[68:71]
	v_mfma_f32_16x16x32_bf16 v[64:67], v[152:155], v[210:213], v[64:67]
	v_mfma_f32_16x16x32_bf16 v[92:95], v[116:119], v[186:189], v[92:95]
	v_mfma_f32_16x16x32_bf16 v[88:91], v[156:159], v[186:189], v[88:91]
	v_mfma_f32_16x16x32_bf16 v[84:87], v[116:119], v[198:201], v[84:87]
	v_mfma_f32_16x16x32_bf16 v[80:83], v[156:159], v[198:201], v[80:83]
	v_mfma_f32_16x16x32_bf16 v[76:79], v[116:119], v[206:209], v[76:79]
	v_mfma_f32_16x16x32_bf16 v[72:75], v[156:159], v[206:209], v[72:75]
	v_mfma_f32_16x16x32_bf16 v[68:71], v[116:119], v[214:217], v[68:71]
	v_mfma_f32_16x16x32_bf16 v[64:67], v[156:159], v[214:217], v[64:67]
	v_mfma_f32_16x16x32_bf16 v[28:31], v[160:163], v[182:185], v[28:31]
	v_mfma_f32_16x16x32_bf16 v[24:27], v[174:177], v[182:185], v[24:27]
	v_mfma_f32_16x16x32_bf16 v[20:23], v[160:163], v[190:193], v[20:23]
	v_mfma_f32_16x16x32_bf16 v[16:19], v[174:177], v[190:193], v[16:19]
	v_mfma_f32_16x16x32_bf16 v[12:15], v[160:163], v[202:205], v[12:15]
	v_mfma_f32_16x16x32_bf16 v[8:11], v[174:177], v[202:205], v[8:11]
	v_mfma_f32_16x16x32_bf16 v[4:7], v[160:163], v[210:213], v[4:7]
	v_mfma_f32_16x16x32_bf16 v[0:3], v[174:177], v[210:213], v[0:3]
	v_mfma_f32_16x16x32_bf16 v[28:31], v[170:173], v[186:189], v[28:31]
	v_mfma_f32_16x16x32_bf16 v[24:27], v[178:181], v[186:189], v[24:27]
	v_mfma_f32_16x16x32_bf16 v[20:23], v[170:173], v[198:201], v[20:23]
	v_mfma_f32_16x16x32_bf16 v[16:19], v[178:181], v[198:201], v[16:19]
	v_mfma_f32_16x16x32_bf16 v[12:15], v[170:173], v[206:209], v[12:15]
	v_mfma_f32_16x16x32_bf16 v[8:11], v[178:181], v[206:209], v[8:11]
	v_mfma_f32_16x16x32_bf16 v[4:7], v[170:173], v[214:217], v[4:7]
	v_mfma_f32_16x16x32_bf16 v[0:3], v[178:181], v[214:217], v[0:3]
	s_barrier
	s_add_i32 s67, s67, 2
	s_add_u32 s20, s20, 0x100
	s_addc_u32 s21, s21, 0
	s_add_u32 s65, s65, 0x100
	s_addc_u32 s66, s66, 0
	s_cmp_gt_u32 s67, 5
	s_cbranch_scc0 .LBB0_624
	s_and_b64 vcc, exec, s[12:13]
	s_cbranch_vccz .LBB0_627
	s_barrier

; #define PG8_STAGE(bufoff, gbase, voff) do { _Pragma("unroll") for (int _i = 0; _i < 2; ++_i) \
;         __builtin_amdgcn_global_load_lds((const unsigned*)((const char*)(gbase) + (voff)[_i]), (PG8_LAS unsigned*)(lds + (bufoff) + ldsw + _i * 8192), 16, 0, 0); } while (0)
; #define PG8_LDA(dst, b, h) do { _Pragma("unroll") for (int m = 0; m < 4; ++m) _Pragma("unroll") for (int k = 0; k < 2; ++k) dst[m][k] = *(const PG8_LAS bf16x8*)(lds + PG8_SA(b, h) + aoff + m * 2048 + k * 1024); } while (0)
; #define PG8_LDB(dst, b, h) do { _Pragma("unroll") for (int n = 0; n < 2; ++n) _Pragma("unroll") for (int k = 0; k < 2; ++k) dst[n][k] = *(const PG8_LAS bf16x8*)(lds + PG8_SB(b, h) + boff + n * 2048 + k * 1024); } while (0)
; #define PG8_WAIT_V(n) asm volatile("s_waitcnt vmcnt(" #n ")" ::: "memory")
; #define PG8_WAIT_L(n) asm volatile("s_waitcnt lgkmcnt(" #n ")" ::: "memory")
; #define PG8_BAR __builtin_amdgcn_s_barrier()
; #define PG8_SCHED __builtin_amdgcn_sched_barrier(0)
; template <class Epi, class Sched, bool ALIGN_EPI = false, bool SP2 = false>
; __device__ __forceinline__ void gemm_phase(PG8_LAS unsigned char* lds, const Gemm g, const Sched& S, const Epi& E) {
;     ...
;         const char* nA = has_next ? (const char*)g.A + (size_t)nxt.pm * tstep : cA; const char* nB = has_next ? (const char*)g.Bt + (size_t)nxt.pn * tstep : cB;
;         for (int t = 0; t < nt; t += 2) {
;             const bool last = (t == nt - 2);
;             const char* a1 = cA + (size_t)(t + 1) * kstep;
;             const char* a2 = last ? nA : cA + (size_t)(t + 2) * kstep; const char* b2 = last ? nB : cB + (size_t)(t + 2) * kstep;
;             const char* a3 = a2 + kstep; const char* b3 = b2 + kstep;
;             if (last && has_next) S.a_ready(nxt);
;             if constexpr (SP2) {
;             PG8_LDB(B0, 0, 0); PG8_LDB(B1, 0, 1); PG8_SCHED; PG8_LDA(At, 0, 0); PG8_STAGE(PG8_SA(1, 1), a1 + hstep, voffA);
;             PG8_WAIT_V(8); PG8_WAIT_L(0); PG8_BAR; PG8_MMA(0, 0, At, B0); PG8_MMA(0, 1, At, B1); PG8_BAR; PG8_SCHED;
;             PG8_LDA(At, 0, 1); PG8_STAGE(PG8_SB(0, 0), b2, voffB); PG8_STAGE(PG8_SB(0, 1), b2 + hstep, voffB); PG8_STAGE(PG8_SA(0, 0), a2, voffA);
;             PG8_WAIT_V(8); PG8_WAIT_L(0); PG8_BAR; PG8_MMA(1, 0, At, B0); PG8_MMA(1, 1, At, B1); PG8_BAR; PG8_SCHED;
.LBB0_704:
	s_ashr_i32 s47, s46, 31
	s_lshl_b64 s[48:49], s[46:47], 19
	s_add_u32 s48, s42, s48
	s_addc_u32 s49, s43, s49
	s_and_b64 s[50:51], s[6:7], exec
	s_cselect_b32 s35, s49, s21
	s_cselect_b32 s47, s48, s20
	s_ashr_i32 s45, s44, 31
	s_lshl_b64 s[50:51], s[44:45], 19
	s_add_u32 s50, s3, s50
	s_addc_u32 s51, s33, s51
	s_and_b64 s[56:57], s[6:7], exec
	s_cselect_b32 s45, s51, s55
	s_cselect_b32 s73, s50, s54
	s_add_u32 s20, s20, 0x40080
	s_addc_u32 s21, s21, 0
	s_add_u32 s74, s54, 0x100
	s_addc_u32 s75, s55, 0
	s_mov_b32 s76, -2
	s_waitcnt lgkmcnt(0)
	ds_read_b128 v[96:99], v223
	ds_read_b128 v[108:111], v223 offset:1024
	ds_read_b128 v[120:123], v223 offset:2048
	ds_read_b128 v[128:131], v223 offset:3072
	ds_read_b128 v[144:147], v224
	ds_read_b128 v[148:151], v224 offset:1024
	ds_read_b128 v[152:155], v224 offset:2048
	ds_read_b128 v[156:159], v224 offset:3072
	s_add_u32 s54, s20, 0xfffc0080
	s_addc_u32 s55, s21, -1
	s_cmp_eq_u32 s76, 12
	s_cselect_b32 s57, s35, s55
	s_cselect_b32 s56, s47, s54
	s_cselect_b32 s55, s45, s75
	s_cselect_b32 s54, s73, s74
	s_add_i32 m0, s53, 0xc000
	ds_read_b128 v[160:163], v225
	ds_read_b128 v[164:167], v225 offset:1024
	ds_read_b128 v[168:171], v225 offset:2048
	ds_read_b128 v[172:175], v225 offset:3072
	ds_read_b128 v[176:179], v225 offset:4096
	ds_read_b128 v[180:183], v225 offset:5120
	ds_read_b128 v[202:205], v225 offset:6144
	ds_read_b128 v[206:209], v225 offset:7168
	global_load_lds_dwordx4 v192, s[20:21]
	s_add_i32 m0, s53, 0xe000
	s_nop 0
	global_load_lds_dwordx4 v194, s[20:21]
	s_nop 0
	s_waitcnt vmcnt(8)
	s_waitcnt lgkmcnt(0)
	s_barrier
	v_mfma_f32_16x16x32_bf16 v[140:143], v[96:99], v[160:163], 0
	v_mfma_f32_16x16x32_bf16 v[136:139], v[120:123], v[160:163], 0
	v_mfma_f32_16x16x32_bf16 v[116:119], v[96:99], v[168:171], 0
	v_mfma_f32_16x16x32_bf16 v[112:115], v[120:123], v[168:171], 0
	v_mfma_f32_16x16x32_bf16 v[92:95], v[96:99], v[176:179], 0
	v_mfma_f32_16x16x32_bf16 v[88:91], v[120:123], v[176:179], 0
	v_mfma_f32_16x16x32_bf16 v[76:79], v[96:99], v[202:205], 0
	v_mfma_f32_16x16x32_bf16 v[72:75], v[120:123], v[202:205], 0
	v_mfma_f32_16x16x32_bf16 v[140:143], v[108:111], v[164:167], v[140:143]
	v_mfma_f32_16x16x32_bf16 v[136:139], v[128:131], v[164:167], v[136:139]
	v_mfma_f32_16x16x32_bf16 v[116:119], v[108:111], v[172:175], v[116:119]
	v_mfma_f32_16x16x32_bf16 v[112:115], v[128:131], v[172:175], v[112:115]
	v_mfma_f32_16x16x32_bf16 v[92:95], v[108:111], v[180:183], v[92:95]
	v_mfma_f32_16x16x32_bf16 v[88:91], v[128:131], v[180:183], v[88:91]
	v_mfma_f32_16x16x32_bf16 v[76:79], v[108:111], v[206:209], v[76:79]
	v_mfma_f32_16x16x32_bf16 v[72:75], v[128:131], v[206:209], v[72:75]
	v_mfma_f32_16x16x32_bf16 v[132:135], v[144:147], v[160:163], 0
	v_mfma_f32_16x16x32_bf16 v[124:127], v[152:155], v[160:163], 0
	v_mfma_f32_16x16x32_bf16 v[104:107], v[144:147], v[168:171], 0
	v_mfma_f32_16x16x32_bf16 v[100:103], v[152:155], v[168:171], 0
	v_mfma_f32_16x16x32_bf16 v[84:87], v[144:147], v[176:179], 0
	v_mfma_f32_16x16x32_bf16 v[80:83], v[152:155], v[176:179], 0
	v_mfma_f32_16x16x32_bf16 v[68:71], v[144:147], v[202:205], 0
	v_mfma_f32_16x16x32_bf16 v[64:67], v[152:155], v[202:205], 0
	v_mfma_f32_16x16x32_bf16 v[132:135], v[148:151], v[164:167], v[132:135]
	v_mfma_f32_16x16x32_bf16 v[124:127], v[156:159], v[164:167], v[124:127]
	v_mfma_f32_16x16x32_bf16 v[104:107], v[148:151], v[172:175], v[104:107]
	v_mfma_f32_16x16x32_bf16 v[100:103], v[156:159], v[172:175], v[100:103]
	v_mfma_f32_16x16x32_bf16 v[84:87], v[148:151], v[180:183], v[84:87]
	v_mfma_f32_16x16x32_bf16 v[80:83], v[156:159], v[180:183], v[80:83]
	v_mfma_f32_16x16x32_bf16 v[68:71], v[148:151], v[206:209], v[68:71]
	v_mfma_f32_16x16x32_bf16 v[64:67], v[156:159], v[206:209], v[64:67]
	s_barrier
	s_add_i32 s77, s71, s58
	s_add_u32 s98, s54, s12
	s_addc_u32 s99, s55, s13
	s_add_u32 s100, s56, s12
	s_addc_u32 s101, s57, s13
	s_mov_b32 m0, s77
	ds_read_b128 v[160:163], v225 offset:16384
	ds_read_b128 v[164:167], v225 offset:17408
	ds_read_b128 v[168:171], v225 offset:18432
	ds_read_b128 v[172:175], v225 offset:19456
	ds_read_b128 v[176:179], v225 offset:20480
	ds_read_b128 v[180:183], v225 offset:21504
	ds_read_b128 v[202:205], v225 offset:22528
	ds_read_b128 v[206:209], v225 offset:23552
	global_load_lds_dwordx4 v186, s[54:55]
	s_add_i32 m0, s77, 0x2000
	s_add_u32 s78, s54, 0x40000
	s_addc_u32 s79, s55, 0
	s_add_i32 s77, s72, s58
	global_load_lds_dwordx4 v190, s[54:55]
	s_mov_b32 m0, s77
	s_nop 0
	global_load_lds_dwordx4 v186, s[78:79]
	s_add_i32 m0, s77, 0x2000
	s_nop 0
	global_load_lds_dwordx4 v190, s[78:79]
	s_mov_b32 m0, s53
	s_nop 0
	global_load_lds_dwordx4 v184, s[56:57]
	s_mov_b32 m0, s59
	s_nop 0
	global_load_lds_dwordx4 v188, s[56:57]
	s_nop 0
	s_waitcnt vmcnt(8)
	s_waitcnt lgkmcnt(0)
	s_barrier
; #define PG8_STAGE(bufoff, gbase, voff) do { _Pragma("unroll") for (int _i = 0; _i < 2; ++_i) \
;         __builtin_amdgcn_global_load_lds((const unsigned*)((const char*)(gbase) + (voff)[_i]), (PG8_LAS unsigned*)(lds + (bufoff) + ldsw + _i * 8192), 16, 0, 0); } while (0)
; #define PG8_LDA(dst, b, h) do { _Pragma("unroll") for (int m = 0; m < 4; ++m) _Pragma("unroll") for (int k = 0; k < 2; ++k) dst[m][k] = *(const PG8_LAS bf16x8*)(lds + PG8_SA(b, h) + aoff + m * 2048 + k * 1024); } while (0)
; #define PG8_LDB(dst, b, h) do { _Pragma("unroll") for (int n = 0; n < 2; ++n) _Pragma("unroll") for (int k = 0; k < 2; ++k) dst[n][k] = *(const PG8_LAS bf16x8*)(lds + PG8_SB(b, h) + boff + n * 2048 + k * 1024); } while (0)
; #define PG8_MMA(ai, bj, At, Bt) do { __builtin_amdgcn_s_setprio(1); _Pragma("unroll") for (int m = 0; m < 4; ++m) _Pragma("unroll") for (int n = 0; n < 2; ++n) _Pragma("unroll") for (int k = 0; k < 2; ++k) \
;         acc[ai][bj][m][n] = __builtin_amdgcn_mfma_f32_16x16x32_bf16(Bt[n][k], At[m][k], acc[ai][bj][m][n], 0, 0, 0); __builtin_amdgcn_s_setprio(0); } while (0)
; #define PG8_WAIT_V(n) asm volatile("s_waitcnt vmcnt(" #n ")" ::: "memory")
; #define PG8_WAIT_L(n) asm volatile("s_waitcnt lgkmcnt(" #n ")" ::: "memory")
; #define PG8_BAR __builtin_amdgcn_s_barrier()
; #define PG8_SCHED __builtin_amdgcn_sched_barrier(0)
; template <class Epi, class Sched, bool ALIGN_EPI = false, bool SP2 = false>
; __device__ __forceinline__ void gemm_phase(PG8_LAS unsigned char* lds, const Gemm g, const Sched& S, const Epi& E) {
;     ...
;             PG8_WAIT_V(8); PG8_WAIT_L(0); PG8_BAR; PG8_MMA(1, 0, At, B0); PG8_MMA(1, 1, At, B1); PG8_BAR; PG8_SCHED;
;             PG8_LDB(B0, 1, 0); PG8_LDB(B1, 1, 1); PG8_SCHED; PG8_LDA(At, 1, 0); PG8_STAGE(PG8_SA(0, 1), a2 + hstep, voffA);
;             PG8_WAIT_V(8); PG8_WAIT_L(0); PG8_BAR; PG8_MMA(0, 0, At, B0); PG8_MMA(0, 1, At, B1); PG8_BAR; PG8_SCHED;
	v_mfma_f32_16x16x32_bf16 v[60:63], v[96:99], v[160:163], 0
	v_mfma_f32_16x16x32_bf16 v[56:59], v[120:123], v[160:163], 0
	v_mfma_f32_16x16x32_bf16 v[44:47], v[96:99], v[168:171], 0
	v_mfma_f32_16x16x32_bf16 v[40:43], v[120:123], v[168:171], 0
	v_mfma_f32_16x16x32_bf16 v[28:31], v[96:99], v[176:179], 0
	v_mfma_f32_16x16x32_bf16 v[24:27], v[120:123], v[176:179], 0
	v_mfma_f32_16x16x32_bf16 v[12:15], v[96:99], v[202:205], 0
	v_mfma_f32_16x16x32_bf16 v[8:11], v[120:123], v[202:205], 0
	v_mfma_f32_16x16x32_bf16 v[60:63], v[108:111], v[164:167], v[60:63]
	v_mfma_f32_16x16x32_bf16 v[56:59], v[128:131], v[164:167], v[56:59]
	v_mfma_f32_16x16x32_bf16 v[44:47], v[108:111], v[172:175], v[44:47]
	v_mfma_f32_16x16x32_bf16 v[40:43], v[128:131], v[172:175], v[40:43]
	v_mfma_f32_16x16x32_bf16 v[28:31], v[108:111], v[180:183], v[28:31]
	v_mfma_f32_16x16x32_bf16 v[24:27], v[128:131], v[180:183], v[24:27]
	v_mfma_f32_16x16x32_bf16 v[12:15], v[108:111], v[206:209], v[12:15]
	v_mfma_f32_16x16x32_bf16 v[8:11], v[128:131], v[206:209], v[8:11]
	v_mfma_f32_16x16x32_bf16 v[52:55], v[144:147], v[160:163], 0
	v_mfma_f32_16x16x32_bf16 v[48:51], v[152:155], v[160:163], 0
	v_mfma_f32_16x16x32_bf16 v[36:39], v[144:147], v[168:171], 0
	v_mfma_f32_16x16x32_bf16 v[32:35], v[152:155], v[168:171], 0
	v_mfma_f32_16x16x32_bf16 v[20:23], v[144:147], v[176:179], 0
	v_mfma_f32_16x16x32_bf16 v[16:19], v[152:155], v[176:179], 0
	v_mfma_f32_16x16x32_bf16 v[4:7], v[144:147], v[202:205], 0
	v_mfma_f32_16x16x32_bf16 v[0:3], v[152:155], v[202:205], 0
	v_mfma_f32_16x16x32_bf16 v[52:55], v[148:151], v[164:167], v[52:55]
	v_mfma_f32_16x16x32_bf16 v[48:51], v[156:159], v[164:167], v[48:51]
	v_mfma_f32_16x16x32_bf16 v[36:39], v[148:151], v[172:175], v[36:39]
	v_mfma_f32_16x16x32_bf16 v[32:35], v[156:159], v[172:175], v[32:35]
	v_mfma_f32_16x16x32_bf16 v[20:23], v[148:151], v[180:183], v[20:23]
	v_mfma_f32_16x16x32_bf16 v[16:19], v[156:159], v[180:183], v[16:19]
	v_mfma_f32_16x16x32_bf16 v[4:7], v[148:151], v[206:209], v[4:7]
	v_mfma_f32_16x16x32_bf16 v[0:3], v[156:159], v[206:209], v[0:3]
	s_barrier
	s_add_i32 s77, 0, 0x18000
	s_add_i32 s78, 0, 0x1c000
	v_add_u32_e32 v128, s77, v221
	v_add_u32_e32 v156, s78, v221
	ds_read_b128 v[96:99], v128
	ds_read_b128 v[108:111], v128 offset:1024
	ds_read_b128 v[120:123], v128 offset:2048
	ds_read_b128 v[128:131], v128 offset:3072
	ds_read_b128 v[144:147], v156
	ds_read_b128 v[148:151], v156 offset:1024
	ds_read_b128 v[152:155], v156 offset:2048
	ds_read_b128 v[156:159], v156 offset:3072
	s_add_u32 s56, s56, 0x40000
	s_addc_u32 s57, s57, 0
	s_mov_b32 m0, s60
	ds_read_b128 v[160:163], v225 offset:32768
	ds_read_b128 v[164:167], v225 offset:33792
	ds_read_b128 v[168:171], v225 offset:34816
	ds_read_b128 v[172:175], v225 offset:35840
	ds_read_b128 v[176:179], v225 offset:36864
	ds_read_b128 v[180:183], v225 offset:37888
	ds_read_b128 v[202:205], v225 offset:38912
	ds_read_b128 v[206:209], v225 offset:39936
	global_load_lds_dwordx4 v184, s[56:57]
	s_mov_b32 m0, s61
	s_nop 0
	global_load_lds_dwordx4 v188, s[56:57]
	s_waitcnt vmcnt(8)
	s_waitcnt lgkmcnt(0)
	s_barrier
	v_mfma_f32_16x16x32_bf16 v[140:143], v[96:99], v[160:163], v[140:143]
	v_mfma_f32_16x16x32_bf16 v[136:139], v[120:123], v[160:163], v[136:139]
	v_mfma_f32_16x16x32_bf16 v[116:119], v[96:99], v[168:171], v[116:119]
	v_mfma_f32_16x16x32_bf16 v[112:115], v[120:123], v[168:171], v[112:115]
	v_mfma_f32_16x16x32_bf16 v[92:95], v[96:99], v[176:179], v[92:95]
	v_mfma_f32_16x16x32_bf16 v[88:91], v[120:123], v[176:179], v[88:91]
	v_mfma_f32_16x16x32_bf16 v[76:79], v[96:99], v[202:205], v[76:79]
	v_mfma_f32_16x16x32_bf16 v[72:75], v[120:123], v[202:205], v[72:75]
	v_mfma_f32_16x16x32_bf16 v[140:143], v[108:111], v[164:167], v[140:143]
	v_mfma_f32_16x16x32_bf16 v[136:139], v[128:131], v[164:167], v[136:139]
	v_mfma_f32_16x16x32_bf16 v[116:119], v[108:111], v[172:175], v[116:119]
	v_mfma_f32_16x16x32_bf16 v[112:115], v[128:131], v[172:175], v[112:115]
	v_mfma_f32_16x16x32_bf16 v[92:95], v[108:111], v[180:183], v[92:95]
	v_mfma_f32_16x16x32_bf16 v[88:91], v[128:131], v[180:183], v[88:91]
	v_mfma_f32_16x16x32_bf16 v[76:79], v[108:111], v[206:209], v[76:79]
	v_mfma_f32_16x16x32_bf16 v[72:75], v[128:131], v[206:209], v[72:75]
	v_mfma_f32_16x16x32_bf16 v[132:135], v[144:147], v[160:163], v[132:135]
	v_mfma_f32_16x16x32_bf16 v[124:127], v[152:155], v[160:163], v[124:127]
	v_mfma_f32_16x16x32_bf16 v[104:107], v[144:147], v[168:171], v[104:107]
	v_mfma_f32_16x16x32_bf16 v[100:103], v[152:155], v[168:171], v[100:103]
	v_mfma_f32_16x16x32_bf16 v[84:87], v[144:147], v[176:179], v[84:87]
	v_mfma_f32_16x16x32_bf16 v[80:83], v[152:155], v[176:179], v[80:83]
	v_mfma_f32_16x16x32_bf16 v[68:71], v[144:147], v[202:205], v[68:71]
	v_mfma_f32_16x16x32_bf16 v[64:67], v[152:155], v[202:205], v[64:67]
	v_mfma_f32_16x16x32_bf16 v[132:135], v[148:151], v[164:167], v[132:135]
	v_mfma_f32_16x16x32_bf16 v[124:127], v[156:159], v[164:167], v[124:127]
	v_mfma_f32_16x16x32_bf16 v[104:107], v[148:151], v[172:175], v[104:107]
	v_mfma_f32_16x16x32_bf16 v[100:103], v[156:159], v[172:175], v[100:103]
	v_mfma_f32_16x16x32_bf16 v[84:87], v[148:151], v[180:183], v[84:87]
	v_mfma_f32_16x16x32_bf16 v[80:83], v[156:159], v[180:183], v[80:83]
	v_mfma_f32_16x16x32_bf16 v[68:71], v[148:151], v[206:209], v[68:71]
	v_mfma_f32_16x16x32_bf16 v[64:67], v[156:159], v[206:209], v[64:67]
	s_barrier
; #define PG8_STAGE(bufoff, gbase, voff) do { _Pragma("unroll") for (int _i = 0; _i < 2; ++_i) \
;         __builtin_amdgcn_global_load_lds((const unsigned*)((const char*)(gbase) + (voff)[_i]), (PG8_LAS unsigned*)(lds + (bufoff) + ldsw + _i * 8192), 16, 0, 0); } while (0)
; #define PG8_LDA(dst, b, h) do { _Pragma("unroll") for (int m = 0; m < 4; ++m) _Pragma("unroll") for (int k = 0; k < 2; ++k) dst[m][k] = *(const PG8_LAS bf16x8*)(lds + PG8_SA(b, h) + aoff + m * 2048 + k * 1024); } while (0)
; #define PG8_LDB(dst, b, h) do { _Pragma("unroll") for (int n = 0; n < 2; ++n) _Pragma("unroll") for (int k = 0; k < 2; ++k) dst[n][k] = *(const PG8_LAS bf16x8*)(lds + PG8_SB(b, h) + boff + n * 2048 + k * 1024); } while (0)
; #define PG8_MMA(ai, bj, At, Bt) do { __builtin_amdgcn_s_setprio(1); _Pragma("unroll") for (int m = 0; m < 4; ++m) _Pragma("unroll") for (int n = 0; n < 2; ++n) _Pragma("unroll") for (int k = 0; k < 2; ++k) \
;         acc[ai][bj][m][n] = __builtin_amdgcn_mfma_f32_16x16x32_bf16(Bt[n][k], At[m][k], acc[ai][bj][m][n], 0, 0, 0); __builtin_amdgcn_s_setprio(0); } while (0)
; #define PG8_WAIT_V(n) asm volatile("s_waitcnt vmcnt(" #n ")" ::: "memory")
; template <class Epi, class Sched, bool ALIGN_EPI = false, bool SP2 = false>
; __device__ __forceinline__ void gemm_phase(PG8_LAS unsigned char* lds, const Gemm g, const Sched& S, const Epi& E) {
;     ...
;             PG8_LDB(B0, 0, 0); PG8_LDB(B1, 0, 1); PG8_SCHED; PG8_LDA(At, 0, 0); PG8_STAGE(PG8_SA(1, 1), a1 + hstep, voffA);
;             PG8_WAIT_V(8); PG8_WAIT_L(0); PG8_BAR; PG8_MMA(0, 0, At, B0); PG8_MMA(0, 1, At, B1); PG8_BAR; PG8_SCHED;
;             PG8_LDA(At, 0, 1); PG8_STAGE(PG8_SB(0, 0), b2, voffB); PG8_STAGE(PG8_SB(0, 1), b2 + hstep, voffB); PG8_STAGE(PG8_SA(0, 0), a2, voffA);
;             PG8_WAIT_V(8); PG8_WAIT_L(0); PG8_BAR; PG8_MMA(1, 0, At, B0); PG8_MMA(1, 1, At, B1); PG8_BAR; PG8_SCHED;
;             PG8_LDB(B0, 1, 0); PG8_LDB(B1, 1, 1); PG8_SCHED; PG8_LDA(At, 1, 0); PG8_STAGE(PG8_SA(0, 1), a2 + hstep, voffA);
;             PG8_WAIT_V(8); PG8_WAIT_L(0); PG8_BAR; PG8_MMA(0, 0, At, B0); PG8_MMA(0, 1, At, B1); PG8_BAR; PG8_SCHED;
;             PG8_LDA(At, 1, 1); PG8_STAGE(PG8_SB(1, 0), b3, voffB); PG8_STAGE(PG8_SB(1, 1), b3 + hstep, voffB); PG8_STAGE(PG8_SA(1, 0), a3, voffA);
;             PG8_WAIT_V(8); PG8_WAIT_L(0); PG8_BAR; PG8_MMA(1, 0, At, B0); PG8_MMA(1, 1, At, B1); PG8_BAR; PG8_SCHED;
	s_add_i32 s56, s77, s58
	s_mov_b32 m0, s56
	ds_read_b128 v[160:163], v225 offset:49152
	ds_read_b128 v[164:167], v225 offset:50176
	ds_read_b128 v[168:171], v225 offset:51200
	ds_read_b128 v[172:175], v225 offset:52224
	ds_read_b128 v[176:179], v225 offset:53248
	ds_read_b128 v[180:183], v225 offset:54272
	ds_read_b128 v[202:205], v225 offset:55296
	ds_read_b128 v[206:209], v225 offset:56320
	global_load_lds_dwordx4 v186, s[98:99]
	s_add_i32 m0, s56, 0x2000
	s_add_u32 s54, s54, 0x40080
	s_addc_u32 s55, s55, 0
	s_add_i32 s56, s78, s58
	global_load_lds_dwordx4 v190, s[98:99]
	s_mov_b32 m0, s56
	s_nop 0
	global_load_lds_dwordx4 v186, s[54:55]
	s_add_i32 m0, s56, 0x2000
	s_nop 0
	global_load_lds_dwordx4 v190, s[54:55]
	s_mov_b32 m0, s66
	s_nop 0
	global_load_lds_dwordx4 v184, s[100:101]
	s_mov_b32 m0, s67
	s_nop 0
	global_load_lds_dwordx4 v188, s[100:101]
	s_nop 0
	s_waitcnt vmcnt(8)
	s_waitcnt lgkmcnt(0)
	s_barrier
	v_mfma_f32_16x16x32_bf16 v[60:63], v[96:99], v[160:163], v[60:63]
	v_mfma_f32_16x16x32_bf16 v[56:59], v[120:123], v[160:163], v[56:59]
	v_mfma_f32_16x16x32_bf16 v[44:47], v[96:99], v[168:171], v[44:47]
	v_mfma_f32_16x16x32_bf16 v[40:43], v[120:123], v[168:171], v[40:43]
	v_mfma_f32_16x16x32_bf16 v[28:31], v[96:99], v[176:179], v[28:31]
	v_mfma_f32_16x16x32_bf16 v[24:27], v[120:123], v[176:179], v[24:27]
	v_mfma_f32_16x16x32_bf16 v[12:15], v[96:99], v[202:205], v[12:15]
	v_mfma_f32_16x16x32_bf16 v[8:11], v[120:123], v[202:205], v[8:11]
	v_mfma_f32_16x16x32_bf16 v[60:63], v[108:111], v[164:167], v[60:63]
	v_mfma_f32_16x16x32_bf16 v[56:59], v[128:131], v[164:167], v[56:59]
	v_mfma_f32_16x16x32_bf16 v[44:47], v[108:111], v[172:175], v[44:47]
	v_mfma_f32_16x16x32_bf16 v[40:43], v[128:131], v[172:175], v[40:43]
	v_mfma_f32_16x16x32_bf16 v[28:31], v[108:111], v[180:183], v[28:31]
	v_mfma_f32_16x16x32_bf16 v[24:27], v[128:131], v[180:183], v[24:27]
	v_mfma_f32_16x16x32_bf16 v[12:15], v[108:111], v[206:209], v[12:15]
	v_mfma_f32_16x16x32_bf16 v[8:11], v[128:131], v[206:209], v[8:11]
	v_mfma_f32_16x16x32_bf16 v[52:55], v[144:147], v[160:163], v[52:55]
	v_mfma_f32_16x16x32_bf16 v[48:51], v[152:155], v[160:163], v[48:51]
	v_mfma_f32_16x16x32_bf16 v[36:39], v[144:147], v[168:171], v[36:39]
	v_mfma_f32_16x16x32_bf16 v[32:35], v[152:155], v[168:171], v[32:35]
	v_mfma_f32_16x16x32_bf16 v[20:23], v[144:147], v[176:179], v[20:23]
	v_mfma_f32_16x16x32_bf16 v[16:19], v[152:155], v[176:179], v[16:19]
	v_mfma_f32_16x16x32_bf16 v[4:7], v[144:147], v[202:205], v[4:7]
	v_mfma_f32_16x16x32_bf16 v[0:3], v[152:155], v[202:205], v[0:3]
	v_mfma_f32_16x16x32_bf16 v[52:55], v[148:151], v[164:167], v[52:55]
	v_mfma_f32_16x16x32_bf16 v[48:51], v[156:159], v[164:167], v[48:51]
	v_mfma_f32_16x16x32_bf16 v[36:39], v[148:151], v[172:175], v[36:39]
	v_mfma_f32_16x16x32_bf16 v[32:35], v[156:159], v[172:175], v[32:35]
	v_mfma_f32_16x16x32_bf16 v[20:23], v[148:151], v[180:183], v[20:23]
	v_mfma_f32_16x16x32_bf16 v[16:19], v[156:159], v[180:183], v[16:19]
	v_mfma_f32_16x16x32_bf16 v[4:7], v[148:151], v[206:209], v[4:7]
	v_mfma_f32_16x16x32_bf16 v[0:3], v[156:159], v[206:209], v[0:3]
	s_barrier
	s_add_i32 s76, s76, 2
	s_add_u32 s20, s20, 0x100
	s_addc_u32 s21, s21, 0
	s_add_u32 s74, s74, 0x100
	s_addc_u32 s75, s75, 0
	s_cmp_gt_u32 s76, 13
.LBB0_705:
	ds_read_b128 v[96:99], v223
	ds_read_b128 v[108:111], v223 offset:1024
	ds_read_b128 v[120:123], v223 offset:2048
	ds_read_b128 v[128:131], v223 offset:3072
	ds_read_b128 v[144:147], v224
	ds_read_b128 v[148:151], v224 offset:1024
	ds_read_b128 v[152:155], v224 offset:2048
	ds_read_b128 v[156:159], v224 offset:3072
	s_add_u32 s54, s20, 0xfffc0080
	s_addc_u32 s55, s21, -1
	s_cmp_eq_u32 s76, 12
	s_cselect_b32 s57, s35, s55
	s_cselect_b32 s56, s47, s54
	s_cselect_b32 s55, s45, s75
	s_cselect_b32 s54, s73, s74
	s_add_i32 m0, s53, 0xc000
	ds_read_b128 v[160:163], v225
	ds_read_b128 v[164:167], v225 offset:1024
	ds_read_b128 v[168:171], v225 offset:2048
	ds_read_b128 v[172:175], v225 offset:3072
	ds_read_b128 v[176:179], v225 offset:4096
	ds_read_b128 v[180:183], v225 offset:5120
	ds_read_b128 v[202:205], v225 offset:6144
	ds_read_b128 v[206:209], v225 offset:7168
	global_load_lds_dwordx4 v192, s[20:21]
	s_add_i32 m0, s53, 0xe000
	s_nop 0
	global_load_lds_dwordx4 v194, s[20:21]
	s_nop 0
	s_waitcnt vmcnt(8)
	s_waitcnt lgkmcnt(0)
	s_barrier
	v_mfma_f32_16x16x32_bf16 v[140:143], v[96:99], v[160:163], v[140:143]
	v_mfma_f32_16x16x32_bf16 v[136:139], v[120:123], v[160:163], v[136:139]
	v_mfma_f32_16x16x32_bf16 v[116:119], v[96:99], v[168:171], v[116:119]
	v_mfma_f32_16x16x32_bf16 v[112:115], v[120:123], v[168:171], v[112:115]
	v_mfma_f32_16x16x32_bf16 v[92:95], v[96:99], v[176:179], v[92:95]
	v_mfma_f32_16x16x32_bf16 v[88:91], v[120:123], v[176:179], v[88:91]
	v_mfma_f32_16x16x32_bf16 v[76:79], v[96:99], v[202:205], v[76:79]
	v_mfma_f32_16x16x32_bf16 v[72:75], v[120:123], v[202:205], v[72:75]
	v_mfma_f32_16x16x32_bf16 v[140:143], v[108:111], v[164:167], v[140:143]
	v_mfma_f32_16x16x32_bf16 v[136:139], v[128:131], v[164:167], v[136:139]
	v_mfma_f32_16x16x32_bf16 v[116:119], v[108:111], v[172:175], v[116:119]
	v_mfma_f32_16x16x32_bf16 v[112:115], v[128:131], v[172:175], v[112:115]
	v_mfma_f32_16x16x32_bf16 v[92:95], v[108:111], v[180:183], v[92:95]
	v_mfma_f32_16x16x32_bf16 v[88:91], v[128:131], v[180:183], v[88:91]
	v_mfma_f32_16x16x32_bf16 v[76:79], v[108:111], v[206:209], v[76:79]
	v_mfma_f32_16x16x32_bf16 v[72:75], v[128:131], v[206:209], v[72:75]
	v_mfma_f32_16x16x32_bf16 v[132:135], v[144:147], v[160:163], v[132:135]
	v_mfma_f32_16x16x32_bf16 v[124:127], v[152:155], v[160:163], v[124:127]
	v_mfma_f32_16x16x32_bf16 v[104:107], v[144:147], v[168:171], v[104:107]
	v_mfma_f32_16x16x32_bf16 v[100:103], v[152:155], v[168:171], v[100:103]
	v_mfma_f32_16x16x32_bf16 v[84:87], v[144:147], v[176:179], v[84:87]
	v_mfma_f32_16x16x32_bf16 v[80:83], v[152:155], v[176:179], v[80:83]
	v_mfma_f32_16x16x32_bf16 v[68:71], v[144:147], v[202:205], v[68:71]
	v_mfma_f32_16x16x32_bf16 v[64:67], v[152:155], v[202:205], v[64:67]
	v_mfma_f32_16x16x32_bf16 v[132:135], v[148:151], v[164:167], v[132:135]
	v_mfma_f32_16x16x32_bf16 v[124:127], v[156:159], v[164:167], v[124:127]
	v_mfma_f32_16x16x32_bf16 v[104:107], v[148:151], v[172:175], v[104:107]
	v_mfma_f32_16x16x32_bf16 v[100:103], v[156:159], v[172:175], v[100:103]
	v_mfma_f32_16x16x32_bf16 v[84:87], v[148:151], v[180:183], v[84:87]
	v_mfma_f32_16x16x32_bf16 v[80:83], v[156:159], v[180:183], v[80:83]
	v_mfma_f32_16x16x32_bf16 v[68:71], v[148:151], v[206:209], v[68:71]
	v_mfma_f32_16x16x32_bf16 v[64:67], v[156:159], v[206:209], v[64:67]
	s_barrier
; #define PG8_STAGE(bufoff, gbase, voff) do { _Pragma("unroll") for (int _i = 0; _i < 2; ++_i) \
;         __builtin_amdgcn_global_load_lds((const unsigned*)((const char*)(gbase) + (voff)[_i]), (PG8_LAS unsigned*)(lds + (bufoff) + ldsw + _i * 8192), 16, 0, 0); } while (0)
; #define PG8_LDA(dst, b, h) do { _Pragma("unroll") for (int m = 0; m < 4; ++m) _Pragma("unroll") for (int k = 0; k < 2; ++k) dst[m][k] = *(const PG8_LAS bf16x8*)(lds + PG8_SA(b, h) + aoff + m * 2048 + k * 1024); } while (0)
; #define PG8_LDB(dst, b, h) do { _Pragma("unroll") for (int n = 0; n < 2; ++n) _Pragma("unroll") for (int k = 0; k < 2; ++k) dst[n][k] = *(const PG8_LAS bf16x8*)(lds + PG8_SB(b, h) + boff + n * 2048 + k * 1024); } while (0)
; #define PG8_MMA(ai, bj, At, Bt) do { __builtin_amdgcn_s_setprio(1); _Pragma("unroll") for (int m = 0; m < 4; ++m) _Pragma("unroll") for (int n = 0; n < 2; ++n) _Pragma("unroll") for (int k = 0; k < 2; ++k) \
;         acc[ai][bj][m][n] = __builtin_amdgcn_mfma_f32_16x16x32_bf16(Bt[n][k], At[m][k], acc[ai][bj][m][n], 0, 0, 0); __builtin_amdgcn_s_setprio(0); } while (0)
; #define PG8_WAIT_V(n) asm volatile("s_waitcnt vmcnt(" #n ")" ::: "memory")
; #define PG8_WAIT_L(n) asm volatile("s_waitcnt lgkmcnt(" #n ")" ::: "memory")
; #define PG8_BAR __builtin_amdgcn_s_barrier()
; #define PG8_SCHED __builtin_amdgcn_sched_barrier(0)
; template <class Epi, class Sched, bool ALIGN_EPI = false, bool SP2 = false>
; __device__ __forceinline__ void gemm_phase(PG8_LAS unsigned char* lds, const Gemm g, const Sched& S, const Epi& E) {
;     ...
;             PG8_LDA(At, 0, 1); PG8_STAGE(PG8_SB(0, 0), b2, voffB); PG8_STAGE(PG8_SB(0, 1), b2 + hstep, voffB); PG8_STAGE(PG8_SA(0, 0), a2, voffA);
;             PG8_WAIT_V(8); PG8_WAIT_L(0); PG8_BAR; PG8_MMA(1, 0, At, B0); PG8_MMA(1, 1, At, B1); PG8_BAR; PG8_SCHED;
;             PG8_LDB(B0, 1, 0); PG8_LDB(B1, 1, 1); PG8_SCHED; PG8_LDA(At, 1, 0); PG8_STAGE(PG8_SA(0, 1), a2 + hstep, voffA);
;             PG8_WAIT_V(8); PG8_WAIT_L(0); PG8_BAR; PG8_MMA(0, 0, At, B0); PG8_MMA(0, 1, At, B1); PG8_BAR; PG8_SCHED;
	s_add_i32 s77, s71, s58
	s_add_u32 s98, s54, s12
	s_addc_u32 s99, s55, s13
	s_add_u32 s100, s56, s12
	s_addc_u32 s101, s57, s13
	s_mov_b32 m0, s77
	ds_read_b128 v[160:163], v225 offset:16384
	ds_read_b128 v[164:167], v225 offset:17408
	ds_read_b128 v[168:171], v225 offset:18432
	ds_read_b128 v[172:175], v225 offset:19456
	ds_read_b128 v[176:179], v225 offset:20480
	ds_read_b128 v[180:183], v225 offset:21504
	ds_read_b128 v[202:205], v225 offset:22528
	ds_read_b128 v[206:209], v225 offset:23552
	global_load_lds_dwordx4 v186, s[54:55]
	s_add_i32 m0, s77, 0x2000
	s_add_u32 s78, s54, 0x40000
	s_addc_u32 s79, s55, 0
	s_add_i32 s77, s72, s58
	global_load_lds_dwordx4 v190, s[54:55]
	s_mov_b32 m0, s77
	s_nop 0
	global_load_lds_dwordx4 v186, s[78:79]
	s_add_i32 m0, s77, 0x2000
	s_nop 0
	global_load_lds_dwordx4 v190, s[78:79]
	s_mov_b32 m0, s53
	s_nop 0
	global_load_lds_dwordx4 v184, s[56:57]
	s_mov_b32 m0, s59
	s_nop 0
	global_load_lds_dwordx4 v188, s[56:57]
	s_nop 0
	s_waitcnt vmcnt(8)
	s_waitcnt lgkmcnt(0)
	s_barrier
	v_mfma_f32_16x16x32_bf16 v[60:63], v[96:99], v[160:163], v[60:63]
	v_mfma_f32_16x16x32_bf16 v[56:59], v[120:123], v[160:163], v[56:59]
	v_mfma_f32_16x16x32_bf16 v[44:47], v[96:99], v[168:171], v[44:47]
	v_mfma_f32_16x16x32_bf16 v[40:43], v[120:123], v[168:171], v[40:43]
	v_mfma_f32_16x16x32_bf16 v[28:31], v[96:99], v[176:179], v[28:31]
	v_mfma_f32_16x16x32_bf16 v[24:27], v[120:123], v[176:179], v[24:27]
	v_mfma_f32_16x16x32_bf16 v[12:15], v[96:99], v[202:205], v[12:15]
	v_mfma_f32_16x16x32_bf16 v[8:11], v[120:123], v[202:205], v[8:11]
	v_mfma_f32_16x16x32_bf16 v[60:63], v[108:111], v[164:167], v[60:63]
	v_mfma_f32_16x16x32_bf16 v[56:59], v[128:131], v[164:167], v[56:59]
	v_mfma_f32_16x16x32_bf16 v[44:47], v[108:111], v[172:175], v[44:47]
	v_mfma_f32_16x16x32_bf16 v[40:43], v[128:131], v[172:175], v[40:43]
	v_mfma_f32_16x16x32_bf16 v[28:31], v[108:111], v[180:183], v[28:31]
	v_mfma_f32_16x16x32_bf16 v[24:27], v[128:131], v[180:183], v[24:27]
	v_mfma_f32_16x16x32_bf16 v[12:15], v[108:111], v[206:209], v[12:15]
	v_mfma_f32_16x16x32_bf16 v[8:11], v[128:131], v[206:209], v[8:11]
	v_mfma_f32_16x16x32_bf16 v[52:55], v[144:147], v[160:163], v[52:55]
	v_mfma_f32_16x16x32_bf16 v[48:51], v[152:155], v[160:163], v[48:51]
	v_mfma_f32_16x16x32_bf16 v[36:39], v[144:147], v[168:171], v[36:39]
	v_mfma_f32_16x16x32_bf16 v[32:35], v[152:155], v[168:171], v[32:35]
	v_mfma_f32_16x16x32_bf16 v[20:23], v[144:147], v[176:179], v[20:23]
	v_mfma_f32_16x16x32_bf16 v[16:19], v[152:155], v[176:179], v[16:19]
	v_mfma_f32_16x16x32_bf16 v[4:7], v[144:147], v[202:205], v[4:7]
	v_mfma_f32_16x16x32_bf16 v[0:3], v[152:155], v[202:205], v[0:3]
	v_mfma_f32_16x16x32_bf16 v[52:55], v[148:151], v[164:167], v[52:55]
	v_mfma_f32_16x16x32_bf16 v[48:51], v[156:159], v[164:167], v[48:51]
	v_mfma_f32_16x16x32_bf16 v[36:39], v[148:151], v[172:175], v[36:39]
	v_mfma_f32_16x16x32_bf16 v[32:35], v[156:159], v[172:175], v[32:35]
	v_mfma_f32_16x16x32_bf16 v[20:23], v[148:151], v[180:183], v[20:23]
	v_mfma_f32_16x16x32_bf16 v[16:19], v[156:159], v[180:183], v[16:19]
	v_mfma_f32_16x16x32_bf16 v[4:7], v[148:151], v[206:209], v[4:7]
	v_mfma_f32_16x16x32_bf16 v[0:3], v[156:159], v[206:209], v[0:3]
	s_barrier
	s_add_i32 s77, 0, 0x18000
	s_add_i32 s78, 0, 0x1c000
	v_add_u32_e32 v128, s77, v221
	v_add_u32_e32 v156, s78, v221
	ds_read_b128 v[96:99], v128
	ds_read_b128 v[108:111], v128 offset:1024
	ds_read_b128 v[120:123], v128 offset:2048
	ds_read_b128 v[128:131], v128 offset:3072
	ds_read_b128 v[144:147], v156
	ds_read_b128 v[148:151], v156 offset:1024
	ds_read_b128 v[152:155], v156 offset:2048
	ds_read_b128 v[156:159], v156 offset:3072
	s_add_u32 s56, s56, 0x40000
	s_addc_u32 s57, s57, 0
	s_mov_b32 m0, s60
	ds_read_b128 v[160:163], v225 offset:32768
	ds_read_b128 v[164:167], v225 offset:33792
	ds_read_b128 v[168:171], v225 offset:34816
	ds_read_b128 v[172:175], v225 offset:35840
	ds_read_b128 v[176:179], v225 offset:36864
	ds_read_b128 v[180:183], v225 offset:37888
	ds_read_b128 v[202:205], v225 offset:38912
	ds_read_b128 v[206:209], v225 offset:39936
	global_load_lds_dwordx4 v184, s[56:57]
	s_mov_b32 m0, s61
	s_nop 0
	global_load_lds_dwordx4 v188, s[56:57]
	s_waitcnt vmcnt(8)
	s_waitcnt lgkmcnt(0)
	s_barrier
; #define PG8_STAGE(bufoff, gbase, voff) do { _Pragma("unroll") for (int _i = 0; _i < 2; ++_i) \
;         __builtin_amdgcn_global_load_lds((const unsigned*)((const char*)(gbase) + (voff)[_i]), (PG8_LAS unsigned*)(lds + (bufoff) + ldsw + _i * 8192), 16, 0, 0); } while (0)
; #define PG8_LDA(dst, b, h) do { _Pragma("unroll") for (int m = 0; m < 4; ++m) _Pragma("unroll") for (int k = 0; k < 2; ++k) dst[m][k] = *(const PG8_LAS bf16x8*)(lds + PG8_SA(b, h) + aoff + m * 2048 + k * 1024); } while (0)
; #define PG8_MMA(ai, bj, At, Bt) do { __builtin_amdgcn_s_setprio(1); _Pragma("unroll") for (int m = 0; m < 4; ++m) _Pragma("unroll") for (int n = 0; n < 2; ++n) _Pragma("unroll") for (int k = 0; k < 2; ++k) \
;         acc[ai][bj][m][n] = __builtin_amdgcn_mfma_f32_16x16x32_bf16(Bt[n][k], At[m][k], acc[ai][bj][m][n], 0, 0, 0); __builtin_amdgcn_s_setprio(0); } while (0)
; #define PG8_WAIT_V(n) asm volatile("s_waitcnt vmcnt(" #n ")" ::: "memory")
; #define PG8_WAIT_L(n) asm volatile("s_waitcnt lgkmcnt(" #n ")" ::: "memory")
; #define PG8_BAR __builtin_amdgcn_s_barrier()
; #define PG8_SCHED __builtin_amdgcn_sched_barrier(0)
; template <class Epi, class Sched, bool ALIGN_EPI = false, bool SP2 = false>
; __device__ __forceinline__ void gemm_phase(PG8_LAS unsigned char* lds, const Gemm g, const Sched& S, const Epi& E) {
;     ...
;             PG8_WAIT_V(8); PG8_WAIT_L(0); PG8_BAR; PG8_MMA(0, 0, At, B0); PG8_MMA(0, 1, At, B1); PG8_BAR; PG8_SCHED;
;             PG8_LDA(At, 1, 1); PG8_STAGE(PG8_SB(1, 0), b3, voffB); PG8_STAGE(PG8_SB(1, 1), b3 + hstep, voffB); PG8_STAGE(PG8_SA(1, 0), a3, voffA);
;             PG8_WAIT_V(8); PG8_WAIT_L(0); PG8_BAR; PG8_MMA(1, 0, At, B0); PG8_MMA(1, 1, At, B1); PG8_BAR; PG8_SCHED;
;     ...
;         if constexpr (ALIGN_EPI) { if (wr == 0) PG8_BAR; }
	v_mfma_f32_16x16x32_bf16 v[140:143], v[96:99], v[160:163], v[140:143]
	v_mfma_f32_16x16x32_bf16 v[136:139], v[120:123], v[160:163], v[136:139]
	v_mfma_f32_16x16x32_bf16 v[116:119], v[96:99], v[168:171], v[116:119]
	v_mfma_f32_16x16x32_bf16 v[112:115], v[120:123], v[168:171], v[112:115]
	v_mfma_f32_16x16x32_bf16 v[92:95], v[96:99], v[176:179], v[92:95]
	v_mfma_f32_16x16x32_bf16 v[88:91], v[120:123], v[176:179], v[88:91]
	v_mfma_f32_16x16x32_bf16 v[76:79], v[96:99], v[202:205], v[76:79]
	v_mfma_f32_16x16x32_bf16 v[72:75], v[120:123], v[202:205], v[72:75]
	v_mfma_f32_16x16x32_bf16 v[140:143], v[108:111], v[164:167], v[140:143]
	v_mfma_f32_16x16x32_bf16 v[136:139], v[128:131], v[164:167], v[136:139]
	v_mfma_f32_16x16x32_bf16 v[116:119], v[108:111], v[172:175], v[116:119]
	v_mfma_f32_16x16x32_bf16 v[112:115], v[128:131], v[172:175], v[112:115]
	v_mfma_f32_16x16x32_bf16 v[92:95], v[108:111], v[180:183], v[92:95]
	v_mfma_f32_16x16x32_bf16 v[88:91], v[128:131], v[180:183], v[88:91]
	v_mfma_f32_16x16x32_bf16 v[76:79], v[108:111], v[206:209], v[76:79]
	v_mfma_f32_16x16x32_bf16 v[72:75], v[128:131], v[206:209], v[72:75]
	v_mfma_f32_16x16x32_bf16 v[132:135], v[144:147], v[160:163], v[132:135]
	v_mfma_f32_16x16x32_bf16 v[124:127], v[152:155], v[160:163], v[124:127]
	v_mfma_f32_16x16x32_bf16 v[104:107], v[144:147], v[168:171], v[104:107]
	v_mfma_f32_16x16x32_bf16 v[100:103], v[152:155], v[168:171], v[100:103]
	v_mfma_f32_16x16x32_bf16 v[84:87], v[144:147], v[176:179], v[84:87]
	v_mfma_f32_16x16x32_bf16 v[80:83], v[152:155], v[176:179], v[80:83]
	v_mfma_f32_16x16x32_bf16 v[68:71], v[144:147], v[202:205], v[68:71]
	v_mfma_f32_16x16x32_bf16 v[64:67], v[152:155], v[202:205], v[64:67]
	v_mfma_f32_16x16x32_bf16 v[132:135], v[148:151], v[164:167], v[132:135]
	v_mfma_f32_16x16x32_bf16 v[124:127], v[156:159], v[164:167], v[124:127]
	v_mfma_f32_16x16x32_bf16 v[104:107], v[148:151], v[172:175], v[104:107]
	v_mfma_f32_16x16x32_bf16 v[100:103], v[156:159], v[172:175], v[100:103]
	v_mfma_f32_16x16x32_bf16 v[84:87], v[148:151], v[180:183], v[84:87]
	v_mfma_f32_16x16x32_bf16 v[80:83], v[156:159], v[180:183], v[80:83]
	v_mfma_f32_16x16x32_bf16 v[68:71], v[148:151], v[206:209], v[68:71]
	v_mfma_f32_16x16x32_bf16 v[64:67], v[156:159], v[206:209], v[64:67]
	s_barrier
	s_add_i32 s56, s77, s58
	s_mov_b32 m0, s56
	ds_read_b128 v[160:163], v225 offset:49152
	ds_read_b128 v[164:167], v225 offset:50176
	ds_read_b128 v[168:171], v225 offset:51200
	ds_read_b128 v[172:175], v225 offset:52224
	ds_read_b128 v[176:179], v225 offset:53248
	ds_read_b128 v[180:183], v225 offset:54272
	ds_read_b128 v[202:205], v225 offset:55296
	ds_read_b128 v[206:209], v225 offset:56320
	global_load_lds_dwordx4 v186, s[98:99]
	s_add_i32 m0, s56, 0x2000
	s_add_u32 s54, s54, 0x40080
	s_addc_u32 s55, s55, 0
	s_add_i32 s56, s78, s58
	global_load_lds_dwordx4 v190, s[98:99]
	s_mov_b32 m0, s56
	s_nop 0
	global_load_lds_dwordx4 v186, s[54:55]
	s_add_i32 m0, s56, 0x2000
	s_nop 0
	global_load_lds_dwordx4 v190, s[54:55]
	s_mov_b32 m0, s66
	s_nop 0
	global_load_lds_dwordx4 v184, s[100:101]
	s_mov_b32 m0, s67
	s_nop 0
	global_load_lds_dwordx4 v188, s[100:101]
	s_nop 0
	s_waitcnt vmcnt(8)
	s_waitcnt lgkmcnt(0)
	s_barrier
	v_mfma_f32_16x16x32_bf16 v[60:63], v[96:99], v[160:163], v[60:63]
	v_mfma_f32_16x16x32_bf16 v[56:59], v[120:123], v[160:163], v[56:59]
	v_mfma_f32_16x16x32_bf16 v[44:47], v[96:99], v[168:171], v[44:47]
	v_mfma_f32_16x16x32_bf16 v[40:43], v[120:123], v[168:171], v[40:43]
	v_mfma_f32_16x16x32_bf16 v[28:31], v[96:99], v[176:179], v[28:31]
	v_mfma_f32_16x16x32_bf16 v[24:27], v[120:123], v[176:179], v[24:27]
	v_mfma_f32_16x16x32_bf16 v[12:15], v[96:99], v[202:205], v[12:15]
	v_mfma_f32_16x16x32_bf16 v[8:11], v[120:123], v[202:205], v[8:11]
	v_mfma_f32_16x16x32_bf16 v[60:63], v[108:111], v[164:167], v[60:63]
	v_mfma_f32_16x16x32_bf16 v[56:59], v[128:131], v[164:167], v[56:59]
	v_mfma_f32_16x16x32_bf16 v[44:47], v[108:111], v[172:175], v[44:47]
	v_mfma_f32_16x16x32_bf16 v[40:43], v[128:131], v[172:175], v[40:43]
	v_mfma_f32_16x16x32_bf16 v[28:31], v[108:111], v[180:183], v[28:31]
	v_mfma_f32_16x16x32_bf16 v[24:27], v[128:131], v[180:183], v[24:27]
	v_mfma_f32_16x16x32_bf16 v[12:15], v[108:111], v[206:209], v[12:15]
	v_mfma_f32_16x16x32_bf16 v[8:11], v[128:131], v[206:209], v[8:11]
	v_mfma_f32_16x16x32_bf16 v[52:55], v[144:147], v[160:163], v[52:55]
	v_mfma_f32_16x16x32_bf16 v[48:51], v[152:155], v[160:163], v[48:51]
	v_mfma_f32_16x16x32_bf16 v[36:39], v[144:147], v[168:171], v[36:39]
	v_mfma_f32_16x16x32_bf16 v[32:35], v[152:155], v[168:171], v[32:35]
	v_mfma_f32_16x16x32_bf16 v[20:23], v[144:147], v[176:179], v[20:23]
	v_mfma_f32_16x16x32_bf16 v[16:19], v[152:155], v[176:179], v[16:19]
	v_mfma_f32_16x16x32_bf16 v[4:7], v[144:147], v[202:205], v[4:7]
	v_mfma_f32_16x16x32_bf16 v[0:3], v[152:155], v[202:205], v[0:3]
	v_mfma_f32_16x16x32_bf16 v[52:55], v[148:151], v[164:167], v[52:55]
	v_mfma_f32_16x16x32_bf16 v[48:51], v[156:159], v[164:167], v[48:51]
	v_mfma_f32_16x16x32_bf16 v[36:39], v[148:151], v[172:175], v[36:39]
	v_mfma_f32_16x16x32_bf16 v[32:35], v[156:159], v[172:175], v[32:35]
	v_mfma_f32_16x16x32_bf16 v[20:23], v[148:151], v[180:183], v[20:23]
	v_mfma_f32_16x16x32_bf16 v[16:19], v[156:159], v[180:183], v[16:19]
	v_mfma_f32_16x16x32_bf16 v[4:7], v[148:151], v[206:209], v[4:7]
	v_mfma_f32_16x16x32_bf16 v[0:3], v[156:159], v[206:209], v[0:3]
	s_barrier
	s_add_i32 s76, s76, 2
	s_add_u32 s20, s20, 0x100
	s_addc_u32 s21, s21, 0
	s_add_u32 s74, s74, 0x100
	s_addc_u32 s75, s75, 0
	s_cmp_gt_u32 s76, 13
	s_cbranch_scc0 .LBB0_705
	s_and_b64 vcc, exec, s[14:15]
	s_cbranch_vccz .LBB0_708
	s_barrier

; #define PG8_STAGE(bufoff, gbase, voff) do { _Pragma("unroll") for (int _i = 0; _i < 2; ++_i) \
;         __builtin_amdgcn_global_load_lds((const unsigned*)((const char*)(gbase) + (voff)[_i]), (PG8_LAS unsigned*)(lds + (bufoff) + ldsw + _i * 8192), 16, 0, 0); } while (0)
; #define PG8_LDA(dst, b, h) do { _Pragma("unroll") for (int m = 0; m < 4; ++m) _Pragma("unroll") for (int k = 0; k < 2; ++k) dst[m][k] = *(const PG8_LAS bf16x8*)(lds + PG8_SA(b, h) + aoff + m * 2048 + k * 1024); } while (0)
; #define PG8_LDB(dst, b, h) do { _Pragma("unroll") for (int n = 0; n < 2; ++n) _Pragma("unroll") for (int k = 0; k < 2; ++k) dst[n][k] = *(const PG8_LAS bf16x8*)(lds + PG8_SB(b, h) + boff + n * 2048 + k * 1024); } while (0)
; #define PG8_WAIT_V(n) asm volatile("s_waitcnt vmcnt(" #n ")" ::: "memory")
; #define PG8_WAIT_L(n) asm volatile("s_waitcnt lgkmcnt(" #n ")" ::: "memory")
; #define PG8_BAR __builtin_amdgcn_s_barrier()
; #define PG8_SCHED __builtin_amdgcn_sched_barrier(0)
; template <class Epi, class Sched, bool ALIGN_EPI = false, bool SP2 = false>
; __device__ __forceinline__ void gemm_phase(PG8_LAS unsigned char* lds, const Gemm g, const Sched& S, const Epi& E) {
;     ...
;         const bool has_next = S.next(ui + 1, nxt);
;         const char* nA = has_next ? (const char*)g.A + (size_t)nxt.pm * tstep : cA; const char* nB = has_next ? (const char*)g.Bt + (size_t)nxt.pn * tstep : cB;
;         for (int t = 0; t < nt; t += 2) {
;             const bool last = (t == nt - 2);
;             const char* a1 = cA + (size_t)(t + 1) * kstep;
;             const char* a2 = last ? nA : cA + (size_t)(t + 2) * kstep; const char* b2 = last ? nB : cB + (size_t)(t + 2) * kstep;
;             const char* a3 = a2 + kstep; const char* b3 = b2 + kstep;
;             if (last && has_next) S.a_ready(nxt);
;             if constexpr (SP2) {
;             PG8_LDB(B0, 0, 0); PG8_LDB(B1, 0, 1); PG8_SCHED; PG8_LDA(At, 0, 0); PG8_STAGE(PG8_SA(1, 1), a1 + hstep, voffA);
;             PG8_WAIT_V(8); PG8_WAIT_L(0); PG8_BAR; PG8_MMA(0, 0, At, B0); PG8_MMA(0, 1, At, B1); PG8_BAR; PG8_SCHED;
;             PG8_LDA(At, 0, 1); PG8_STAGE(PG8_SB(0, 0), b2, voffB); PG8_STAGE(PG8_SB(0, 1), b2 + hstep, voffB); PG8_STAGE(PG8_SA(0, 0), a2, voffA);
;             PG8_WAIT_V(8); PG8_WAIT_L(0); PG8_BAR; PG8_MMA(1, 0, At, B0); PG8_MMA(1, 1, At, B1); PG8_BAR; PG8_SCHED;
.LBB0_809:
	s_ashr_i32 s15, s14, 31
	s_lshl_b64 s[16:17], s[14:15], 19
	s_add_u32 s16, s36, s16
	s_addc_u32 s17, s37, s17
	s_and_b64 s[18:19], s[4:5], exec
	s_cselect_b32 s15, s17, s21
	s_cselect_b32 s65, s16, s20
	s_ashr_i32 s13, s12, 31
	s_lshl_b64 s[18:19], s[12:13], 19
	s_add_u32 s18, s50, s18
	s_addc_u32 s19, s51, s19
	s_and_b64 s[44:45], s[4:5], exec
	s_cselect_b32 s13, s19, s39
	s_cselect_b32 s66, s18, s38
	s_add_u32 s20, s20, 0x40080
	s_addc_u32 s21, s21, 0
	s_add_u32 s67, s38, 0x100
	s_addc_u32 s68, s39, 0
	s_mov_b32 s69, -2
	ds_read_b128 v[154:157], v150
	ds_read_b128 v[158:161], v150 offset:1024
	ds_read_b128 v[162:165], v150 offset:2048
	ds_read_b128 v[166:169], v150 offset:3072
	ds_read_b128 v[170:173], v151
	ds_read_b128 v[174:177], v151 offset:1024
	ds_read_b128 v[178:181], v151 offset:2048
	ds_read_b128 v[182:185], v151 offset:3072
	s_add_u32 s38, s20, 0xfffc0080
	s_addc_u32 s39, s21, -1
	s_cmp_eq_u32 s69, 12
	s_cselect_b32 s45, s15, s39
	s_cselect_b32 s44, s65, s38
	s_cselect_b32 s39, s13, s68
	s_cselect_b32 s38, s66, s67
	s_add_i32 m0, s35, 0xc000
	ds_read_b128 v[186:189], v152
	ds_read_b128 v[190:193], v152 offset:1024
	ds_read_b128 v[198:201], v152 offset:2048
	ds_read_b128 v[202:205], v152 offset:3072
	ds_read_b128 v[206:209], v152 offset:4096
	ds_read_b128 v[210:213], v152 offset:5120
	ds_read_b128 v[214:217], v152 offset:6144
	ds_read_b128 v[218:221], v152 offset:7168
	global_load_lds_dwordx4 v136, s[20:21]
	s_add_i32 m0, s35, 0xe000
	s_nop 0
	global_load_lds_dwordx4 v138, s[20:21]
	s_nop 0
	s_waitcnt vmcnt(8)
	s_waitcnt lgkmcnt(0)
	s_barrier
	v_mfma_f32_16x16x32_bf16 v[124:127], v[154:157], v[186:189], 0
	v_mfma_f32_16x16x32_bf16 v[116:119], v[162:165], v[186:189], 0
	v_mfma_f32_16x16x32_bf16 v[108:111], v[154:157], v[198:201], 0
	v_mfma_f32_16x16x32_bf16 v[100:103], v[162:165], v[198:201], 0
	v_mfma_f32_16x16x32_bf16 v[92:95], v[154:157], v[206:209], 0
	v_mfma_f32_16x16x32_bf16 v[84:87], v[162:165], v[206:209], 0
	v_mfma_f32_16x16x32_bf16 v[76:79], v[154:157], v[214:217], 0
	v_mfma_f32_16x16x32_bf16 v[68:71], v[162:165], v[214:217], 0
	v_mfma_f32_16x16x32_bf16 v[124:127], v[158:161], v[190:193], v[124:127]
	v_mfma_f32_16x16x32_bf16 v[116:119], v[166:169], v[190:193], v[116:119]
	v_mfma_f32_16x16x32_bf16 v[108:111], v[158:161], v[202:205], v[108:111]
	v_mfma_f32_16x16x32_bf16 v[100:103], v[166:169], v[202:205], v[100:103]
	v_mfma_f32_16x16x32_bf16 v[92:95], v[158:161], v[210:213], v[92:95]
	v_mfma_f32_16x16x32_bf16 v[84:87], v[166:169], v[210:213], v[84:87]
	v_mfma_f32_16x16x32_bf16 v[76:79], v[158:161], v[218:221], v[76:79]
	v_mfma_f32_16x16x32_bf16 v[68:71], v[166:169], v[218:221], v[68:71]
	v_mfma_f32_16x16x32_bf16 v[120:123], v[170:173], v[186:189], 0
	v_mfma_f32_16x16x32_bf16 v[112:115], v[178:181], v[186:189], 0
	v_mfma_f32_16x16x32_bf16 v[104:107], v[170:173], v[198:201], 0
	v_mfma_f32_16x16x32_bf16 v[96:99], v[178:181], v[198:201], 0
	v_mfma_f32_16x16x32_bf16 v[88:91], v[170:173], v[206:209], 0
	v_mfma_f32_16x16x32_bf16 v[80:83], v[178:181], v[206:209], 0
	v_mfma_f32_16x16x32_bf16 v[72:75], v[170:173], v[214:217], 0
	v_mfma_f32_16x16x32_bf16 v[64:67], v[178:181], v[214:217], 0
	v_mfma_f32_16x16x32_bf16 v[120:123], v[174:177], v[190:193], v[120:123]
	v_mfma_f32_16x16x32_bf16 v[112:115], v[182:185], v[190:193], v[112:115]
	v_mfma_f32_16x16x32_bf16 v[104:107], v[174:177], v[202:205], v[104:107]
	v_mfma_f32_16x16x32_bf16 v[96:99], v[182:185], v[202:205], v[96:99]
	v_mfma_f32_16x16x32_bf16 v[88:91], v[174:177], v[210:213], v[88:91]
	v_mfma_f32_16x16x32_bf16 v[80:83], v[182:185], v[210:213], v[80:83]
	v_mfma_f32_16x16x32_bf16 v[72:75], v[174:177], v[218:221], v[72:75]
	v_mfma_f32_16x16x32_bf16 v[64:67], v[182:185], v[218:221], v[64:67]
	s_barrier
	s_add_i32 s70, s60, s52
	s_add_u32 s98, s38, s8
	s_addc_u32 s99, s39, s9
	s_add_u32 s100, s44, s8
	s_addc_u32 s101, s45, s9
	s_mov_b32 m0, s70
	ds_read_b128 v[186:189], v152 offset:16384
	ds_read_b128 v[190:193], v152 offset:17408
	ds_read_b128 v[198:201], v152 offset:18432
	ds_read_b128 v[202:205], v152 offset:19456
	ds_read_b128 v[206:209], v152 offset:20480
	ds_read_b128 v[210:213], v152 offset:21504
	ds_read_b128 v[214:217], v152 offset:22528
	ds_read_b128 v[218:221], v152 offset:23552
	global_load_lds_dwordx4 v132, s[38:39]
	s_add_i32 m0, s70, 0x2000
	s_add_u32 s70, s38, 0x40000
	s_addc_u32 s71, s39, 0
	s_add_i32 s72, s61, s52
	global_load_lds_dwordx4 v128, s[38:39]
	s_mov_b32 m0, s72
	s_nop 0
	global_load_lds_dwordx4 v132, s[70:71]
	s_add_i32 m0, s72, 0x2000
	s_nop 0
	global_load_lds_dwordx4 v128, s[70:71]
	s_mov_b32 m0, s35
	s_nop 0
	global_load_lds_dwordx4 v134, s[44:45]
	s_mov_b32 m0, s54
	s_nop 0
	global_load_lds_dwordx4 v130, s[44:45]
	s_nop 0
	s_waitcnt vmcnt(8)
	s_waitcnt lgkmcnt(0)
	s_barrier
; #define PG8_STAGE(bufoff, gbase, voff) do { _Pragma("unroll") for (int _i = 0; _i < 2; ++_i) \
;         __builtin_amdgcn_global_load_lds((const unsigned*)((const char*)(gbase) + (voff)[_i]), (PG8_LAS unsigned*)(lds + (bufoff) + ldsw + _i * 8192), 16, 0, 0); } while (0)
; #define PG8_LDA(dst, b, h) do { _Pragma("unroll") for (int m = 0; m < 4; ++m) _Pragma("unroll") for (int k = 0; k < 2; ++k) dst[m][k] = *(const PG8_LAS bf16x8*)(lds + PG8_SA(b, h) + aoff + m * 2048 + k * 1024); } while (0)
; #define PG8_LDB(dst, b, h) do { _Pragma("unroll") for (int n = 0; n < 2; ++n) _Pragma("unroll") for (int k = 0; k < 2; ++k) dst[n][k] = *(const PG8_LAS bf16x8*)(lds + PG8_SB(b, h) + boff + n * 2048 + k * 1024); } while (0)
; #define PG8_MMA(ai, bj, At, Bt) do { __builtin_amdgcn_s_setprio(1); _Pragma("unroll") for (int m = 0; m < 4; ++m) _Pragma("unroll") for (int n = 0; n < 2; ++n) _Pragma("unroll") for (int k = 0; k < 2; ++k) \
;         acc[ai][bj][m][n] = __builtin_amdgcn_mfma_f32_16x16x32_bf16(Bt[n][k], At[m][k], acc[ai][bj][m][n], 0, 0, 0); __builtin_amdgcn_s_setprio(0); } while (0)
; #define PG8_WAIT_V(n) asm volatile("s_waitcnt vmcnt(" #n ")" ::: "memory")
; #define PG8_WAIT_L(n) asm volatile("s_waitcnt lgkmcnt(" #n ")" ::: "memory")
; #define PG8_BAR __builtin_amdgcn_s_barrier()
; #define PG8_SCHED __builtin_amdgcn_sched_barrier(0)
; template <class Epi, class Sched, bool ALIGN_EPI = false, bool SP2 = false>
; __device__ __forceinline__ void gemm_phase(PG8_LAS unsigned char* lds, const Gemm g, const Sched& S, const Epi& E) {
;     ...
;             PG8_WAIT_V(8); PG8_WAIT_L(0); PG8_BAR; PG8_MMA(1, 0, At, B0); PG8_MMA(1, 1, At, B1); PG8_BAR; PG8_SCHED;
;             PG8_LDB(B0, 1, 0); PG8_LDB(B1, 1, 1); PG8_SCHED; PG8_LDA(At, 1, 0); PG8_STAGE(PG8_SA(0, 1), a2 + hstep, voffA);
;             PG8_WAIT_V(8); PG8_WAIT_L(0); PG8_BAR; PG8_MMA(0, 0, At, B0); PG8_MMA(0, 1, At, B1); PG8_BAR; PG8_SCHED;
	v_mfma_f32_16x16x32_bf16 v[60:63], v[154:157], v[186:189], 0
	v_mfma_f32_16x16x32_bf16 v[52:55], v[162:165], v[186:189], 0
	v_mfma_f32_16x16x32_bf16 v[44:47], v[154:157], v[198:201], 0
	v_mfma_f32_16x16x32_bf16 v[36:39], v[162:165], v[198:201], 0
	v_mfma_f32_16x16x32_bf16 v[28:31], v[154:157], v[206:209], 0
	v_mfma_f32_16x16x32_bf16 v[20:23], v[162:165], v[206:209], 0
	v_mfma_f32_16x16x32_bf16 v[12:15], v[154:157], v[214:217], 0
	v_mfma_f32_16x16x32_bf16 v[4:7], v[162:165], v[214:217], 0
	v_mfma_f32_16x16x32_bf16 v[60:63], v[158:161], v[190:193], v[60:63]
	v_mfma_f32_16x16x32_bf16 v[52:55], v[166:169], v[190:193], v[52:55]
	v_mfma_f32_16x16x32_bf16 v[44:47], v[158:161], v[202:205], v[44:47]
	v_mfma_f32_16x16x32_bf16 v[36:39], v[166:169], v[202:205], v[36:39]
	v_mfma_f32_16x16x32_bf16 v[28:31], v[158:161], v[210:213], v[28:31]
	v_mfma_f32_16x16x32_bf16 v[20:23], v[166:169], v[210:213], v[20:23]
	v_mfma_f32_16x16x32_bf16 v[12:15], v[158:161], v[218:221], v[12:15]
	v_mfma_f32_16x16x32_bf16 v[4:7], v[166:169], v[218:221], v[4:7]
	v_mfma_f32_16x16x32_bf16 v[56:59], v[170:173], v[186:189], 0
	v_mfma_f32_16x16x32_bf16 v[48:51], v[178:181], v[186:189], 0
	v_mfma_f32_16x16x32_bf16 v[40:43], v[170:173], v[198:201], 0
	v_mfma_f32_16x16x32_bf16 v[32:35], v[178:181], v[198:201], 0
	v_mfma_f32_16x16x32_bf16 v[24:27], v[170:173], v[206:209], 0
	v_mfma_f32_16x16x32_bf16 v[16:19], v[178:181], v[206:209], 0
	v_mfma_f32_16x16x32_bf16 v[8:11], v[170:173], v[214:217], 0
	v_mfma_f32_16x16x32_bf16 v[0:3], v[178:181], v[214:217], 0
	v_mfma_f32_16x16x32_bf16 v[56:59], v[174:177], v[190:193], v[56:59]
	v_mfma_f32_16x16x32_bf16 v[48:51], v[182:185], v[190:193], v[48:51]
	v_mfma_f32_16x16x32_bf16 v[40:43], v[174:177], v[202:205], v[40:43]
	v_mfma_f32_16x16x32_bf16 v[32:35], v[182:185], v[202:205], v[32:35]
	v_mfma_f32_16x16x32_bf16 v[24:27], v[174:177], v[210:213], v[24:27]
	v_mfma_f32_16x16x32_bf16 v[16:19], v[182:185], v[210:213], v[16:19]
	v_mfma_f32_16x16x32_bf16 v[8:11], v[174:177], v[218:221], v[8:11]
	v_mfma_f32_16x16x32_bf16 v[0:3], v[182:185], v[218:221], v[0:3]
	s_barrier
	s_add_i32 s70, 0, 0x18000
	v_add_u32_e32 v153, s70, v147
	s_add_i32 s71, 0, 0x1c000
	ds_read_b128 v[154:157], v153
	ds_read_b128 v[158:161], v153 offset:1024
	ds_read_b128 v[162:165], v153 offset:2048
	ds_read_b128 v[166:169], v153 offset:3072
	v_add_u32_e32 v153, s71, v147
	ds_read_b128 v[170:173], v153
	ds_read_b128 v[174:177], v153 offset:1024
	ds_read_b128 v[178:181], v153 offset:2048
	ds_read_b128 v[182:185], v153 offset:3072
	s_add_u32 s44, s44, 0x40000
	s_addc_u32 s45, s45, 0
	s_mov_b32 m0, s55
	ds_read_b128 v[186:189], v152 offset:32768
	ds_read_b128 v[190:193], v152 offset:33792
	ds_read_b128 v[198:201], v152 offset:34816
	ds_read_b128 v[202:205], v152 offset:35840
	ds_read_b128 v[206:209], v152 offset:36864
	ds_read_b128 v[210:213], v152 offset:37888
	ds_read_b128 v[214:217], v152 offset:38912
	ds_read_b128 v[218:221], v152 offset:39936
	global_load_lds_dwordx4 v134, s[44:45]
	s_mov_b32 m0, s56
	s_nop 0
	global_load_lds_dwordx4 v130, s[44:45]
	s_waitcnt vmcnt(8)
	s_waitcnt lgkmcnt(0)
	s_barrier
	v_mfma_f32_16x16x32_bf16 v[124:127], v[154:157], v[186:189], v[124:127]
	v_mfma_f32_16x16x32_bf16 v[116:119], v[162:165], v[186:189], v[116:119]
	v_mfma_f32_16x16x32_bf16 v[108:111], v[154:157], v[198:201], v[108:111]
	v_mfma_f32_16x16x32_bf16 v[100:103], v[162:165], v[198:201], v[100:103]
	v_mfma_f32_16x16x32_bf16 v[92:95], v[154:157], v[206:209], v[92:95]
	v_mfma_f32_16x16x32_bf16 v[84:87], v[162:165], v[206:209], v[84:87]
	v_mfma_f32_16x16x32_bf16 v[76:79], v[154:157], v[214:217], v[76:79]
	v_mfma_f32_16x16x32_bf16 v[68:71], v[162:165], v[214:217], v[68:71]
	v_mfma_f32_16x16x32_bf16 v[124:127], v[158:161], v[190:193], v[124:127]
	v_mfma_f32_16x16x32_bf16 v[116:119], v[166:169], v[190:193], v[116:119]
	v_mfma_f32_16x16x32_bf16 v[108:111], v[158:161], v[202:205], v[108:111]
	v_mfma_f32_16x16x32_bf16 v[100:103], v[166:169], v[202:205], v[100:103]
	v_mfma_f32_16x16x32_bf16 v[92:95], v[158:161], v[210:213], v[92:95]
	v_mfma_f32_16x16x32_bf16 v[84:87], v[166:169], v[210:213], v[84:87]
	v_mfma_f32_16x16x32_bf16 v[76:79], v[158:161], v[218:221], v[76:79]
	v_mfma_f32_16x16x32_bf16 v[68:71], v[166:169], v[218:221], v[68:71]
	v_mfma_f32_16x16x32_bf16 v[120:123], v[170:173], v[186:189], v[120:123]
	v_mfma_f32_16x16x32_bf16 v[112:115], v[178:181], v[186:189], v[112:115]
	v_mfma_f32_16x16x32_bf16 v[104:107], v[170:173], v[198:201], v[104:107]
	v_mfma_f32_16x16x32_bf16 v[96:99], v[178:181], v[198:201], v[96:99]
	v_mfma_f32_16x16x32_bf16 v[88:91], v[170:173], v[206:209], v[88:91]
	v_mfma_f32_16x16x32_bf16 v[80:83], v[178:181], v[206:209], v[80:83]
	v_mfma_f32_16x16x32_bf16 v[72:75], v[170:173], v[214:217], v[72:75]
	v_mfma_f32_16x16x32_bf16 v[64:67], v[178:181], v[214:217], v[64:67]
	v_mfma_f32_16x16x32_bf16 v[120:123], v[174:177], v[190:193], v[120:123]
	v_mfma_f32_16x16x32_bf16 v[112:115], v[182:185], v[190:193], v[112:115]
	v_mfma_f32_16x16x32_bf16 v[104:107], v[174:177], v[202:205], v[104:107]
	v_mfma_f32_16x16x32_bf16 v[96:99], v[182:185], v[202:205], v[96:99]
	v_mfma_f32_16x16x32_bf16 v[88:91], v[174:177], v[210:213], v[88:91]
	v_mfma_f32_16x16x32_bf16 v[80:83], v[182:185], v[210:213], v[80:83]
	v_mfma_f32_16x16x32_bf16 v[72:75], v[174:177], v[218:221], v[72:75]
	v_mfma_f32_16x16x32_bf16 v[64:67], v[182:185], v[218:221], v[64:67]
	s_barrier
; #define PG8_STAGE(bufoff, gbase, voff) do { _Pragma("unroll") for (int _i = 0; _i < 2; ++_i) \
;         __builtin_amdgcn_global_load_lds((const unsigned*)((const char*)(gbase) + (voff)[_i]), (PG8_LAS unsigned*)(lds + (bufoff) + ldsw + _i * 8192), 16, 0, 0); } while (0)
; #define PG8_LDA(dst, b, h) do { _Pragma("unroll") for (int m = 0; m < 4; ++m) _Pragma("unroll") for (int k = 0; k < 2; ++k) dst[m][k] = *(const PG8_LAS bf16x8*)(lds + PG8_SA(b, h) + aoff + m * 2048 + k * 1024); } while (0)
; #define PG8_LDB(dst, b, h) do { _Pragma("unroll") for (int n = 0; n < 2; ++n) _Pragma("unroll") for (int k = 0; k < 2; ++k) dst[n][k] = *(const PG8_LAS bf16x8*)(lds + PG8_SB(b, h) + boff + n * 2048 + k * 1024); } while (0)
; #define PG8_MMA(ai, bj, At, Bt) do { __builtin_amdgcn_s_setprio(1); _Pragma("unroll") for (int m = 0; m < 4; ++m) _Pragma("unroll") for (int n = 0; n < 2; ++n) _Pragma("unroll") for (int k = 0; k < 2; ++k) \
;         acc[ai][bj][m][n] = __builtin_amdgcn_mfma_f32_16x16x32_bf16(Bt[n][k], At[m][k], acc[ai][bj][m][n], 0, 0, 0); __builtin_amdgcn_s_setprio(0); } while (0)
; #define PG8_WAIT_V(n) asm volatile("s_waitcnt vmcnt(" #n ")" ::: "memory")
; template <class Epi, class Sched, bool ALIGN_EPI = false, bool SP2 = false>
; __device__ __forceinline__ void gemm_phase(PG8_LAS unsigned char* lds, const Gemm g, const Sched& S, const Epi& E) {
;     ...
;             PG8_LDB(B0, 0, 0); PG8_LDB(B1, 0, 1); PG8_SCHED; PG8_LDA(At, 0, 0); PG8_STAGE(PG8_SA(1, 1), a1 + hstep, voffA);
;             PG8_WAIT_V(8); PG8_WAIT_L(0); PG8_BAR; PG8_MMA(0, 0, At, B0); PG8_MMA(0, 1, At, B1); PG8_BAR; PG8_SCHED;
;             PG8_LDA(At, 0, 1); PG8_STAGE(PG8_SB(0, 0), b2, voffB); PG8_STAGE(PG8_SB(0, 1), b2 + hstep, voffB); PG8_STAGE(PG8_SA(0, 0), a2, voffA);
;             PG8_WAIT_V(8); PG8_WAIT_L(0); PG8_BAR; PG8_MMA(1, 0, At, B0); PG8_MMA(1, 1, At, B1); PG8_BAR; PG8_SCHED;
;             PG8_LDB(B0, 1, 0); PG8_LDB(B1, 1, 1); PG8_SCHED; PG8_LDA(At, 1, 0); PG8_STAGE(PG8_SA(0, 1), a2 + hstep, voffA);
;             PG8_WAIT_V(8); PG8_WAIT_L(0); PG8_BAR; PG8_MMA(0, 0, At, B0); PG8_MMA(0, 1, At, B1); PG8_BAR; PG8_SCHED;
;             PG8_LDA(At, 1, 1); PG8_STAGE(PG8_SB(1, 0), b3, voffB); PG8_STAGE(PG8_SB(1, 1), b3 + hstep, voffB); PG8_STAGE(PG8_SA(1, 0), a3, voffA);
;             PG8_WAIT_V(8); PG8_WAIT_L(0); PG8_BAR; PG8_MMA(1, 0, At, B0); PG8_MMA(1, 1, At, B1); PG8_BAR; PG8_SCHED;
	s_add_i32 s44, s70, s52
	s_mov_b32 m0, s44
	ds_read_b128 v[186:189], v152 offset:49152
	ds_read_b128 v[190:193], v152 offset:50176
	ds_read_b128 v[198:201], v152 offset:51200
	ds_read_b128 v[202:205], v152 offset:52224
	ds_read_b128 v[206:209], v152 offset:53248
	ds_read_b128 v[210:213], v152 offset:54272
	ds_read_b128 v[214:217], v152 offset:55296
	ds_read_b128 v[218:221], v152 offset:56320
	global_load_lds_dwordx4 v132, s[98:99]
	s_add_i32 m0, s44, 0x2000
	s_add_u32 s38, s38, 0x40080
	s_addc_u32 s39, s39, 0
	s_add_i32 s44, s71, s52
	global_load_lds_dwordx4 v128, s[98:99]
	s_mov_b32 m0, s44
	s_nop 0
	global_load_lds_dwordx4 v132, s[38:39]
	s_add_i32 m0, s44, 0x2000
	s_nop 0
	global_load_lds_dwordx4 v128, s[38:39]
	s_mov_b32 m0, s58
	s_nop 0
	global_load_lds_dwordx4 v134, s[100:101]
	s_mov_b32 m0, s59
	s_nop 0
	global_load_lds_dwordx4 v130, s[100:101]
	s_nop 0
	s_waitcnt vmcnt(8)
	s_waitcnt lgkmcnt(0)
	s_barrier
	v_mfma_f32_16x16x32_bf16 v[60:63], v[154:157], v[186:189], v[60:63]
	v_mfma_f32_16x16x32_bf16 v[52:55], v[162:165], v[186:189], v[52:55]
	v_mfma_f32_16x16x32_bf16 v[44:47], v[154:157], v[198:201], v[44:47]
	v_mfma_f32_16x16x32_bf16 v[36:39], v[162:165], v[198:201], v[36:39]
	v_mfma_f32_16x16x32_bf16 v[28:31], v[154:157], v[206:209], v[28:31]
	v_mfma_f32_16x16x32_bf16 v[20:23], v[162:165], v[206:209], v[20:23]
	v_mfma_f32_16x16x32_bf16 v[12:15], v[154:157], v[214:217], v[12:15]
	v_mfma_f32_16x16x32_bf16 v[4:7], v[162:165], v[214:217], v[4:7]
	v_mfma_f32_16x16x32_bf16 v[60:63], v[158:161], v[190:193], v[60:63]
	v_mfma_f32_16x16x32_bf16 v[52:55], v[166:169], v[190:193], v[52:55]
	v_mfma_f32_16x16x32_bf16 v[44:47], v[158:161], v[202:205], v[44:47]
	v_mfma_f32_16x16x32_bf16 v[36:39], v[166:169], v[202:205], v[36:39]
	v_mfma_f32_16x16x32_bf16 v[28:31], v[158:161], v[210:213], v[28:31]
	v_mfma_f32_16x16x32_bf16 v[20:23], v[166:169], v[210:213], v[20:23]
	v_mfma_f32_16x16x32_bf16 v[12:15], v[158:161], v[218:221], v[12:15]
	v_mfma_f32_16x16x32_bf16 v[4:7], v[166:169], v[218:221], v[4:7]
	v_mfma_f32_16x16x32_bf16 v[56:59], v[170:173], v[186:189], v[56:59]
	v_mfma_f32_16x16x32_bf16 v[48:51], v[178:181], v[186:189], v[48:51]
	v_mfma_f32_16x16x32_bf16 v[40:43], v[170:173], v[198:201], v[40:43]
	v_mfma_f32_16x16x32_bf16 v[32:35], v[178:181], v[198:201], v[32:35]
	v_mfma_f32_16x16x32_bf16 v[24:27], v[170:173], v[206:209], v[24:27]
	v_mfma_f32_16x16x32_bf16 v[16:19], v[178:181], v[206:209], v[16:19]
	v_mfma_f32_16x16x32_bf16 v[8:11], v[170:173], v[214:217], v[8:11]
	v_mfma_f32_16x16x32_bf16 v[0:3], v[178:181], v[214:217], v[0:3]
	v_mfma_f32_16x16x32_bf16 v[56:59], v[174:177], v[190:193], v[56:59]
	v_mfma_f32_16x16x32_bf16 v[48:51], v[182:185], v[190:193], v[48:51]
	v_mfma_f32_16x16x32_bf16 v[40:43], v[174:177], v[202:205], v[40:43]
	v_mfma_f32_16x16x32_bf16 v[32:35], v[182:185], v[202:205], v[32:35]
	v_mfma_f32_16x16x32_bf16 v[24:27], v[174:177], v[210:213], v[24:27]
	v_mfma_f32_16x16x32_bf16 v[16:19], v[182:185], v[210:213], v[16:19]
	v_mfma_f32_16x16x32_bf16 v[8:11], v[174:177], v[218:221], v[8:11]
	v_mfma_f32_16x16x32_bf16 v[0:3], v[182:185], v[218:221], v[0:3]
	s_barrier
	s_add_i32 s69, s69, 2
	s_add_u32 s20, s20, 0x100
	s_addc_u32 s21, s21, 0
	s_add_u32 s67, s67, 0x100
	s_addc_u32 s68, s68, 0
	s_cmp_gt_u32 s69, 13
.LBB0_810:
	ds_read_b128 v[154:157], v150
	ds_read_b128 v[158:161], v150 offset:1024
	ds_read_b128 v[162:165], v150 offset:2048
	ds_read_b128 v[166:169], v150 offset:3072
	ds_read_b128 v[170:173], v151
	ds_read_b128 v[174:177], v151 offset:1024
	ds_read_b128 v[178:181], v151 offset:2048
	ds_read_b128 v[182:185], v151 offset:3072
	s_add_u32 s38, s20, 0xfffc0080
	s_addc_u32 s39, s21, -1
	s_cmp_eq_u32 s69, 12
	s_cselect_b32 s45, s15, s39
	s_cselect_b32 s44, s65, s38
	s_cselect_b32 s39, s13, s68
	s_cselect_b32 s38, s66, s67
	s_add_i32 m0, s35, 0xc000
	ds_read_b128 v[186:189], v152
	ds_read_b128 v[190:193], v152 offset:1024
	ds_read_b128 v[198:201], v152 offset:2048
	ds_read_b128 v[202:205], v152 offset:3072
	ds_read_b128 v[206:209], v152 offset:4096
	ds_read_b128 v[210:213], v152 offset:5120
	ds_read_b128 v[214:217], v152 offset:6144
	ds_read_b128 v[218:221], v152 offset:7168
	global_load_lds_dwordx4 v136, s[20:21]
	s_add_i32 m0, s35, 0xe000
	s_nop 0
	global_load_lds_dwordx4 v138, s[20:21]
	s_nop 0
	s_waitcnt vmcnt(8)
	s_waitcnt lgkmcnt(0)
	s_barrier
	v_mfma_f32_16x16x32_bf16 v[124:127], v[154:157], v[186:189], v[124:127]
	v_mfma_f32_16x16x32_bf16 v[116:119], v[162:165], v[186:189], v[116:119]
	v_mfma_f32_16x16x32_bf16 v[108:111], v[154:157], v[198:201], v[108:111]
	v_mfma_f32_16x16x32_bf16 v[100:103], v[162:165], v[198:201], v[100:103]
	v_mfma_f32_16x16x32_bf16 v[92:95], v[154:157], v[206:209], v[92:95]
	v_mfma_f32_16x16x32_bf16 v[84:87], v[162:165], v[206:209], v[84:87]
	v_mfma_f32_16x16x32_bf16 v[76:79], v[154:157], v[214:217], v[76:79]
	v_mfma_f32_16x16x32_bf16 v[68:71], v[162:165], v[214:217], v[68:71]
	v_mfma_f32_16x16x32_bf16 v[124:127], v[158:161], v[190:193], v[124:127]
	v_mfma_f32_16x16x32_bf16 v[116:119], v[166:169], v[190:193], v[116:119]
	v_mfma_f32_16x16x32_bf16 v[108:111], v[158:161], v[202:205], v[108:111]
	v_mfma_f32_16x16x32_bf16 v[100:103], v[166:169], v[202:205], v[100:103]
	v_mfma_f32_16x16x32_bf16 v[92:95], v[158:161], v[210:213], v[92:95]
	v_mfma_f32_16x16x32_bf16 v[84:87], v[166:169], v[210:213], v[84:87]
	v_mfma_f32_16x16x32_bf16 v[76:79], v[158:161], v[218:221], v[76:79]
	v_mfma_f32_16x16x32_bf16 v[68:71], v[166:169], v[218:221], v[68:71]
	v_mfma_f32_16x16x32_bf16 v[120:123], v[170:173], v[186:189], v[120:123]
	v_mfma_f32_16x16x32_bf16 v[112:115], v[178:181], v[186:189], v[112:115]
	v_mfma_f32_16x16x32_bf16 v[104:107], v[170:173], v[198:201], v[104:107]
	v_mfma_f32_16x16x32_bf16 v[96:99], v[178:181], v[198:201], v[96:99]
	v_mfma_f32_16x16x32_bf16 v[88:91], v[170:173], v[206:209], v[88:91]
	v_mfma_f32_16x16x32_bf16 v[80:83], v[178:181], v[206:209], v[80:83]
	v_mfma_f32_16x16x32_bf16 v[72:75], v[170:173], v[214:217], v[72:75]
	v_mfma_f32_16x16x32_bf16 v[64:67], v[178:181], v[214:217], v[64:67]
	v_mfma_f32_16x16x32_bf16 v[120:123], v[174:177], v[190:193], v[120:123]
	v_mfma_f32_16x16x32_bf16 v[112:115], v[182:185], v[190:193], v[112:115]
	v_mfma_f32_16x16x32_bf16 v[104:107], v[174:177], v[202:205], v[104:107]
	v_mfma_f32_16x16x32_bf16 v[96:99], v[182:185], v[202:205], v[96:99]
	v_mfma_f32_16x16x32_bf16 v[88:91], v[174:177], v[210:213], v[88:91]
	v_mfma_f32_16x16x32_bf16 v[80:83], v[182:185], v[210:213], v[80:83]
	v_mfma_f32_16x16x32_bf16 v[72:75], v[174:177], v[218:221], v[72:75]
	v_mfma_f32_16x16x32_bf16 v[64:67], v[182:185], v[218:221], v[64:67]
	s_barrier
; #define PG8_STAGE(bufoff, gbase, voff) do { _Pragma("unroll") for (int _i = 0; _i < 2; ++_i) \
;         __builtin_amdgcn_global_load_lds((const unsigned*)((const char*)(gbase) + (voff)[_i]), (PG8_LAS unsigned*)(lds + (bufoff) + ldsw + _i * 8192), 16, 0, 0); } while (0)
; #define PG8_LDA(dst, b, h) do { _Pragma("unroll") for (int m = 0; m < 4; ++m) _Pragma("unroll") for (int k = 0; k < 2; ++k) dst[m][k] = *(const PG8_LAS bf16x8*)(lds + PG8_SA(b, h) + aoff + m * 2048 + k * 1024); } while (0)
; #define PG8_LDB(dst, b, h) do { _Pragma("unroll") for (int n = 0; n < 2; ++n) _Pragma("unroll") for (int k = 0; k < 2; ++k) dst[n][k] = *(const PG8_LAS bf16x8*)(lds + PG8_SB(b, h) + boff + n * 2048 + k * 1024); } while (0)
; #define PG8_MMA(ai, bj, At, Bt) do { __builtin_amdgcn_s_setprio(1); _Pragma("unroll") for (int m = 0; m < 4; ++m) _Pragma("unroll") for (int n = 0; n < 2; ++n) _Pragma("unroll") for (int k = 0; k < 2; ++k) \
;         acc[ai][bj][m][n] = __builtin_amdgcn_mfma_f32_16x16x32_bf16(Bt[n][k], At[m][k], acc[ai][bj][m][n], 0, 0, 0); __builtin_amdgcn_s_setprio(0); } while (0)
; #define PG8_WAIT_V(n) asm volatile("s_waitcnt vmcnt(" #n ")" ::: "memory")
; #define PG8_WAIT_L(n) asm volatile("s_waitcnt lgkmcnt(" #n ")" ::: "memory")
; #define PG8_BAR __builtin_amdgcn_s_barrier()
; #define PG8_SCHED __builtin_amdgcn_sched_barrier(0)
; template <class Epi, class Sched, bool ALIGN_EPI = false, bool SP2 = false>
; __device__ __forceinline__ void gemm_phase(PG8_LAS unsigned char* lds, const Gemm g, const Sched& S, const Epi& E) {
;     ...
;             PG8_LDA(At, 0, 1); PG8_STAGE(PG8_SB(0, 0), b2, voffB); PG8_STAGE(PG8_SB(0, 1), b2 + hstep, voffB); PG8_STAGE(PG8_SA(0, 0), a2, voffA);
;             PG8_WAIT_V(8); PG8_WAIT_L(0); PG8_BAR; PG8_MMA(1, 0, At, B0); PG8_MMA(1, 1, At, B1); PG8_BAR; PG8_SCHED;
;             PG8_LDB(B0, 1, 0); PG8_LDB(B1, 1, 1); PG8_SCHED; PG8_LDA(At, 1, 0); PG8_STAGE(PG8_SA(0, 1), a2 + hstep, voffA);
;             PG8_WAIT_V(8); PG8_WAIT_L(0); PG8_BAR; PG8_MMA(0, 0, At, B0); PG8_MMA(0, 1, At, B1); PG8_BAR; PG8_SCHED;
	s_add_i32 s70, s60, s52
	s_add_u32 s98, s38, s8
	s_addc_u32 s99, s39, s9
	s_add_u32 s100, s44, s8
	s_addc_u32 s101, s45, s9
	s_mov_b32 m0, s70
	ds_read_b128 v[186:189], v152 offset:16384
	ds_read_b128 v[190:193], v152 offset:17408
	ds_read_b128 v[198:201], v152 offset:18432
	ds_read_b128 v[202:205], v152 offset:19456
	ds_read_b128 v[206:209], v152 offset:20480
	ds_read_b128 v[210:213], v152 offset:21504
	ds_read_b128 v[214:217], v152 offset:22528
	ds_read_b128 v[218:221], v152 offset:23552
	global_load_lds_dwordx4 v132, s[38:39]
	s_add_i32 m0, s70, 0x2000
	s_add_u32 s70, s38, 0x40000
	s_addc_u32 s71, s39, 0
	s_add_i32 s72, s61, s52
	global_load_lds_dwordx4 v128, s[38:39]
	s_mov_b32 m0, s72
	s_nop 0
	global_load_lds_dwordx4 v132, s[70:71]
	s_add_i32 m0, s72, 0x2000
	s_nop 0
	global_load_lds_dwordx4 v128, s[70:71]
	s_mov_b32 m0, s35
	s_nop 0
	global_load_lds_dwordx4 v134, s[44:45]
	s_mov_b32 m0, s54
	s_nop 0
	global_load_lds_dwordx4 v130, s[44:45]
	s_nop 0
	s_waitcnt vmcnt(8)
	s_waitcnt lgkmcnt(0)
	s_barrier
	v_mfma_f32_16x16x32_bf16 v[60:63], v[154:157], v[186:189], v[60:63]
	v_mfma_f32_16x16x32_bf16 v[52:55], v[162:165], v[186:189], v[52:55]
	v_mfma_f32_16x16x32_bf16 v[44:47], v[154:157], v[198:201], v[44:47]
	v_mfma_f32_16x16x32_bf16 v[36:39], v[162:165], v[198:201], v[36:39]
	v_mfma_f32_16x16x32_bf16 v[28:31], v[154:157], v[206:209], v[28:31]
	v_mfma_f32_16x16x32_bf16 v[20:23], v[162:165], v[206:209], v[20:23]
	v_mfma_f32_16x16x32_bf16 v[12:15], v[154:157], v[214:217], v[12:15]
	v_mfma_f32_16x16x32_bf16 v[4:7], v[162:165], v[214:217], v[4:7]
	v_mfma_f32_16x16x32_bf16 v[60:63], v[158:161], v[190:193], v[60:63]
	v_mfma_f32_16x16x32_bf16 v[52:55], v[166:169], v[190:193], v[52:55]
	v_mfma_f32_16x16x32_bf16 v[44:47], v[158:161], v[202:205], v[44:47]
	v_mfma_f32_16x16x32_bf16 v[36:39], v[166:169], v[202:205], v[36:39]
	v_mfma_f32_16x16x32_bf16 v[28:31], v[158:161], v[210:213], v[28:31]
	v_mfma_f32_16x16x32_bf16 v[20:23], v[166:169], v[210:213], v[20:23]
	v_mfma_f32_16x16x32_bf16 v[12:15], v[158:161], v[218:221], v[12:15]
	v_mfma_f32_16x16x32_bf16 v[4:7], v[166:169], v[218:221], v[4:7]
	v_mfma_f32_16x16x32_bf16 v[56:59], v[170:173], v[186:189], v[56:59]
	v_mfma_f32_16x16x32_bf16 v[48:51], v[178:181], v[186:189], v[48:51]
	v_mfma_f32_16x16x32_bf16 v[40:43], v[170:173], v[198:201], v[40:43]
	v_mfma_f32_16x16x32_bf16 v[32:35], v[178:181], v[198:201], v[32:35]
	v_mfma_f32_16x16x32_bf16 v[24:27], v[170:173], v[206:209], v[24:27]
	v_mfma_f32_16x16x32_bf16 v[16:19], v[178:181], v[206:209], v[16:19]
	v_mfma_f32_16x16x32_bf16 v[8:11], v[170:173], v[214:217], v[8:11]
	v_mfma_f32_16x16x32_bf16 v[0:3], v[178:181], v[214:217], v[0:3]
	v_mfma_f32_16x16x32_bf16 v[56:59], v[174:177], v[190:193], v[56:59]
	v_mfma_f32_16x16x32_bf16 v[48:51], v[182:185], v[190:193], v[48:51]
	v_mfma_f32_16x16x32_bf16 v[40:43], v[174:177], v[202:205], v[40:43]
	v_mfma_f32_16x16x32_bf16 v[32:35], v[182:185], v[202:205], v[32:35]
	v_mfma_f32_16x16x32_bf16 v[24:27], v[174:177], v[210:213], v[24:27]
	v_mfma_f32_16x16x32_bf16 v[16:19], v[182:185], v[210:213], v[16:19]
	v_mfma_f32_16x16x32_bf16 v[8:11], v[174:177], v[218:221], v[8:11]
	v_mfma_f32_16x16x32_bf16 v[0:3], v[182:185], v[218:221], v[0:3]
	s_barrier
	s_add_i32 s70, 0, 0x18000
	v_add_u32_e32 v153, s70, v147
	s_add_i32 s71, 0, 0x1c000
	ds_read_b128 v[154:157], v153
	ds_read_b128 v[158:161], v153 offset:1024
	ds_read_b128 v[162:165], v153 offset:2048
	ds_read_b128 v[166:169], v153 offset:3072
	v_add_u32_e32 v153, s71, v147
	ds_read_b128 v[170:173], v153
	ds_read_b128 v[174:177], v153 offset:1024
	ds_read_b128 v[178:181], v153 offset:2048
	ds_read_b128 v[182:185], v153 offset:3072
	s_add_u32 s44, s44, 0x40000
	s_addc_u32 s45, s45, 0
	s_mov_b32 m0, s55
	ds_read_b128 v[186:189], v152 offset:32768
	ds_read_b128 v[190:193], v152 offset:33792
	ds_read_b128 v[198:201], v152 offset:34816
	ds_read_b128 v[202:205], v152 offset:35840
	ds_read_b128 v[206:209], v152 offset:36864
	ds_read_b128 v[210:213], v152 offset:37888
	ds_read_b128 v[214:217], v152 offset:38912
	ds_read_b128 v[218:221], v152 offset:39936
	global_load_lds_dwordx4 v134, s[44:45]
	s_mov_b32 m0, s56
	s_nop 0
	global_load_lds_dwordx4 v130, s[44:45]
	s_waitcnt vmcnt(8)
	s_waitcnt lgkmcnt(0)
	s_barrier
; #define PG8_STAGE(bufoff, gbase, voff) do { _Pragma("unroll") for (int _i = 0; _i < 2; ++_i) \
;         __builtin_amdgcn_global_load_lds((const unsigned*)((const char*)(gbase) + (voff)[_i]), (PG8_LAS unsigned*)(lds + (bufoff) + ldsw + _i * 8192), 16, 0, 0); } while (0)
; #define PG8_LDA(dst, b, h) do { _Pragma("unroll") for (int m = 0; m < 4; ++m) _Pragma("unroll") for (int k = 0; k < 2; ++k) dst[m][k] = *(const PG8_LAS bf16x8*)(lds + PG8_SA(b, h) + aoff + m * 2048 + k * 1024); } while (0)
; #define PG8_MMA(ai, bj, At, Bt) do { __builtin_amdgcn_s_setprio(1); _Pragma("unroll") for (int m = 0; m < 4; ++m) _Pragma("unroll") for (int n = 0; n < 2; ++n) _Pragma("unroll") for (int k = 0; k < 2; ++k) \
;         acc[ai][bj][m][n] = __builtin_amdgcn_mfma_f32_16x16x32_bf16(Bt[n][k], At[m][k], acc[ai][bj][m][n], 0, 0, 0); __builtin_amdgcn_s_setprio(0); } while (0)
; #define PG8_WAIT_V(n) asm volatile("s_waitcnt vmcnt(" #n ")" ::: "memory")
; #define PG8_WAIT_L(n) asm volatile("s_waitcnt lgkmcnt(" #n ")" ::: "memory")
; #define PG8_BAR __builtin_amdgcn_s_barrier()
; #define PG8_SCHED __builtin_amdgcn_sched_barrier(0)
; template <class Epi, class Sched, bool ALIGN_EPI = false, bool SP2 = false>
; __device__ __forceinline__ void gemm_phase(PG8_LAS unsigned char* lds, const Gemm g, const Sched& S, const Epi& E) {
;     ...
;             PG8_WAIT_V(8); PG8_WAIT_L(0); PG8_BAR; PG8_MMA(0, 0, At, B0); PG8_MMA(0, 1, At, B1); PG8_BAR; PG8_SCHED;
;             PG8_LDA(At, 1, 1); PG8_STAGE(PG8_SB(1, 0), b3, voffB); PG8_STAGE(PG8_SB(1, 1), b3 + hstep, voffB); PG8_STAGE(PG8_SA(1, 0), a3, voffA);
;             PG8_WAIT_V(8); PG8_WAIT_L(0); PG8_BAR; PG8_MMA(1, 0, At, B0); PG8_MMA(1, 1, At, B1); PG8_BAR; PG8_SCHED;
;     ...
;         if constexpr (ALIGN_EPI) { if (wr == 0) PG8_BAR; }
	v_mfma_f32_16x16x32_bf16 v[124:127], v[154:157], v[186:189], v[124:127]
	v_mfma_f32_16x16x32_bf16 v[116:119], v[162:165], v[186:189], v[116:119]
	v_mfma_f32_16x16x32_bf16 v[108:111], v[154:157], v[198:201], v[108:111]
	v_mfma_f32_16x16x32_bf16 v[100:103], v[162:165], v[198:201], v[100:103]
	v_mfma_f32_16x16x32_bf16 v[92:95], v[154:157], v[206:209], v[92:95]
	v_mfma_f32_16x16x32_bf16 v[84:87], v[162:165], v[206:209], v[84:87]
	v_mfma_f32_16x16x32_bf16 v[76:79], v[154:157], v[214:217], v[76:79]
	v_mfma_f32_16x16x32_bf16 v[68:71], v[162:165], v[214:217], v[68:71]
	v_mfma_f32_16x16x32_bf16 v[124:127], v[158:161], v[190:193], v[124:127]
	v_mfma_f32_16x16x32_bf16 v[116:119], v[166:169], v[190:193], v[116:119]
	v_mfma_f32_16x16x32_bf16 v[108:111], v[158:161], v[202:205], v[108:111]
	v_mfma_f32_16x16x32_bf16 v[100:103], v[166:169], v[202:205], v[100:103]
	v_mfma_f32_16x16x32_bf16 v[92:95], v[158:161], v[210:213], v[92:95]
	v_mfma_f32_16x16x32_bf16 v[84:87], v[166:169], v[210:213], v[84:87]
	v_mfma_f32_16x16x32_bf16 v[76:79], v[158:161], v[218:221], v[76:79]
	v_mfma_f32_16x16x32_bf16 v[68:71], v[166:169], v[218:221], v[68:71]
	v_mfma_f32_16x16x32_bf16 v[120:123], v[170:173], v[186:189], v[120:123]
	v_mfma_f32_16x16x32_bf16 v[112:115], v[178:181], v[186:189], v[112:115]
	v_mfma_f32_16x16x32_bf16 v[104:107], v[170:173], v[198:201], v[104:107]
	v_mfma_f32_16x16x32_bf16 v[96:99], v[178:181], v[198:201], v[96:99]
	v_mfma_f32_16x16x32_bf16 v[88:91], v[170:173], v[206:209], v[88:91]
	v_mfma_f32_16x16x32_bf16 v[80:83], v[178:181], v[206:209], v[80:83]
	v_mfma_f32_16x16x32_bf16 v[72:75], v[170:173], v[214:217], v[72:75]
	v_mfma_f32_16x16x32_bf16 v[64:67], v[178:181], v[214:217], v[64:67]
	v_mfma_f32_16x16x32_bf16 v[120:123], v[174:177], v[190:193], v[120:123]
	v_mfma_f32_16x16x32_bf16 v[112:115], v[182:185], v[190:193], v[112:115]
	v_mfma_f32_16x16x32_bf16 v[104:107], v[174:177], v[202:205], v[104:107]
	v_mfma_f32_16x16x32_bf16 v[96:99], v[182:185], v[202:205], v[96:99]
	v_mfma_f32_16x16x32_bf16 v[88:91], v[174:177], v[210:213], v[88:91]
	v_mfma_f32_16x16x32_bf16 v[80:83], v[182:185], v[210:213], v[80:83]
	v_mfma_f32_16x16x32_bf16 v[72:75], v[174:177], v[218:221], v[72:75]
	v_mfma_f32_16x16x32_bf16 v[64:67], v[182:185], v[218:221], v[64:67]
	s_barrier
	s_add_i32 s44, s70, s52
	s_mov_b32 m0, s44
	ds_read_b128 v[186:189], v152 offset:49152
	ds_read_b128 v[190:193], v152 offset:50176
	ds_read_b128 v[198:201], v152 offset:51200
	ds_read_b128 v[202:205], v152 offset:52224
	ds_read_b128 v[206:209], v152 offset:53248
	ds_read_b128 v[210:213], v152 offset:54272
	ds_read_b128 v[214:217], v152 offset:55296
	ds_read_b128 v[218:221], v152 offset:56320
	global_load_lds_dwordx4 v132, s[98:99]
	s_add_i32 m0, s44, 0x2000
	s_add_u32 s38, s38, 0x40080
	s_addc_u32 s39, s39, 0
	s_add_i32 s44, s71, s52
	global_load_lds_dwordx4 v128, s[98:99]
	s_mov_b32 m0, s44
	s_nop 0
	global_load_lds_dwordx4 v132, s[38:39]
	s_add_i32 m0, s44, 0x2000
	s_nop 0
	global_load_lds_dwordx4 v128, s[38:39]
	s_mov_b32 m0, s58
	s_nop 0
	global_load_lds_dwordx4 v134, s[100:101]
	s_mov_b32 m0, s59
	s_nop 0
	global_load_lds_dwordx4 v130, s[100:101]
	s_nop 0
	s_waitcnt vmcnt(8)
	s_waitcnt lgkmcnt(0)
	s_barrier
	v_mfma_f32_16x16x32_bf16 v[60:63], v[154:157], v[186:189], v[60:63]
	v_mfma_f32_16x16x32_bf16 v[52:55], v[162:165], v[186:189], v[52:55]
	v_mfma_f32_16x16x32_bf16 v[44:47], v[154:157], v[198:201], v[44:47]
	v_mfma_f32_16x16x32_bf16 v[36:39], v[162:165], v[198:201], v[36:39]
	v_mfma_f32_16x16x32_bf16 v[28:31], v[154:157], v[206:209], v[28:31]
	v_mfma_f32_16x16x32_bf16 v[20:23], v[162:165], v[206:209], v[20:23]
	v_mfma_f32_16x16x32_bf16 v[12:15], v[154:157], v[214:217], v[12:15]
	v_mfma_f32_16x16x32_bf16 v[4:7], v[162:165], v[214:217], v[4:7]
	v_mfma_f32_16x16x32_bf16 v[60:63], v[158:161], v[190:193], v[60:63]
	v_mfma_f32_16x16x32_bf16 v[52:55], v[166:169], v[190:193], v[52:55]
	v_mfma_f32_16x16x32_bf16 v[44:47], v[158:161], v[202:205], v[44:47]
	v_mfma_f32_16x16x32_bf16 v[36:39], v[166:169], v[202:205], v[36:39]
	v_mfma_f32_16x16x32_bf16 v[28:31], v[158:161], v[210:213], v[28:31]
	v_mfma_f32_16x16x32_bf16 v[20:23], v[166:169], v[210:213], v[20:23]
	v_mfma_f32_16x16x32_bf16 v[12:15], v[158:161], v[218:221], v[12:15]
	v_mfma_f32_16x16x32_bf16 v[4:7], v[166:169], v[218:221], v[4:7]
	v_mfma_f32_16x16x32_bf16 v[56:59], v[170:173], v[186:189], v[56:59]
	v_mfma_f32_16x16x32_bf16 v[48:51], v[178:181], v[186:189], v[48:51]
	v_mfma_f32_16x16x32_bf16 v[40:43], v[170:173], v[198:201], v[40:43]
	v_mfma_f32_16x16x32_bf16 v[32:35], v[178:181], v[198:201], v[32:35]
	v_mfma_f32_16x16x32_bf16 v[24:27], v[170:173], v[206:209], v[24:27]
	v_mfma_f32_16x16x32_bf16 v[16:19], v[178:181], v[206:209], v[16:19]
	v_mfma_f32_16x16x32_bf16 v[8:11], v[170:173], v[214:217], v[8:11]
	v_mfma_f32_16x16x32_bf16 v[0:3], v[178:181], v[214:217], v[0:3]
	v_mfma_f32_16x16x32_bf16 v[56:59], v[174:177], v[190:193], v[56:59]
	v_mfma_f32_16x16x32_bf16 v[48:51], v[182:185], v[190:193], v[48:51]
	v_mfma_f32_16x16x32_bf16 v[40:43], v[174:177], v[202:205], v[40:43]
	v_mfma_f32_16x16x32_bf16 v[32:35], v[182:185], v[202:205], v[32:35]
	v_mfma_f32_16x16x32_bf16 v[24:27], v[174:177], v[210:213], v[24:27]
	v_mfma_f32_16x16x32_bf16 v[16:19], v[182:185], v[210:213], v[16:19]
	v_mfma_f32_16x16x32_bf16 v[8:11], v[174:177], v[218:221], v[8:11]
	v_mfma_f32_16x16x32_bf16 v[0:3], v[182:185], v[218:221], v[0:3]
	s_barrier
	s_add_i32 s69, s69, 2
	s_add_u32 s20, s20, 0x100
	s_addc_u32 s21, s21, 0
	s_add_u32 s67, s67, 0x100
	s_addc_u32 s68, s68, 0
	s_cmp_gt_u32 s69, 13
	s_cbranch_scc0 .LBB0_810
	s_and_b64 vcc, exec, s[10:11]
	s_cbranch_vccz .LBB0_813
	s_barrier

; #define PG8_STAGE(bufoff, gbase, voff) do { _Pragma("unroll") for (int _i = 0; _i < 2; ++_i) \
;         __builtin_amdgcn_global_load_lds((const unsigned*)((const char*)(gbase) + (voff)[_i]), (PG8_LAS unsigned*)(lds + (bufoff) + ldsw + _i * 8192), 16, 0, 0); } while (0)
; #define PG8_LDA(dst, b, h) do { _Pragma("unroll") for (int m = 0; m < 4; ++m) _Pragma("unroll") for (int k = 0; k < 2; ++k) dst[m][k] = *(const PG8_LAS bf16x8*)(lds + PG8_SA(b, h) + aoff + m * 2048 + k * 1024); } while (0)
; #define PG8_LDB(dst, b, h) do { _Pragma("unroll") for (int n = 0; n < 2; ++n) _Pragma("unroll") for (int k = 0; k < 2; ++k) dst[n][k] = *(const PG8_LAS bf16x8*)(lds + PG8_SB(b, h) + boff + n * 2048 + k * 1024); } while (0)
; #define PG8_MMA(ai, bj, At, Bt) do { __builtin_amdgcn_s_setprio(1); _Pragma("unroll") for (int m = 0; m < 4; ++m) _Pragma("unroll") for (int n = 0; n < 2; ++n) _Pragma("unroll") for (int k = 0; k < 2; ++k) \
;         acc[ai][bj][m][n] = __builtin_amdgcn_mfma_f32_16x16x32_bf16(Bt[n][k], At[m][k], acc[ai][bj][m][n], 0, 0, 0); __builtin_amdgcn_s_setprio(0); } while (0)
; #define PG8_WAIT_V(n) asm volatile("s_waitcnt vmcnt(" #n ")" ::: "memory")
; #define PG8_BAR __builtin_amdgcn_s_barrier()
; template <class Epi, class Sched, bool ALIGN_EPI = false, bool SP2 = false>
; __device__ __forceinline__ void gemm_phase(PG8_LAS unsigned char* lds, const Gemm g, const Sched& S, const Epi& E) {
;     ...
;         for (int t = 0; t < nt; t += 2) {
;             const bool last = (t == nt - 2);
;             const char* a1 = cA + (size_t)(t + 1) * kstep;
;             const char* a2 = last ? nA : cA + (size_t)(t + 2) * kstep; const char* b2 = last ? nB : cB + (size_t)(t + 2) * kstep;
;             const char* a3 = a2 + kstep; const char* b3 = b2 + kstep;
;             if (last && has_next) S.a_ready(nxt);
;             if constexpr (SP2) {
;             PG8_LDB(B0, 0, 0); PG8_LDB(B1, 0, 1); PG8_SCHED; PG8_LDA(At, 0, 0); PG8_STAGE(PG8_SA(1, 1), a1 + hstep, voffA);
;             PG8_WAIT_V(8); PG8_WAIT_L(0); PG8_BAR; PG8_MMA(0, 0, At, B0); PG8_MMA(0, 1, At, B1); PG8_BAR; PG8_SCHED;
;             PG8_LDA(At, 0, 1); PG8_STAGE(PG8_SB(0, 0), b2, voffB); PG8_STAGE(PG8_SB(0, 1), b2 + hstep, voffB); PG8_STAGE(PG8_SA(0, 0), a2, voffA);
;             PG8_WAIT_V(8); PG8_WAIT_L(0); PG8_BAR; PG8_MMA(1, 0, At, B0); PG8_MMA(1, 1, At, B1); PG8_BAR; PG8_SCHED;
.LBB0_894:
	s_add_u32 s20, s20, 0xb0080
	s_addc_u32 s21, s21, 0
	s_add_u32 s70, s34, 0x100
	s_addc_u32 s71, s35, 0
	s_mov_b32 s72, -2
	s_waitcnt lgkmcnt(0)
	ds_read_b128 v[96:99], v223
	ds_read_b128 v[108:111], v223 offset:1024
	ds_read_b128 v[120:123], v223 offset:2048
	ds_read_b128 v[128:131], v223 offset:3072
	ds_read_b128 v[144:147], v224
	ds_read_b128 v[148:151], v224 offset:1024
	ds_read_b128 v[152:155], v224 offset:2048
	ds_read_b128 v[156:159], v224 offset:3072
	s_add_u32 s34, s20, 0xfff50080
	s_addc_u32 s35, s21, -1
	s_cmp_eq_u32 s72, 40
	s_cselect_b32 s49, s1, s35
	s_cselect_b32 s48, s0, s34
	s_cselect_b32 s35, s47, s71
	s_cselect_b32 s34, s46, s70
	s_add_i32 m0, s51, 0xc000
	ds_read_b128 v[160:163], v225
	ds_read_b128 v[164:167], v225 offset:1024
	ds_read_b128 v[168:171], v225 offset:2048
	ds_read_b128 v[172:175], v225 offset:3072
	ds_read_b128 v[176:179], v225 offset:4096
	ds_read_b128 v[180:183], v225 offset:5120
	ds_read_b128 v[202:205], v225 offset:6144
	ds_read_b128 v[206:209], v225 offset:7168
	global_load_lds_dwordx4 v192, s[20:21]
	s_add_i32 m0, s51, 0xe000
	s_nop 0
	global_load_lds_dwordx4 v194, s[20:21]
	s_nop 0
	s_waitcnt vmcnt(8)
	s_waitcnt lgkmcnt(0)
	s_barrier
	v_mfma_f32_16x16x32_bf16 v[140:143], v[96:99], v[160:163], 0
	v_mfma_f32_16x16x32_bf16 v[136:139], v[120:123], v[160:163], 0
	v_mfma_f32_16x16x32_bf16 v[116:119], v[96:99], v[168:171], 0
	v_mfma_f32_16x16x32_bf16 v[112:115], v[120:123], v[168:171], 0
	v_mfma_f32_16x16x32_bf16 v[92:95], v[96:99], v[176:179], 0
	v_mfma_f32_16x16x32_bf16 v[88:91], v[120:123], v[176:179], 0
	v_mfma_f32_16x16x32_bf16 v[76:79], v[96:99], v[202:205], 0
	v_mfma_f32_16x16x32_bf16 v[72:75], v[120:123], v[202:205], 0
	v_mfma_f32_16x16x32_bf16 v[140:143], v[108:111], v[164:167], v[140:143]
	v_mfma_f32_16x16x32_bf16 v[136:139], v[128:131], v[164:167], v[136:139]
	v_mfma_f32_16x16x32_bf16 v[116:119], v[108:111], v[172:175], v[116:119]
	v_mfma_f32_16x16x32_bf16 v[112:115], v[128:131], v[172:175], v[112:115]
	v_mfma_f32_16x16x32_bf16 v[92:95], v[108:111], v[180:183], v[92:95]
	v_mfma_f32_16x16x32_bf16 v[88:91], v[128:131], v[180:183], v[88:91]
	v_mfma_f32_16x16x32_bf16 v[76:79], v[108:111], v[206:209], v[76:79]
	v_mfma_f32_16x16x32_bf16 v[72:75], v[128:131], v[206:209], v[72:75]
	v_mfma_f32_16x16x32_bf16 v[132:135], v[144:147], v[160:163], 0
	v_mfma_f32_16x16x32_bf16 v[124:127], v[152:155], v[160:163], 0
	v_mfma_f32_16x16x32_bf16 v[104:107], v[144:147], v[168:171], 0
	v_mfma_f32_16x16x32_bf16 v[100:103], v[152:155], v[168:171], 0
	v_mfma_f32_16x16x32_bf16 v[84:87], v[144:147], v[176:179], 0
	v_mfma_f32_16x16x32_bf16 v[80:83], v[152:155], v[176:179], 0
	v_mfma_f32_16x16x32_bf16 v[68:71], v[144:147], v[202:205], 0
	v_mfma_f32_16x16x32_bf16 v[64:67], v[152:155], v[202:205], 0
	v_mfma_f32_16x16x32_bf16 v[132:135], v[148:151], v[164:167], v[132:135]
	v_mfma_f32_16x16x32_bf16 v[124:127], v[156:159], v[164:167], v[124:127]
	v_mfma_f32_16x16x32_bf16 v[104:107], v[148:151], v[172:175], v[104:107]
	v_mfma_f32_16x16x32_bf16 v[100:103], v[156:159], v[172:175], v[100:103]
	v_mfma_f32_16x16x32_bf16 v[84:87], v[148:151], v[180:183], v[84:87]
	v_mfma_f32_16x16x32_bf16 v[80:83], v[156:159], v[180:183], v[80:83]
	v_mfma_f32_16x16x32_bf16 v[68:71], v[148:151], v[206:209], v[68:71]
	v_mfma_f32_16x16x32_bf16 v[64:67], v[156:159], v[206:209], v[64:67]
	s_barrier
	s_add_i32 s73, s64, s50
	s_add_u32 s98, s34, s12
	s_addc_u32 s99, s35, s13
	s_add_u32 s100, s48, s12
	s_addc_u32 s101, s49, s13
	s_mov_b32 m0, s73
	ds_read_b128 v[160:163], v225 offset:16384
	ds_read_b128 v[164:167], v225 offset:17408
	ds_read_b128 v[168:171], v225 offset:18432
	ds_read_b128 v[172:175], v225 offset:19456
	ds_read_b128 v[176:179], v225 offset:20480
	ds_read_b128 v[180:183], v225 offset:21504
	ds_read_b128 v[202:205], v225 offset:22528
	ds_read_b128 v[206:209], v225 offset:23552
	global_load_lds_dwordx4 v186, s[34:35]
	s_add_i32 m0, s73, 0x2000
	s_add_u32 s74, s34, 0xb0000
	s_addc_u32 s75, s35, 0
	s_add_i32 s73, s65, s50
	global_load_lds_dwordx4 v190, s[34:35]
	s_mov_b32 m0, s73
	s_nop 0
	global_load_lds_dwordx4 v186, s[74:75]
	s_add_i32 m0, s73, 0x2000
	s_nop 0
	global_load_lds_dwordx4 v190, s[74:75]
	s_mov_b32 m0, s51
	s_nop 0
	global_load_lds_dwordx4 v184, s[48:49]
	s_mov_b32 m0, s52
	s_nop 0
	global_load_lds_dwordx4 v188, s[48:49]
	s_nop 0
	s_waitcnt vmcnt(8)
	s_waitcnt lgkmcnt(0)
	s_barrier
	v_mfma_f32_16x16x32_bf16 v[60:63], v[96:99], v[160:163], 0
	v_mfma_f32_16x16x32_bf16 v[56:59], v[120:123], v[160:163], 0
	v_mfma_f32_16x16x32_bf16 v[44:47], v[96:99], v[168:171], 0
	v_mfma_f32_16x16x32_bf16 v[40:43], v[120:123], v[168:171], 0
	v_mfma_f32_16x16x32_bf16 v[28:31], v[96:99], v[176:179], 0
	v_mfma_f32_16x16x32_bf16 v[24:27], v[120:123], v[176:179], 0
	v_mfma_f32_16x16x32_bf16 v[12:15], v[96:99], v[202:205], 0
	v_mfma_f32_16x16x32_bf16 v[8:11], v[120:123], v[202:205], 0
	v_mfma_f32_16x16x32_bf16 v[60:63], v[108:111], v[164:167], v[60:63]
	v_mfma_f32_16x16x32_bf16 v[56:59], v[128:131], v[164:167], v[56:59]
	v_mfma_f32_16x16x32_bf16 v[44:47], v[108:111], v[172:175], v[44:47]
	v_mfma_f32_16x16x32_bf16 v[40:43], v[128:131], v[172:175], v[40:43]
	v_mfma_f32_16x16x32_bf16 v[28:31], v[108:111], v[180:183], v[28:31]
	v_mfma_f32_16x16x32_bf16 v[24:27], v[128:131], v[180:183], v[24:27]
	v_mfma_f32_16x16x32_bf16 v[12:15], v[108:111], v[206:209], v[12:15]
	v_mfma_f32_16x16x32_bf16 v[8:11], v[128:131], v[206:209], v[8:11]
	v_mfma_f32_16x16x32_bf16 v[52:55], v[144:147], v[160:163], 0
	v_mfma_f32_16x16x32_bf16 v[48:51], v[152:155], v[160:163], 0
	v_mfma_f32_16x16x32_bf16 v[36:39], v[144:147], v[168:171], 0
	v_mfma_f32_16x16x32_bf16 v[32:35], v[152:155], v[168:171], 0
	v_mfma_f32_16x16x32_bf16 v[20:23], v[144:147], v[176:179], 0
	v_mfma_f32_16x16x32_bf16 v[16:19], v[152:155], v[176:179], 0
	v_mfma_f32_16x16x32_bf16 v[4:7], v[144:147], v[202:205], 0
	v_mfma_f32_16x16x32_bf16 v[0:3], v[152:155], v[202:205], 0
	v_mfma_f32_16x16x32_bf16 v[52:55], v[148:151], v[164:167], v[52:55]
	v_mfma_f32_16x16x32_bf16 v[48:51], v[156:159], v[164:167], v[48:51]
	v_mfma_f32_16x16x32_bf16 v[36:39], v[148:151], v[172:175], v[36:39]
	v_mfma_f32_16x16x32_bf16 v[32:35], v[156:159], v[172:175], v[32:35]
	v_mfma_f32_16x16x32_bf16 v[20:23], v[148:151], v[180:183], v[20:23]
	v_mfma_f32_16x16x32_bf16 v[16:19], v[156:159], v[180:183], v[16:19]
	v_mfma_f32_16x16x32_bf16 v[4:7], v[148:151], v[206:209], v[4:7]
	v_mfma_f32_16x16x32_bf16 v[0:3], v[156:159], v[206:209], v[0:3]
	s_barrier
; #define PG8_STAGE(bufoff, gbase, voff) do { _Pragma("unroll") for (int _i = 0; _i < 2; ++_i) \
;         __builtin_amdgcn_global_load_lds((const unsigned*)((const char*)(gbase) + (voff)[_i]), (PG8_LAS unsigned*)(lds + (bufoff) + ldsw + _i * 8192), 16, 0, 0); } while (0)
; #define PG8_LDA(dst, b, h) do { _Pragma("unroll") for (int m = 0; m < 4; ++m) _Pragma("unroll") for (int k = 0; k < 2; ++k) dst[m][k] = *(const PG8_LAS bf16x8*)(lds + PG8_SA(b, h) + aoff + m * 2048 + k * 1024); } while (0)
; #define PG8_LDB(dst, b, h) do { _Pragma("unroll") for (int n = 0; n < 2; ++n) _Pragma("unroll") for (int k = 0; k < 2; ++k) dst[n][k] = *(const PG8_LAS bf16x8*)(lds + PG8_SB(b, h) + boff + n * 2048 + k * 1024); } while (0)
; #define PG8_MMA(ai, bj, At, Bt) do { __builtin_amdgcn_s_setprio(1); _Pragma("unroll") for (int m = 0; m < 4; ++m) _Pragma("unroll") for (int n = 0; n < 2; ++n) _Pragma("unroll") for (int k = 0; k < 2; ++k) \
;         acc[ai][bj][m][n] = __builtin_amdgcn_mfma_f32_16x16x32_bf16(Bt[n][k], At[m][k], acc[ai][bj][m][n], 0, 0, 0); __builtin_amdgcn_s_setprio(0); } while (0)
; #define PG8_WAIT_V(n) asm volatile("s_waitcnt vmcnt(" #n ")" ::: "memory")
; #define PG8_WAIT_L(n) asm volatile("s_waitcnt lgkmcnt(" #n ")" ::: "memory")
; #define PG8_BAR __builtin_amdgcn_s_barrier()
; #define PG8_SCHED __builtin_amdgcn_sched_barrier(0)
; template <class Epi, class Sched, bool ALIGN_EPI = false, bool SP2 = false>
; __device__ __forceinline__ void gemm_phase(PG8_LAS unsigned char* lds, const Gemm g, const Sched& S, const Epi& E) {
;     ...
;             PG8_LDB(B0, 1, 0); PG8_LDB(B1, 1, 1); PG8_SCHED; PG8_LDA(At, 1, 0); PG8_STAGE(PG8_SA(0, 1), a2 + hstep, voffA);
;             PG8_WAIT_V(8); PG8_WAIT_L(0); PG8_BAR; PG8_MMA(0, 0, At, B0); PG8_MMA(0, 1, At, B1); PG8_BAR; PG8_SCHED;
;             PG8_LDA(At, 1, 1); PG8_STAGE(PG8_SB(1, 0), b3, voffB); PG8_STAGE(PG8_SB(1, 1), b3 + hstep, voffB); PG8_STAGE(PG8_SA(1, 0), a3, voffA);
;             PG8_WAIT_V(8); PG8_WAIT_L(0); PG8_BAR; PG8_MMA(1, 0, At, B0); PG8_MMA(1, 1, At, B1); PG8_BAR; PG8_SCHED;
	s_add_i32 s73, 0, 0x18000
	s_add_i32 s74, 0, 0x1c000
	v_add_u32_e32 v128, s73, v221
	v_add_u32_e32 v156, s74, v221
	ds_read_b128 v[96:99], v128
	ds_read_b128 v[108:111], v128 offset:1024
	ds_read_b128 v[120:123], v128 offset:2048
	ds_read_b128 v[128:131], v128 offset:3072
	ds_read_b128 v[144:147], v156
	ds_read_b128 v[148:151], v156 offset:1024
	ds_read_b128 v[152:155], v156 offset:2048
	ds_read_b128 v[156:159], v156 offset:3072
	s_add_u32 s48, s48, 0xb0000
	s_addc_u32 s49, s49, 0
	s_mov_b32 m0, s53
	ds_read_b128 v[160:163], v225 offset:32768
	ds_read_b128 v[164:167], v225 offset:33792
	ds_read_b128 v[168:171], v225 offset:34816
	ds_read_b128 v[172:175], v225 offset:35840
	ds_read_b128 v[176:179], v225 offset:36864
	ds_read_b128 v[180:183], v225 offset:37888
	ds_read_b128 v[202:205], v225 offset:38912
	ds_read_b128 v[206:209], v225 offset:39936
	global_load_lds_dwordx4 v184, s[48:49]
	s_mov_b32 m0, s54
	s_nop 0
	global_load_lds_dwordx4 v188, s[48:49]
	s_waitcnt vmcnt(8)
	s_waitcnt lgkmcnt(0)
	s_barrier
	v_mfma_f32_16x16x32_bf16 v[140:143], v[96:99], v[160:163], v[140:143]
	v_mfma_f32_16x16x32_bf16 v[136:139], v[120:123], v[160:163], v[136:139]
	v_mfma_f32_16x16x32_bf16 v[116:119], v[96:99], v[168:171], v[116:119]
	v_mfma_f32_16x16x32_bf16 v[112:115], v[120:123], v[168:171], v[112:115]
	v_mfma_f32_16x16x32_bf16 v[92:95], v[96:99], v[176:179], v[92:95]
	v_mfma_f32_16x16x32_bf16 v[88:91], v[120:123], v[176:179], v[88:91]
	v_mfma_f32_16x16x32_bf16 v[76:79], v[96:99], v[202:205], v[76:79]
	v_mfma_f32_16x16x32_bf16 v[72:75], v[120:123], v[202:205], v[72:75]
	v_mfma_f32_16x16x32_bf16 v[140:143], v[108:111], v[164:167], v[140:143]
	v_mfma_f32_16x16x32_bf16 v[136:139], v[128:131], v[164:167], v[136:139]
	v_mfma_f32_16x16x32_bf16 v[116:119], v[108:111], v[172:175], v[116:119]
	v_mfma_f32_16x16x32_bf16 v[112:115], v[128:131], v[172:175], v[112:115]
	v_mfma_f32_16x16x32_bf16 v[92:95], v[108:111], v[180:183], v[92:95]
	v_mfma_f32_16x16x32_bf16 v[88:91], v[128:131], v[180:183], v[88:91]
	v_mfma_f32_16x16x32_bf16 v[76:79], v[108:111], v[206:209], v[76:79]
	v_mfma_f32_16x16x32_bf16 v[72:75], v[128:131], v[206:209], v[72:75]
	v_mfma_f32_16x16x32_bf16 v[132:135], v[144:147], v[160:163], v[132:135]
	v_mfma_f32_16x16x32_bf16 v[124:127], v[152:155], v[160:163], v[124:127]
	v_mfma_f32_16x16x32_bf16 v[104:107], v[144:147], v[168:171], v[104:107]
	v_mfma_f32_16x16x32_bf16 v[100:103], v[152:155], v[168:171], v[100:103]
	v_mfma_f32_16x16x32_bf16 v[84:87], v[144:147], v[176:179], v[84:87]
	v_mfma_f32_16x16x32_bf16 v[80:83], v[152:155], v[176:179], v[80:83]
	v_mfma_f32_16x16x32_bf16 v[68:71], v[144:147], v[202:205], v[68:71]
	v_mfma_f32_16x16x32_bf16 v[64:67], v[152:155], v[202:205], v[64:67]
	v_mfma_f32_16x16x32_bf16 v[132:135], v[148:151], v[164:167], v[132:135]
	v_mfma_f32_16x16x32_bf16 v[124:127], v[156:159], v[164:167], v[124:127]
	v_mfma_f32_16x16x32_bf16 v[104:107], v[148:151], v[172:175], v[104:107]
	v_mfma_f32_16x16x32_bf16 v[100:103], v[156:159], v[172:175], v[100:103]
	v_mfma_f32_16x16x32_bf16 v[84:87], v[148:151], v[180:183], v[84:87]
	v_mfma_f32_16x16x32_bf16 v[80:83], v[156:159], v[180:183], v[80:83]
	v_mfma_f32_16x16x32_bf16 v[68:71], v[148:151], v[206:209], v[68:71]
	v_mfma_f32_16x16x32_bf16 v[64:67], v[156:159], v[206:209], v[64:67]
	s_barrier
	s_add_i32 s48, s73, s50
	s_mov_b32 m0, s48
	ds_read_b128 v[160:163], v225 offset:49152
	ds_read_b128 v[164:167], v225 offset:50176
	ds_read_b128 v[168:171], v225 offset:51200
	ds_read_b128 v[172:175], v225 offset:52224
	ds_read_b128 v[176:179], v225 offset:53248
	ds_read_b128 v[180:183], v225 offset:54272
	ds_read_b128 v[202:205], v225 offset:55296
	ds_read_b128 v[206:209], v225 offset:56320
	global_load_lds_dwordx4 v186, s[98:99]
	s_add_i32 m0, s48, 0x2000
	s_add_u32 s34, s34, 0xb0080
	s_addc_u32 s35, s35, 0
	s_add_i32 s48, s74, s50
	global_load_lds_dwordx4 v190, s[98:99]
	s_mov_b32 m0, s48
	s_nop 0
	global_load_lds_dwordx4 v186, s[34:35]
	s_add_i32 m0, s48, 0x2000
	s_nop 0
	global_load_lds_dwordx4 v190, s[34:35]
	s_mov_b32 m0, s59
	s_nop 0
	global_load_lds_dwordx4 v184, s[100:101]
	s_mov_b32 m0, s60
	s_nop 0
	global_load_lds_dwordx4 v188, s[100:101]
	s_nop 0
	s_waitcnt vmcnt(8)
	s_waitcnt lgkmcnt(0)
	s_barrier
	v_mfma_f32_16x16x32_bf16 v[60:63], v[96:99], v[160:163], v[60:63]
	v_mfma_f32_16x16x32_bf16 v[56:59], v[120:123], v[160:163], v[56:59]
	v_mfma_f32_16x16x32_bf16 v[44:47], v[96:99], v[168:171], v[44:47]
	v_mfma_f32_16x16x32_bf16 v[40:43], v[120:123], v[168:171], v[40:43]
	v_mfma_f32_16x16x32_bf16 v[28:31], v[96:99], v[176:179], v[28:31]
	v_mfma_f32_16x16x32_bf16 v[24:27], v[120:123], v[176:179], v[24:27]
	v_mfma_f32_16x16x32_bf16 v[12:15], v[96:99], v[202:205], v[12:15]
	v_mfma_f32_16x16x32_bf16 v[8:11], v[120:123], v[202:205], v[8:11]
	v_mfma_f32_16x16x32_bf16 v[60:63], v[108:111], v[164:167], v[60:63]
	v_mfma_f32_16x16x32_bf16 v[56:59], v[128:131], v[164:167], v[56:59]
	v_mfma_f32_16x16x32_bf16 v[44:47], v[108:111], v[172:175], v[44:47]
	v_mfma_f32_16x16x32_bf16 v[40:43], v[128:131], v[172:175], v[40:43]
	v_mfma_f32_16x16x32_bf16 v[28:31], v[108:111], v[180:183], v[28:31]
	v_mfma_f32_16x16x32_bf16 v[24:27], v[128:131], v[180:183], v[24:27]
	v_mfma_f32_16x16x32_bf16 v[12:15], v[108:111], v[206:209], v[12:15]
	v_mfma_f32_16x16x32_bf16 v[8:11], v[128:131], v[206:209], v[8:11]
	v_mfma_f32_16x16x32_bf16 v[52:55], v[144:147], v[160:163], v[52:55]
	v_mfma_f32_16x16x32_bf16 v[48:51], v[152:155], v[160:163], v[48:51]
	v_mfma_f32_16x16x32_bf16 v[36:39], v[144:147], v[168:171], v[36:39]
	v_mfma_f32_16x16x32_bf16 v[32:35], v[152:155], v[168:171], v[32:35]
	v_mfma_f32_16x16x32_bf16 v[20:23], v[144:147], v[176:179], v[20:23]
	v_mfma_f32_16x16x32_bf16 v[16:19], v[152:155], v[176:179], v[16:19]
	v_mfma_f32_16x16x32_bf16 v[4:7], v[144:147], v[202:205], v[4:7]
	v_mfma_f32_16x16x32_bf16 v[0:3], v[152:155], v[202:205], v[0:3]
	v_mfma_f32_16x16x32_bf16 v[52:55], v[148:151], v[164:167], v[52:55]
	v_mfma_f32_16x16x32_bf16 v[48:51], v[156:159], v[164:167], v[48:51]
	v_mfma_f32_16x16x32_bf16 v[36:39], v[148:151], v[172:175], v[36:39]
	v_mfma_f32_16x16x32_bf16 v[32:35], v[156:159], v[172:175], v[32:35]
	v_mfma_f32_16x16x32_bf16 v[20:23], v[148:151], v[180:183], v[20:23]
	v_mfma_f32_16x16x32_bf16 v[16:19], v[156:159], v[180:183], v[16:19]
	v_mfma_f32_16x16x32_bf16 v[4:7], v[148:151], v[206:209], v[4:7]
	v_mfma_f32_16x16x32_bf16 v[0:3], v[156:159], v[206:209], v[0:3]
	s_barrier
	s_add_i32 s72, s72, 2
	s_add_u32 s20, s20, 0x100
	s_addc_u32 s21, s21, 0
	s_add_u32 s70, s70, 0x100
	s_addc_u32 s71, s71, 0
	s_cmp_gt_u32 s72, 41
; #define PG8_STAGE(bufoff, gbase, voff) do { _Pragma("unroll") for (int _i = 0; _i < 2; ++_i) \
;         __builtin_amdgcn_global_load_lds((const unsigned*)((const char*)(gbase) + (voff)[_i]), (PG8_LAS unsigned*)(lds + (bufoff) + ldsw + _i * 8192), 16, 0, 0); } while (0)
; #define PG8_LDA(dst, b, h) do { _Pragma("unroll") for (int m = 0; m < 4; ++m) _Pragma("unroll") for (int k = 0; k < 2; ++k) dst[m][k] = *(const PG8_LAS bf16x8*)(lds + PG8_SA(b, h) + aoff + m * 2048 + k * 1024); } while (0)
; #define PG8_LDB(dst, b, h) do { _Pragma("unroll") for (int n = 0; n < 2; ++n) _Pragma("unroll") for (int k = 0; k < 2; ++k) dst[n][k] = *(const PG8_LAS bf16x8*)(lds + PG8_SB(b, h) + boff + n * 2048 + k * 1024); } while (0)
; #define PG8_MMA(ai, bj, At, Bt) do { __builtin_amdgcn_s_setprio(1); _Pragma("unroll") for (int m = 0; m < 4; ++m) _Pragma("unroll") for (int n = 0; n < 2; ++n) _Pragma("unroll") for (int k = 0; k < 2; ++k) \
;         acc[ai][bj][m][n] = __builtin_amdgcn_mfma_f32_16x16x32_bf16(Bt[n][k], At[m][k], acc[ai][bj][m][n], 0, 0, 0); __builtin_amdgcn_s_setprio(0); } while (0)
; #define PG8_WAIT_V(n) asm volatile("s_waitcnt vmcnt(" #n ")" ::: "memory")
; #define PG8_WAIT_L(n) asm volatile("s_waitcnt lgkmcnt(" #n ")" ::: "memory")
; #define PG8_BAR __builtin_amdgcn_s_barrier()
; #define PG8_SCHED __builtin_amdgcn_sched_barrier(0)
; template <class Epi, class Sched, bool ALIGN_EPI = false, bool SP2 = false>
; __device__ __forceinline__ void gemm_phase(PG8_LAS unsigned char* lds, const Gemm g, const Sched& S, const Epi& E) {
;     ...
;             PG8_LDB(B0, 0, 0); PG8_LDB(B1, 0, 1); PG8_SCHED; PG8_LDA(At, 0, 0); PG8_STAGE(PG8_SA(1, 1), a1 + hstep, voffA);
;             PG8_WAIT_V(8); PG8_WAIT_L(0); PG8_BAR; PG8_MMA(0, 0, At, B0); PG8_MMA(0, 1, At, B1); PG8_BAR; PG8_SCHED;
;             PG8_LDA(At, 0, 1); PG8_STAGE(PG8_SB(0, 0), b2, voffB); PG8_STAGE(PG8_SB(0, 1), b2 + hstep, voffB); PG8_STAGE(PG8_SA(0, 0), a2, voffA);
;             PG8_WAIT_V(8); PG8_WAIT_L(0); PG8_BAR; PG8_MMA(1, 0, At, B0); PG8_MMA(1, 1, At, B1); PG8_BAR; PG8_SCHED;
.LBB0_895:
	ds_read_b128 v[96:99], v223
	ds_read_b128 v[108:111], v223 offset:1024
	ds_read_b128 v[120:123], v223 offset:2048
	ds_read_b128 v[128:131], v223 offset:3072
	ds_read_b128 v[144:147], v224
	ds_read_b128 v[148:151], v224 offset:1024
	ds_read_b128 v[152:155], v224 offset:2048
	ds_read_b128 v[156:159], v224 offset:3072
	s_add_u32 s34, s20, 0xfff50080
	s_addc_u32 s35, s21, -1
	s_cmp_eq_u32 s72, 40
	s_cselect_b32 s49, s1, s35
	s_cselect_b32 s48, s0, s34
	s_cselect_b32 s35, s47, s71
	s_cselect_b32 s34, s46, s70
	s_add_i32 m0, s51, 0xc000
	ds_read_b128 v[160:163], v225
	ds_read_b128 v[164:167], v225 offset:1024
	ds_read_b128 v[168:171], v225 offset:2048
	ds_read_b128 v[172:175], v225 offset:3072
	ds_read_b128 v[176:179], v225 offset:4096
	ds_read_b128 v[180:183], v225 offset:5120
	ds_read_b128 v[202:205], v225 offset:6144
	ds_read_b128 v[206:209], v225 offset:7168
	global_load_lds_dwordx4 v192, s[20:21]
	s_add_i32 m0, s51, 0xe000
	s_nop 0
	global_load_lds_dwordx4 v194, s[20:21]
	s_nop 0
	s_waitcnt vmcnt(8)
	s_waitcnt lgkmcnt(0)
	s_barrier
	v_mfma_f32_16x16x32_bf16 v[140:143], v[96:99], v[160:163], v[140:143]
	v_mfma_f32_16x16x32_bf16 v[136:139], v[120:123], v[160:163], v[136:139]
	v_mfma_f32_16x16x32_bf16 v[116:119], v[96:99], v[168:171], v[116:119]
	v_mfma_f32_16x16x32_bf16 v[112:115], v[120:123], v[168:171], v[112:115]
	v_mfma_f32_16x16x32_bf16 v[92:95], v[96:99], v[176:179], v[92:95]
	v_mfma_f32_16x16x32_bf16 v[88:91], v[120:123], v[176:179], v[88:91]
	v_mfma_f32_16x16x32_bf16 v[76:79], v[96:99], v[202:205], v[76:79]
	v_mfma_f32_16x16x32_bf16 v[72:75], v[120:123], v[202:205], v[72:75]
	v_mfma_f32_16x16x32_bf16 v[140:143], v[108:111], v[164:167], v[140:143]
	v_mfma_f32_16x16x32_bf16 v[136:139], v[128:131], v[164:167], v[136:139]
	v_mfma_f32_16x16x32_bf16 v[116:119], v[108:111], v[172:175], v[116:119]
	v_mfma_f32_16x16x32_bf16 v[112:115], v[128:131], v[172:175], v[112:115]
	v_mfma_f32_16x16x32_bf16 v[92:95], v[108:111], v[180:183], v[92:95]
	v_mfma_f32_16x16x32_bf16 v[88:91], v[128:131], v[180:183], v[88:91]
	v_mfma_f32_16x16x32_bf16 v[76:79], v[108:111], v[206:209], v[76:79]
	v_mfma_f32_16x16x32_bf16 v[72:75], v[128:131], v[206:209], v[72:75]
	v_mfma_f32_16x16x32_bf16 v[132:135], v[144:147], v[160:163], v[132:135]
	v_mfma_f32_16x16x32_bf16 v[124:127], v[152:155], v[160:163], v[124:127]
	v_mfma_f32_16x16x32_bf16 v[104:107], v[144:147], v[168:171], v[104:107]
	v_mfma_f32_16x16x32_bf16 v[100:103], v[152:155], v[168:171], v[100:103]
	v_mfma_f32_16x16x32_bf16 v[84:87], v[144:147], v[176:179], v[84:87]
	v_mfma_f32_16x16x32_bf16 v[80:83], v[152:155], v[176:179], v[80:83]
	v_mfma_f32_16x16x32_bf16 v[68:71], v[144:147], v[202:205], v[68:71]
	v_mfma_f32_16x16x32_bf16 v[64:67], v[152:155], v[202:205], v[64:67]
	v_mfma_f32_16x16x32_bf16 v[132:135], v[148:151], v[164:167], v[132:135]
	v_mfma_f32_16x16x32_bf16 v[124:127], v[156:159], v[164:167], v[124:127]
	v_mfma_f32_16x16x32_bf16 v[104:107], v[148:151], v[172:175], v[104:107]
	v_mfma_f32_16x16x32_bf16 v[100:103], v[156:159], v[172:175], v[100:103]
	v_mfma_f32_16x16x32_bf16 v[84:87], v[148:151], v[180:183], v[84:87]
	v_mfma_f32_16x16x32_bf16 v[80:83], v[156:159], v[180:183], v[80:83]
	v_mfma_f32_16x16x32_bf16 v[68:71], v[148:151], v[206:209], v[68:71]
	v_mfma_f32_16x16x32_bf16 v[64:67], v[156:159], v[206:209], v[64:67]
	s_barrier
	s_add_i32 s73, s64, s50
	s_add_u32 s98, s34, s12
	s_addc_u32 s99, s35, s13
	s_add_u32 s100, s48, s12
	s_addc_u32 s101, s49, s13
	s_mov_b32 m0, s73
	ds_read_b128 v[160:163], v225 offset:16384
	ds_read_b128 v[164:167], v225 offset:17408
	ds_read_b128 v[168:171], v225 offset:18432
	ds_read_b128 v[172:175], v225 offset:19456
	ds_read_b128 v[176:179], v225 offset:20480
	ds_read_b128 v[180:183], v225 offset:21504
	ds_read_b128 v[202:205], v225 offset:22528
	ds_read_b128 v[206:209], v225 offset:23552
	global_load_lds_dwordx4 v186, s[34:35]
	s_add_i32 m0, s73, 0x2000
	s_add_u32 s74, s34, 0xb0000
	s_addc_u32 s75, s35, 0
	s_add_i32 s73, s65, s50
	global_load_lds_dwordx4 v190, s[34:35]
	s_mov_b32 m0, s73
	s_nop 0
	global_load_lds_dwordx4 v186, s[74:75]
	s_add_i32 m0, s73, 0x2000
	s_nop 0
	global_load_lds_dwordx4 v190, s[74:75]
	s_mov_b32 m0, s51
	s_nop 0
	global_load_lds_dwordx4 v184, s[48:49]
	s_mov_b32 m0, s52
	s_nop 0
	global_load_lds_dwordx4 v188, s[48:49]
	s_nop 0
	s_waitcnt vmcnt(8)
	s_waitcnt lgkmcnt(0)
	s_barrier
	v_mfma_f32_16x16x32_bf16 v[60:63], v[96:99], v[160:163], v[60:63]
	v_mfma_f32_16x16x32_bf16 v[56:59], v[120:123], v[160:163], v[56:59]
	v_mfma_f32_16x16x32_bf16 v[44:47], v[96:99], v[168:171], v[44:47]
	v_mfma_f32_16x16x32_bf16 v[40:43], v[120:123], v[168:171], v[40:43]
	v_mfma_f32_16x16x32_bf16 v[28:31], v[96:99], v[176:179], v[28:31]
	v_mfma_f32_16x16x32_bf16 v[24:27], v[120:123], v[176:179], v[24:27]
	v_mfma_f32_16x16x32_bf16 v[12:15], v[96:99], v[202:205], v[12:15]
	v_mfma_f32_16x16x32_bf16 v[8:11], v[120:123], v[202:205], v[8:11]
	v_mfma_f32_16x16x32_bf16 v[60:63], v[108:111], v[164:167], v[60:63]
	v_mfma_f32_16x16x32_bf16 v[56:59], v[128:131], v[164:167], v[56:59]
	v_mfma_f32_16x16x32_bf16 v[44:47], v[108:111], v[172:175], v[44:47]
	v_mfma_f32_16x16x32_bf16 v[40:43], v[128:131], v[172:175], v[40:43]
	v_mfma_f32_16x16x32_bf16 v[28:31], v[108:111], v[180:183], v[28:31]
	v_mfma_f32_16x16x32_bf16 v[24:27], v[128:131], v[180:183], v[24:27]
	v_mfma_f32_16x16x32_bf16 v[12:15], v[108:111], v[206:209], v[12:15]
	v_mfma_f32_16x16x32_bf16 v[8:11], v[128:131], v[206:209], v[8:11]
	v_mfma_f32_16x16x32_bf16 v[52:55], v[144:147], v[160:163], v[52:55]
	v_mfma_f32_16x16x32_bf16 v[48:51], v[152:155], v[160:163], v[48:51]
	v_mfma_f32_16x16x32_bf16 v[36:39], v[144:147], v[168:171], v[36:39]
	v_mfma_f32_16x16x32_bf16 v[32:35], v[152:155], v[168:171], v[32:35]
	v_mfma_f32_16x16x32_bf16 v[20:23], v[144:147], v[176:179], v[20:23]
	v_mfma_f32_16x16x32_bf16 v[16:19], v[152:155], v[176:179], v[16:19]
	v_mfma_f32_16x16x32_bf16 v[4:7], v[144:147], v[202:205], v[4:7]
	v_mfma_f32_16x16x32_bf16 v[0:3], v[152:155], v[202:205], v[0:3]
	v_mfma_f32_16x16x32_bf16 v[52:55], v[148:151], v[164:167], v[52:55]
	v_mfma_f32_16x16x32_bf16 v[48:51], v[156:159], v[164:167], v[48:51]
	v_mfma_f32_16x16x32_bf16 v[36:39], v[148:151], v[172:175], v[36:39]
	v_mfma_f32_16x16x32_bf16 v[32:35], v[156:159], v[172:175], v[32:35]
	v_mfma_f32_16x16x32_bf16 v[20:23], v[148:151], v[180:183], v[20:23]
	v_mfma_f32_16x16x32_bf16 v[16:19], v[156:159], v[180:183], v[16:19]
	v_mfma_f32_16x16x32_bf16 v[4:7], v[148:151], v[206:209], v[4:7]
	v_mfma_f32_16x16x32_bf16 v[0:3], v[156:159], v[206:209], v[0:3]
	s_barrier
; #define PG8_STAGE(bufoff, gbase, voff) do { _Pragma("unroll") for (int _i = 0; _i < 2; ++_i) \
;         __builtin_amdgcn_global_load_lds((const unsigned*)((const char*)(gbase) + (voff)[_i]), (PG8_LAS unsigned*)(lds + (bufoff) + ldsw + _i * 8192), 16, 0, 0); } while (0)
; #define PG8_LDA(dst, b, h) do { _Pragma("unroll") for (int m = 0; m < 4; ++m) _Pragma("unroll") for (int k = 0; k < 2; ++k) dst[m][k] = *(const PG8_LAS bf16x8*)(lds + PG8_SA(b, h) + aoff + m * 2048 + k * 1024); } while (0)
; #define PG8_LDB(dst, b, h) do { _Pragma("unroll") for (int n = 0; n < 2; ++n) _Pragma("unroll") for (int k = 0; k < 2; ++k) dst[n][k] = *(const PG8_LAS bf16x8*)(lds + PG8_SB(b, h) + boff + n * 2048 + k * 1024); } while (0)
; #define PG8_MMA(ai, bj, At, Bt) do { __builtin_amdgcn_s_setprio(1); _Pragma("unroll") for (int m = 0; m < 4; ++m) _Pragma("unroll") for (int n = 0; n < 2; ++n) _Pragma("unroll") for (int k = 0; k < 2; ++k) \
;         acc[ai][bj][m][n] = __builtin_amdgcn_mfma_f32_16x16x32_bf16(Bt[n][k], At[m][k], acc[ai][bj][m][n], 0, 0, 0); __builtin_amdgcn_s_setprio(0); } while (0)
; #define PG8_WAIT_V(n) asm volatile("s_waitcnt vmcnt(" #n ")" ::: "memory")
; #define PG8_WAIT_L(n) asm volatile("s_waitcnt lgkmcnt(" #n ")" ::: "memory")
; #define PG8_BAR __builtin_amdgcn_s_barrier()
; #define PG8_SCHED __builtin_amdgcn_sched_barrier(0)
; template <class Epi, class Sched, bool ALIGN_EPI = false, bool SP2 = false>
; __device__ __forceinline__ void gemm_phase(PG8_LAS unsigned char* lds, const Gemm g, const Sched& S, const Epi& E) {
;     ...
;             PG8_LDB(B0, 1, 0); PG8_LDB(B1, 1, 1); PG8_SCHED; PG8_LDA(At, 1, 0); PG8_STAGE(PG8_SA(0, 1), a2 + hstep, voffA);
;             PG8_WAIT_V(8); PG8_WAIT_L(0); PG8_BAR; PG8_MMA(0, 0, At, B0); PG8_MMA(0, 1, At, B1); PG8_BAR; PG8_SCHED;
;             PG8_LDA(At, 1, 1); PG8_STAGE(PG8_SB(1, 0), b3, voffB); PG8_STAGE(PG8_SB(1, 1), b3 + hstep, voffB); PG8_STAGE(PG8_SA(1, 0), a3, voffA);
;             PG8_WAIT_V(8); PG8_WAIT_L(0); PG8_BAR; PG8_MMA(1, 0, At, B0); PG8_MMA(1, 1, At, B1); PG8_BAR; PG8_SCHED;
;     ...
;         if constexpr (ALIGN_EPI) { if (wr == 0) PG8_BAR; }
	s_add_i32 s73, 0, 0x18000
	s_add_i32 s74, 0, 0x1c000
	v_add_u32_e32 v128, s73, v221
	v_add_u32_e32 v156, s74, v221
	ds_read_b128 v[96:99], v128
	ds_read_b128 v[108:111], v128 offset:1024
	ds_read_b128 v[120:123], v128 offset:2048
	ds_read_b128 v[128:131], v128 offset:3072
	ds_read_b128 v[144:147], v156
	ds_read_b128 v[148:151], v156 offset:1024
	ds_read_b128 v[152:155], v156 offset:2048
	ds_read_b128 v[156:159], v156 offset:3072
	s_add_u32 s48, s48, 0xb0000
	s_addc_u32 s49, s49, 0
	s_mov_b32 m0, s53
	ds_read_b128 v[160:163], v225 offset:32768
	ds_read_b128 v[164:167], v225 offset:33792
	ds_read_b128 v[168:171], v225 offset:34816
	ds_read_b128 v[172:175], v225 offset:35840
	ds_read_b128 v[176:179], v225 offset:36864
	ds_read_b128 v[180:183], v225 offset:37888
	ds_read_b128 v[202:205], v225 offset:38912
	ds_read_b128 v[206:209], v225 offset:39936
	global_load_lds_dwordx4 v184, s[48:49]
	s_mov_b32 m0, s54
	s_nop 0
	global_load_lds_dwordx4 v188, s[48:49]
	s_waitcnt vmcnt(8)
	s_waitcnt lgkmcnt(0)
	s_barrier
	v_mfma_f32_16x16x32_bf16 v[140:143], v[96:99], v[160:163], v[140:143]
	v_mfma_f32_16x16x32_bf16 v[136:139], v[120:123], v[160:163], v[136:139]
	v_mfma_f32_16x16x32_bf16 v[116:119], v[96:99], v[168:171], v[116:119]
	v_mfma_f32_16x16x32_bf16 v[112:115], v[120:123], v[168:171], v[112:115]
	v_mfma_f32_16x16x32_bf16 v[92:95], v[96:99], v[176:179], v[92:95]
	v_mfma_f32_16x16x32_bf16 v[88:91], v[120:123], v[176:179], v[88:91]
	v_mfma_f32_16x16x32_bf16 v[76:79], v[96:99], v[202:205], v[76:79]
	v_mfma_f32_16x16x32_bf16 v[72:75], v[120:123], v[202:205], v[72:75]
	v_mfma_f32_16x16x32_bf16 v[140:143], v[108:111], v[164:167], v[140:143]
	v_mfma_f32_16x16x32_bf16 v[136:139], v[128:131], v[164:167], v[136:139]
	v_mfma_f32_16x16x32_bf16 v[116:119], v[108:111], v[172:175], v[116:119]
	v_mfma_f32_16x16x32_bf16 v[112:115], v[128:131], v[172:175], v[112:115]
	v_mfma_f32_16x16x32_bf16 v[92:95], v[108:111], v[180:183], v[92:95]
	v_mfma_f32_16x16x32_bf16 v[88:91], v[128:131], v[180:183], v[88:91]
	v_mfma_f32_16x16x32_bf16 v[76:79], v[108:111], v[206:209], v[76:79]
	v_mfma_f32_16x16x32_bf16 v[72:75], v[128:131], v[206:209], v[72:75]
	v_mfma_f32_16x16x32_bf16 v[132:135], v[144:147], v[160:163], v[132:135]
	v_mfma_f32_16x16x32_bf16 v[124:127], v[152:155], v[160:163], v[124:127]
	v_mfma_f32_16x16x32_bf16 v[104:107], v[144:147], v[168:171], v[104:107]
	v_mfma_f32_16x16x32_bf16 v[100:103], v[152:155], v[168:171], v[100:103]
	v_mfma_f32_16x16x32_bf16 v[84:87], v[144:147], v[176:179], v[84:87]
	v_mfma_f32_16x16x32_bf16 v[80:83], v[152:155], v[176:179], v[80:83]
	v_mfma_f32_16x16x32_bf16 v[68:71], v[144:147], v[202:205], v[68:71]
	v_mfma_f32_16x16x32_bf16 v[64:67], v[152:155], v[202:205], v[64:67]
	v_mfma_f32_16x16x32_bf16 v[132:135], v[148:151], v[164:167], v[132:135]
	v_mfma_f32_16x16x32_bf16 v[124:127], v[156:159], v[164:167], v[124:127]
	v_mfma_f32_16x16x32_bf16 v[104:107], v[148:151], v[172:175], v[104:107]
	v_mfma_f32_16x16x32_bf16 v[100:103], v[156:159], v[172:175], v[100:103]
	v_mfma_f32_16x16x32_bf16 v[84:87], v[148:151], v[180:183], v[84:87]
	v_mfma_f32_16x16x32_bf16 v[80:83], v[156:159], v[180:183], v[80:83]
	v_mfma_f32_16x16x32_bf16 v[68:71], v[148:151], v[206:209], v[68:71]
	v_mfma_f32_16x16x32_bf16 v[64:67], v[156:159], v[206:209], v[64:67]
	s_barrier
	s_add_i32 s48, s73, s50
	s_mov_b32 m0, s48
	ds_read_b128 v[160:163], v225 offset:49152
	ds_read_b128 v[164:167], v225 offset:50176
	ds_read_b128 v[168:171], v225 offset:51200
	ds_read_b128 v[172:175], v225 offset:52224
	ds_read_b128 v[176:179], v225 offset:53248
	ds_read_b128 v[180:183], v225 offset:54272
	ds_read_b128 v[202:205], v225 offset:55296
	ds_read_b128 v[206:209], v225 offset:56320
	global_load_lds_dwordx4 v186, s[98:99]
	s_add_i32 m0, s48, 0x2000
	s_add_u32 s34, s34, 0xb0080
	s_addc_u32 s35, s35, 0
	s_add_i32 s48, s74, s50
	global_load_lds_dwordx4 v190, s[98:99]
	s_mov_b32 m0, s48
	s_nop 0
	global_load_lds_dwordx4 v186, s[34:35]
	s_add_i32 m0, s48, 0x2000
	s_nop 0
	global_load_lds_dwordx4 v190, s[34:35]
	s_mov_b32 m0, s59
	s_nop 0
	global_load_lds_dwordx4 v184, s[100:101]
	s_mov_b32 m0, s60
	s_nop 0
	global_load_lds_dwordx4 v188, s[100:101]
	s_nop 0
	s_waitcnt vmcnt(8)
	s_waitcnt lgkmcnt(0)
	s_barrier
	v_mfma_f32_16x16x32_bf16 v[60:63], v[96:99], v[160:163], v[60:63]
	v_mfma_f32_16x16x32_bf16 v[56:59], v[120:123], v[160:163], v[56:59]
	v_mfma_f32_16x16x32_bf16 v[44:47], v[96:99], v[168:171], v[44:47]
	v_mfma_f32_16x16x32_bf16 v[40:43], v[120:123], v[168:171], v[40:43]
	v_mfma_f32_16x16x32_bf16 v[28:31], v[96:99], v[176:179], v[28:31]
	v_mfma_f32_16x16x32_bf16 v[24:27], v[120:123], v[176:179], v[24:27]
	v_mfma_f32_16x16x32_bf16 v[12:15], v[96:99], v[202:205], v[12:15]
	v_mfma_f32_16x16x32_bf16 v[8:11], v[120:123], v[202:205], v[8:11]
	v_mfma_f32_16x16x32_bf16 v[60:63], v[108:111], v[164:167], v[60:63]
	v_mfma_f32_16x16x32_bf16 v[56:59], v[128:131], v[164:167], v[56:59]
	v_mfma_f32_16x16x32_bf16 v[44:47], v[108:111], v[172:175], v[44:47]
	v_mfma_f32_16x16x32_bf16 v[40:43], v[128:131], v[172:175], v[40:43]
	v_mfma_f32_16x16x32_bf16 v[28:31], v[108:111], v[180:183], v[28:31]
	v_mfma_f32_16x16x32_bf16 v[24:27], v[128:131], v[180:183], v[24:27]
	v_mfma_f32_16x16x32_bf16 v[12:15], v[108:111], v[206:209], v[12:15]
	v_mfma_f32_16x16x32_bf16 v[8:11], v[128:131], v[206:209], v[8:11]
	v_mfma_f32_16x16x32_bf16 v[52:55], v[144:147], v[160:163], v[52:55]
	v_mfma_f32_16x16x32_bf16 v[48:51], v[152:155], v[160:163], v[48:51]
	v_mfma_f32_16x16x32_bf16 v[36:39], v[144:147], v[168:171], v[36:39]
	v_mfma_f32_16x16x32_bf16 v[32:35], v[152:155], v[168:171], v[32:35]
	v_mfma_f32_16x16x32_bf16 v[20:23], v[144:147], v[176:179], v[20:23]
	v_mfma_f32_16x16x32_bf16 v[16:19], v[152:155], v[176:179], v[16:19]
	v_mfma_f32_16x16x32_bf16 v[4:7], v[144:147], v[202:205], v[4:7]
	v_mfma_f32_16x16x32_bf16 v[0:3], v[152:155], v[202:205], v[0:3]
	v_mfma_f32_16x16x32_bf16 v[52:55], v[148:151], v[164:167], v[52:55]
	v_mfma_f32_16x16x32_bf16 v[48:51], v[156:159], v[164:167], v[48:51]
	v_mfma_f32_16x16x32_bf16 v[36:39], v[148:151], v[172:175], v[36:39]
	v_mfma_f32_16x16x32_bf16 v[32:35], v[156:159], v[172:175], v[32:35]
	v_mfma_f32_16x16x32_bf16 v[20:23], v[148:151], v[180:183], v[20:23]
	v_mfma_f32_16x16x32_bf16 v[16:19], v[156:159], v[180:183], v[16:19]
	v_mfma_f32_16x16x32_bf16 v[4:7], v[148:151], v[206:209], v[4:7]
	v_mfma_f32_16x16x32_bf16 v[0:3], v[156:159], v[206:209], v[0:3]
	s_barrier
	s_add_i32 s72, s72, 2
	s_add_u32 s20, s20, 0x100
	s_addc_u32 s21, s21, 0
	s_add_u32 s70, s70, 0x100
	s_addc_u32 s71, s71, 0
	s_cmp_gt_u32 s72, 41
	s_cbranch_scc0 .LBB0_895
	s_and_b64 vcc, exec, s[14:15]
	s_cbranch_vccz .LBB0_898
	s_barrier

; #define PG8_STAGE(bufoff, gbase, voff) do { _Pragma("unroll") for (int _i = 0; _i < 2; ++_i) \
;         __builtin_amdgcn_global_load_lds((const unsigned*)((const char*)(gbase) + (voff)[_i]), (PG8_LAS unsigned*)(lds + (bufoff) + ldsw + _i * 8192), 16, 0, 0); } while (0)
; #define PG8_LDA(dst, b, h) do { _Pragma("unroll") for (int m = 0; m < 4; ++m) _Pragma("unroll") for (int k = 0; k < 2; ++k) dst[m][k] = *(const PG8_LAS bf16x8*)(lds + PG8_SA(b, h) + aoff + m * 2048 + k * 1024); } while (0)
; #define PG8_LDB(dst, b, h) do { _Pragma("unroll") for (int n = 0; n < 2; ++n) _Pragma("unroll") for (int k = 0; k < 2; ++k) dst[n][k] = *(const PG8_LAS bf16x8*)(lds + PG8_SB(b, h) + boff + n * 2048 + k * 1024); } while (0)
; #define PG8_WAIT_V(n) asm volatile("s_waitcnt vmcnt(" #n ")" ::: "memory")
; #define PG8_WAIT_L(n) asm volatile("s_waitcnt lgkmcnt(" #n ")" ::: "memory")
; #define PG8_BAR __builtin_amdgcn_s_barrier()
; #define PG8_SCHED __builtin_amdgcn_sched_barrier(0)
; template <class Epi, class Sched, bool ALIGN_EPI = false, bool SP2 = false>
; __device__ __forceinline__ void gemm_phase(PG8_LAS unsigned char* lds, const Gemm g, const Sched& S, const Epi& E) {
;     ...
;         const bool has_next = S.next(ui + 1, nxt);
;         const char* nA = has_next ? (const char*)g.A + (size_t)nxt.pm * tstep : cA; const char* nB = has_next ? (const char*)g.Bt + (size_t)nxt.pn * tstep : cB;
;         for (int t = 0; t < nt; t += 2) {
;             const bool last = (t == nt - 2);
;             const char* a1 = cA + (size_t)(t + 1) * kstep;
;             const char* a2 = last ? nA : cA + (size_t)(t + 2) * kstep; const char* b2 = last ? nB : cB + (size_t)(t + 2) * kstep;
;             const char* a3 = a2 + kstep; const char* b3 = b2 + kstep;
;             if (last && has_next) S.a_ready(nxt);
;             if constexpr (SP2) {
;             PG8_LDB(B0, 0, 0); PG8_LDB(B1, 0, 1); PG8_SCHED; PG8_LDA(At, 0, 0); PG8_STAGE(PG8_SA(1, 1), a1 + hstep, voffA);
;             PG8_WAIT_V(8); PG8_WAIT_L(0); PG8_BAR; PG8_MMA(0, 0, At, B0); PG8_MMA(0, 1, At, B1); PG8_BAR; PG8_SCHED;
;             PG8_LDA(At, 0, 1); PG8_STAGE(PG8_SB(0, 0), b2, voffB); PG8_STAGE(PG8_SB(0, 1), b2 + hstep, voffB); PG8_STAGE(PG8_SA(0, 0), a2, voffA);
;             PG8_WAIT_V(8); PG8_WAIT_L(0); PG8_BAR; PG8_MMA(1, 0, At, B0); PG8_MMA(1, 1, At, B1); PG8_BAR; PG8_SCHED;
.LBB0_1199:
	s_ashr_i32 s57, s56, 31
	s_lshl_b64 s[58:59], s[56:57], 19
	s_add_u32 s58, s36, s58
	s_addc_u32 s59, s37, s59
	s_and_b64 s[60:61], s[8:9], exec
	s_cselect_b32 s1, s59, s21
	s_cselect_b32 s57, s58, s20
	s_ashr_i32 s55, s54, 31
	s_lshl_b64 s[60:61], s[54:55], 19
	s_add_u32 s60, s68, s60
	s_addc_u32 s61, s69, s61
	s_and_b64 s[62:63], s[8:9], exec
	s_cselect_b32 s55, s61, s35
	s_cselect_b32 s85, s60, s34
	s_add_u32 s20, s20, 0x40080
	s_addc_u32 s21, s21, 0
	s_add_u32 s86, s34, 0x100
	s_addc_u32 s87, s35, 0
	s_mov_b32 s88, -2
	s_waitcnt lgkmcnt(0)
	ds_read_b128 v[140:143], v163
	ds_read_b128 v[168:171], v163 offset:1024
	ds_read_b128 v[172:175], v163 offset:2048
	ds_read_b128 v[176:179], v163 offset:3072
	ds_read_b128 v[180:183], v164
	ds_read_b128 v[184:187], v164 offset:1024
	ds_read_b128 v[188:191], v164 offset:2048
	ds_read_b128 v[192:195], v164 offset:3072
	s_add_u32 s34, s20, 0xfffc0080
	s_addc_u32 s35, s21, -1
	s_cmp_eq_u32 s88, 12
	s_cselect_b32 s63, s1, s35
	s_cselect_b32 s62, s57, s34
	s_cselect_b32 s35, s55, s87
	s_cselect_b32 s34, s85, s86
	s_add_i32 m0, s71, 0xc000
	ds_read_b128 v[198:201], v165
	ds_read_b128 v[202:205], v165 offset:1024
	ds_read_b128 v[206:209], v165 offset:2048
	ds_read_b128 v[210:213], v165 offset:3072
	ds_read_b128 v[214:217], v165 offset:4096
	ds_read_b128 v[218:221], v165 offset:5120
	ds_read_b128 v[222:225], v165 offset:6144
	ds_read_b128 v[226:229], v165 offset:7168
	global_load_lds_dwordx4 v132, s[20:21]
	s_add_i32 m0, s71, 0xe000
	s_nop 0
	global_load_lds_dwordx4 v134, s[20:21]
	s_waitcnt vmcnt(8)
	s_waitcnt lgkmcnt(0)
	s_barrier
	v_mfma_f32_16x16x32_bf16 v[124:127], v[140:143], v[198:201], 0
	v_mfma_f32_16x16x32_bf16 v[120:123], v[172:175], v[198:201], 0
	v_mfma_f32_16x16x32_bf16 v[108:111], v[140:143], v[206:209], 0
	v_mfma_f32_16x16x32_bf16 v[104:107], v[172:175], v[206:209], 0
	v_mfma_f32_16x16x32_bf16 v[92:95], v[140:143], v[214:217], 0
	v_mfma_f32_16x16x32_bf16 v[88:91], v[172:175], v[214:217], 0
	v_mfma_f32_16x16x32_bf16 v[76:79], v[140:143], v[222:225], 0
	v_mfma_f32_16x16x32_bf16 v[72:75], v[172:175], v[222:225], 0
	v_mfma_f32_16x16x32_bf16 v[124:127], v[168:171], v[202:205], v[124:127]
	v_mfma_f32_16x16x32_bf16 v[120:123], v[176:179], v[202:205], v[120:123]
	v_mfma_f32_16x16x32_bf16 v[108:111], v[168:171], v[210:213], v[108:111]
	v_mfma_f32_16x16x32_bf16 v[104:107], v[176:179], v[210:213], v[104:107]
	v_mfma_f32_16x16x32_bf16 v[92:95], v[168:171], v[218:221], v[92:95]
	v_mfma_f32_16x16x32_bf16 v[88:91], v[176:179], v[218:221], v[88:91]
	v_mfma_f32_16x16x32_bf16 v[76:79], v[168:171], v[226:229], v[76:79]
	v_mfma_f32_16x16x32_bf16 v[72:75], v[176:179], v[226:229], v[72:75]
	v_mfma_f32_16x16x32_bf16 v[116:119], v[180:183], v[198:201], 0
	v_mfma_f32_16x16x32_bf16 v[112:115], v[188:191], v[198:201], 0
	v_mfma_f32_16x16x32_bf16 v[100:103], v[180:183], v[206:209], 0
	v_mfma_f32_16x16x32_bf16 v[96:99], v[188:191], v[206:209], 0
	v_mfma_f32_16x16x32_bf16 v[84:87], v[180:183], v[214:217], 0
	v_mfma_f32_16x16x32_bf16 v[80:83], v[188:191], v[214:217], 0
	v_mfma_f32_16x16x32_bf16 v[68:71], v[180:183], v[222:225], 0
	v_mfma_f32_16x16x32_bf16 v[64:67], v[188:191], v[222:225], 0
	v_mfma_f32_16x16x32_bf16 v[116:119], v[184:187], v[202:205], v[116:119]
	v_mfma_f32_16x16x32_bf16 v[112:115], v[192:195], v[202:205], v[112:115]
	v_mfma_f32_16x16x32_bf16 v[100:103], v[184:187], v[210:213], v[100:103]
	v_mfma_f32_16x16x32_bf16 v[96:99], v[192:195], v[210:213], v[96:99]
	v_mfma_f32_16x16x32_bf16 v[84:87], v[184:187], v[218:221], v[84:87]
	v_mfma_f32_16x16x32_bf16 v[80:83], v[192:195], v[218:221], v[80:83]
	v_mfma_f32_16x16x32_bf16 v[68:71], v[184:187], v[226:229], v[68:71]
	v_mfma_f32_16x16x32_bf16 v[64:67], v[192:195], v[226:229], v[64:67]
	s_barrier
	s_add_i32 s89, s77, s70
	s_add_u32 s98, s34, s18
	s_addc_u32 s99, s35, s19
	s_add_u32 s100, s62, s18
	s_addc_u32 s101, s63, s19
	s_mov_b32 m0, s89
	ds_read_b128 v[198:201], v165 offset:16384
	ds_read_b128 v[202:205], v165 offset:17408
	ds_read_b128 v[206:209], v165 offset:18432
	ds_read_b128 v[210:213], v165 offset:19456
	ds_read_b128 v[214:217], v165 offset:20480
	ds_read_b128 v[218:221], v165 offset:21504
	ds_read_b128 v[222:225], v165 offset:22528
	ds_read_b128 v[226:229], v165 offset:23552
	global_load_lds_dwordx4 v146, s[34:35]
	s_add_i32 m0, s89, 0x2000
	s_add_u32 s90, s34, 0x40000
	s_addc_u32 s91, s35, 0
	s_add_i32 s89, s78, s70
	global_load_lds_dwordx4 v150, s[34:35]
	s_mov_b32 m0, s89
	s_nop 0
	global_load_lds_dwordx4 v146, s[90:91]
	s_add_i32 m0, s89, 0x2000
	s_nop 0
	global_load_lds_dwordx4 v150, s[90:91]
	s_mov_b32 m0, s71
	s_nop 0
	global_load_lds_dwordx4 v144, s[62:63]
	s_mov_b32 m0, s72
	s_nop 0
	global_load_lds_dwordx4 v148, s[62:63]
	s_nop 0
	s_waitcnt vmcnt(8)
	s_waitcnt lgkmcnt(0)
	s_barrier
; #define PG8_STAGE(bufoff, gbase, voff) do { _Pragma("unroll") for (int _i = 0; _i < 2; ++_i) \
;         __builtin_amdgcn_global_load_lds((const unsigned*)((const char*)(gbase) + (voff)[_i]), (PG8_LAS unsigned*)(lds + (bufoff) + ldsw + _i * 8192), 16, 0, 0); } while (0)
; #define PG8_LDA(dst, b, h) do { _Pragma("unroll") for (int m = 0; m < 4; ++m) _Pragma("unroll") for (int k = 0; k < 2; ++k) dst[m][k] = *(const PG8_LAS bf16x8*)(lds + PG8_SA(b, h) + aoff + m * 2048 + k * 1024); } while (0)
; #define PG8_LDB(dst, b, h) do { _Pragma("unroll") for (int n = 0; n < 2; ++n) _Pragma("unroll") for (int k = 0; k < 2; ++k) dst[n][k] = *(const PG8_LAS bf16x8*)(lds + PG8_SB(b, h) + boff + n * 2048 + k * 1024); } while (0)
; #define PG8_MMA(ai, bj, At, Bt) do { __builtin_amdgcn_s_setprio(1); _Pragma("unroll") for (int m = 0; m < 4; ++m) _Pragma("unroll") for (int n = 0; n < 2; ++n) _Pragma("unroll") for (int k = 0; k < 2; ++k) \
;         acc[ai][bj][m][n] = __builtin_amdgcn_mfma_f32_16x16x32_bf16(Bt[n][k], At[m][k], acc[ai][bj][m][n], 0, 0, 0); __builtin_amdgcn_s_setprio(0); } while (0)
; #define PG8_WAIT_V(n) asm volatile("s_waitcnt vmcnt(" #n ")" ::: "memory")
; #define PG8_WAIT_L(n) asm volatile("s_waitcnt lgkmcnt(" #n ")" ::: "memory")
; #define PG8_BAR __builtin_amdgcn_s_barrier()
; #define PG8_SCHED __builtin_amdgcn_sched_barrier(0)
; template <class Epi, class Sched, bool ALIGN_EPI = false, bool SP2 = false>
; __device__ __forceinline__ void gemm_phase(PG8_LAS unsigned char* lds, const Gemm g, const Sched& S, const Epi& E) {
;     ...
;             PG8_WAIT_V(8); PG8_WAIT_L(0); PG8_BAR; PG8_MMA(1, 0, At, B0); PG8_MMA(1, 1, At, B1); PG8_BAR; PG8_SCHED;
;             PG8_LDB(B0, 1, 0); PG8_LDB(B1, 1, 1); PG8_SCHED; PG8_LDA(At, 1, 0); PG8_STAGE(PG8_SA(0, 1), a2 + hstep, voffA);
;             PG8_WAIT_V(8); PG8_WAIT_L(0); PG8_BAR; PG8_MMA(0, 0, At, B0); PG8_MMA(0, 1, At, B1); PG8_BAR; PG8_SCHED;
	v_mfma_f32_16x16x32_bf16 v[60:63], v[140:143], v[198:201], 0
	v_mfma_f32_16x16x32_bf16 v[56:59], v[172:175], v[198:201], 0
	v_mfma_f32_16x16x32_bf16 v[48:51], v[140:143], v[206:209], 0
	v_mfma_f32_16x16x32_bf16 v[40:43], v[172:175], v[206:209], 0
	v_mfma_f32_16x16x32_bf16 v[32:35], v[140:143], v[214:217], 0
	v_mfma_f32_16x16x32_bf16 v[24:27], v[172:175], v[214:217], 0
	v_mfma_f32_16x16x32_bf16 v[16:19], v[140:143], v[222:225], 0
	v_mfma_f32_16x16x32_bf16 v[8:11], v[172:175], v[222:225], 0
	v_mfma_f32_16x16x32_bf16 v[60:63], v[168:171], v[202:205], v[60:63]
	v_mfma_f32_16x16x32_bf16 v[56:59], v[176:179], v[202:205], v[56:59]
	v_mfma_f32_16x16x32_bf16 v[48:51], v[168:171], v[210:213], v[48:51]
	v_mfma_f32_16x16x32_bf16 v[40:43], v[176:179], v[210:213], v[40:43]
	v_mfma_f32_16x16x32_bf16 v[32:35], v[168:171], v[218:221], v[32:35]
	v_mfma_f32_16x16x32_bf16 v[24:27], v[176:179], v[218:221], v[24:27]
	v_mfma_f32_16x16x32_bf16 v[16:19], v[168:171], v[226:229], v[16:19]
	v_mfma_f32_16x16x32_bf16 v[8:11], v[176:179], v[226:229], v[8:11]
	v_mfma_f32_16x16x32_bf16 v[52:55], v[180:183], v[198:201], 0
	v_mfma_f32_16x16x32_bf16 v[44:47], v[188:191], v[198:201], 0
	v_mfma_f32_16x16x32_bf16 v[36:39], v[180:183], v[206:209], 0
	v_mfma_f32_16x16x32_bf16 v[28:31], v[188:191], v[206:209], 0
	v_mfma_f32_16x16x32_bf16 v[20:23], v[180:183], v[214:217], 0
	v_mfma_f32_16x16x32_bf16 v[12:15], v[188:191], v[214:217], 0
	v_mfma_f32_16x16x32_bf16 v[4:7], v[180:183], v[222:225], 0
	v_mfma_f32_16x16x32_bf16 v[0:3], v[188:191], v[222:225], 0
	v_mfma_f32_16x16x32_bf16 v[52:55], v[184:187], v[202:205], v[52:55]
	v_mfma_f32_16x16x32_bf16 v[44:47], v[192:195], v[202:205], v[44:47]
	v_mfma_f32_16x16x32_bf16 v[36:39], v[184:187], v[210:213], v[36:39]
	v_mfma_f32_16x16x32_bf16 v[28:31], v[192:195], v[210:213], v[28:31]
	v_mfma_f32_16x16x32_bf16 v[20:23], v[184:187], v[218:221], v[20:23]
	v_mfma_f32_16x16x32_bf16 v[12:15], v[192:195], v[218:221], v[12:15]
	v_mfma_f32_16x16x32_bf16 v[4:7], v[184:187], v[226:229], v[4:7]
	v_mfma_f32_16x16x32_bf16 v[0:3], v[192:195], v[226:229], v[0:3]
	s_barrier
	s_add_i32 s89, 0, 0x18000
	v_add_u32_e32 v128, s89, v161
	s_add_i32 s90, 0, 0x1c000
	ds_read_b128 v[140:143], v128
	ds_read_b128 v[168:171], v128 offset:1024
	ds_read_b128 v[172:175], v128 offset:2048
	ds_read_b128 v[176:179], v128 offset:3072
	v_add_u32_e32 v128, s90, v161
	ds_read_b128 v[180:183], v128
	ds_read_b128 v[184:187], v128 offset:1024
	ds_read_b128 v[188:191], v128 offset:2048
	ds_read_b128 v[192:195], v128 offset:3072
	s_add_u32 s62, s62, 0x40000
	s_addc_u32 s63, s63, 0
	s_mov_b32 m0, s73
	ds_read_b128 v[198:201], v165 offset:32768
	ds_read_b128 v[202:205], v165 offset:33792
	ds_read_b128 v[206:209], v165 offset:34816
	ds_read_b128 v[210:213], v165 offset:35840
	ds_read_b128 v[214:217], v165 offset:36864
	ds_read_b128 v[218:221], v165 offset:37888
	ds_read_b128 v[222:225], v165 offset:38912
	ds_read_b128 v[226:229], v165 offset:39936
	global_load_lds_dwordx4 v144, s[62:63]
	s_mov_b32 m0, s74
	s_nop 0
	global_load_lds_dwordx4 v148, s[62:63]
	s_waitcnt vmcnt(8)
	s_waitcnt lgkmcnt(0)
	s_barrier
	v_mfma_f32_16x16x32_bf16 v[124:127], v[140:143], v[198:201], v[124:127]
	v_mfma_f32_16x16x32_bf16 v[120:123], v[172:175], v[198:201], v[120:123]
	v_mfma_f32_16x16x32_bf16 v[108:111], v[140:143], v[206:209], v[108:111]
	v_mfma_f32_16x16x32_bf16 v[104:107], v[172:175], v[206:209], v[104:107]
	v_mfma_f32_16x16x32_bf16 v[92:95], v[140:143], v[214:217], v[92:95]
	v_mfma_f32_16x16x32_bf16 v[88:91], v[172:175], v[214:217], v[88:91]
	v_mfma_f32_16x16x32_bf16 v[76:79], v[140:143], v[222:225], v[76:79]
	v_mfma_f32_16x16x32_bf16 v[72:75], v[172:175], v[222:225], v[72:75]
	v_mfma_f32_16x16x32_bf16 v[124:127], v[168:171], v[202:205], v[124:127]
	v_mfma_f32_16x16x32_bf16 v[120:123], v[176:179], v[202:205], v[120:123]
	v_mfma_f32_16x16x32_bf16 v[108:111], v[168:171], v[210:213], v[108:111]
	v_mfma_f32_16x16x32_bf16 v[104:107], v[176:179], v[210:213], v[104:107]
	v_mfma_f32_16x16x32_bf16 v[92:95], v[168:171], v[218:221], v[92:95]
	v_mfma_f32_16x16x32_bf16 v[88:91], v[176:179], v[218:221], v[88:91]
	v_mfma_f32_16x16x32_bf16 v[76:79], v[168:171], v[226:229], v[76:79]
	v_mfma_f32_16x16x32_bf16 v[72:75], v[176:179], v[226:229], v[72:75]
	v_mfma_f32_16x16x32_bf16 v[116:119], v[180:183], v[198:201], v[116:119]
	v_mfma_f32_16x16x32_bf16 v[112:115], v[188:191], v[198:201], v[112:115]
	v_mfma_f32_16x16x32_bf16 v[100:103], v[180:183], v[206:209], v[100:103]
	v_mfma_f32_16x16x32_bf16 v[96:99], v[188:191], v[206:209], v[96:99]
	v_mfma_f32_16x16x32_bf16 v[84:87], v[180:183], v[214:217], v[84:87]
	v_mfma_f32_16x16x32_bf16 v[80:83], v[188:191], v[214:217], v[80:83]
	v_mfma_f32_16x16x32_bf16 v[68:71], v[180:183], v[222:225], v[68:71]
	v_mfma_f32_16x16x32_bf16 v[64:67], v[188:191], v[222:225], v[64:67]
	v_mfma_f32_16x16x32_bf16 v[116:119], v[184:187], v[202:205], v[116:119]
	v_mfma_f32_16x16x32_bf16 v[112:115], v[192:195], v[202:205], v[112:115]
	v_mfma_f32_16x16x32_bf16 v[100:103], v[184:187], v[210:213], v[100:103]
	v_mfma_f32_16x16x32_bf16 v[96:99], v[192:195], v[210:213], v[96:99]
	v_mfma_f32_16x16x32_bf16 v[84:87], v[184:187], v[218:221], v[84:87]
	v_mfma_f32_16x16x32_bf16 v[80:83], v[192:195], v[218:221], v[80:83]
	v_mfma_f32_16x16x32_bf16 v[68:71], v[184:187], v[226:229], v[68:71]
	v_mfma_f32_16x16x32_bf16 v[64:67], v[192:195], v[226:229], v[64:67]
	s_barrier
; #define PG8_STAGE(bufoff, gbase, voff) do { _Pragma("unroll") for (int _i = 0; _i < 2; ++_i) \
;         __builtin_amdgcn_global_load_lds((const unsigned*)((const char*)(gbase) + (voff)[_i]), (PG8_LAS unsigned*)(lds + (bufoff) + ldsw + _i * 8192), 16, 0, 0); } while (0)
; #define PG8_LDA(dst, b, h) do { _Pragma("unroll") for (int m = 0; m < 4; ++m) _Pragma("unroll") for (int k = 0; k < 2; ++k) dst[m][k] = *(const PG8_LAS bf16x8*)(lds + PG8_SA(b, h) + aoff + m * 2048 + k * 1024); } while (0)
; #define PG8_LDB(dst, b, h) do { _Pragma("unroll") for (int n = 0; n < 2; ++n) _Pragma("unroll") for (int k = 0; k < 2; ++k) dst[n][k] = *(const PG8_LAS bf16x8*)(lds + PG8_SB(b, h) + boff + n * 2048 + k * 1024); } while (0)
; #define PG8_MMA(ai, bj, At, Bt) do { __builtin_amdgcn_s_setprio(1); _Pragma("unroll") for (int m = 0; m < 4; ++m) _Pragma("unroll") for (int n = 0; n < 2; ++n) _Pragma("unroll") for (int k = 0; k < 2; ++k) \
;         acc[ai][bj][m][n] = __builtin_amdgcn_mfma_f32_16x16x32_bf16(Bt[n][k], At[m][k], acc[ai][bj][m][n], 0, 0, 0); __builtin_amdgcn_s_setprio(0); } while (0)
; #define PG8_WAIT_V(n) asm volatile("s_waitcnt vmcnt(" #n ")" ::: "memory")
; template <class Epi, class Sched, bool ALIGN_EPI = false, bool SP2 = false>
; __device__ __forceinline__ void gemm_phase(PG8_LAS unsigned char* lds, const Gemm g, const Sched& S, const Epi& E) {
;     ...
;             PG8_LDB(B0, 0, 0); PG8_LDB(B1, 0, 1); PG8_SCHED; PG8_LDA(At, 0, 0); PG8_STAGE(PG8_SA(1, 1), a1 + hstep, voffA);
;             PG8_WAIT_V(8); PG8_WAIT_L(0); PG8_BAR; PG8_MMA(0, 0, At, B0); PG8_MMA(0, 1, At, B1); PG8_BAR; PG8_SCHED;
;             PG8_LDA(At, 0, 1); PG8_STAGE(PG8_SB(0, 0), b2, voffB); PG8_STAGE(PG8_SB(0, 1), b2 + hstep, voffB); PG8_STAGE(PG8_SA(0, 0), a2, voffA);
;             PG8_WAIT_V(8); PG8_WAIT_L(0); PG8_BAR; PG8_MMA(1, 0, At, B0); PG8_MMA(1, 1, At, B1); PG8_BAR; PG8_SCHED;
;             PG8_LDB(B0, 1, 0); PG8_LDB(B1, 1, 1); PG8_SCHED; PG8_LDA(At, 1, 0); PG8_STAGE(PG8_SA(0, 1), a2 + hstep, voffA);
;             PG8_WAIT_V(8); PG8_WAIT_L(0); PG8_BAR; PG8_MMA(0, 0, At, B0); PG8_MMA(0, 1, At, B1); PG8_BAR; PG8_SCHED;
;             PG8_LDA(At, 1, 1); PG8_STAGE(PG8_SB(1, 0), b3, voffB); PG8_STAGE(PG8_SB(1, 1), b3 + hstep, voffB); PG8_STAGE(PG8_SA(1, 0), a3, voffA);
;             PG8_WAIT_V(8); PG8_WAIT_L(0); PG8_BAR; PG8_MMA(1, 0, At, B0); PG8_MMA(1, 1, At, B1); PG8_BAR; PG8_SCHED;
	s_add_i32 s62, s89, s70
	s_mov_b32 m0, s62
	ds_read_b128 v[198:201], v165 offset:49152
	ds_read_b128 v[202:205], v165 offset:50176
	ds_read_b128 v[206:209], v165 offset:51200
	ds_read_b128 v[210:213], v165 offset:52224
	ds_read_b128 v[214:217], v165 offset:53248
	ds_read_b128 v[218:221], v165 offset:54272
	ds_read_b128 v[222:225], v165 offset:55296
	ds_read_b128 v[226:229], v165 offset:56320
	global_load_lds_dwordx4 v146, s[98:99]
	s_add_i32 m0, s62, 0x2000
	s_add_u32 s34, s34, 0x40080
	s_addc_u32 s35, s35, 0
	s_add_i32 s62, s90, s70
	global_load_lds_dwordx4 v150, s[98:99]
	s_mov_b32 m0, s62
	s_nop 0
	global_load_lds_dwordx4 v146, s[34:35]
	s_add_i32 m0, s62, 0x2000
	s_nop 0
	global_load_lds_dwordx4 v150, s[34:35]
	s_mov_b32 m0, s75
	s_nop 0
	global_load_lds_dwordx4 v144, s[100:101]
	s_mov_b32 m0, s76
	s_nop 0
	global_load_lds_dwordx4 v148, s[100:101]
	s_nop 0
	s_waitcnt vmcnt(8)
	s_waitcnt lgkmcnt(0)
	s_barrier
	v_mfma_f32_16x16x32_bf16 v[60:63], v[140:143], v[198:201], v[60:63]
	v_mfma_f32_16x16x32_bf16 v[56:59], v[172:175], v[198:201], v[56:59]
	v_mfma_f32_16x16x32_bf16 v[48:51], v[140:143], v[206:209], v[48:51]
	v_mfma_f32_16x16x32_bf16 v[40:43], v[172:175], v[206:209], v[40:43]
	v_mfma_f32_16x16x32_bf16 v[32:35], v[140:143], v[214:217], v[32:35]
	v_mfma_f32_16x16x32_bf16 v[24:27], v[172:175], v[214:217], v[24:27]
	v_mfma_f32_16x16x32_bf16 v[16:19], v[140:143], v[222:225], v[16:19]
	v_mfma_f32_16x16x32_bf16 v[8:11], v[172:175], v[222:225], v[8:11]
	v_mfma_f32_16x16x32_bf16 v[60:63], v[168:171], v[202:205], v[60:63]
	v_mfma_f32_16x16x32_bf16 v[56:59], v[176:179], v[202:205], v[56:59]
	v_mfma_f32_16x16x32_bf16 v[48:51], v[168:171], v[210:213], v[48:51]
	v_mfma_f32_16x16x32_bf16 v[40:43], v[176:179], v[210:213], v[40:43]
	v_mfma_f32_16x16x32_bf16 v[32:35], v[168:171], v[218:221], v[32:35]
	v_mfma_f32_16x16x32_bf16 v[24:27], v[176:179], v[218:221], v[24:27]
	v_mfma_f32_16x16x32_bf16 v[16:19], v[168:171], v[226:229], v[16:19]
	v_mfma_f32_16x16x32_bf16 v[8:11], v[176:179], v[226:229], v[8:11]
	v_mfma_f32_16x16x32_bf16 v[52:55], v[180:183], v[198:201], v[52:55]
	v_mfma_f32_16x16x32_bf16 v[44:47], v[188:191], v[198:201], v[44:47]
	v_mfma_f32_16x16x32_bf16 v[36:39], v[180:183], v[206:209], v[36:39]
	v_mfma_f32_16x16x32_bf16 v[28:31], v[188:191], v[206:209], v[28:31]
	v_mfma_f32_16x16x32_bf16 v[20:23], v[180:183], v[214:217], v[20:23]
	v_mfma_f32_16x16x32_bf16 v[12:15], v[188:191], v[214:217], v[12:15]
	v_mfma_f32_16x16x32_bf16 v[4:7], v[180:183], v[222:225], v[4:7]
	v_mfma_f32_16x16x32_bf16 v[0:3], v[188:191], v[222:225], v[0:3]
	v_mfma_f32_16x16x32_bf16 v[52:55], v[184:187], v[202:205], v[52:55]
	v_mfma_f32_16x16x32_bf16 v[44:47], v[192:195], v[202:205], v[44:47]
	v_mfma_f32_16x16x32_bf16 v[36:39], v[184:187], v[210:213], v[36:39]
	v_mfma_f32_16x16x32_bf16 v[28:31], v[192:195], v[210:213], v[28:31]
	v_mfma_f32_16x16x32_bf16 v[20:23], v[184:187], v[218:221], v[20:23]
	v_mfma_f32_16x16x32_bf16 v[12:15], v[192:195], v[218:221], v[12:15]
	v_mfma_f32_16x16x32_bf16 v[4:7], v[184:187], v[226:229], v[4:7]
	v_mfma_f32_16x16x32_bf16 v[0:3], v[192:195], v[226:229], v[0:3]
	s_barrier
	s_add_i32 s88, s88, 2
	s_add_u32 s20, s20, 0x100
	s_addc_u32 s21, s21, 0
	s_add_u32 s86, s86, 0x100
	s_addc_u32 s87, s87, 0
	s_cmp_gt_u32 s88, 13
.LBB0_1200:
	ds_read_b128 v[140:143], v163
	ds_read_b128 v[168:171], v163 offset:1024
	ds_read_b128 v[172:175], v163 offset:2048
	ds_read_b128 v[176:179], v163 offset:3072
	ds_read_b128 v[180:183], v164
	ds_read_b128 v[184:187], v164 offset:1024
	ds_read_b128 v[188:191], v164 offset:2048
	ds_read_b128 v[192:195], v164 offset:3072
	s_add_u32 s34, s20, 0xfffc0080
	s_addc_u32 s35, s21, -1
	s_cmp_eq_u32 s88, 12
	s_cselect_b32 s63, s1, s35
	s_cselect_b32 s62, s57, s34
	s_cselect_b32 s35, s55, s87
	s_cselect_b32 s34, s85, s86
	s_add_i32 m0, s71, 0xc000
	ds_read_b128 v[198:201], v165
	ds_read_b128 v[202:205], v165 offset:1024
	ds_read_b128 v[206:209], v165 offset:2048
	ds_read_b128 v[210:213], v165 offset:3072
	ds_read_b128 v[214:217], v165 offset:4096
	ds_read_b128 v[218:221], v165 offset:5120
	ds_read_b128 v[222:225], v165 offset:6144
	ds_read_b128 v[226:229], v165 offset:7168
	global_load_lds_dwordx4 v132, s[20:21]
	s_add_i32 m0, s71, 0xe000
	s_nop 0
	global_load_lds_dwordx4 v134, s[20:21]
	s_nop 0
	s_waitcnt vmcnt(8)
	s_waitcnt lgkmcnt(0)
	s_barrier
	v_mfma_f32_16x16x32_bf16 v[124:127], v[140:143], v[198:201], v[124:127]
	v_mfma_f32_16x16x32_bf16 v[120:123], v[172:175], v[198:201], v[120:123]
	v_mfma_f32_16x16x32_bf16 v[108:111], v[140:143], v[206:209], v[108:111]
	v_mfma_f32_16x16x32_bf16 v[104:107], v[172:175], v[206:209], v[104:107]
	v_mfma_f32_16x16x32_bf16 v[92:95], v[140:143], v[214:217], v[92:95]
	v_mfma_f32_16x16x32_bf16 v[88:91], v[172:175], v[214:217], v[88:91]
	v_mfma_f32_16x16x32_bf16 v[76:79], v[140:143], v[222:225], v[76:79]
	v_mfma_f32_16x16x32_bf16 v[72:75], v[172:175], v[222:225], v[72:75]
	v_mfma_f32_16x16x32_bf16 v[124:127], v[168:171], v[202:205], v[124:127]
	v_mfma_f32_16x16x32_bf16 v[120:123], v[176:179], v[202:205], v[120:123]
	v_mfma_f32_16x16x32_bf16 v[108:111], v[168:171], v[210:213], v[108:111]
	v_mfma_f32_16x16x32_bf16 v[104:107], v[176:179], v[210:213], v[104:107]
	v_mfma_f32_16x16x32_bf16 v[92:95], v[168:171], v[218:221], v[92:95]
	v_mfma_f32_16x16x32_bf16 v[88:91], v[176:179], v[218:221], v[88:91]
	v_mfma_f32_16x16x32_bf16 v[76:79], v[168:171], v[226:229], v[76:79]
	v_mfma_f32_16x16x32_bf16 v[72:75], v[176:179], v[226:229], v[72:75]
	v_mfma_f32_16x16x32_bf16 v[116:119], v[180:183], v[198:201], v[116:119]
	v_mfma_f32_16x16x32_bf16 v[112:115], v[188:191], v[198:201], v[112:115]
	v_mfma_f32_16x16x32_bf16 v[100:103], v[180:183], v[206:209], v[100:103]
	v_mfma_f32_16x16x32_bf16 v[96:99], v[188:191], v[206:209], v[96:99]
	v_mfma_f32_16x16x32_bf16 v[84:87], v[180:183], v[214:217], v[84:87]
	v_mfma_f32_16x16x32_bf16 v[80:83], v[188:191], v[214:217], v[80:83]
	v_mfma_f32_16x16x32_bf16 v[68:71], v[180:183], v[222:225], v[68:71]
	v_mfma_f32_16x16x32_bf16 v[64:67], v[188:191], v[222:225], v[64:67]
	v_mfma_f32_16x16x32_bf16 v[116:119], v[184:187], v[202:205], v[116:119]
	v_mfma_f32_16x16x32_bf16 v[112:115], v[192:195], v[202:205], v[112:115]
	v_mfma_f32_16x16x32_bf16 v[100:103], v[184:187], v[210:213], v[100:103]
	v_mfma_f32_16x16x32_bf16 v[96:99], v[192:195], v[210:213], v[96:99]
	v_mfma_f32_16x16x32_bf16 v[84:87], v[184:187], v[218:221], v[84:87]
	v_mfma_f32_16x16x32_bf16 v[80:83], v[192:195], v[218:221], v[80:83]
	v_mfma_f32_16x16x32_bf16 v[68:71], v[184:187], v[226:229], v[68:71]
	v_mfma_f32_16x16x32_bf16 v[64:67], v[192:195], v[226:229], v[64:67]
	s_barrier
; #define PG8_STAGE(bufoff, gbase, voff) do { _Pragma("unroll") for (int _i = 0; _i < 2; ++_i) \
;         __builtin_amdgcn_global_load_lds((const unsigned*)((const char*)(gbase) + (voff)[_i]), (PG8_LAS unsigned*)(lds + (bufoff) + ldsw + _i * 8192), 16, 0, 0); } while (0)
; #define PG8_LDA(dst, b, h) do { _Pragma("unroll") for (int m = 0; m < 4; ++m) _Pragma("unroll") for (int k = 0; k < 2; ++k) dst[m][k] = *(const PG8_LAS bf16x8*)(lds + PG8_SA(b, h) + aoff + m * 2048 + k * 1024); } while (0)
; #define PG8_LDB(dst, b, h) do { _Pragma("unroll") for (int n = 0; n < 2; ++n) _Pragma("unroll") for (int k = 0; k < 2; ++k) dst[n][k] = *(const PG8_LAS bf16x8*)(lds + PG8_SB(b, h) + boff + n * 2048 + k * 1024); } while (0)
; #define PG8_MMA(ai, bj, At, Bt) do { __builtin_amdgcn_s_setprio(1); _Pragma("unroll") for (int m = 0; m < 4; ++m) _Pragma("unroll") for (int n = 0; n < 2; ++n) _Pragma("unroll") for (int k = 0; k < 2; ++k) \
;         acc[ai][bj][m][n] = __builtin_amdgcn_mfma_f32_16x16x32_bf16(Bt[n][k], At[m][k], acc[ai][bj][m][n], 0, 0, 0); __builtin_amdgcn_s_setprio(0); } while (0)
; #define PG8_WAIT_V(n) asm volatile("s_waitcnt vmcnt(" #n ")" ::: "memory")
; #define PG8_WAIT_L(n) asm volatile("s_waitcnt lgkmcnt(" #n ")" ::: "memory")
; #define PG8_BAR __builtin_amdgcn_s_barrier()
; #define PG8_SCHED __builtin_amdgcn_sched_barrier(0)
; template <class Epi, class Sched, bool ALIGN_EPI = false, bool SP2 = false>
; __device__ __forceinline__ void gemm_phase(PG8_LAS unsigned char* lds, const Gemm g, const Sched& S, const Epi& E) {
;     ...
;             PG8_LDA(At, 0, 1); PG8_STAGE(PG8_SB(0, 0), b2, voffB); PG8_STAGE(PG8_SB(0, 1), b2 + hstep, voffB); PG8_STAGE(PG8_SA(0, 0), a2, voffA);
;             PG8_WAIT_V(8); PG8_WAIT_L(0); PG8_BAR; PG8_MMA(1, 0, At, B0); PG8_MMA(1, 1, At, B1); PG8_BAR; PG8_SCHED;
;             PG8_LDB(B0, 1, 0); PG8_LDB(B1, 1, 1); PG8_SCHED; PG8_LDA(At, 1, 0); PG8_STAGE(PG8_SA(0, 1), a2 + hstep, voffA);
;             PG8_WAIT_V(8); PG8_WAIT_L(0); PG8_BAR; PG8_MMA(0, 0, At, B0); PG8_MMA(0, 1, At, B1); PG8_BAR; PG8_SCHED;
	s_add_i32 s89, s77, s70
	s_add_u32 s98, s34, s18
	s_addc_u32 s99, s35, s19
	s_add_u32 s100, s62, s18
	s_addc_u32 s101, s63, s19
	s_mov_b32 m0, s89
	ds_read_b128 v[198:201], v165 offset:16384
	ds_read_b128 v[202:205], v165 offset:17408
	ds_read_b128 v[206:209], v165 offset:18432
	ds_read_b128 v[210:213], v165 offset:19456
	ds_read_b128 v[214:217], v165 offset:20480
	ds_read_b128 v[218:221], v165 offset:21504
	ds_read_b128 v[222:225], v165 offset:22528
	ds_read_b128 v[226:229], v165 offset:23552
	global_load_lds_dwordx4 v146, s[34:35]
	s_add_i32 m0, s89, 0x2000
	s_add_u32 s90, s34, 0x40000
	s_addc_u32 s91, s35, 0
	s_add_i32 s89, s78, s70
	global_load_lds_dwordx4 v150, s[34:35]
	s_mov_b32 m0, s89
	s_nop 0
	global_load_lds_dwordx4 v146, s[90:91]
	s_add_i32 m0, s89, 0x2000
	s_nop 0
	global_load_lds_dwordx4 v150, s[90:91]
	s_mov_b32 m0, s71
	s_nop 0
	global_load_lds_dwordx4 v144, s[62:63]
	s_mov_b32 m0, s72
	s_nop 0
	global_load_lds_dwordx4 v148, s[62:63]
	s_nop 0
	s_waitcnt vmcnt(8)
	s_waitcnt lgkmcnt(0)
	s_barrier
	v_mfma_f32_16x16x32_bf16 v[60:63], v[140:143], v[198:201], v[60:63]
	v_mfma_f32_16x16x32_bf16 v[56:59], v[172:175], v[198:201], v[56:59]
	v_mfma_f32_16x16x32_bf16 v[48:51], v[140:143], v[206:209], v[48:51]
	v_mfma_f32_16x16x32_bf16 v[40:43], v[172:175], v[206:209], v[40:43]
	v_mfma_f32_16x16x32_bf16 v[32:35], v[140:143], v[214:217], v[32:35]
	v_mfma_f32_16x16x32_bf16 v[24:27], v[172:175], v[214:217], v[24:27]
	v_mfma_f32_16x16x32_bf16 v[16:19], v[140:143], v[222:225], v[16:19]
	v_mfma_f32_16x16x32_bf16 v[8:11], v[172:175], v[222:225], v[8:11]
	v_mfma_f32_16x16x32_bf16 v[60:63], v[168:171], v[202:205], v[60:63]
	v_mfma_f32_16x16x32_bf16 v[56:59], v[176:179], v[202:205], v[56:59]
	v_mfma_f32_16x16x32_bf16 v[48:51], v[168:171], v[210:213], v[48:51]
	v_mfma_f32_16x16x32_bf16 v[40:43], v[176:179], v[210:213], v[40:43]
	v_mfma_f32_16x16x32_bf16 v[32:35], v[168:171], v[218:221], v[32:35]
	v_mfma_f32_16x16x32_bf16 v[24:27], v[176:179], v[218:221], v[24:27]
	v_mfma_f32_16x16x32_bf16 v[16:19], v[168:171], v[226:229], v[16:19]
	v_mfma_f32_16x16x32_bf16 v[8:11], v[176:179], v[226:229], v[8:11]
	v_mfma_f32_16x16x32_bf16 v[52:55], v[180:183], v[198:201], v[52:55]
	v_mfma_f32_16x16x32_bf16 v[44:47], v[188:191], v[198:201], v[44:47]
	v_mfma_f32_16x16x32_bf16 v[36:39], v[180:183], v[206:209], v[36:39]
	v_mfma_f32_16x16x32_bf16 v[28:31], v[188:191], v[206:209], v[28:31]
	v_mfma_f32_16x16x32_bf16 v[20:23], v[180:183], v[214:217], v[20:23]
	v_mfma_f32_16x16x32_bf16 v[12:15], v[188:191], v[214:217], v[12:15]
	v_mfma_f32_16x16x32_bf16 v[4:7], v[180:183], v[222:225], v[4:7]
	v_mfma_f32_16x16x32_bf16 v[0:3], v[188:191], v[222:225], v[0:3]
	v_mfma_f32_16x16x32_bf16 v[52:55], v[184:187], v[202:205], v[52:55]
	v_mfma_f32_16x16x32_bf16 v[44:47], v[192:195], v[202:205], v[44:47]
	v_mfma_f32_16x16x32_bf16 v[36:39], v[184:187], v[210:213], v[36:39]
	v_mfma_f32_16x16x32_bf16 v[28:31], v[192:195], v[210:213], v[28:31]
	v_mfma_f32_16x16x32_bf16 v[20:23], v[184:187], v[218:221], v[20:23]
	v_mfma_f32_16x16x32_bf16 v[12:15], v[192:195], v[218:221], v[12:15]
	v_mfma_f32_16x16x32_bf16 v[4:7], v[184:187], v[226:229], v[4:7]
	v_mfma_f32_16x16x32_bf16 v[0:3], v[192:195], v[226:229], v[0:3]
	s_barrier
	s_add_i32 s89, 0, 0x18000
	v_add_u32_e32 v128, s89, v161
	s_add_i32 s90, 0, 0x1c000
	ds_read_b128 v[140:143], v128
	ds_read_b128 v[168:171], v128 offset:1024
	ds_read_b128 v[172:175], v128 offset:2048
	ds_read_b128 v[176:179], v128 offset:3072
	v_add_u32_e32 v128, s90, v161
	ds_read_b128 v[180:183], v128
	ds_read_b128 v[184:187], v128 offset:1024
	ds_read_b128 v[188:191], v128 offset:2048
	ds_read_b128 v[192:195], v128 offset:3072
	s_add_u32 s62, s62, 0x40000
	s_addc_u32 s63, s63, 0
	s_mov_b32 m0, s73
	ds_read_b128 v[198:201], v165 offset:32768
	ds_read_b128 v[202:205], v165 offset:33792
	ds_read_b128 v[206:209], v165 offset:34816
	ds_read_b128 v[210:213], v165 offset:35840
	ds_read_b128 v[214:217], v165 offset:36864
	ds_read_b128 v[218:221], v165 offset:37888
	ds_read_b128 v[222:225], v165 offset:38912
	ds_read_b128 v[226:229], v165 offset:39936
	global_load_lds_dwordx4 v144, s[62:63]
	s_mov_b32 m0, s74
	s_nop 0
	global_load_lds_dwordx4 v148, s[62:63]
	s_waitcnt vmcnt(8)
	s_waitcnt lgkmcnt(0)
	s_barrier
; #define PG8_STAGE(bufoff, gbase, voff) do { _Pragma("unroll") for (int _i = 0; _i < 2; ++_i) \
;         __builtin_amdgcn_global_load_lds((const unsigned*)((const char*)(gbase) + (voff)[_i]), (PG8_LAS unsigned*)(lds + (bufoff) + ldsw + _i * 8192), 16, 0, 0); } while (0)
; #define PG8_LDA(dst, b, h) do { _Pragma("unroll") for (int m = 0; m < 4; ++m) _Pragma("unroll") for (int k = 0; k < 2; ++k) dst[m][k] = *(const PG8_LAS bf16x8*)(lds + PG8_SA(b, h) + aoff + m * 2048 + k * 1024); } while (0)
; #define PG8_MMA(ai, bj, At, Bt) do { __builtin_amdgcn_s_setprio(1); _Pragma("unroll") for (int m = 0; m < 4; ++m) _Pragma("unroll") for (int n = 0; n < 2; ++n) _Pragma("unroll") for (int k = 0; k < 2; ++k) \
;         acc[ai][bj][m][n] = __builtin_amdgcn_mfma_f32_16x16x32_bf16(Bt[n][k], At[m][k], acc[ai][bj][m][n], 0, 0, 0); __builtin_amdgcn_s_setprio(0); } while (0)
; #define PG8_WAIT_V(n) asm volatile("s_waitcnt vmcnt(" #n ")" ::: "memory")
; #define PG8_WAIT_L(n) asm volatile("s_waitcnt lgkmcnt(" #n ")" ::: "memory")
; #define PG8_BAR __builtin_amdgcn_s_barrier()
; #define PG8_SCHED __builtin_amdgcn_sched_barrier(0)
; template <class Epi, class Sched, bool ALIGN_EPI = false, bool SP2 = false>
; __device__ __forceinline__ void gemm_phase(PG8_LAS unsigned char* lds, const Gemm g, const Sched& S, const Epi& E) {
;     ...
;             PG8_WAIT_V(8); PG8_WAIT_L(0); PG8_BAR; PG8_MMA(0, 0, At, B0); PG8_MMA(0, 1, At, B1); PG8_BAR; PG8_SCHED;
;             PG8_LDA(At, 1, 1); PG8_STAGE(PG8_SB(1, 0), b3, voffB); PG8_STAGE(PG8_SB(1, 1), b3 + hstep, voffB); PG8_STAGE(PG8_SA(1, 0), a3, voffA);
;             PG8_WAIT_V(8); PG8_WAIT_L(0); PG8_BAR; PG8_MMA(1, 0, At, B0); PG8_MMA(1, 1, At, B1); PG8_BAR; PG8_SCHED;
;     ...
;         if constexpr (ALIGN_EPI) { if (wr == 0) PG8_BAR; }
	v_mfma_f32_16x16x32_bf16 v[124:127], v[140:143], v[198:201], v[124:127]
	v_mfma_f32_16x16x32_bf16 v[120:123], v[172:175], v[198:201], v[120:123]
	v_mfma_f32_16x16x32_bf16 v[108:111], v[140:143], v[206:209], v[108:111]
	v_mfma_f32_16x16x32_bf16 v[104:107], v[172:175], v[206:209], v[104:107]
	v_mfma_f32_16x16x32_bf16 v[92:95], v[140:143], v[214:217], v[92:95]
	v_mfma_f32_16x16x32_bf16 v[88:91], v[172:175], v[214:217], v[88:91]
	v_mfma_f32_16x16x32_bf16 v[76:79], v[140:143], v[222:225], v[76:79]
	v_mfma_f32_16x16x32_bf16 v[72:75], v[172:175], v[222:225], v[72:75]
	v_mfma_f32_16x16x32_bf16 v[124:127], v[168:171], v[202:205], v[124:127]
	v_mfma_f32_16x16x32_bf16 v[120:123], v[176:179], v[202:205], v[120:123]
	v_mfma_f32_16x16x32_bf16 v[108:111], v[168:171], v[210:213], v[108:111]
	v_mfma_f32_16x16x32_bf16 v[104:107], v[176:179], v[210:213], v[104:107]
	v_mfma_f32_16x16x32_bf16 v[92:95], v[168:171], v[218:221], v[92:95]
	v_mfma_f32_16x16x32_bf16 v[88:91], v[176:179], v[218:221], v[88:91]
	v_mfma_f32_16x16x32_bf16 v[76:79], v[168:171], v[226:229], v[76:79]
	v_mfma_f32_16x16x32_bf16 v[72:75], v[176:179], v[226:229], v[72:75]
	v_mfma_f32_16x16x32_bf16 v[116:119], v[180:183], v[198:201], v[116:119]
	v_mfma_f32_16x16x32_bf16 v[112:115], v[188:191], v[198:201], v[112:115]
	v_mfma_f32_16x16x32_bf16 v[100:103], v[180:183], v[206:209], v[100:103]
	v_mfma_f32_16x16x32_bf16 v[96:99], v[188:191], v[206:209], v[96:99]
	v_mfma_f32_16x16x32_bf16 v[84:87], v[180:183], v[214:217], v[84:87]
	v_mfma_f32_16x16x32_bf16 v[80:83], v[188:191], v[214:217], v[80:83]
	v_mfma_f32_16x16x32_bf16 v[68:71], v[180:183], v[222:225], v[68:71]
	v_mfma_f32_16x16x32_bf16 v[64:67], v[188:191], v[222:225], v[64:67]
	v_mfma_f32_16x16x32_bf16 v[116:119], v[184:187], v[202:205], v[116:119]
	v_mfma_f32_16x16x32_bf16 v[112:115], v[192:195], v[202:205], v[112:115]
	v_mfma_f32_16x16x32_bf16 v[100:103], v[184:187], v[210:213], v[100:103]
	v_mfma_f32_16x16x32_bf16 v[96:99], v[192:195], v[210:213], v[96:99]
	v_mfma_f32_16x16x32_bf16 v[84:87], v[184:187], v[218:221], v[84:87]
	v_mfma_f32_16x16x32_bf16 v[80:83], v[192:195], v[218:221], v[80:83]
	v_mfma_f32_16x16x32_bf16 v[68:71], v[184:187], v[226:229], v[68:71]
	v_mfma_f32_16x16x32_bf16 v[64:67], v[192:195], v[226:229], v[64:67]
	s_barrier
	s_add_i32 s62, s89, s70
	s_mov_b32 m0, s62
	ds_read_b128 v[198:201], v165 offset:49152
	ds_read_b128 v[202:205], v165 offset:50176
	ds_read_b128 v[206:209], v165 offset:51200
	ds_read_b128 v[210:213], v165 offset:52224
	ds_read_b128 v[214:217], v165 offset:53248
	ds_read_b128 v[218:221], v165 offset:54272
	ds_read_b128 v[222:225], v165 offset:55296
	ds_read_b128 v[226:229], v165 offset:56320
	global_load_lds_dwordx4 v146, s[98:99]
	s_add_i32 m0, s62, 0x2000
	s_add_u32 s34, s34, 0x40080
	s_addc_u32 s35, s35, 0
	s_add_i32 s62, s90, s70
	global_load_lds_dwordx4 v150, s[98:99]
	s_mov_b32 m0, s62
	s_nop 0
	global_load_lds_dwordx4 v146, s[34:35]
	s_add_i32 m0, s62, 0x2000
	s_nop 0
	global_load_lds_dwordx4 v150, s[34:35]
	s_mov_b32 m0, s75
	s_nop 0
	global_load_lds_dwordx4 v144, s[100:101]
	s_mov_b32 m0, s76
	s_nop 0
	global_load_lds_dwordx4 v148, s[100:101]
	s_nop 0
	s_waitcnt vmcnt(8)
	s_waitcnt lgkmcnt(0)
	s_barrier
	v_mfma_f32_16x16x32_bf16 v[60:63], v[140:143], v[198:201], v[60:63]
	v_mfma_f32_16x16x32_bf16 v[56:59], v[172:175], v[198:201], v[56:59]
	v_mfma_f32_16x16x32_bf16 v[48:51], v[140:143], v[206:209], v[48:51]
	v_mfma_f32_16x16x32_bf16 v[40:43], v[172:175], v[206:209], v[40:43]
	v_mfma_f32_16x16x32_bf16 v[32:35], v[140:143], v[214:217], v[32:35]
	v_mfma_f32_16x16x32_bf16 v[24:27], v[172:175], v[214:217], v[24:27]
	v_mfma_f32_16x16x32_bf16 v[16:19], v[140:143], v[222:225], v[16:19]
	v_mfma_f32_16x16x32_bf16 v[8:11], v[172:175], v[222:225], v[8:11]
	v_mfma_f32_16x16x32_bf16 v[60:63], v[168:171], v[202:205], v[60:63]
	v_mfma_f32_16x16x32_bf16 v[56:59], v[176:179], v[202:205], v[56:59]
	v_mfma_f32_16x16x32_bf16 v[48:51], v[168:171], v[210:213], v[48:51]
	v_mfma_f32_16x16x32_bf16 v[40:43], v[176:179], v[210:213], v[40:43]
	v_mfma_f32_16x16x32_bf16 v[32:35], v[168:171], v[218:221], v[32:35]
	v_mfma_f32_16x16x32_bf16 v[24:27], v[176:179], v[218:221], v[24:27]
	v_mfma_f32_16x16x32_bf16 v[16:19], v[168:171], v[226:229], v[16:19]
	v_mfma_f32_16x16x32_bf16 v[8:11], v[176:179], v[226:229], v[8:11]
	v_mfma_f32_16x16x32_bf16 v[52:55], v[180:183], v[198:201], v[52:55]
	v_mfma_f32_16x16x32_bf16 v[44:47], v[188:191], v[198:201], v[44:47]
	v_mfma_f32_16x16x32_bf16 v[36:39], v[180:183], v[206:209], v[36:39]
	v_mfma_f32_16x16x32_bf16 v[28:31], v[188:191], v[206:209], v[28:31]
	v_mfma_f32_16x16x32_bf16 v[20:23], v[180:183], v[214:217], v[20:23]
	v_mfma_f32_16x16x32_bf16 v[12:15], v[188:191], v[214:217], v[12:15]
	v_mfma_f32_16x16x32_bf16 v[4:7], v[180:183], v[222:225], v[4:7]
	v_mfma_f32_16x16x32_bf16 v[0:3], v[188:191], v[222:225], v[0:3]
	v_mfma_f32_16x16x32_bf16 v[52:55], v[184:187], v[202:205], v[52:55]
	v_mfma_f32_16x16x32_bf16 v[44:47], v[192:195], v[202:205], v[44:47]
	v_mfma_f32_16x16x32_bf16 v[36:39], v[184:187], v[210:213], v[36:39]
	v_mfma_f32_16x16x32_bf16 v[28:31], v[192:195], v[210:213], v[28:31]
	v_mfma_f32_16x16x32_bf16 v[20:23], v[184:187], v[218:221], v[20:23]
	v_mfma_f32_16x16x32_bf16 v[12:15], v[192:195], v[218:221], v[12:15]
	v_mfma_f32_16x16x32_bf16 v[4:7], v[184:187], v[226:229], v[4:7]
	v_mfma_f32_16x16x32_bf16 v[0:3], v[192:195], v[226:229], v[0:3]
	s_barrier
	s_add_i32 s88, s88, 2
	s_add_u32 s20, s20, 0x100
	s_addc_u32 s21, s21, 0
	s_add_u32 s86, s86, 0x100
	s_addc_u32 s87, s87, 0
	s_cmp_gt_u32 s88, 13
	s_cbranch_scc0 .LBB0_1200
	s_and_b64 vcc, exec, s[38:39]
	s_cbranch_vccz .LBB0_1203
	s_barrier

; #define PG8_STAGE(bufoff, gbase, voff) do { _Pragma("unroll") for (int _i = 0; _i < 2; ++_i) \
;         __builtin_amdgcn_global_load_lds((const unsigned*)((const char*)(gbase) + (voff)[_i]), (PG8_LAS unsigned*)(lds + (bufoff) + ldsw + _i * 8192), 16, 0, 0); } while (0)
; #define PG8_LDA(dst, b, h) do { _Pragma("unroll") for (int m = 0; m < 4; ++m) _Pragma("unroll") for (int k = 0; k < 2; ++k) dst[m][k] = *(const PG8_LAS bf16x8*)(lds + PG8_SA(b, h) + aoff + m * 2048 + k * 1024); } while (0)
; #define PG8_LDB(dst, b, h) do { _Pragma("unroll") for (int n = 0; n < 2; ++n) _Pragma("unroll") for (int k = 0; k < 2; ++k) dst[n][k] = *(const PG8_LAS bf16x8*)(lds + PG8_SB(b, h) + boff + n * 2048 + k * 1024); } while (0)
; #define PG8_WAIT_V(n) asm volatile("s_waitcnt vmcnt(" #n ")" ::: "memory")
; #define PG8_WAIT_L(n) asm volatile("s_waitcnt lgkmcnt(" #n ")" ::: "memory")
; #define PG8_BAR __builtin_amdgcn_s_barrier()
; #define PG8_SCHED __builtin_amdgcn_sched_barrier(0)
; template <class Epi, class Sched, bool ALIGN_EPI = false, bool SP2 = false>
; __device__ __forceinline__ void gemm_phase(PG8_LAS unsigned char* lds, const Gemm g, const Sched& S, const Epi& E) {
;     ...
;         const bool has_next = S.next(ui + 1, nxt);
;         const char* nA = has_next ? (const char*)g.A + (size_t)nxt.pm * tstep : cA; const char* nB = has_next ? (const char*)g.Bt + (size_t)nxt.pn * tstep : cB;
;         for (int t = 0; t < nt; t += 2) {
;             const bool last = (t == nt - 2);
;             const char* a1 = cA + (size_t)(t + 1) * kstep;
;             const char* a2 = last ? nA : cA + (size_t)(t + 2) * kstep; const char* b2 = last ? nB : cB + (size_t)(t + 2) * kstep;
;             const char* a3 = a2 + kstep; const char* b3 = b2 + kstep;
;             if (last && has_next) S.a_ready(nxt);
;             if constexpr (SP2) {
;             PG8_LDB(B0, 0, 0); PG8_LDB(B1, 0, 1); PG8_SCHED; PG8_LDA(At, 0, 0); PG8_STAGE(PG8_SA(1, 1), a1 + hstep, voffA);
;             PG8_WAIT_V(8); PG8_WAIT_L(0); PG8_BAR; PG8_MMA(0, 0, At, B0); PG8_MMA(0, 1, At, B1); PG8_BAR; PG8_SCHED;
;             PG8_LDA(At, 0, 1); PG8_STAGE(PG8_SB(0, 0), b2, voffB); PG8_STAGE(PG8_SB(0, 1), b2 + hstep, voffB); PG8_STAGE(PG8_SA(0, 0), a2, voffA);
;             PG8_WAIT_V(8); PG8_WAIT_L(0); PG8_BAR; PG8_MMA(1, 0, At, B0); PG8_MMA(1, 1, At, B1); PG8_BAR; PG8_SCHED;
.LBB0_1445:
	s_ashr_i32 s15, s14, 31
	s_lshl_b64 s[16:17], s[14:15], 19
	s_add_u32 s16, s49, s16
	s_addc_u32 s17, s50, s17
	s_and_b64 s[18:19], s[4:5], exec
	s_cselect_b32 s15, s17, s21
	s_cselect_b32 s65, s16, s20
	s_ashr_i32 s13, s12, 31
	s_lshl_b64 s[18:19], s[12:13], 19
	s_add_u32 s18, s36, s18
	s_addc_u32 s19, s37, s19
	s_and_b64 s[44:45], s[4:5], exec
	s_cselect_b32 s13, s19, s39
	s_cselect_b32 s66, s18, s38
	s_add_u32 s20, s20, 0x40080
	s_addc_u32 s21, s21, 0
	s_add_u32 s67, s38, 0x100
	s_addc_u32 s68, s39, 0
	s_mov_b32 s69, -2
	ds_read_b128 v[128:131], v153
	ds_read_b128 v[132:135], v153 offset:1024
	ds_read_b128 v[136:139], v153 offset:2048
	ds_read_b128 v[140:143], v153 offset:3072
	ds_read_b128 v[172:175], v155
	ds_read_b128 v[176:179], v155 offset:1024
	ds_read_b128 v[180:183], v155 offset:2048
	ds_read_b128 v[184:187], v155 offset:3072
	s_add_u32 s38, s20, 0xfffc0080
	s_addc_u32 s39, s21, -1
	s_cmp_eq_u32 s69, 12
	s_cselect_b32 s45, s15, s39
	s_cselect_b32 s44, s65, s38
	s_cselect_b32 s39, s13, s68
	s_cselect_b32 s38, s66, s67
	s_add_i32 m0, s35, 0xc000
	ds_read_b128 v[188:191], v157
	ds_read_b128 v[192:195], v157 offset:1024
	ds_read_b128 v[198:201], v157 offset:2048
	ds_read_b128 v[202:205], v157 offset:3072
	ds_read_b128 v[206:209], v157 offset:4096
	ds_read_b128 v[210:213], v157 offset:5120
	ds_read_b128 v[214:217], v157 offset:6144
	ds_read_b128 v[218:221], v157 offset:7168
	global_load_lds_dwordx4 v162, s[20:21]
	s_add_i32 m0, s35, 0xe000
	s_nop 0
	global_load_lds_dwordx4 v164, s[20:21]
	s_nop 0
	s_waitcnt vmcnt(8)
	s_waitcnt lgkmcnt(0)
	s_barrier
	v_mfma_f32_16x16x32_bf16 v[124:127], v[128:131], v[188:191], 0
	v_mfma_f32_16x16x32_bf16 v[120:123], v[136:139], v[188:191], 0
	v_mfma_f32_16x16x32_bf16 v[108:111], v[128:131], v[198:201], 0
	v_mfma_f32_16x16x32_bf16 v[104:107], v[136:139], v[198:201], 0
	v_mfma_f32_16x16x32_bf16 v[96:99], v[128:131], v[206:209], 0
	v_mfma_f32_16x16x32_bf16 v[88:91], v[136:139], v[206:209], 0
	v_mfma_f32_16x16x32_bf16 v[80:83], v[128:131], v[214:217], 0
	v_mfma_f32_16x16x32_bf16 v[72:75], v[136:139], v[214:217], 0
	v_mfma_f32_16x16x32_bf16 v[124:127], v[132:135], v[192:195], v[124:127]
	v_mfma_f32_16x16x32_bf16 v[120:123], v[140:143], v[192:195], v[120:123]
	v_mfma_f32_16x16x32_bf16 v[108:111], v[132:135], v[202:205], v[108:111]
	v_mfma_f32_16x16x32_bf16 v[104:107], v[140:143], v[202:205], v[104:107]
	v_mfma_f32_16x16x32_bf16 v[96:99], v[132:135], v[210:213], v[96:99]
	v_mfma_f32_16x16x32_bf16 v[88:91], v[140:143], v[210:213], v[88:91]
	v_mfma_f32_16x16x32_bf16 v[80:83], v[132:135], v[218:221], v[80:83]
	v_mfma_f32_16x16x32_bf16 v[72:75], v[140:143], v[218:221], v[72:75]
	v_mfma_f32_16x16x32_bf16 v[116:119], v[172:175], v[188:191], 0
	v_mfma_f32_16x16x32_bf16 v[112:115], v[180:183], v[188:191], 0
	v_mfma_f32_16x16x32_bf16 v[100:103], v[172:175], v[198:201], 0
	v_mfma_f32_16x16x32_bf16 v[92:95], v[180:183], v[198:201], 0
	v_mfma_f32_16x16x32_bf16 v[84:87], v[172:175], v[206:209], 0
	v_mfma_f32_16x16x32_bf16 v[76:79], v[180:183], v[206:209], 0
	v_mfma_f32_16x16x32_bf16 v[68:71], v[172:175], v[214:217], 0
	v_mfma_f32_16x16x32_bf16 v[64:67], v[180:183], v[214:217], 0
	v_mfma_f32_16x16x32_bf16 v[116:119], v[176:179], v[192:195], v[116:119]
	v_mfma_f32_16x16x32_bf16 v[112:115], v[184:187], v[192:195], v[112:115]
	v_mfma_f32_16x16x32_bf16 v[100:103], v[176:179], v[202:205], v[100:103]
	v_mfma_f32_16x16x32_bf16 v[92:95], v[184:187], v[202:205], v[92:95]
	v_mfma_f32_16x16x32_bf16 v[84:87], v[176:179], v[210:213], v[84:87]
	v_mfma_f32_16x16x32_bf16 v[76:79], v[184:187], v[210:213], v[76:79]
	v_mfma_f32_16x16x32_bf16 v[68:71], v[176:179], v[218:221], v[68:71]
	v_mfma_f32_16x16x32_bf16 v[64:67], v[184:187], v[218:221], v[64:67]
	s_barrier
	s_add_i32 s70, s60, s51
	s_add_u32 s98, s38, s6
	s_addc_u32 s99, s39, s7
	s_add_u32 s100, s44, s6
	s_addc_u32 s101, s45, s7
	s_mov_b32 m0, s70
	ds_read_b128 v[188:191], v157 offset:16384
	ds_read_b128 v[192:195], v157 offset:17408
	ds_read_b128 v[198:201], v157 offset:18432
	ds_read_b128 v[202:205], v157 offset:19456
	ds_read_b128 v[206:209], v157 offset:20480
	ds_read_b128 v[210:213], v157 offset:21504
	ds_read_b128 v[214:217], v157 offset:22528
	ds_read_b128 v[218:221], v157 offset:23552
	global_load_lds_dwordx4 v146, s[38:39]
	s_add_i32 m0, s70, 0x2000
	s_add_u32 s70, s38, 0x40000
	s_addc_u32 s71, s39, 0
	s_add_i32 s72, s61, s51
	global_load_lds_dwordx4 v150, s[38:39]
	s_mov_b32 m0, s72
	s_nop 0
	global_load_lds_dwordx4 v146, s[70:71]
	s_add_i32 m0, s72, 0x2000
	s_nop 0
	global_load_lds_dwordx4 v150, s[70:71]
	s_mov_b32 m0, s35
	s_nop 0
	global_load_lds_dwordx4 v144, s[44:45]
	s_mov_b32 m0, s52
	s_nop 0
	global_load_lds_dwordx4 v148, s[44:45]
	s_nop 0
	s_waitcnt vmcnt(8)
	s_waitcnt lgkmcnt(0)
	s_barrier
; #define PG8_STAGE(bufoff, gbase, voff) do { _Pragma("unroll") for (int _i = 0; _i < 2; ++_i) \
;         __builtin_amdgcn_global_load_lds((const unsigned*)((const char*)(gbase) + (voff)[_i]), (PG8_LAS unsigned*)(lds + (bufoff) + ldsw + _i * 8192), 16, 0, 0); } while (0)
; #define PG8_LDA(dst, b, h) do { _Pragma("unroll") for (int m = 0; m < 4; ++m) _Pragma("unroll") for (int k = 0; k < 2; ++k) dst[m][k] = *(const PG8_LAS bf16x8*)(lds + PG8_SA(b, h) + aoff + m * 2048 + k * 1024); } while (0)
; #define PG8_LDB(dst, b, h) do { _Pragma("unroll") for (int n = 0; n < 2; ++n) _Pragma("unroll") for (int k = 0; k < 2; ++k) dst[n][k] = *(const PG8_LAS bf16x8*)(lds + PG8_SB(b, h) + boff + n * 2048 + k * 1024); } while (0)
; #define PG8_MMA(ai, bj, At, Bt) do { __builtin_amdgcn_s_setprio(1); _Pragma("unroll") for (int m = 0; m < 4; ++m) _Pragma("unroll") for (int n = 0; n < 2; ++n) _Pragma("unroll") for (int k = 0; k < 2; ++k) \
;         acc[ai][bj][m][n] = __builtin_amdgcn_mfma_f32_16x16x32_bf16(Bt[n][k], At[m][k], acc[ai][bj][m][n], 0, 0, 0); __builtin_amdgcn_s_setprio(0); } while (0)
; #define PG8_WAIT_V(n) asm volatile("s_waitcnt vmcnt(" #n ")" ::: "memory")
; #define PG8_WAIT_L(n) asm volatile("s_waitcnt lgkmcnt(" #n ")" ::: "memory")
; #define PG8_BAR __builtin_amdgcn_s_barrier()
; #define PG8_SCHED __builtin_amdgcn_sched_barrier(0)
; template <class Epi, class Sched, bool ALIGN_EPI = false, bool SP2 = false>
; __device__ __forceinline__ void gemm_phase(PG8_LAS unsigned char* lds, const Gemm g, const Sched& S, const Epi& E) {
;     ...
;             PG8_WAIT_V(8); PG8_WAIT_L(0); PG8_BAR; PG8_MMA(1, 0, At, B0); PG8_MMA(1, 1, At, B1); PG8_BAR; PG8_SCHED;
;             PG8_LDB(B0, 1, 0); PG8_LDB(B1, 1, 1); PG8_SCHED; PG8_LDA(At, 1, 0); PG8_STAGE(PG8_SA(0, 1), a2 + hstep, voffA);
;             PG8_WAIT_V(8); PG8_WAIT_L(0); PG8_BAR; PG8_MMA(0, 0, At, B0); PG8_MMA(0, 1, At, B1); PG8_BAR; PG8_SCHED;
	v_mfma_f32_16x16x32_bf16 v[60:63], v[128:131], v[188:191], 0
	v_mfma_f32_16x16x32_bf16 v[56:59], v[136:139], v[188:191], 0
	v_mfma_f32_16x16x32_bf16 v[48:51], v[128:131], v[198:201], 0
	v_mfma_f32_16x16x32_bf16 v[40:43], v[136:139], v[198:201], 0
	v_mfma_f32_16x16x32_bf16 v[32:35], v[128:131], v[206:209], 0
	v_mfma_f32_16x16x32_bf16 v[24:27], v[136:139], v[206:209], 0
	v_mfma_f32_16x16x32_bf16 v[16:19], v[128:131], v[214:217], 0
	v_mfma_f32_16x16x32_bf16 v[8:11], v[136:139], v[214:217], 0
	v_mfma_f32_16x16x32_bf16 v[60:63], v[132:135], v[192:195], v[60:63]
	v_mfma_f32_16x16x32_bf16 v[56:59], v[140:143], v[192:195], v[56:59]
	v_mfma_f32_16x16x32_bf16 v[48:51], v[132:135], v[202:205], v[48:51]
	v_mfma_f32_16x16x32_bf16 v[40:43], v[140:143], v[202:205], v[40:43]
	v_mfma_f32_16x16x32_bf16 v[32:35], v[132:135], v[210:213], v[32:35]
	v_mfma_f32_16x16x32_bf16 v[24:27], v[140:143], v[210:213], v[24:27]
	v_mfma_f32_16x16x32_bf16 v[16:19], v[132:135], v[218:221], v[16:19]
	v_mfma_f32_16x16x32_bf16 v[8:11], v[140:143], v[218:221], v[8:11]
	v_mfma_f32_16x16x32_bf16 v[52:55], v[172:175], v[188:191], 0
	v_mfma_f32_16x16x32_bf16 v[44:47], v[180:183], v[188:191], 0
	v_mfma_f32_16x16x32_bf16 v[36:39], v[172:175], v[198:201], 0
	v_mfma_f32_16x16x32_bf16 v[28:31], v[180:183], v[198:201], 0
	v_mfma_f32_16x16x32_bf16 v[20:23], v[172:175], v[206:209], 0
	v_mfma_f32_16x16x32_bf16 v[12:15], v[180:183], v[206:209], 0
	v_mfma_f32_16x16x32_bf16 v[4:7], v[172:175], v[214:217], 0
	v_mfma_f32_16x16x32_bf16 v[0:3], v[180:183], v[214:217], 0
	v_mfma_f32_16x16x32_bf16 v[52:55], v[176:179], v[192:195], v[52:55]
	v_mfma_f32_16x16x32_bf16 v[44:47], v[184:187], v[192:195], v[44:47]
	v_mfma_f32_16x16x32_bf16 v[36:39], v[176:179], v[202:205], v[36:39]
	v_mfma_f32_16x16x32_bf16 v[28:31], v[184:187], v[202:205], v[28:31]
	v_mfma_f32_16x16x32_bf16 v[20:23], v[176:179], v[210:213], v[20:23]
	v_mfma_f32_16x16x32_bf16 v[12:15], v[184:187], v[210:213], v[12:15]
	v_mfma_f32_16x16x32_bf16 v[4:7], v[176:179], v[218:221], v[4:7]
	v_mfma_f32_16x16x32_bf16 v[0:3], v[184:187], v[218:221], v[0:3]
	s_barrier
	s_add_i32 s70, 0, 0x18000
	s_add_i32 s71, 0, 0x1c000
	v_add_u32_e32 v140, s70, v170
	v_add_u32_e32 v159, s71, v170
	ds_read_b128 v[128:131], v140
	ds_read_b128 v[132:135], v140 offset:1024
	ds_read_b128 v[136:139], v140 offset:2048
	ds_read_b128 v[140:143], v140 offset:3072
	ds_read_b128 v[172:175], v159
	ds_read_b128 v[176:179], v159 offset:1024
	ds_read_b128 v[180:183], v159 offset:2048
	ds_read_b128 v[184:187], v159 offset:3072
	s_add_u32 s44, s44, 0x40000
	s_addc_u32 s45, s45, 0
	s_mov_b32 m0, s53
	ds_read_b128 v[188:191], v157 offset:32768
	ds_read_b128 v[192:195], v157 offset:33792
	ds_read_b128 v[198:201], v157 offset:34816
	ds_read_b128 v[202:205], v157 offset:35840
	ds_read_b128 v[206:209], v157 offset:36864
	ds_read_b128 v[210:213], v157 offset:37888
	ds_read_b128 v[214:217], v157 offset:38912
	ds_read_b128 v[218:221], v157 offset:39936
	global_load_lds_dwordx4 v144, s[44:45]
	s_mov_b32 m0, s54
	s_nop 0
	global_load_lds_dwordx4 v148, s[44:45]
	s_waitcnt vmcnt(8)
	s_waitcnt lgkmcnt(0)
	s_barrier
	v_mfma_f32_16x16x32_bf16 v[124:127], v[128:131], v[188:191], v[124:127]
	v_mfma_f32_16x16x32_bf16 v[120:123], v[136:139], v[188:191], v[120:123]
	v_mfma_f32_16x16x32_bf16 v[108:111], v[128:131], v[198:201], v[108:111]
	v_mfma_f32_16x16x32_bf16 v[104:107], v[136:139], v[198:201], v[104:107]
	v_mfma_f32_16x16x32_bf16 v[96:99], v[128:131], v[206:209], v[96:99]
	v_mfma_f32_16x16x32_bf16 v[88:91], v[136:139], v[206:209], v[88:91]
	v_mfma_f32_16x16x32_bf16 v[80:83], v[128:131], v[214:217], v[80:83]
	v_mfma_f32_16x16x32_bf16 v[72:75], v[136:139], v[214:217], v[72:75]
	v_mfma_f32_16x16x32_bf16 v[124:127], v[132:135], v[192:195], v[124:127]
	v_mfma_f32_16x16x32_bf16 v[120:123], v[140:143], v[192:195], v[120:123]
	v_mfma_f32_16x16x32_bf16 v[108:111], v[132:135], v[202:205], v[108:111]
	v_mfma_f32_16x16x32_bf16 v[104:107], v[140:143], v[202:205], v[104:107]
	v_mfma_f32_16x16x32_bf16 v[96:99], v[132:135], v[210:213], v[96:99]
	v_mfma_f32_16x16x32_bf16 v[88:91], v[140:143], v[210:213], v[88:91]
	v_mfma_f32_16x16x32_bf16 v[80:83], v[132:135], v[218:221], v[80:83]
	v_mfma_f32_16x16x32_bf16 v[72:75], v[140:143], v[218:221], v[72:75]
	v_mfma_f32_16x16x32_bf16 v[116:119], v[172:175], v[188:191], v[116:119]
	v_mfma_f32_16x16x32_bf16 v[112:115], v[180:183], v[188:191], v[112:115]
	v_mfma_f32_16x16x32_bf16 v[100:103], v[172:175], v[198:201], v[100:103]
	v_mfma_f32_16x16x32_bf16 v[92:95], v[180:183], v[198:201], v[92:95]
	v_mfma_f32_16x16x32_bf16 v[84:87], v[172:175], v[206:209], v[84:87]
	v_mfma_f32_16x16x32_bf16 v[76:79], v[180:183], v[206:209], v[76:79]
	v_mfma_f32_16x16x32_bf16 v[68:71], v[172:175], v[214:217], v[68:71]
	v_mfma_f32_16x16x32_bf16 v[64:67], v[180:183], v[214:217], v[64:67]
	v_mfma_f32_16x16x32_bf16 v[116:119], v[176:179], v[192:195], v[116:119]
	v_mfma_f32_16x16x32_bf16 v[112:115], v[184:187], v[192:195], v[112:115]
	v_mfma_f32_16x16x32_bf16 v[100:103], v[176:179], v[202:205], v[100:103]
	v_mfma_f32_16x16x32_bf16 v[92:95], v[184:187], v[202:205], v[92:95]
	v_mfma_f32_16x16x32_bf16 v[84:87], v[176:179], v[210:213], v[84:87]
	v_mfma_f32_16x16x32_bf16 v[76:79], v[184:187], v[210:213], v[76:79]
	v_mfma_f32_16x16x32_bf16 v[68:71], v[176:179], v[218:221], v[68:71]
	v_mfma_f32_16x16x32_bf16 v[64:67], v[184:187], v[218:221], v[64:67]
	s_barrier
; #define PG8_STAGE(bufoff, gbase, voff) do { _Pragma("unroll") for (int _i = 0; _i < 2; ++_i) \
;         __builtin_amdgcn_global_load_lds((const unsigned*)((const char*)(gbase) + (voff)[_i]), (PG8_LAS unsigned*)(lds + (bufoff) + ldsw + _i * 8192), 16, 0, 0); } while (0)
; #define PG8_LDA(dst, b, h) do { _Pragma("unroll") for (int m = 0; m < 4; ++m) _Pragma("unroll") for (int k = 0; k < 2; ++k) dst[m][k] = *(const PG8_LAS bf16x8*)(lds + PG8_SA(b, h) + aoff + m * 2048 + k * 1024); } while (0)
; #define PG8_LDB(dst, b, h) do { _Pragma("unroll") for (int n = 0; n < 2; ++n) _Pragma("unroll") for (int k = 0; k < 2; ++k) dst[n][k] = *(const PG8_LAS bf16x8*)(lds + PG8_SB(b, h) + boff + n * 2048 + k * 1024); } while (0)
; #define PG8_MMA(ai, bj, At, Bt) do { __builtin_amdgcn_s_setprio(1); _Pragma("unroll") for (int m = 0; m < 4; ++m) _Pragma("unroll") for (int n = 0; n < 2; ++n) _Pragma("unroll") for (int k = 0; k < 2; ++k) \
;         acc[ai][bj][m][n] = __builtin_amdgcn_mfma_f32_16x16x32_bf16(Bt[n][k], At[m][k], acc[ai][bj][m][n], 0, 0, 0); __builtin_amdgcn_s_setprio(0); } while (0)
; #define PG8_WAIT_V(n) asm volatile("s_waitcnt vmcnt(" #n ")" ::: "memory")
; template <class Epi, class Sched, bool ALIGN_EPI = false, bool SP2 = false>
; __device__ __forceinline__ void gemm_phase(PG8_LAS unsigned char* lds, const Gemm g, const Sched& S, const Epi& E) {
;     ...
;             PG8_LDB(B0, 0, 0); PG8_LDB(B1, 0, 1); PG8_SCHED; PG8_LDA(At, 0, 0); PG8_STAGE(PG8_SA(1, 1), a1 + hstep, voffA);
;             PG8_WAIT_V(8); PG8_WAIT_L(0); PG8_BAR; PG8_MMA(0, 0, At, B0); PG8_MMA(0, 1, At, B1); PG8_BAR; PG8_SCHED;
;             PG8_LDA(At, 0, 1); PG8_STAGE(PG8_SB(0, 0), b2, voffB); PG8_STAGE(PG8_SB(0, 1), b2 + hstep, voffB); PG8_STAGE(PG8_SA(0, 0), a2, voffA);
;             PG8_WAIT_V(8); PG8_WAIT_L(0); PG8_BAR; PG8_MMA(1, 0, At, B0); PG8_MMA(1, 1, At, B1); PG8_BAR; PG8_SCHED;
;             PG8_LDB(B0, 1, 0); PG8_LDB(B1, 1, 1); PG8_SCHED; PG8_LDA(At, 1, 0); PG8_STAGE(PG8_SA(0, 1), a2 + hstep, voffA);
;             PG8_WAIT_V(8); PG8_WAIT_L(0); PG8_BAR; PG8_MMA(0, 0, At, B0); PG8_MMA(0, 1, At, B1); PG8_BAR; PG8_SCHED;
;             PG8_LDA(At, 1, 1); PG8_STAGE(PG8_SB(1, 0), b3, voffB); PG8_STAGE(PG8_SB(1, 1), b3 + hstep, voffB); PG8_STAGE(PG8_SA(1, 0), a3, voffA);
;             PG8_WAIT_V(8); PG8_WAIT_L(0); PG8_BAR; PG8_MMA(1, 0, At, B0); PG8_MMA(1, 1, At, B1); PG8_BAR; PG8_SCHED;
	s_add_i32 s44, s70, s51
	s_mov_b32 m0, s44
	ds_read_b128 v[188:191], v157 offset:49152
	ds_read_b128 v[192:195], v157 offset:50176
	ds_read_b128 v[198:201], v157 offset:51200
	ds_read_b128 v[202:205], v157 offset:52224
	ds_read_b128 v[206:209], v157 offset:53248
	ds_read_b128 v[210:213], v157 offset:54272
	ds_read_b128 v[214:217], v157 offset:55296
	ds_read_b128 v[218:221], v157 offset:56320
	global_load_lds_dwordx4 v146, s[98:99]
	s_add_i32 m0, s44, 0x2000
	s_add_u32 s38, s38, 0x40080
	s_addc_u32 s39, s39, 0
	s_add_i32 s44, s71, s51
	global_load_lds_dwordx4 v150, s[98:99]
	s_mov_b32 m0, s44
	s_nop 0
	global_load_lds_dwordx4 v146, s[38:39]
	s_add_i32 m0, s44, 0x2000
	s_nop 0
	global_load_lds_dwordx4 v150, s[38:39]
	s_mov_b32 m0, s58
	s_nop 0
	global_load_lds_dwordx4 v144, s[100:101]
	s_mov_b32 m0, s59
	s_nop 0
	global_load_lds_dwordx4 v148, s[100:101]
	s_nop 0
	s_waitcnt vmcnt(8)
	s_waitcnt lgkmcnt(0)
	s_barrier
	v_mfma_f32_16x16x32_bf16 v[60:63], v[128:131], v[188:191], v[60:63]
	v_mfma_f32_16x16x32_bf16 v[56:59], v[136:139], v[188:191], v[56:59]
	v_mfma_f32_16x16x32_bf16 v[48:51], v[128:131], v[198:201], v[48:51]
	v_mfma_f32_16x16x32_bf16 v[40:43], v[136:139], v[198:201], v[40:43]
	v_mfma_f32_16x16x32_bf16 v[32:35], v[128:131], v[206:209], v[32:35]
	v_mfma_f32_16x16x32_bf16 v[24:27], v[136:139], v[206:209], v[24:27]
	v_mfma_f32_16x16x32_bf16 v[16:19], v[128:131], v[214:217], v[16:19]
	v_mfma_f32_16x16x32_bf16 v[8:11], v[136:139], v[214:217], v[8:11]
	v_mfma_f32_16x16x32_bf16 v[60:63], v[132:135], v[192:195], v[60:63]
	v_mfma_f32_16x16x32_bf16 v[56:59], v[140:143], v[192:195], v[56:59]
	v_mfma_f32_16x16x32_bf16 v[48:51], v[132:135], v[202:205], v[48:51]
	v_mfma_f32_16x16x32_bf16 v[40:43], v[140:143], v[202:205], v[40:43]
	v_mfma_f32_16x16x32_bf16 v[32:35], v[132:135], v[210:213], v[32:35]
	v_mfma_f32_16x16x32_bf16 v[24:27], v[140:143], v[210:213], v[24:27]
	v_mfma_f32_16x16x32_bf16 v[16:19], v[132:135], v[218:221], v[16:19]
	v_mfma_f32_16x16x32_bf16 v[8:11], v[140:143], v[218:221], v[8:11]
	v_mfma_f32_16x16x32_bf16 v[52:55], v[172:175], v[188:191], v[52:55]
	v_mfma_f32_16x16x32_bf16 v[44:47], v[180:183], v[188:191], v[44:47]
	v_mfma_f32_16x16x32_bf16 v[36:39], v[172:175], v[198:201], v[36:39]
	v_mfma_f32_16x16x32_bf16 v[28:31], v[180:183], v[198:201], v[28:31]
	v_mfma_f32_16x16x32_bf16 v[20:23], v[172:175], v[206:209], v[20:23]
	v_mfma_f32_16x16x32_bf16 v[12:15], v[180:183], v[206:209], v[12:15]
	v_mfma_f32_16x16x32_bf16 v[4:7], v[172:175], v[214:217], v[4:7]
	v_mfma_f32_16x16x32_bf16 v[0:3], v[180:183], v[214:217], v[0:3]
	v_mfma_f32_16x16x32_bf16 v[52:55], v[176:179], v[192:195], v[52:55]
	v_mfma_f32_16x16x32_bf16 v[44:47], v[184:187], v[192:195], v[44:47]
	v_mfma_f32_16x16x32_bf16 v[36:39], v[176:179], v[202:205], v[36:39]
	v_mfma_f32_16x16x32_bf16 v[28:31], v[184:187], v[202:205], v[28:31]
	v_mfma_f32_16x16x32_bf16 v[20:23], v[176:179], v[210:213], v[20:23]
	v_mfma_f32_16x16x32_bf16 v[12:15], v[184:187], v[210:213], v[12:15]
	v_mfma_f32_16x16x32_bf16 v[4:7], v[176:179], v[218:221], v[4:7]
	v_mfma_f32_16x16x32_bf16 v[0:3], v[184:187], v[218:221], v[0:3]
	s_barrier
	s_add_i32 s69, s69, 2
	s_add_u32 s20, s20, 0x100
	s_addc_u32 s21, s21, 0
	s_add_u32 s67, s67, 0x100
	s_addc_u32 s68, s68, 0
	s_cmp_gt_u32 s69, 13
.LBB0_1446:
	ds_read_b128 v[128:131], v153
	ds_read_b128 v[132:135], v153 offset:1024
	ds_read_b128 v[136:139], v153 offset:2048
	ds_read_b128 v[140:143], v153 offset:3072
	ds_read_b128 v[172:175], v155
	ds_read_b128 v[176:179], v155 offset:1024
	ds_read_b128 v[180:183], v155 offset:2048
	ds_read_b128 v[184:187], v155 offset:3072
	s_add_u32 s38, s20, 0xfffc0080
	s_addc_u32 s39, s21, -1
	s_cmp_eq_u32 s69, 12
	s_cselect_b32 s45, s15, s39
	s_cselect_b32 s44, s65, s38
	s_cselect_b32 s39, s13, s68
	s_cselect_b32 s38, s66, s67
	s_add_i32 m0, s35, 0xc000
	ds_read_b128 v[188:191], v157
	ds_read_b128 v[192:195], v157 offset:1024
	ds_read_b128 v[198:201], v157 offset:2048
	ds_read_b128 v[202:205], v157 offset:3072
	ds_read_b128 v[206:209], v157 offset:4096
	ds_read_b128 v[210:213], v157 offset:5120
	ds_read_b128 v[214:217], v157 offset:6144
	ds_read_b128 v[218:221], v157 offset:7168
	global_load_lds_dwordx4 v162, s[20:21]
	s_add_i32 m0, s35, 0xe000
	s_nop 0
	global_load_lds_dwordx4 v164, s[20:21]
	s_nop 0
	s_waitcnt vmcnt(8)
	s_waitcnt lgkmcnt(0)
	s_barrier
	v_mfma_f32_16x16x32_bf16 v[124:127], v[128:131], v[188:191], v[124:127]
	v_mfma_f32_16x16x32_bf16 v[120:123], v[136:139], v[188:191], v[120:123]
	v_mfma_f32_16x16x32_bf16 v[108:111], v[128:131], v[198:201], v[108:111]
	v_mfma_f32_16x16x32_bf16 v[104:107], v[136:139], v[198:201], v[104:107]
	v_mfma_f32_16x16x32_bf16 v[96:99], v[128:131], v[206:209], v[96:99]
	v_mfma_f32_16x16x32_bf16 v[88:91], v[136:139], v[206:209], v[88:91]
	v_mfma_f32_16x16x32_bf16 v[80:83], v[128:131], v[214:217], v[80:83]
	v_mfma_f32_16x16x32_bf16 v[72:75], v[136:139], v[214:217], v[72:75]
	v_mfma_f32_16x16x32_bf16 v[124:127], v[132:135], v[192:195], v[124:127]
	v_mfma_f32_16x16x32_bf16 v[120:123], v[140:143], v[192:195], v[120:123]
	v_mfma_f32_16x16x32_bf16 v[108:111], v[132:135], v[202:205], v[108:111]
	v_mfma_f32_16x16x32_bf16 v[104:107], v[140:143], v[202:205], v[104:107]
	v_mfma_f32_16x16x32_bf16 v[96:99], v[132:135], v[210:213], v[96:99]
	v_mfma_f32_16x16x32_bf16 v[88:91], v[140:143], v[210:213], v[88:91]
	v_mfma_f32_16x16x32_bf16 v[80:83], v[132:135], v[218:221], v[80:83]
	v_mfma_f32_16x16x32_bf16 v[72:75], v[140:143], v[218:221], v[72:75]
	v_mfma_f32_16x16x32_bf16 v[116:119], v[172:175], v[188:191], v[116:119]
	v_mfma_f32_16x16x32_bf16 v[112:115], v[180:183], v[188:191], v[112:115]
	v_mfma_f32_16x16x32_bf16 v[100:103], v[172:175], v[198:201], v[100:103]
	v_mfma_f32_16x16x32_bf16 v[92:95], v[180:183], v[198:201], v[92:95]
	v_mfma_f32_16x16x32_bf16 v[84:87], v[172:175], v[206:209], v[84:87]
	v_mfma_f32_16x16x32_bf16 v[76:79], v[180:183], v[206:209], v[76:79]
	v_mfma_f32_16x16x32_bf16 v[68:71], v[172:175], v[214:217], v[68:71]
	v_mfma_f32_16x16x32_bf16 v[64:67], v[180:183], v[214:217], v[64:67]
	v_mfma_f32_16x16x32_bf16 v[116:119], v[176:179], v[192:195], v[116:119]
	v_mfma_f32_16x16x32_bf16 v[112:115], v[184:187], v[192:195], v[112:115]
	v_mfma_f32_16x16x32_bf16 v[100:103], v[176:179], v[202:205], v[100:103]
	v_mfma_f32_16x16x32_bf16 v[92:95], v[184:187], v[202:205], v[92:95]
	v_mfma_f32_16x16x32_bf16 v[84:87], v[176:179], v[210:213], v[84:87]
	v_mfma_f32_16x16x32_bf16 v[76:79], v[184:187], v[210:213], v[76:79]
	v_mfma_f32_16x16x32_bf16 v[68:71], v[176:179], v[218:221], v[68:71]
	v_mfma_f32_16x16x32_bf16 v[64:67], v[184:187], v[218:221], v[64:67]
	s_barrier
; #define PG8_STAGE(bufoff, gbase, voff) do { _Pragma("unroll") for (int _i = 0; _i < 2; ++_i) \
;         __builtin_amdgcn_global_load_lds((const unsigned*)((const char*)(gbase) + (voff)[_i]), (PG8_LAS unsigned*)(lds + (bufoff) + ldsw + _i * 8192), 16, 0, 0); } while (0)
; #define PG8_LDA(dst, b, h) do { _Pragma("unroll") for (int m = 0; m < 4; ++m) _Pragma("unroll") for (int k = 0; k < 2; ++k) dst[m][k] = *(const PG8_LAS bf16x8*)(lds + PG8_SA(b, h) + aoff + m * 2048 + k * 1024); } while (0)
; #define PG8_LDB(dst, b, h) do { _Pragma("unroll") for (int n = 0; n < 2; ++n) _Pragma("unroll") for (int k = 0; k < 2; ++k) dst[n][k] = *(const PG8_LAS bf16x8*)(lds + PG8_SB(b, h) + boff + n * 2048 + k * 1024); } while (0)
; #define PG8_MMA(ai, bj, At, Bt) do { __builtin_amdgcn_s_setprio(1); _Pragma("unroll") for (int m = 0; m < 4; ++m) _Pragma("unroll") for (int n = 0; n < 2; ++n) _Pragma("unroll") for (int k = 0; k < 2; ++k) \
;         acc[ai][bj][m][n] = __builtin_amdgcn_mfma_f32_16x16x32_bf16(Bt[n][k], At[m][k], acc[ai][bj][m][n], 0, 0, 0); __builtin_amdgcn_s_setprio(0); } while (0)
; #define PG8_WAIT_V(n) asm volatile("s_waitcnt vmcnt(" #n ")" ::: "memory")
; #define PG8_WAIT_L(n) asm volatile("s_waitcnt lgkmcnt(" #n ")" ::: "memory")
; #define PG8_BAR __builtin_amdgcn_s_barrier()
; #define PG8_SCHED __builtin_amdgcn_sched_barrier(0)
; template <class Epi, class Sched, bool ALIGN_EPI = false, bool SP2 = false>
; __device__ __forceinline__ void gemm_phase(PG8_LAS unsigned char* lds, const Gemm g, const Sched& S, const Epi& E) {
;     ...
;             PG8_LDA(At, 0, 1); PG8_STAGE(PG8_SB(0, 0), b2, voffB); PG8_STAGE(PG8_SB(0, 1), b2 + hstep, voffB); PG8_STAGE(PG8_SA(0, 0), a2, voffA);
;             PG8_WAIT_V(8); PG8_WAIT_L(0); PG8_BAR; PG8_MMA(1, 0, At, B0); PG8_MMA(1, 1, At, B1); PG8_BAR; PG8_SCHED;
;             PG8_LDB(B0, 1, 0); PG8_LDB(B1, 1, 1); PG8_SCHED; PG8_LDA(At, 1, 0); PG8_STAGE(PG8_SA(0, 1), a2 + hstep, voffA);
;             PG8_WAIT_V(8); PG8_WAIT_L(0); PG8_BAR; PG8_MMA(0, 0, At, B0); PG8_MMA(0, 1, At, B1); PG8_BAR; PG8_SCHED;
	s_add_i32 s70, s60, s51
	s_add_u32 s98, s38, s6
	s_addc_u32 s99, s39, s7
	s_add_u32 s100, s44, s6
	s_addc_u32 s101, s45, s7
	s_mov_b32 m0, s70
	ds_read_b128 v[188:191], v157 offset:16384
	ds_read_b128 v[192:195], v157 offset:17408
	ds_read_b128 v[198:201], v157 offset:18432
	ds_read_b128 v[202:205], v157 offset:19456
	ds_read_b128 v[206:209], v157 offset:20480
	ds_read_b128 v[210:213], v157 offset:21504
	ds_read_b128 v[214:217], v157 offset:22528
	ds_read_b128 v[218:221], v157 offset:23552
	global_load_lds_dwordx4 v146, s[38:39]
	s_add_i32 m0, s70, 0x2000
	s_add_u32 s70, s38, 0x40000
	s_addc_u32 s71, s39, 0
	s_add_i32 s72, s61, s51
	global_load_lds_dwordx4 v150, s[38:39]
	s_mov_b32 m0, s72
	s_nop 0
	global_load_lds_dwordx4 v146, s[70:71]
	s_add_i32 m0, s72, 0x2000
	s_nop 0
	global_load_lds_dwordx4 v150, s[70:71]
	s_mov_b32 m0, s35
	s_nop 0
	global_load_lds_dwordx4 v144, s[44:45]
	s_mov_b32 m0, s52
	s_nop 0
	global_load_lds_dwordx4 v148, s[44:45]
	s_nop 0
	s_waitcnt vmcnt(8)
	s_waitcnt lgkmcnt(0)
	s_barrier
	v_mfma_f32_16x16x32_bf16 v[60:63], v[128:131], v[188:191], v[60:63]
	v_mfma_f32_16x16x32_bf16 v[56:59], v[136:139], v[188:191], v[56:59]
	v_mfma_f32_16x16x32_bf16 v[48:51], v[128:131], v[198:201], v[48:51]
	v_mfma_f32_16x16x32_bf16 v[40:43], v[136:139], v[198:201], v[40:43]
	v_mfma_f32_16x16x32_bf16 v[32:35], v[128:131], v[206:209], v[32:35]
	v_mfma_f32_16x16x32_bf16 v[24:27], v[136:139], v[206:209], v[24:27]
	v_mfma_f32_16x16x32_bf16 v[16:19], v[128:131], v[214:217], v[16:19]
	v_mfma_f32_16x16x32_bf16 v[8:11], v[136:139], v[214:217], v[8:11]
	v_mfma_f32_16x16x32_bf16 v[60:63], v[132:135], v[192:195], v[60:63]
	v_mfma_f32_16x16x32_bf16 v[56:59], v[140:143], v[192:195], v[56:59]
	v_mfma_f32_16x16x32_bf16 v[48:51], v[132:135], v[202:205], v[48:51]
	v_mfma_f32_16x16x32_bf16 v[40:43], v[140:143], v[202:205], v[40:43]
	v_mfma_f32_16x16x32_bf16 v[32:35], v[132:135], v[210:213], v[32:35]
	v_mfma_f32_16x16x32_bf16 v[24:27], v[140:143], v[210:213], v[24:27]
	v_mfma_f32_16x16x32_bf16 v[16:19], v[132:135], v[218:221], v[16:19]
	v_mfma_f32_16x16x32_bf16 v[8:11], v[140:143], v[218:221], v[8:11]
	v_mfma_f32_16x16x32_bf16 v[52:55], v[172:175], v[188:191], v[52:55]
	v_mfma_f32_16x16x32_bf16 v[44:47], v[180:183], v[188:191], v[44:47]
	v_mfma_f32_16x16x32_bf16 v[36:39], v[172:175], v[198:201], v[36:39]
	v_mfma_f32_16x16x32_bf16 v[28:31], v[180:183], v[198:201], v[28:31]
	v_mfma_f32_16x16x32_bf16 v[20:23], v[172:175], v[206:209], v[20:23]
	v_mfma_f32_16x16x32_bf16 v[12:15], v[180:183], v[206:209], v[12:15]
	v_mfma_f32_16x16x32_bf16 v[4:7], v[172:175], v[214:217], v[4:7]
	v_mfma_f32_16x16x32_bf16 v[0:3], v[180:183], v[214:217], v[0:3]
	v_mfma_f32_16x16x32_bf16 v[52:55], v[176:179], v[192:195], v[52:55]
	v_mfma_f32_16x16x32_bf16 v[44:47], v[184:187], v[192:195], v[44:47]
	v_mfma_f32_16x16x32_bf16 v[36:39], v[176:179], v[202:205], v[36:39]
	v_mfma_f32_16x16x32_bf16 v[28:31], v[184:187], v[202:205], v[28:31]
	v_mfma_f32_16x16x32_bf16 v[20:23], v[176:179], v[210:213], v[20:23]
	v_mfma_f32_16x16x32_bf16 v[12:15], v[184:187], v[210:213], v[12:15]
	v_mfma_f32_16x16x32_bf16 v[4:7], v[176:179], v[218:221], v[4:7]
	v_mfma_f32_16x16x32_bf16 v[0:3], v[184:187], v[218:221], v[0:3]
	s_barrier
	s_add_i32 s70, 0, 0x18000
	s_add_i32 s71, 0, 0x1c000
	v_add_u32_e32 v140, s70, v170
	v_add_u32_e32 v159, s71, v170
	ds_read_b128 v[128:131], v140
	ds_read_b128 v[132:135], v140 offset:1024
	ds_read_b128 v[136:139], v140 offset:2048
	ds_read_b128 v[140:143], v140 offset:3072
	ds_read_b128 v[172:175], v159
	ds_read_b128 v[176:179], v159 offset:1024
	ds_read_b128 v[180:183], v159 offset:2048
	ds_read_b128 v[184:187], v159 offset:3072
	s_add_u32 s44, s44, 0x40000
	s_addc_u32 s45, s45, 0
	s_mov_b32 m0, s53
	ds_read_b128 v[188:191], v157 offset:32768
	ds_read_b128 v[192:195], v157 offset:33792
	ds_read_b128 v[198:201], v157 offset:34816
	ds_read_b128 v[202:205], v157 offset:35840
	ds_read_b128 v[206:209], v157 offset:36864
	ds_read_b128 v[210:213], v157 offset:37888
	ds_read_b128 v[214:217], v157 offset:38912
	ds_read_b128 v[218:221], v157 offset:39936
	global_load_lds_dwordx4 v144, s[44:45]
	s_mov_b32 m0, s54
	s_nop 0
	global_load_lds_dwordx4 v148, s[44:45]
	s_waitcnt vmcnt(8)
	s_waitcnt lgkmcnt(0)
	s_barrier
; #define PG8_STAGE(bufoff, gbase, voff) do { _Pragma("unroll") for (int _i = 0; _i < 2; ++_i) \
;         __builtin_amdgcn_global_load_lds((const unsigned*)((const char*)(gbase) + (voff)[_i]), (PG8_LAS unsigned*)(lds + (bufoff) + ldsw + _i * 8192), 16, 0, 0); } while (0)
; #define PG8_LDA(dst, b, h) do { _Pragma("unroll") for (int m = 0; m < 4; ++m) _Pragma("unroll") for (int k = 0; k < 2; ++k) dst[m][k] = *(const PG8_LAS bf16x8*)(lds + PG8_SA(b, h) + aoff + m * 2048 + k * 1024); } while (0)
; #define PG8_MMA(ai, bj, At, Bt) do { __builtin_amdgcn_s_setprio(1); _Pragma("unroll") for (int m = 0; m < 4; ++m) _Pragma("unroll") for (int n = 0; n < 2; ++n) _Pragma("unroll") for (int k = 0; k < 2; ++k) \
;         acc[ai][bj][m][n] = __builtin_amdgcn_mfma_f32_16x16x32_bf16(Bt[n][k], At[m][k], acc[ai][bj][m][n], 0, 0, 0); __builtin_amdgcn_s_setprio(0); } while (0)
; #define PG8_WAIT_V(n) asm volatile("s_waitcnt vmcnt(" #n ")" ::: "memory")
; #define PG8_WAIT_L(n) asm volatile("s_waitcnt lgkmcnt(" #n ")" ::: "memory")
; #define PG8_BAR __builtin_amdgcn_s_barrier()
; #define PG8_SCHED __builtin_amdgcn_sched_barrier(0)
; template <class Epi, class Sched, bool ALIGN_EPI = false, bool SP2 = false>
; __device__ __forceinline__ void gemm_phase(PG8_LAS unsigned char* lds, const Gemm g, const Sched& S, const Epi& E) {
;     ...
;             PG8_WAIT_V(8); PG8_WAIT_L(0); PG8_BAR; PG8_MMA(0, 0, At, B0); PG8_MMA(0, 1, At, B1); PG8_BAR; PG8_SCHED;
;             PG8_LDA(At, 1, 1); PG8_STAGE(PG8_SB(1, 0), b3, voffB); PG8_STAGE(PG8_SB(1, 1), b3 + hstep, voffB); PG8_STAGE(PG8_SA(1, 0), a3, voffA);
;             PG8_WAIT_V(8); PG8_WAIT_L(0); PG8_BAR; PG8_MMA(1, 0, At, B0); PG8_MMA(1, 1, At, B1); PG8_BAR; PG8_SCHED;
;     ...
;         if constexpr (ALIGN_EPI) { if (wr == 0) PG8_BAR; }
	v_mfma_f32_16x16x32_bf16 v[124:127], v[128:131], v[188:191], v[124:127]
	v_mfma_f32_16x16x32_bf16 v[120:123], v[136:139], v[188:191], v[120:123]
	v_mfma_f32_16x16x32_bf16 v[108:111], v[128:131], v[198:201], v[108:111]
	v_mfma_f32_16x16x32_bf16 v[104:107], v[136:139], v[198:201], v[104:107]
	v_mfma_f32_16x16x32_bf16 v[96:99], v[128:131], v[206:209], v[96:99]
	v_mfma_f32_16x16x32_bf16 v[88:91], v[136:139], v[206:209], v[88:91]
	v_mfma_f32_16x16x32_bf16 v[80:83], v[128:131], v[214:217], v[80:83]
	v_mfma_f32_16x16x32_bf16 v[72:75], v[136:139], v[214:217], v[72:75]
	v_mfma_f32_16x16x32_bf16 v[124:127], v[132:135], v[192:195], v[124:127]
	v_mfma_f32_16x16x32_bf16 v[120:123], v[140:143], v[192:195], v[120:123]
	v_mfma_f32_16x16x32_bf16 v[108:111], v[132:135], v[202:205], v[108:111]
	v_mfma_f32_16x16x32_bf16 v[104:107], v[140:143], v[202:205], v[104:107]
	v_mfma_f32_16x16x32_bf16 v[96:99], v[132:135], v[210:213], v[96:99]
	v_mfma_f32_16x16x32_bf16 v[88:91], v[140:143], v[210:213], v[88:91]
	v_mfma_f32_16x16x32_bf16 v[80:83], v[132:135], v[218:221], v[80:83]
	v_mfma_f32_16x16x32_bf16 v[72:75], v[140:143], v[218:221], v[72:75]
	v_mfma_f32_16x16x32_bf16 v[116:119], v[172:175], v[188:191], v[116:119]
	v_mfma_f32_16x16x32_bf16 v[112:115], v[180:183], v[188:191], v[112:115]
	v_mfma_f32_16x16x32_bf16 v[100:103], v[172:175], v[198:201], v[100:103]
	v_mfma_f32_16x16x32_bf16 v[92:95], v[180:183], v[198:201], v[92:95]
	v_mfma_f32_16x16x32_bf16 v[84:87], v[172:175], v[206:209], v[84:87]
	v_mfma_f32_16x16x32_bf16 v[76:79], v[180:183], v[206:209], v[76:79]
	v_mfma_f32_16x16x32_bf16 v[68:71], v[172:175], v[214:217], v[68:71]
	v_mfma_f32_16x16x32_bf16 v[64:67], v[180:183], v[214:217], v[64:67]
	v_mfma_f32_16x16x32_bf16 v[116:119], v[176:179], v[192:195], v[116:119]
	v_mfma_f32_16x16x32_bf16 v[112:115], v[184:187], v[192:195], v[112:115]
	v_mfma_f32_16x16x32_bf16 v[100:103], v[176:179], v[202:205], v[100:103]
	v_mfma_f32_16x16x32_bf16 v[92:95], v[184:187], v[202:205], v[92:95]
	v_mfma_f32_16x16x32_bf16 v[84:87], v[176:179], v[210:213], v[84:87]
	v_mfma_f32_16x16x32_bf16 v[76:79], v[184:187], v[210:213], v[76:79]
	v_mfma_f32_16x16x32_bf16 v[68:71], v[176:179], v[218:221], v[68:71]
	v_mfma_f32_16x16x32_bf16 v[64:67], v[184:187], v[218:221], v[64:67]
	s_barrier
	s_add_i32 s44, s70, s51
	s_mov_b32 m0, s44
	ds_read_b128 v[188:191], v157 offset:49152
	ds_read_b128 v[192:195], v157 offset:50176
	ds_read_b128 v[198:201], v157 offset:51200
	ds_read_b128 v[202:205], v157 offset:52224
	ds_read_b128 v[206:209], v157 offset:53248
	ds_read_b128 v[210:213], v157 offset:54272
	ds_read_b128 v[214:217], v157 offset:55296
	ds_read_b128 v[218:221], v157 offset:56320
	global_load_lds_dwordx4 v146, s[98:99]
	s_add_i32 m0, s44, 0x2000
	s_add_u32 s38, s38, 0x40080
	s_addc_u32 s39, s39, 0
	s_add_i32 s44, s71, s51
	global_load_lds_dwordx4 v150, s[98:99]
	s_mov_b32 m0, s44
	s_nop 0
	global_load_lds_dwordx4 v146, s[38:39]
	s_add_i32 m0, s44, 0x2000
	s_nop 0
	global_load_lds_dwordx4 v150, s[38:39]
	s_mov_b32 m0, s58
	s_nop 0
	global_load_lds_dwordx4 v144, s[100:101]
	s_mov_b32 m0, s59
	s_nop 0
	global_load_lds_dwordx4 v148, s[100:101]
	s_nop 0
	s_waitcnt vmcnt(8)
	s_waitcnt lgkmcnt(0)
	s_barrier
	v_mfma_f32_16x16x32_bf16 v[60:63], v[128:131], v[188:191], v[60:63]
	v_mfma_f32_16x16x32_bf16 v[56:59], v[136:139], v[188:191], v[56:59]
	v_mfma_f32_16x16x32_bf16 v[48:51], v[128:131], v[198:201], v[48:51]
	v_mfma_f32_16x16x32_bf16 v[40:43], v[136:139], v[198:201], v[40:43]
	v_mfma_f32_16x16x32_bf16 v[32:35], v[128:131], v[206:209], v[32:35]
	v_mfma_f32_16x16x32_bf16 v[24:27], v[136:139], v[206:209], v[24:27]
	v_mfma_f32_16x16x32_bf16 v[16:19], v[128:131], v[214:217], v[16:19]
	v_mfma_f32_16x16x32_bf16 v[8:11], v[136:139], v[214:217], v[8:11]
	v_mfma_f32_16x16x32_bf16 v[60:63], v[132:135], v[192:195], v[60:63]
	v_mfma_f32_16x16x32_bf16 v[56:59], v[140:143], v[192:195], v[56:59]
	v_mfma_f32_16x16x32_bf16 v[48:51], v[132:135], v[202:205], v[48:51]
	v_mfma_f32_16x16x32_bf16 v[40:43], v[140:143], v[202:205], v[40:43]
	v_mfma_f32_16x16x32_bf16 v[32:35], v[132:135], v[210:213], v[32:35]
	v_mfma_f32_16x16x32_bf16 v[24:27], v[140:143], v[210:213], v[24:27]
	v_mfma_f32_16x16x32_bf16 v[16:19], v[132:135], v[218:221], v[16:19]
	v_mfma_f32_16x16x32_bf16 v[8:11], v[140:143], v[218:221], v[8:11]
	v_mfma_f32_16x16x32_bf16 v[52:55], v[172:175], v[188:191], v[52:55]
	v_mfma_f32_16x16x32_bf16 v[44:47], v[180:183], v[188:191], v[44:47]
	v_mfma_f32_16x16x32_bf16 v[36:39], v[172:175], v[198:201], v[36:39]
	v_mfma_f32_16x16x32_bf16 v[28:31], v[180:183], v[198:201], v[28:31]
	v_mfma_f32_16x16x32_bf16 v[20:23], v[172:175], v[206:209], v[20:23]
	v_mfma_f32_16x16x32_bf16 v[12:15], v[180:183], v[206:209], v[12:15]
	v_mfma_f32_16x16x32_bf16 v[4:7], v[172:175], v[214:217], v[4:7]
	v_mfma_f32_16x16x32_bf16 v[0:3], v[180:183], v[214:217], v[0:3]
	v_mfma_f32_16x16x32_bf16 v[52:55], v[176:179], v[192:195], v[52:55]
	v_mfma_f32_16x16x32_bf16 v[44:47], v[184:187], v[192:195], v[44:47]
	v_mfma_f32_16x16x32_bf16 v[36:39], v[176:179], v[202:205], v[36:39]
	v_mfma_f32_16x16x32_bf16 v[28:31], v[184:187], v[202:205], v[28:31]
	v_mfma_f32_16x16x32_bf16 v[20:23], v[176:179], v[210:213], v[20:23]
	v_mfma_f32_16x16x32_bf16 v[12:15], v[184:187], v[210:213], v[12:15]
	v_mfma_f32_16x16x32_bf16 v[4:7], v[176:179], v[218:221], v[4:7]
	v_mfma_f32_16x16x32_bf16 v[0:3], v[184:187], v[218:221], v[0:3]
	s_barrier
	s_add_i32 s69, s69, 2
	s_add_u32 s20, s20, 0x100
	s_addc_u32 s21, s21, 0
	s_add_u32 s67, s67, 0x100
	s_addc_u32 s68, s68, 0
	s_cmp_gt_u32 s69, 13
	s_cbranch_scc0 .LBB0_1446
	s_and_b64 vcc, exec, s[8:9]
	s_cbranch_vccz .LBB0_1449
	s_barrier

; #define PG8_STAGE(bufoff, gbase, voff) do { _Pragma("unroll") for (int _i = 0; _i < 2; ++_i) \
;         __builtin_amdgcn_global_load_lds((const unsigned*)((const char*)(gbase) + (voff)[_i]), (PG8_LAS unsigned*)(lds + (bufoff) + ldsw + _i * 8192), 16, 0, 0); } while (0)
; #define PG8_LDA(dst, b, h) do { _Pragma("unroll") for (int m = 0; m < 4; ++m) _Pragma("unroll") for (int k = 0; k < 2; ++k) dst[m][k] = *(const PG8_LAS bf16x8*)(lds + PG8_SA(b, h) + aoff + m * 2048 + k * 1024); } while (0)
; #define PG8_LDB(dst, b, h) do { _Pragma("unroll") for (int n = 0; n < 2; ++n) _Pragma("unroll") for (int k = 0; k < 2; ++k) dst[n][k] = *(const PG8_LAS bf16x8*)(lds + PG8_SB(b, h) + boff + n * 2048 + k * 1024); } while (0)
; #define PG8_WAIT_V(n) asm volatile("s_waitcnt vmcnt(" #n ")" ::: "memory")
; #define PG8_WAIT_L(n) asm volatile("s_waitcnt lgkmcnt(" #n ")" ::: "memory")
; #define PG8_BAR __builtin_amdgcn_s_barrier()
; #define PG8_SCHED __builtin_amdgcn_sched_barrier(0)
; template <class Epi, class Sched, bool ALIGN_EPI = false, bool SP2 = false>
; __device__ __forceinline__ void gemm_phase(PG8_LAS unsigned char* lds, const Gemm g, const Sched& S, const Epi& E) {
;     ...
;         const bool has_next = S.next(ui + 1, nxt);
;         const char* nA = has_next ? (const char*)g.A + (size_t)nxt.pm * tstep : cA; const char* nB = has_next ? (const char*)g.Bt + (size_t)nxt.pn * tstep : cB;
;         for (int t = 0; t < nt; t += 2) {
;             const bool last = (t == nt - 2);
;             const char* a1 = cA + (size_t)(t + 1) * kstep;
;             const char* a2 = last ? nA : cA + (size_t)(t + 2) * kstep; const char* b2 = last ? nB : cB + (size_t)(t + 2) * kstep;
;             const char* a3 = a2 + kstep; const char* b3 = b2 + kstep;
;             if (last && has_next) S.a_ready(nxt);
;             if constexpr (SP2) {
;             PG8_LDB(B0, 0, 0); PG8_LDB(B1, 0, 1); PG8_SCHED; PG8_LDA(At, 0, 0); PG8_STAGE(PG8_SA(1, 1), a1 + hstep, voffA);
;             PG8_WAIT_V(8); PG8_WAIT_L(0); PG8_BAR; PG8_MMA(0, 0, At, B0); PG8_MMA(0, 1, At, B1); PG8_BAR; PG8_SCHED;
;             PG8_LDA(At, 0, 1); PG8_STAGE(PG8_SB(0, 0), b2, voffB); PG8_STAGE(PG8_SB(0, 1), b2 + hstep, voffB); PG8_STAGE(PG8_SA(0, 0), a2, voffA);
;             PG8_WAIT_V(8); PG8_WAIT_L(0); PG8_BAR; PG8_MMA(1, 0, At, B0); PG8_MMA(1, 1, At, B1); PG8_BAR; PG8_SCHED;
.LBB0_1634:
	s_ashr_i32 s47, s46, 31
	s_lshl_b64 s[48:49], s[46:47], 19
	s_add_u32 s48, s18, s48
	s_addc_u32 s49, s19, s49
	s_and_b64 s[50:51], s[6:7], exec
	s_cselect_b32 s35, s49, s21
	s_cselect_b32 s47, s48, s20
	s_ashr_i32 s45, s44, 31
	s_lshl_b64 s[50:51], s[44:45], 19
	s_add_u32 s50, s3, s50
	s_addc_u32 s51, s33, s51
	s_and_b64 s[56:57], s[6:7], exec
	s_cselect_b32 s45, s51, s55
	s_cselect_b32 s73, s50, s54
	s_add_u32 s20, s20, 0x40080
	s_addc_u32 s21, s21, 0
	s_add_u32 s74, s54, 0x100
	s_addc_u32 s75, s55, 0
	s_mov_b32 s76, -2
	s_waitcnt lgkmcnt(0)
	ds_read_b128 v[96:99], v223
	ds_read_b128 v[108:111], v223 offset:1024
	ds_read_b128 v[120:123], v223 offset:2048
	ds_read_b128 v[128:131], v223 offset:3072
	ds_read_b128 v[144:147], v224
	ds_read_b128 v[148:151], v224 offset:1024
	ds_read_b128 v[152:155], v224 offset:2048
	ds_read_b128 v[156:159], v224 offset:3072
	s_add_u32 s54, s20, 0xfffc0080
	s_addc_u32 s55, s21, -1
	s_cmp_eq_u32 s76, 12
	s_cselect_b32 s57, s35, s55
	s_cselect_b32 s56, s47, s54
	s_cselect_b32 s55, s45, s75
	s_cselect_b32 s54, s73, s74
	s_add_i32 m0, s53, 0xc000
	ds_read_b128 v[160:163], v225
	ds_read_b128 v[164:167], v225 offset:1024
	ds_read_b128 v[168:171], v225 offset:2048
	ds_read_b128 v[172:175], v225 offset:3072
	ds_read_b128 v[176:179], v225 offset:4096
	ds_read_b128 v[180:183], v225 offset:5120
	ds_read_b128 v[202:205], v225 offset:6144
	ds_read_b128 v[206:209], v225 offset:7168
	global_load_lds_dwordx4 v192, s[20:21]
	s_add_i32 m0, s53, 0xe000
	s_nop 0
	global_load_lds_dwordx4 v194, s[20:21]
	s_nop 0
	s_waitcnt vmcnt(8)
	s_waitcnt lgkmcnt(0)
	s_barrier
	v_mfma_f32_16x16x32_bf16 v[140:143], v[96:99], v[160:163], 0
	v_mfma_f32_16x16x32_bf16 v[136:139], v[120:123], v[160:163], 0
	v_mfma_f32_16x16x32_bf16 v[116:119], v[96:99], v[168:171], 0
	v_mfma_f32_16x16x32_bf16 v[112:115], v[120:123], v[168:171], 0
	v_mfma_f32_16x16x32_bf16 v[92:95], v[96:99], v[176:179], 0
	v_mfma_f32_16x16x32_bf16 v[88:91], v[120:123], v[176:179], 0
	v_mfma_f32_16x16x32_bf16 v[76:79], v[96:99], v[202:205], 0
	v_mfma_f32_16x16x32_bf16 v[72:75], v[120:123], v[202:205], 0
	v_mfma_f32_16x16x32_bf16 v[140:143], v[108:111], v[164:167], v[140:143]
	v_mfma_f32_16x16x32_bf16 v[136:139], v[128:131], v[164:167], v[136:139]
	v_mfma_f32_16x16x32_bf16 v[116:119], v[108:111], v[172:175], v[116:119]
	v_mfma_f32_16x16x32_bf16 v[112:115], v[128:131], v[172:175], v[112:115]
	v_mfma_f32_16x16x32_bf16 v[92:95], v[108:111], v[180:183], v[92:95]
	v_mfma_f32_16x16x32_bf16 v[88:91], v[128:131], v[180:183], v[88:91]
	v_mfma_f32_16x16x32_bf16 v[76:79], v[108:111], v[206:209], v[76:79]
	v_mfma_f32_16x16x32_bf16 v[72:75], v[128:131], v[206:209], v[72:75]
	v_mfma_f32_16x16x32_bf16 v[132:135], v[144:147], v[160:163], 0
	v_mfma_f32_16x16x32_bf16 v[124:127], v[152:155], v[160:163], 0
	v_mfma_f32_16x16x32_bf16 v[104:107], v[144:147], v[168:171], 0
	v_mfma_f32_16x16x32_bf16 v[100:103], v[152:155], v[168:171], 0
	v_mfma_f32_16x16x32_bf16 v[84:87], v[144:147], v[176:179], 0
	v_mfma_f32_16x16x32_bf16 v[80:83], v[152:155], v[176:179], 0
	v_mfma_f32_16x16x32_bf16 v[68:71], v[144:147], v[202:205], 0
	v_mfma_f32_16x16x32_bf16 v[64:67], v[152:155], v[202:205], 0
	v_mfma_f32_16x16x32_bf16 v[132:135], v[148:151], v[164:167], v[132:135]
	v_mfma_f32_16x16x32_bf16 v[124:127], v[156:159], v[164:167], v[124:127]
	v_mfma_f32_16x16x32_bf16 v[104:107], v[148:151], v[172:175], v[104:107]
	v_mfma_f32_16x16x32_bf16 v[100:103], v[156:159], v[172:175], v[100:103]
	v_mfma_f32_16x16x32_bf16 v[84:87], v[148:151], v[180:183], v[84:87]
	v_mfma_f32_16x16x32_bf16 v[80:83], v[156:159], v[180:183], v[80:83]
	v_mfma_f32_16x16x32_bf16 v[68:71], v[148:151], v[206:209], v[68:71]
	v_mfma_f32_16x16x32_bf16 v[64:67], v[156:159], v[206:209], v[64:67]
	s_barrier
	s_add_i32 s77, s71, s58
	s_add_u32 s98, s54, s12
	s_addc_u32 s99, s55, s13
	s_add_u32 s100, s56, s12
	s_addc_u32 s101, s57, s13
	s_mov_b32 m0, s77
	ds_read_b128 v[160:163], v225 offset:16384
	ds_read_b128 v[164:167], v225 offset:17408
	ds_read_b128 v[168:171], v225 offset:18432
	ds_read_b128 v[172:175], v225 offset:19456
	ds_read_b128 v[176:179], v225 offset:20480
	ds_read_b128 v[180:183], v225 offset:21504
	ds_read_b128 v[202:205], v225 offset:22528
	ds_read_b128 v[206:209], v225 offset:23552
	global_load_lds_dwordx4 v186, s[54:55]
	s_add_i32 m0, s77, 0x2000
	s_add_u32 s78, s54, 0x40000
	s_addc_u32 s79, s55, 0
	s_add_i32 s77, s72, s58
	global_load_lds_dwordx4 v190, s[54:55]
	s_mov_b32 m0, s77
	s_nop 0
	global_load_lds_dwordx4 v186, s[78:79]
	s_add_i32 m0, s77, 0x2000
	s_nop 0
	global_load_lds_dwordx4 v190, s[78:79]
	s_mov_b32 m0, s53
	s_nop 0
	global_load_lds_dwordx4 v184, s[56:57]
	s_mov_b32 m0, s59
	s_nop 0
	global_load_lds_dwordx4 v188, s[56:57]
	s_nop 0
	s_waitcnt vmcnt(8)
	s_waitcnt lgkmcnt(0)
	s_barrier
; #define PG8_STAGE(bufoff, gbase, voff) do { _Pragma("unroll") for (int _i = 0; _i < 2; ++_i) \
;         __builtin_amdgcn_global_load_lds((const unsigned*)((const char*)(gbase) + (voff)[_i]), (PG8_LAS unsigned*)(lds + (bufoff) + ldsw + _i * 8192), 16, 0, 0); } while (0)
; #define PG8_LDA(dst, b, h) do { _Pragma("unroll") for (int m = 0; m < 4; ++m) _Pragma("unroll") for (int k = 0; k < 2; ++k) dst[m][k] = *(const PG8_LAS bf16x8*)(lds + PG8_SA(b, h) + aoff + m * 2048 + k * 1024); } while (0)
; #define PG8_LDB(dst, b, h) do { _Pragma("unroll") for (int n = 0; n < 2; ++n) _Pragma("unroll") for (int k = 0; k < 2; ++k) dst[n][k] = *(const PG8_LAS bf16x8*)(lds + PG8_SB(b, h) + boff + n * 2048 + k * 1024); } while (0)
; #define PG8_MMA(ai, bj, At, Bt) do { __builtin_amdgcn_s_setprio(1); _Pragma("unroll") for (int m = 0; m < 4; ++m) _Pragma("unroll") for (int n = 0; n < 2; ++n) _Pragma("unroll") for (int k = 0; k < 2; ++k) \
;         acc[ai][bj][m][n] = __builtin_amdgcn_mfma_f32_16x16x32_bf16(Bt[n][k], At[m][k], acc[ai][bj][m][n], 0, 0, 0); __builtin_amdgcn_s_setprio(0); } while (0)
; #define PG8_WAIT_V(n) asm volatile("s_waitcnt vmcnt(" #n ")" ::: "memory")
; #define PG8_WAIT_L(n) asm volatile("s_waitcnt lgkmcnt(" #n ")" ::: "memory")
; #define PG8_BAR __builtin_amdgcn_s_barrier()
; #define PG8_SCHED __builtin_amdgcn_sched_barrier(0)
; template <class Epi, class Sched, bool ALIGN_EPI = false, bool SP2 = false>
; __device__ __forceinline__ void gemm_phase(PG8_LAS unsigned char* lds, const Gemm g, const Sched& S, const Epi& E) {
;     ...
;             PG8_WAIT_V(8); PG8_WAIT_L(0); PG8_BAR; PG8_MMA(1, 0, At, B0); PG8_MMA(1, 1, At, B1); PG8_BAR; PG8_SCHED;
;             PG8_LDB(B0, 1, 0); PG8_LDB(B1, 1, 1); PG8_SCHED; PG8_LDA(At, 1, 0); PG8_STAGE(PG8_SA(0, 1), a2 + hstep, voffA);
;             PG8_WAIT_V(8); PG8_WAIT_L(0); PG8_BAR; PG8_MMA(0, 0, At, B0); PG8_MMA(0, 1, At, B1); PG8_BAR; PG8_SCHED;
	v_mfma_f32_16x16x32_bf16 v[60:63], v[96:99], v[160:163], 0
	v_mfma_f32_16x16x32_bf16 v[56:59], v[120:123], v[160:163], 0
	v_mfma_f32_16x16x32_bf16 v[44:47], v[96:99], v[168:171], 0
	v_mfma_f32_16x16x32_bf16 v[40:43], v[120:123], v[168:171], 0
	v_mfma_f32_16x16x32_bf16 v[28:31], v[96:99], v[176:179], 0
	v_mfma_f32_16x16x32_bf16 v[24:27], v[120:123], v[176:179], 0
	v_mfma_f32_16x16x32_bf16 v[12:15], v[96:99], v[202:205], 0
	v_mfma_f32_16x16x32_bf16 v[8:11], v[120:123], v[202:205], 0
	v_mfma_f32_16x16x32_bf16 v[60:63], v[108:111], v[164:167], v[60:63]
	v_mfma_f32_16x16x32_bf16 v[56:59], v[128:131], v[164:167], v[56:59]
	v_mfma_f32_16x16x32_bf16 v[44:47], v[108:111], v[172:175], v[44:47]
	v_mfma_f32_16x16x32_bf16 v[40:43], v[128:131], v[172:175], v[40:43]
	v_mfma_f32_16x16x32_bf16 v[28:31], v[108:111], v[180:183], v[28:31]
	v_mfma_f32_16x16x32_bf16 v[24:27], v[128:131], v[180:183], v[24:27]
	v_mfma_f32_16x16x32_bf16 v[12:15], v[108:111], v[206:209], v[12:15]
	v_mfma_f32_16x16x32_bf16 v[8:11], v[128:131], v[206:209], v[8:11]
	v_mfma_f32_16x16x32_bf16 v[52:55], v[144:147], v[160:163], 0
	v_mfma_f32_16x16x32_bf16 v[48:51], v[152:155], v[160:163], 0
	v_mfma_f32_16x16x32_bf16 v[36:39], v[144:147], v[168:171], 0
	v_mfma_f32_16x16x32_bf16 v[32:35], v[152:155], v[168:171], 0
	v_mfma_f32_16x16x32_bf16 v[20:23], v[144:147], v[176:179], 0
	v_mfma_f32_16x16x32_bf16 v[16:19], v[152:155], v[176:179], 0
	v_mfma_f32_16x16x32_bf16 v[4:7], v[144:147], v[202:205], 0
	v_mfma_f32_16x16x32_bf16 v[0:3], v[152:155], v[202:205], 0
	v_mfma_f32_16x16x32_bf16 v[52:55], v[148:151], v[164:167], v[52:55]
	v_mfma_f32_16x16x32_bf16 v[48:51], v[156:159], v[164:167], v[48:51]
	v_mfma_f32_16x16x32_bf16 v[36:39], v[148:151], v[172:175], v[36:39]
	v_mfma_f32_16x16x32_bf16 v[32:35], v[156:159], v[172:175], v[32:35]
	v_mfma_f32_16x16x32_bf16 v[20:23], v[148:151], v[180:183], v[20:23]
	v_mfma_f32_16x16x32_bf16 v[16:19], v[156:159], v[180:183], v[16:19]
	v_mfma_f32_16x16x32_bf16 v[4:7], v[148:151], v[206:209], v[4:7]
	v_mfma_f32_16x16x32_bf16 v[0:3], v[156:159], v[206:209], v[0:3]
	s_barrier
	s_add_i32 s77, 0, 0x18000
	s_add_i32 s78, 0, 0x1c000
	v_add_u32_e32 v128, s77, v221
	v_add_u32_e32 v156, s78, v221
	ds_read_b128 v[96:99], v128
	ds_read_b128 v[108:111], v128 offset:1024
	ds_read_b128 v[120:123], v128 offset:2048
	ds_read_b128 v[128:131], v128 offset:3072
	ds_read_b128 v[144:147], v156
	ds_read_b128 v[148:151], v156 offset:1024
	ds_read_b128 v[152:155], v156 offset:2048
	ds_read_b128 v[156:159], v156 offset:3072
	s_add_u32 s56, s56, 0x40000
	s_addc_u32 s57, s57, 0
	s_mov_b32 m0, s60
	ds_read_b128 v[160:163], v225 offset:32768
	ds_read_b128 v[164:167], v225 offset:33792
	ds_read_b128 v[168:171], v225 offset:34816
	ds_read_b128 v[172:175], v225 offset:35840
	ds_read_b128 v[176:179], v225 offset:36864
	ds_read_b128 v[180:183], v225 offset:37888
	ds_read_b128 v[202:205], v225 offset:38912
	ds_read_b128 v[206:209], v225 offset:39936
	global_load_lds_dwordx4 v184, s[56:57]
	s_mov_b32 m0, s61
	s_nop 0
	global_load_lds_dwordx4 v188, s[56:57]
	s_waitcnt vmcnt(8)
	s_waitcnt lgkmcnt(0)
	s_barrier
	v_mfma_f32_16x16x32_bf16 v[140:143], v[96:99], v[160:163], v[140:143]
	v_mfma_f32_16x16x32_bf16 v[136:139], v[120:123], v[160:163], v[136:139]
	v_mfma_f32_16x16x32_bf16 v[116:119], v[96:99], v[168:171], v[116:119]
	v_mfma_f32_16x16x32_bf16 v[112:115], v[120:123], v[168:171], v[112:115]
	v_mfma_f32_16x16x32_bf16 v[92:95], v[96:99], v[176:179], v[92:95]
	v_mfma_f32_16x16x32_bf16 v[88:91], v[120:123], v[176:179], v[88:91]
	v_mfma_f32_16x16x32_bf16 v[76:79], v[96:99], v[202:205], v[76:79]
	v_mfma_f32_16x16x32_bf16 v[72:75], v[120:123], v[202:205], v[72:75]
	v_mfma_f32_16x16x32_bf16 v[140:143], v[108:111], v[164:167], v[140:143]
	v_mfma_f32_16x16x32_bf16 v[136:139], v[128:131], v[164:167], v[136:139]
	v_mfma_f32_16x16x32_bf16 v[116:119], v[108:111], v[172:175], v[116:119]
	v_mfma_f32_16x16x32_bf16 v[112:115], v[128:131], v[172:175], v[112:115]
	v_mfma_f32_16x16x32_bf16 v[92:95], v[108:111], v[180:183], v[92:95]
	v_mfma_f32_16x16x32_bf16 v[88:91], v[128:131], v[180:183], v[88:91]
	v_mfma_f32_16x16x32_bf16 v[76:79], v[108:111], v[206:209], v[76:79]
	v_mfma_f32_16x16x32_bf16 v[72:75], v[128:131], v[206:209], v[72:75]
	v_mfma_f32_16x16x32_bf16 v[132:135], v[144:147], v[160:163], v[132:135]
	v_mfma_f32_16x16x32_bf16 v[124:127], v[152:155], v[160:163], v[124:127]
	v_mfma_f32_16x16x32_bf16 v[104:107], v[144:147], v[168:171], v[104:107]
	v_mfma_f32_16x16x32_bf16 v[100:103], v[152:155], v[168:171], v[100:103]
	v_mfma_f32_16x16x32_bf16 v[84:87], v[144:147], v[176:179], v[84:87]
	v_mfma_f32_16x16x32_bf16 v[80:83], v[152:155], v[176:179], v[80:83]
	v_mfma_f32_16x16x32_bf16 v[68:71], v[144:147], v[202:205], v[68:71]
	v_mfma_f32_16x16x32_bf16 v[64:67], v[152:155], v[202:205], v[64:67]
	v_mfma_f32_16x16x32_bf16 v[132:135], v[148:151], v[164:167], v[132:135]
	v_mfma_f32_16x16x32_bf16 v[124:127], v[156:159], v[164:167], v[124:127]
	v_mfma_f32_16x16x32_bf16 v[104:107], v[148:151], v[172:175], v[104:107]
	v_mfma_f32_16x16x32_bf16 v[100:103], v[156:159], v[172:175], v[100:103]
	v_mfma_f32_16x16x32_bf16 v[84:87], v[148:151], v[180:183], v[84:87]
	v_mfma_f32_16x16x32_bf16 v[80:83], v[156:159], v[180:183], v[80:83]
	v_mfma_f32_16x16x32_bf16 v[68:71], v[148:151], v[206:209], v[68:71]
	v_mfma_f32_16x16x32_bf16 v[64:67], v[156:159], v[206:209], v[64:67]
	s_barrier
; #define PG8_STAGE(bufoff, gbase, voff) do { _Pragma("unroll") for (int _i = 0; _i < 2; ++_i) \
;         __builtin_amdgcn_global_load_lds((const unsigned*)((const char*)(gbase) + (voff)[_i]), (PG8_LAS unsigned*)(lds + (bufoff) + ldsw + _i * 8192), 16, 0, 0); } while (0)
; #define PG8_LDA(dst, b, h) do { _Pragma("unroll") for (int m = 0; m < 4; ++m) _Pragma("unroll") for (int k = 0; k < 2; ++k) dst[m][k] = *(const PG8_LAS bf16x8*)(lds + PG8_SA(b, h) + aoff + m * 2048 + k * 1024); } while (0)
; #define PG8_MMA(ai, bj, At, Bt) do { __builtin_amdgcn_s_setprio(1); _Pragma("unroll") for (int m = 0; m < 4; ++m) _Pragma("unroll") for (int n = 0; n < 2; ++n) _Pragma("unroll") for (int k = 0; k < 2; ++k) \
;         acc[ai][bj][m][n] = __builtin_amdgcn_mfma_f32_16x16x32_bf16(Bt[n][k], At[m][k], acc[ai][bj][m][n], 0, 0, 0); __builtin_amdgcn_s_setprio(0); } while (0)
; #define PG8_WAIT_V(n) asm volatile("s_waitcnt vmcnt(" #n ")" ::: "memory")
; #define PG8_WAIT_L(n) asm volatile("s_waitcnt lgkmcnt(" #n ")" ::: "memory")
; #define PG8_BAR __builtin_amdgcn_s_barrier()
; #define PG8_SCHED __builtin_amdgcn_sched_barrier(0)
; template <class Epi, class Sched, bool ALIGN_EPI = false, bool SP2 = false>
; __device__ __forceinline__ void gemm_phase(PG8_LAS unsigned char* lds, const Gemm g, const Sched& S, const Epi& E) {
;     ...
;         for (int t = 0; t < nt; t += 2) {
;             const bool last = (t == nt - 2);
;             const char* a1 = cA + (size_t)(t + 1) * kstep;
;             const char* a2 = last ? nA : cA + (size_t)(t + 2) * kstep; const char* b2 = last ? nB : cB + (size_t)(t + 2) * kstep;
;             const char* a3 = a2 + kstep; const char* b3 = b2 + kstep;
;     ...
;             PG8_LDA(At, 1, 1); PG8_STAGE(PG8_SB(1, 0), b3, voffB); PG8_STAGE(PG8_SB(1, 1), b3 + hstep, voffB); PG8_STAGE(PG8_SA(1, 0), a3, voffA);
;             PG8_WAIT_V(8); PG8_WAIT_L(0); PG8_BAR; PG8_MMA(1, 0, At, B0); PG8_MMA(1, 1, At, B1); PG8_BAR; PG8_SCHED;
	s_add_i32 s56, s77, s58
	s_mov_b32 m0, s56
	ds_read_b128 v[160:163], v225 offset:49152
	ds_read_b128 v[164:167], v225 offset:50176
	ds_read_b128 v[168:171], v225 offset:51200
	ds_read_b128 v[172:175], v225 offset:52224
	ds_read_b128 v[176:179], v225 offset:53248
	ds_read_b128 v[180:183], v225 offset:54272
	ds_read_b128 v[202:205], v225 offset:55296
	ds_read_b128 v[206:209], v225 offset:56320
	global_load_lds_dwordx4 v186, s[98:99]
	s_add_i32 m0, s56, 0x2000
	s_add_u32 s54, s54, 0x40080
	s_addc_u32 s55, s55, 0
	s_add_i32 s56, s78, s58
	global_load_lds_dwordx4 v190, s[98:99]
	s_mov_b32 m0, s56
	s_nop 0
	global_load_lds_dwordx4 v186, s[54:55]
	s_add_i32 m0, s56, 0x2000
	s_nop 0
	global_load_lds_dwordx4 v190, s[54:55]
	s_mov_b32 m0, s66
	s_nop 0
	global_load_lds_dwordx4 v184, s[100:101]
	s_mov_b32 m0, s67
	s_nop 0
	global_load_lds_dwordx4 v188, s[100:101]
	s_nop 0
	s_waitcnt vmcnt(8)
	s_waitcnt lgkmcnt(0)
	s_barrier
	v_mfma_f32_16x16x32_bf16 v[60:63], v[96:99], v[160:163], v[60:63]
	v_mfma_f32_16x16x32_bf16 v[56:59], v[120:123], v[160:163], v[56:59]
	v_mfma_f32_16x16x32_bf16 v[44:47], v[96:99], v[168:171], v[44:47]
	v_mfma_f32_16x16x32_bf16 v[40:43], v[120:123], v[168:171], v[40:43]
	v_mfma_f32_16x16x32_bf16 v[28:31], v[96:99], v[176:179], v[28:31]
	v_mfma_f32_16x16x32_bf16 v[24:27], v[120:123], v[176:179], v[24:27]
	v_mfma_f32_16x16x32_bf16 v[12:15], v[96:99], v[202:205], v[12:15]
	v_mfma_f32_16x16x32_bf16 v[8:11], v[120:123], v[202:205], v[8:11]
	v_mfma_f32_16x16x32_bf16 v[60:63], v[108:111], v[164:167], v[60:63]
	v_mfma_f32_16x16x32_bf16 v[56:59], v[128:131], v[164:167], v[56:59]
	v_mfma_f32_16x16x32_bf16 v[44:47], v[108:111], v[172:175], v[44:47]
	v_mfma_f32_16x16x32_bf16 v[40:43], v[128:131], v[172:175], v[40:43]
	v_mfma_f32_16x16x32_bf16 v[28:31], v[108:111], v[180:183], v[28:31]
	v_mfma_f32_16x16x32_bf16 v[24:27], v[128:131], v[180:183], v[24:27]
	v_mfma_f32_16x16x32_bf16 v[12:15], v[108:111], v[206:209], v[12:15]
	v_mfma_f32_16x16x32_bf16 v[8:11], v[128:131], v[206:209], v[8:11]
	v_mfma_f32_16x16x32_bf16 v[52:55], v[144:147], v[160:163], v[52:55]
	v_mfma_f32_16x16x32_bf16 v[48:51], v[152:155], v[160:163], v[48:51]
	v_mfma_f32_16x16x32_bf16 v[36:39], v[144:147], v[168:171], v[36:39]
	v_mfma_f32_16x16x32_bf16 v[32:35], v[152:155], v[168:171], v[32:35]
	v_mfma_f32_16x16x32_bf16 v[20:23], v[144:147], v[176:179], v[20:23]
	v_mfma_f32_16x16x32_bf16 v[16:19], v[152:155], v[176:179], v[16:19]
	v_mfma_f32_16x16x32_bf16 v[4:7], v[144:147], v[202:205], v[4:7]
	v_mfma_f32_16x16x32_bf16 v[0:3], v[152:155], v[202:205], v[0:3]
	v_mfma_f32_16x16x32_bf16 v[52:55], v[148:151], v[164:167], v[52:55]
	v_mfma_f32_16x16x32_bf16 v[48:51], v[156:159], v[164:167], v[48:51]
	v_mfma_f32_16x16x32_bf16 v[36:39], v[148:151], v[172:175], v[36:39]
	v_mfma_f32_16x16x32_bf16 v[32:35], v[156:159], v[172:175], v[32:35]
	v_mfma_f32_16x16x32_bf16 v[20:23], v[148:151], v[180:183], v[20:23]
	v_mfma_f32_16x16x32_bf16 v[16:19], v[156:159], v[180:183], v[16:19]
	v_mfma_f32_16x16x32_bf16 v[4:7], v[148:151], v[206:209], v[4:7]
	v_mfma_f32_16x16x32_bf16 v[0:3], v[156:159], v[206:209], v[0:3]
	s_barrier
	s_add_i32 s76, s76, 2
	s_add_u32 s20, s20, 0x100
	s_addc_u32 s21, s21, 0
	s_add_u32 s74, s74, 0x100
	s_addc_u32 s75, s75, 0
	s_cmp_gt_u32 s76, 13

; #define PG8_STAGE(bufoff, gbase, voff) do { _Pragma("unroll") for (int _i = 0; _i < 2; ++_i) \
;         __builtin_amdgcn_global_load_lds((const unsigned*)((const char*)(gbase) + (voff)[_i]), (PG8_LAS unsigned*)(lds + (bufoff) + ldsw + _i * 8192), 16, 0, 0); } while (0)
; #define PG8_LDA(dst, b, h) do { _Pragma("unroll") for (int m = 0; m < 4; ++m) _Pragma("unroll") for (int k = 0; k < 2; ++k) dst[m][k] = *(const PG8_LAS bf16x8*)(lds + PG8_SA(b, h) + aoff + m * 2048 + k * 1024); } while (0)
; #define PG8_LDB(dst, b, h) do { _Pragma("unroll") for (int n = 0; n < 2; ++n) _Pragma("unroll") for (int k = 0; k < 2; ++k) dst[n][k] = *(const PG8_LAS bf16x8*)(lds + PG8_SB(b, h) + boff + n * 2048 + k * 1024); } while (0)
; #define PG8_WAIT_V(n) asm volatile("s_waitcnt vmcnt(" #n ")" ::: "memory")
; #define PG8_WAIT_L(n) asm volatile("s_waitcnt lgkmcnt(" #n ")" ::: "memory")
; #define PG8_BAR __builtin_amdgcn_s_barrier()
; #define PG8_SCHED __builtin_amdgcn_sched_barrier(0)
; template <class Epi, class Sched, bool ALIGN_EPI = false, bool SP2 = false>
; __device__ __forceinline__ void gemm_phase(PG8_LAS unsigned char* lds, const Gemm g, const Sched& S, const Epi& E) {
;     ...
;         const bool has_next = S.next(ui + 1, nxt);
;         const char* nA = has_next ? (const char*)g.A + (size_t)nxt.pm * tstep : cA; const char* nB = has_next ? (const char*)g.Bt + (size_t)nxt.pn * tstep : cB;
;         for (int t = 0; t < nt; t += 2) {
;             const bool last = (t == nt - 2);
;             const char* a1 = cA + (size_t)(t + 1) * kstep;
;             const char* a2 = last ? nA : cA + (size_t)(t + 2) * kstep; const char* b2 = last ? nB : cB + (size_t)(t + 2) * kstep;
;             const char* a3 = a2 + kstep; const char* b3 = b2 + kstep;
;             if (last && has_next) S.a_ready(nxt);
;             if constexpr (SP2) {
;             PG8_LDB(B0, 0, 0); PG8_LDB(B1, 0, 1); PG8_SCHED; PG8_LDA(At, 0, 0); PG8_STAGE(PG8_SA(1, 1), a1 + hstep, voffA);
;             PG8_WAIT_V(8); PG8_WAIT_L(0); PG8_BAR; PG8_MMA(0, 0, At, B0); PG8_MMA(0, 1, At, B1); PG8_BAR; PG8_SCHED;
;             PG8_LDA(At, 0, 1); PG8_STAGE(PG8_SB(0, 0), b2, voffB); PG8_STAGE(PG8_SB(0, 1), b2 + hstep, voffB); PG8_STAGE(PG8_SA(0, 0), a2, voffA);
;             PG8_WAIT_V(8); PG8_WAIT_L(0); PG8_BAR; PG8_MMA(1, 0, At, B0); PG8_MMA(1, 1, At, B1); PG8_BAR; PG8_SCHED;
.LBB0_1739:
	s_ashr_i32 s15, s14, 31
	s_lshl_b64 s[16:17], s[14:15], 19
	s_add_u32 s16, s36, s16
	s_addc_u32 s17, s37, s17
	s_and_b64 s[18:19], s[4:5], exec
	s_cselect_b32 s15, s17, s21
	s_cselect_b32 s63, s16, s20
	s_ashr_i32 s13, s12, 31
	s_lshl_b64 s[18:19], s[12:13], 19
	s_add_u32 s18, s48, s18
	s_addc_u32 s19, s49, s19
	s_and_b64 s[42:43], s[4:5], exec
	s_cselect_b32 s13, s19, s39
	s_cselect_b32 s64, s18, s38
	s_add_u32 s20, s20, 0x40080
	s_addc_u32 s21, s21, 0
	s_add_u32 s65, s38, 0x100
	s_addc_u32 s66, s39, 0
	s_mov_b32 s67, -2
	ds_read_b128 v[154:157], v150
	ds_read_b128 v[158:161], v150 offset:1024
	ds_read_b128 v[162:165], v150 offset:2048
	ds_read_b128 v[166:169], v150 offset:3072
	ds_read_b128 v[170:173], v151
	ds_read_b128 v[174:177], v151 offset:1024
	ds_read_b128 v[178:181], v151 offset:2048
	ds_read_b128 v[182:185], v151 offset:3072
	s_add_u32 s38, s20, 0xfffc0080
	s_addc_u32 s39, s21, -1
	s_cmp_eq_u32 s67, 12
	s_cselect_b32 s43, s15, s39
	s_cselect_b32 s42, s63, s38
	s_cselect_b32 s39, s13, s66
	s_cselect_b32 s38, s64, s65
	s_add_i32 m0, s35, 0xc000
	ds_read_b128 v[186:189], v152
	ds_read_b128 v[190:193], v152 offset:1024
	ds_read_b128 v[198:201], v152 offset:2048
	ds_read_b128 v[202:205], v152 offset:3072
	ds_read_b128 v[206:209], v152 offset:4096
	ds_read_b128 v[210:213], v152 offset:5120
	ds_read_b128 v[214:217], v152 offset:6144
	ds_read_b128 v[218:221], v152 offset:7168
	global_load_lds_dwordx4 v136, s[20:21]
	s_add_i32 m0, s35, 0xe000
	s_nop 0
	global_load_lds_dwordx4 v138, s[20:21]
	s_nop 0
	s_waitcnt vmcnt(8)
	s_waitcnt lgkmcnt(0)
	s_barrier
	v_mfma_f32_16x16x32_bf16 v[124:127], v[154:157], v[186:189], 0
	v_mfma_f32_16x16x32_bf16 v[116:119], v[162:165], v[186:189], 0
	v_mfma_f32_16x16x32_bf16 v[108:111], v[154:157], v[198:201], 0
	v_mfma_f32_16x16x32_bf16 v[100:103], v[162:165], v[198:201], 0
	v_mfma_f32_16x16x32_bf16 v[92:95], v[154:157], v[206:209], 0
	v_mfma_f32_16x16x32_bf16 v[84:87], v[162:165], v[206:209], 0
	v_mfma_f32_16x16x32_bf16 v[76:79], v[154:157], v[214:217], 0
	v_mfma_f32_16x16x32_bf16 v[68:71], v[162:165], v[214:217], 0
	v_mfma_f32_16x16x32_bf16 v[124:127], v[158:161], v[190:193], v[124:127]
	v_mfma_f32_16x16x32_bf16 v[116:119], v[166:169], v[190:193], v[116:119]
	v_mfma_f32_16x16x32_bf16 v[108:111], v[158:161], v[202:205], v[108:111]
	v_mfma_f32_16x16x32_bf16 v[100:103], v[166:169], v[202:205], v[100:103]
	v_mfma_f32_16x16x32_bf16 v[92:95], v[158:161], v[210:213], v[92:95]
	v_mfma_f32_16x16x32_bf16 v[84:87], v[166:169], v[210:213], v[84:87]
	v_mfma_f32_16x16x32_bf16 v[76:79], v[158:161], v[218:221], v[76:79]
	v_mfma_f32_16x16x32_bf16 v[68:71], v[166:169], v[218:221], v[68:71]
	v_mfma_f32_16x16x32_bf16 v[120:123], v[170:173], v[186:189], 0
	v_mfma_f32_16x16x32_bf16 v[112:115], v[178:181], v[186:189], 0
	v_mfma_f32_16x16x32_bf16 v[104:107], v[170:173], v[198:201], 0
	v_mfma_f32_16x16x32_bf16 v[96:99], v[178:181], v[198:201], 0
	v_mfma_f32_16x16x32_bf16 v[88:91], v[170:173], v[206:209], 0
	v_mfma_f32_16x16x32_bf16 v[80:83], v[178:181], v[206:209], 0
	v_mfma_f32_16x16x32_bf16 v[72:75], v[170:173], v[214:217], 0
	v_mfma_f32_16x16x32_bf16 v[64:67], v[178:181], v[214:217], 0
	v_mfma_f32_16x16x32_bf16 v[120:123], v[174:177], v[190:193], v[120:123]
	v_mfma_f32_16x16x32_bf16 v[112:115], v[182:185], v[190:193], v[112:115]
	v_mfma_f32_16x16x32_bf16 v[104:107], v[174:177], v[202:205], v[104:107]
	v_mfma_f32_16x16x32_bf16 v[96:99], v[182:185], v[202:205], v[96:99]
	v_mfma_f32_16x16x32_bf16 v[88:91], v[174:177], v[210:213], v[88:91]
	v_mfma_f32_16x16x32_bf16 v[80:83], v[182:185], v[210:213], v[80:83]
	v_mfma_f32_16x16x32_bf16 v[72:75], v[174:177], v[218:221], v[72:75]
	v_mfma_f32_16x16x32_bf16 v[64:67], v[182:185], v[218:221], v[64:67]
	s_barrier
	s_add_i32 s68, s58, s50
	s_add_u32 s98, s38, s8
	s_addc_u32 s99, s39, s9
	s_add_u32 s100, s42, s8
	s_addc_u32 s101, s43, s9
	s_mov_b32 m0, s68
	ds_read_b128 v[186:189], v152 offset:16384
	ds_read_b128 v[190:193], v152 offset:17408
	ds_read_b128 v[198:201], v152 offset:18432
	ds_read_b128 v[202:205], v152 offset:19456
	ds_read_b128 v[206:209], v152 offset:20480
	ds_read_b128 v[210:213], v152 offset:21504
	ds_read_b128 v[214:217], v152 offset:22528
	ds_read_b128 v[218:221], v152 offset:23552
	global_load_lds_dwordx4 v132, s[38:39]
	s_add_i32 m0, s68, 0x2000
	s_add_u32 s68, s38, 0x40000
	s_addc_u32 s69, s39, 0
	s_add_i32 s70, s59, s50
	global_load_lds_dwordx4 v128, s[38:39]
	s_mov_b32 m0, s70
	s_nop 0
	global_load_lds_dwordx4 v132, s[68:69]
	s_add_i32 m0, s70, 0x2000
	s_nop 0
	global_load_lds_dwordx4 v128, s[68:69]
	s_mov_b32 m0, s35
	s_nop 0
	global_load_lds_dwordx4 v134, s[42:43]
	s_mov_b32 m0, s52
	s_nop 0
	global_load_lds_dwordx4 v130, s[42:43]
	s_nop 0
	s_waitcnt vmcnt(8)
	s_waitcnt lgkmcnt(0)
	s_barrier
; #define PG8_STAGE(bufoff, gbase, voff) do { _Pragma("unroll") for (int _i = 0; _i < 2; ++_i) \
;         __builtin_amdgcn_global_load_lds((const unsigned*)((const char*)(gbase) + (voff)[_i]), (PG8_LAS unsigned*)(lds + (bufoff) + ldsw + _i * 8192), 16, 0, 0); } while (0)
; #define PG8_LDA(dst, b, h) do { _Pragma("unroll") for (int m = 0; m < 4; ++m) _Pragma("unroll") for (int k = 0; k < 2; ++k) dst[m][k] = *(const PG8_LAS bf16x8*)(lds + PG8_SA(b, h) + aoff + m * 2048 + k * 1024); } while (0)
; #define PG8_LDB(dst, b, h) do { _Pragma("unroll") for (int n = 0; n < 2; ++n) _Pragma("unroll") for (int k = 0; k < 2; ++k) dst[n][k] = *(const PG8_LAS bf16x8*)(lds + PG8_SB(b, h) + boff + n * 2048 + k * 1024); } while (0)
; #define PG8_MMA(ai, bj, At, Bt) do { __builtin_amdgcn_s_setprio(1); _Pragma("unroll") for (int m = 0; m < 4; ++m) _Pragma("unroll") for (int n = 0; n < 2; ++n) _Pragma("unroll") for (int k = 0; k < 2; ++k) \
;         acc[ai][bj][m][n] = __builtin_amdgcn_mfma_f32_16x16x32_bf16(Bt[n][k], At[m][k], acc[ai][bj][m][n], 0, 0, 0); __builtin_amdgcn_s_setprio(0); } while (0)
; #define PG8_WAIT_V(n) asm volatile("s_waitcnt vmcnt(" #n ")" ::: "memory")
; #define PG8_WAIT_L(n) asm volatile("s_waitcnt lgkmcnt(" #n ")" ::: "memory")
; #define PG8_BAR __builtin_amdgcn_s_barrier()
; #define PG8_SCHED __builtin_amdgcn_sched_barrier(0)
; template <class Epi, class Sched, bool ALIGN_EPI = false, bool SP2 = false>
; __device__ __forceinline__ void gemm_phase(PG8_LAS unsigned char* lds, const Gemm g, const Sched& S, const Epi& E) {
;     ...
;             PG8_WAIT_V(8); PG8_WAIT_L(0); PG8_BAR; PG8_MMA(1, 0, At, B0); PG8_MMA(1, 1, At, B1); PG8_BAR; PG8_SCHED;
;             PG8_LDB(B0, 1, 0); PG8_LDB(B1, 1, 1); PG8_SCHED; PG8_LDA(At, 1, 0); PG8_STAGE(PG8_SA(0, 1), a2 + hstep, voffA);
;             PG8_WAIT_V(8); PG8_WAIT_L(0); PG8_BAR; PG8_MMA(0, 0, At, B0); PG8_MMA(0, 1, At, B1); PG8_BAR; PG8_SCHED;
	v_mfma_f32_16x16x32_bf16 v[60:63], v[154:157], v[186:189], 0
	v_mfma_f32_16x16x32_bf16 v[52:55], v[162:165], v[186:189], 0
	v_mfma_f32_16x16x32_bf16 v[44:47], v[154:157], v[198:201], 0
	v_mfma_f32_16x16x32_bf16 v[36:39], v[162:165], v[198:201], 0
	v_mfma_f32_16x16x32_bf16 v[28:31], v[154:157], v[206:209], 0
	v_mfma_f32_16x16x32_bf16 v[20:23], v[162:165], v[206:209], 0
	v_mfma_f32_16x16x32_bf16 v[12:15], v[154:157], v[214:217], 0
	v_mfma_f32_16x16x32_bf16 v[4:7], v[162:165], v[214:217], 0
	v_mfma_f32_16x16x32_bf16 v[60:63], v[158:161], v[190:193], v[60:63]
	v_mfma_f32_16x16x32_bf16 v[52:55], v[166:169], v[190:193], v[52:55]
	v_mfma_f32_16x16x32_bf16 v[44:47], v[158:161], v[202:205], v[44:47]
	v_mfma_f32_16x16x32_bf16 v[36:39], v[166:169], v[202:205], v[36:39]
	v_mfma_f32_16x16x32_bf16 v[28:31], v[158:161], v[210:213], v[28:31]
	v_mfma_f32_16x16x32_bf16 v[20:23], v[166:169], v[210:213], v[20:23]
	v_mfma_f32_16x16x32_bf16 v[12:15], v[158:161], v[218:221], v[12:15]
	v_mfma_f32_16x16x32_bf16 v[4:7], v[166:169], v[218:221], v[4:7]
	v_mfma_f32_16x16x32_bf16 v[56:59], v[170:173], v[186:189], 0
	v_mfma_f32_16x16x32_bf16 v[48:51], v[178:181], v[186:189], 0
	v_mfma_f32_16x16x32_bf16 v[40:43], v[170:173], v[198:201], 0
	v_mfma_f32_16x16x32_bf16 v[32:35], v[178:181], v[198:201], 0
	v_mfma_f32_16x16x32_bf16 v[24:27], v[170:173], v[206:209], 0
	v_mfma_f32_16x16x32_bf16 v[16:19], v[178:181], v[206:209], 0
	v_mfma_f32_16x16x32_bf16 v[8:11], v[170:173], v[214:217], 0
	v_mfma_f32_16x16x32_bf16 v[0:3], v[178:181], v[214:217], 0
	v_mfma_f32_16x16x32_bf16 v[56:59], v[174:177], v[190:193], v[56:59]
	v_mfma_f32_16x16x32_bf16 v[48:51], v[182:185], v[190:193], v[48:51]
	v_mfma_f32_16x16x32_bf16 v[40:43], v[174:177], v[202:205], v[40:43]
	v_mfma_f32_16x16x32_bf16 v[32:35], v[182:185], v[202:205], v[32:35]
	v_mfma_f32_16x16x32_bf16 v[24:27], v[174:177], v[210:213], v[24:27]
	v_mfma_f32_16x16x32_bf16 v[16:19], v[182:185], v[210:213], v[16:19]
	v_mfma_f32_16x16x32_bf16 v[8:11], v[174:177], v[218:221], v[8:11]
	v_mfma_f32_16x16x32_bf16 v[0:3], v[182:185], v[218:221], v[0:3]
	s_barrier
	s_add_i32 s68, 0, 0x18000
	v_add_u32_e32 v153, s68, v147
	s_add_i32 s69, 0, 0x1c000
	ds_read_b128 v[154:157], v153
	ds_read_b128 v[158:161], v153 offset:1024
	ds_read_b128 v[162:165], v153 offset:2048
	ds_read_b128 v[166:169], v153 offset:3072
	v_add_u32_e32 v153, s69, v147
	ds_read_b128 v[170:173], v153
	ds_read_b128 v[174:177], v153 offset:1024
	ds_read_b128 v[178:181], v153 offset:2048
	ds_read_b128 v[182:185], v153 offset:3072
	s_add_u32 s42, s42, 0x40000
	s_addc_u32 s43, s43, 0
	s_mov_b32 m0, s53
	ds_read_b128 v[186:189], v152 offset:32768
	ds_read_b128 v[190:193], v152 offset:33792
	ds_read_b128 v[198:201], v152 offset:34816
	ds_read_b128 v[202:205], v152 offset:35840
	ds_read_b128 v[206:209], v152 offset:36864
	ds_read_b128 v[210:213], v152 offset:37888
	ds_read_b128 v[214:217], v152 offset:38912
	ds_read_b128 v[218:221], v152 offset:39936
	global_load_lds_dwordx4 v134, s[42:43]
	s_mov_b32 m0, s54
	s_nop 0
	global_load_lds_dwordx4 v130, s[42:43]
	s_waitcnt vmcnt(8)
	s_waitcnt lgkmcnt(0)
	s_barrier
	v_mfma_f32_16x16x32_bf16 v[124:127], v[154:157], v[186:189], v[124:127]
	v_mfma_f32_16x16x32_bf16 v[116:119], v[162:165], v[186:189], v[116:119]
	v_mfma_f32_16x16x32_bf16 v[108:111], v[154:157], v[198:201], v[108:111]
	v_mfma_f32_16x16x32_bf16 v[100:103], v[162:165], v[198:201], v[100:103]
	v_mfma_f32_16x16x32_bf16 v[92:95], v[154:157], v[206:209], v[92:95]
	v_mfma_f32_16x16x32_bf16 v[84:87], v[162:165], v[206:209], v[84:87]
	v_mfma_f32_16x16x32_bf16 v[76:79], v[154:157], v[214:217], v[76:79]
	v_mfma_f32_16x16x32_bf16 v[68:71], v[162:165], v[214:217], v[68:71]
	v_mfma_f32_16x16x32_bf16 v[124:127], v[158:161], v[190:193], v[124:127]
	v_mfma_f32_16x16x32_bf16 v[116:119], v[166:169], v[190:193], v[116:119]
	v_mfma_f32_16x16x32_bf16 v[108:111], v[158:161], v[202:205], v[108:111]
	v_mfma_f32_16x16x32_bf16 v[100:103], v[166:169], v[202:205], v[100:103]
	v_mfma_f32_16x16x32_bf16 v[92:95], v[158:161], v[210:213], v[92:95]
	v_mfma_f32_16x16x32_bf16 v[84:87], v[166:169], v[210:213], v[84:87]
	v_mfma_f32_16x16x32_bf16 v[76:79], v[158:161], v[218:221], v[76:79]
	v_mfma_f32_16x16x32_bf16 v[68:71], v[166:169], v[218:221], v[68:71]
	v_mfma_f32_16x16x32_bf16 v[120:123], v[170:173], v[186:189], v[120:123]
	v_mfma_f32_16x16x32_bf16 v[112:115], v[178:181], v[186:189], v[112:115]
	v_mfma_f32_16x16x32_bf16 v[104:107], v[170:173], v[198:201], v[104:107]
	v_mfma_f32_16x16x32_bf16 v[96:99], v[178:181], v[198:201], v[96:99]
	v_mfma_f32_16x16x32_bf16 v[88:91], v[170:173], v[206:209], v[88:91]
	v_mfma_f32_16x16x32_bf16 v[80:83], v[178:181], v[206:209], v[80:83]
	v_mfma_f32_16x16x32_bf16 v[72:75], v[170:173], v[214:217], v[72:75]
	v_mfma_f32_16x16x32_bf16 v[64:67], v[178:181], v[214:217], v[64:67]
	v_mfma_f32_16x16x32_bf16 v[120:123], v[174:177], v[190:193], v[120:123]
	v_mfma_f32_16x16x32_bf16 v[112:115], v[182:185], v[190:193], v[112:115]
	v_mfma_f32_16x16x32_bf16 v[104:107], v[174:177], v[202:205], v[104:107]
	v_mfma_f32_16x16x32_bf16 v[96:99], v[182:185], v[202:205], v[96:99]
	v_mfma_f32_16x16x32_bf16 v[88:91], v[174:177], v[210:213], v[88:91]
	v_mfma_f32_16x16x32_bf16 v[80:83], v[182:185], v[210:213], v[80:83]
	v_mfma_f32_16x16x32_bf16 v[72:75], v[174:177], v[218:221], v[72:75]
	v_mfma_f32_16x16x32_bf16 v[64:67], v[182:185], v[218:221], v[64:67]
	s_barrier
; #define PG8_STAGE(bufoff, gbase, voff) do { _Pragma("unroll") for (int _i = 0; _i < 2; ++_i) \
;         __builtin_amdgcn_global_load_lds((const unsigned*)((const char*)(gbase) + (voff)[_i]), (PG8_LAS unsigned*)(lds + (bufoff) + ldsw + _i * 8192), 16, 0, 0); } while (0)
; #define PG8_LDA(dst, b, h) do { _Pragma("unroll") for (int m = 0; m < 4; ++m) _Pragma("unroll") for (int k = 0; k < 2; ++k) dst[m][k] = *(const PG8_LAS bf16x8*)(lds + PG8_SA(b, h) + aoff + m * 2048 + k * 1024); } while (0)
; #define PG8_LDB(dst, b, h) do { _Pragma("unroll") for (int n = 0; n < 2; ++n) _Pragma("unroll") for (int k = 0; k < 2; ++k) dst[n][k] = *(const PG8_LAS bf16x8*)(lds + PG8_SB(b, h) + boff + n * 2048 + k * 1024); } while (0)
; #define PG8_MMA(ai, bj, At, Bt) do { __builtin_amdgcn_s_setprio(1); _Pragma("unroll") for (int m = 0; m < 4; ++m) _Pragma("unroll") for (int n = 0; n < 2; ++n) _Pragma("unroll") for (int k = 0; k < 2; ++k) \
;         acc[ai][bj][m][n] = __builtin_amdgcn_mfma_f32_16x16x32_bf16(Bt[n][k], At[m][k], acc[ai][bj][m][n], 0, 0, 0); __builtin_amdgcn_s_setprio(0); } while (0)
; #define PG8_WAIT_V(n) asm volatile("s_waitcnt vmcnt(" #n ")" ::: "memory")
; #define PG8_WAIT_L(n) asm volatile("s_waitcnt lgkmcnt(" #n ")" ::: "memory")
; #define PG8_BAR __builtin_amdgcn_s_barrier()
; #define PG8_SCHED __builtin_amdgcn_sched_barrier(0)
; template <class Epi, class Sched, bool ALIGN_EPI = false, bool SP2 = false>
; __device__ __forceinline__ void gemm_phase(PG8_LAS unsigned char* lds, const Gemm g, const Sched& S, const Epi& E) {
;     ...
;             PG8_LDB(B0, 0, 0); PG8_LDB(B1, 0, 1); PG8_SCHED; PG8_LDA(At, 0, 0); PG8_STAGE(PG8_SA(1, 1), a1 + hstep, voffA);
;             PG8_WAIT_V(8); PG8_WAIT_L(0); PG8_BAR; PG8_MMA(0, 0, At, B0); PG8_MMA(0, 1, At, B1); PG8_BAR; PG8_SCHED;
;     ...
;             PG8_LDA(At, 1, 1); PG8_STAGE(PG8_SB(1, 0), b3, voffB); PG8_STAGE(PG8_SB(1, 1), b3 + hstep, voffB); PG8_STAGE(PG8_SA(1, 0), a3, voffA);
;             PG8_WAIT_V(8); PG8_WAIT_L(0); PG8_BAR; PG8_MMA(1, 0, At, B0); PG8_MMA(1, 1, At, B1); PG8_BAR; PG8_SCHED;
	s_add_i32 s42, s68, s50
	s_mov_b32 m0, s42
	ds_read_b128 v[186:189], v152 offset:49152
	ds_read_b128 v[190:193], v152 offset:50176
	ds_read_b128 v[198:201], v152 offset:51200
	ds_read_b128 v[202:205], v152 offset:52224
	ds_read_b128 v[206:209], v152 offset:53248
	ds_read_b128 v[210:213], v152 offset:54272
	ds_read_b128 v[214:217], v152 offset:55296
	ds_read_b128 v[218:221], v152 offset:56320
	global_load_lds_dwordx4 v132, s[98:99]
	s_add_i32 m0, s42, 0x2000
	s_add_u32 s38, s38, 0x40080
	s_addc_u32 s39, s39, 0
	s_add_i32 s42, s69, s50
	global_load_lds_dwordx4 v128, s[98:99]
	s_mov_b32 m0, s42
	s_nop 0
	global_load_lds_dwordx4 v132, s[38:39]
	s_add_i32 m0, s42, 0x2000
	s_nop 0
	global_load_lds_dwordx4 v128, s[38:39]
	s_mov_b32 m0, s56
	s_nop 0
	global_load_lds_dwordx4 v134, s[100:101]
	s_mov_b32 m0, s57
	s_nop 0
	global_load_lds_dwordx4 v130, s[100:101]
	s_nop 0
	s_waitcnt vmcnt(8)
	s_waitcnt lgkmcnt(0)
	s_barrier
	v_mfma_f32_16x16x32_bf16 v[60:63], v[154:157], v[186:189], v[60:63]
	v_mfma_f32_16x16x32_bf16 v[52:55], v[162:165], v[186:189], v[52:55]
	v_mfma_f32_16x16x32_bf16 v[44:47], v[154:157], v[198:201], v[44:47]
	v_mfma_f32_16x16x32_bf16 v[36:39], v[162:165], v[198:201], v[36:39]
	v_mfma_f32_16x16x32_bf16 v[28:31], v[154:157], v[206:209], v[28:31]
	v_mfma_f32_16x16x32_bf16 v[20:23], v[162:165], v[206:209], v[20:23]
	v_mfma_f32_16x16x32_bf16 v[12:15], v[154:157], v[214:217], v[12:15]
	v_mfma_f32_16x16x32_bf16 v[4:7], v[162:165], v[214:217], v[4:7]
	v_mfma_f32_16x16x32_bf16 v[60:63], v[158:161], v[190:193], v[60:63]
	v_mfma_f32_16x16x32_bf16 v[52:55], v[166:169], v[190:193], v[52:55]
	v_mfma_f32_16x16x32_bf16 v[44:47], v[158:161], v[202:205], v[44:47]
	v_mfma_f32_16x16x32_bf16 v[36:39], v[166:169], v[202:205], v[36:39]
	v_mfma_f32_16x16x32_bf16 v[28:31], v[158:161], v[210:213], v[28:31]
	v_mfma_f32_16x16x32_bf16 v[20:23], v[166:169], v[210:213], v[20:23]
	v_mfma_f32_16x16x32_bf16 v[12:15], v[158:161], v[218:221], v[12:15]
	v_mfma_f32_16x16x32_bf16 v[4:7], v[166:169], v[218:221], v[4:7]
	v_mfma_f32_16x16x32_bf16 v[56:59], v[170:173], v[186:189], v[56:59]
	v_mfma_f32_16x16x32_bf16 v[48:51], v[178:181], v[186:189], v[48:51]
	v_mfma_f32_16x16x32_bf16 v[40:43], v[170:173], v[198:201], v[40:43]
	v_mfma_f32_16x16x32_bf16 v[32:35], v[178:181], v[198:201], v[32:35]
	v_mfma_f32_16x16x32_bf16 v[24:27], v[170:173], v[206:209], v[24:27]
	v_mfma_f32_16x16x32_bf16 v[16:19], v[178:181], v[206:209], v[16:19]
	v_mfma_f32_16x16x32_bf16 v[8:11], v[170:173], v[214:217], v[8:11]
	v_mfma_f32_16x16x32_bf16 v[0:3], v[178:181], v[214:217], v[0:3]
	v_mfma_f32_16x16x32_bf16 v[56:59], v[174:177], v[190:193], v[56:59]
	v_mfma_f32_16x16x32_bf16 v[48:51], v[182:185], v[190:193], v[48:51]
	v_mfma_f32_16x16x32_bf16 v[40:43], v[174:177], v[202:205], v[40:43]
	v_mfma_f32_16x16x32_bf16 v[32:35], v[182:185], v[202:205], v[32:35]
	v_mfma_f32_16x16x32_bf16 v[24:27], v[174:177], v[210:213], v[24:27]
	v_mfma_f32_16x16x32_bf16 v[16:19], v[182:185], v[210:213], v[16:19]
	v_mfma_f32_16x16x32_bf16 v[8:11], v[174:177], v[218:221], v[8:11]
	v_mfma_f32_16x16x32_bf16 v[0:3], v[182:185], v[218:221], v[0:3]
	s_barrier
	s_add_i32 s67, s67, 2
	s_add_u32 s20, s20, 0x100
	s_addc_u32 s21, s21, 0
	s_add_u32 s65, s65, 0x100
	s_addc_u32 s66, s66, 0
	s_cmp_gt_u32 s67, 13
.LBB0_1740:
	ds_read_b128 v[154:157], v150
	ds_read_b128 v[158:161], v150 offset:1024
	ds_read_b128 v[162:165], v150 offset:2048
	ds_read_b128 v[166:169], v150 offset:3072
	ds_read_b128 v[170:173], v151
	ds_read_b128 v[174:177], v151 offset:1024
	ds_read_b128 v[178:181], v151 offset:2048
	ds_read_b128 v[182:185], v151 offset:3072
	s_add_u32 s38, s20, 0xfffc0080
	s_addc_u32 s39, s21, -1
	s_cmp_eq_u32 s67, 12
	s_cselect_b32 s43, s15, s39
	s_cselect_b32 s42, s63, s38
	s_cselect_b32 s39, s13, s66
	s_cselect_b32 s38, s64, s65
	s_add_i32 m0, s35, 0xc000
	ds_read_b128 v[186:189], v152
	ds_read_b128 v[190:193], v152 offset:1024
	ds_read_b128 v[198:201], v152 offset:2048
	ds_read_b128 v[202:205], v152 offset:3072
	ds_read_b128 v[206:209], v152 offset:4096
	ds_read_b128 v[210:213], v152 offset:5120
	ds_read_b128 v[214:217], v152 offset:6144
	ds_read_b128 v[218:221], v152 offset:7168
	global_load_lds_dwordx4 v136, s[20:21]
	s_add_i32 m0, s35, 0xe000
	s_nop 0
	global_load_lds_dwordx4 v138, s[20:21]
	s_nop 0
	s_waitcnt vmcnt(8)
	s_waitcnt lgkmcnt(0)
	s_barrier
	v_mfma_f32_16x16x32_bf16 v[124:127], v[154:157], v[186:189], v[124:127]
	v_mfma_f32_16x16x32_bf16 v[116:119], v[162:165], v[186:189], v[116:119]
	v_mfma_f32_16x16x32_bf16 v[108:111], v[154:157], v[198:201], v[108:111]
	v_mfma_f32_16x16x32_bf16 v[100:103], v[162:165], v[198:201], v[100:103]
	v_mfma_f32_16x16x32_bf16 v[92:95], v[154:157], v[206:209], v[92:95]
	v_mfma_f32_16x16x32_bf16 v[84:87], v[162:165], v[206:209], v[84:87]
	v_mfma_f32_16x16x32_bf16 v[76:79], v[154:157], v[214:217], v[76:79]
	v_mfma_f32_16x16x32_bf16 v[68:71], v[162:165], v[214:217], v[68:71]
	v_mfma_f32_16x16x32_bf16 v[124:127], v[158:161], v[190:193], v[124:127]
	v_mfma_f32_16x16x32_bf16 v[116:119], v[166:169], v[190:193], v[116:119]
	v_mfma_f32_16x16x32_bf16 v[108:111], v[158:161], v[202:205], v[108:111]
	v_mfma_f32_16x16x32_bf16 v[100:103], v[166:169], v[202:205], v[100:103]
	v_mfma_f32_16x16x32_bf16 v[92:95], v[158:161], v[210:213], v[92:95]
	v_mfma_f32_16x16x32_bf16 v[84:87], v[166:169], v[210:213], v[84:87]
	v_mfma_f32_16x16x32_bf16 v[76:79], v[158:161], v[218:221], v[76:79]
	v_mfma_f32_16x16x32_bf16 v[68:71], v[166:169], v[218:221], v[68:71]
	v_mfma_f32_16x16x32_bf16 v[120:123], v[170:173], v[186:189], v[120:123]
	v_mfma_f32_16x16x32_bf16 v[112:115], v[178:181], v[186:189], v[112:115]
	v_mfma_f32_16x16x32_bf16 v[104:107], v[170:173], v[198:201], v[104:107]
	v_mfma_f32_16x16x32_bf16 v[96:99], v[178:181], v[198:201], v[96:99]
	v_mfma_f32_16x16x32_bf16 v[88:91], v[170:173], v[206:209], v[88:91]
	v_mfma_f32_16x16x32_bf16 v[80:83], v[178:181], v[206:209], v[80:83]
	v_mfma_f32_16x16x32_bf16 v[72:75], v[170:173], v[214:217], v[72:75]
	v_mfma_f32_16x16x32_bf16 v[64:67], v[178:181], v[214:217], v[64:67]
	v_mfma_f32_16x16x32_bf16 v[120:123], v[174:177], v[190:193], v[120:123]
	v_mfma_f32_16x16x32_bf16 v[112:115], v[182:185], v[190:193], v[112:115]
	v_mfma_f32_16x16x32_bf16 v[104:107], v[174:177], v[202:205], v[104:107]
	v_mfma_f32_16x16x32_bf16 v[96:99], v[182:185], v[202:205], v[96:99]
	v_mfma_f32_16x16x32_bf16 v[88:91], v[174:177], v[210:213], v[88:91]
	v_mfma_f32_16x16x32_bf16 v[80:83], v[182:185], v[210:213], v[80:83]
	v_mfma_f32_16x16x32_bf16 v[72:75], v[174:177], v[218:221], v[72:75]
	v_mfma_f32_16x16x32_bf16 v[64:67], v[182:185], v[218:221], v[64:67]
	s_barrier
; #define PG8_STAGE(bufoff, gbase, voff) do { _Pragma("unroll") for (int _i = 0; _i < 2; ++_i) \
;         __builtin_amdgcn_global_load_lds((const unsigned*)((const char*)(gbase) + (voff)[_i]), (PG8_LAS unsigned*)(lds + (bufoff) + ldsw + _i * 8192), 16, 0, 0); } while (0)
; #define PG8_LDA(dst, b, h) do { _Pragma("unroll") for (int m = 0; m < 4; ++m) _Pragma("unroll") for (int k = 0; k < 2; ++k) dst[m][k] = *(const PG8_LAS bf16x8*)(lds + PG8_SA(b, h) + aoff + m * 2048 + k * 1024); } while (0)
; #define PG8_LDB(dst, b, h) do { _Pragma("unroll") for (int n = 0; n < 2; ++n) _Pragma("unroll") for (int k = 0; k < 2; ++k) dst[n][k] = *(const PG8_LAS bf16x8*)(lds + PG8_SB(b, h) + boff + n * 2048 + k * 1024); } while (0)
; #define PG8_MMA(ai, bj, At, Bt) do { __builtin_amdgcn_s_setprio(1); _Pragma("unroll") for (int m = 0; m < 4; ++m) _Pragma("unroll") for (int n = 0; n < 2; ++n) _Pragma("unroll") for (int k = 0; k < 2; ++k) \
;         acc[ai][bj][m][n] = __builtin_amdgcn_mfma_f32_16x16x32_bf16(Bt[n][k], At[m][k], acc[ai][bj][m][n], 0, 0, 0); __builtin_amdgcn_s_setprio(0); } while (0)
; #define PG8_WAIT_V(n) asm volatile("s_waitcnt vmcnt(" #n ")" ::: "memory")
; #define PG8_WAIT_L(n) asm volatile("s_waitcnt lgkmcnt(" #n ")" ::: "memory")
; #define PG8_BAR __builtin_amdgcn_s_barrier()
; #define PG8_SCHED __builtin_amdgcn_sched_barrier(0)
; template <class Epi, class Sched, bool ALIGN_EPI = false, bool SP2 = false>
; __device__ __forceinline__ void gemm_phase(PG8_LAS unsigned char* lds, const Gemm g, const Sched& S, const Epi& E) {
;     ...
;             PG8_LDA(At, 0, 1); PG8_STAGE(PG8_SB(0, 0), b2, voffB); PG8_STAGE(PG8_SB(0, 1), b2 + hstep, voffB); PG8_STAGE(PG8_SA(0, 0), a2, voffA);
;             PG8_WAIT_V(8); PG8_WAIT_L(0); PG8_BAR; PG8_MMA(1, 0, At, B0); PG8_MMA(1, 1, At, B1); PG8_BAR; PG8_SCHED;
;             PG8_LDB(B0, 1, 0); PG8_LDB(B1, 1, 1); PG8_SCHED; PG8_LDA(At, 1, 0); PG8_STAGE(PG8_SA(0, 1), a2 + hstep, voffA);
;             PG8_WAIT_V(8); PG8_WAIT_L(0); PG8_BAR; PG8_MMA(0, 0, At, B0); PG8_MMA(0, 1, At, B1); PG8_BAR; PG8_SCHED;
	s_add_i32 s68, s58, s50
	s_add_u32 s98, s38, s8
	s_addc_u32 s99, s39, s9
	s_add_u32 s100, s42, s8
	s_addc_u32 s101, s43, s9
	s_mov_b32 m0, s68
	ds_read_b128 v[186:189], v152 offset:16384
	ds_read_b128 v[190:193], v152 offset:17408
	ds_read_b128 v[198:201], v152 offset:18432
	ds_read_b128 v[202:205], v152 offset:19456
	ds_read_b128 v[206:209], v152 offset:20480
	ds_read_b128 v[210:213], v152 offset:21504
	ds_read_b128 v[214:217], v152 offset:22528
	ds_read_b128 v[218:221], v152 offset:23552
	global_load_lds_dwordx4 v132, s[38:39]
	s_add_i32 m0, s68, 0x2000
	s_add_u32 s68, s38, 0x40000
	s_addc_u32 s69, s39, 0
	s_add_i32 s70, s59, s50
	global_load_lds_dwordx4 v128, s[38:39]
	s_mov_b32 m0, s70
	s_nop 0
	global_load_lds_dwordx4 v132, s[68:69]
	s_add_i32 m0, s70, 0x2000
	s_nop 0
	global_load_lds_dwordx4 v128, s[68:69]
	s_mov_b32 m0, s35
	s_nop 0
	global_load_lds_dwordx4 v134, s[42:43]
	s_mov_b32 m0, s52
	s_nop 0
	global_load_lds_dwordx4 v130, s[42:43]
	s_nop 0
	s_waitcnt vmcnt(8)
	s_waitcnt lgkmcnt(0)
	s_barrier
	v_mfma_f32_16x16x32_bf16 v[60:63], v[154:157], v[186:189], v[60:63]
	v_mfma_f32_16x16x32_bf16 v[52:55], v[162:165], v[186:189], v[52:55]
	v_mfma_f32_16x16x32_bf16 v[44:47], v[154:157], v[198:201], v[44:47]
	v_mfma_f32_16x16x32_bf16 v[36:39], v[162:165], v[198:201], v[36:39]
	v_mfma_f32_16x16x32_bf16 v[28:31], v[154:157], v[206:209], v[28:31]
	v_mfma_f32_16x16x32_bf16 v[20:23], v[162:165], v[206:209], v[20:23]
	v_mfma_f32_16x16x32_bf16 v[12:15], v[154:157], v[214:217], v[12:15]
	v_mfma_f32_16x16x32_bf16 v[4:7], v[162:165], v[214:217], v[4:7]
	v_mfma_f32_16x16x32_bf16 v[60:63], v[158:161], v[190:193], v[60:63]
	v_mfma_f32_16x16x32_bf16 v[52:55], v[166:169], v[190:193], v[52:55]
	v_mfma_f32_16x16x32_bf16 v[44:47], v[158:161], v[202:205], v[44:47]
	v_mfma_f32_16x16x32_bf16 v[36:39], v[166:169], v[202:205], v[36:39]
	v_mfma_f32_16x16x32_bf16 v[28:31], v[158:161], v[210:213], v[28:31]
	v_mfma_f32_16x16x32_bf16 v[20:23], v[166:169], v[210:213], v[20:23]
	v_mfma_f32_16x16x32_bf16 v[12:15], v[158:161], v[218:221], v[12:15]
	v_mfma_f32_16x16x32_bf16 v[4:7], v[166:169], v[218:221], v[4:7]
	v_mfma_f32_16x16x32_bf16 v[56:59], v[170:173], v[186:189], v[56:59]
	v_mfma_f32_16x16x32_bf16 v[48:51], v[178:181], v[186:189], v[48:51]
	v_mfma_f32_16x16x32_bf16 v[40:43], v[170:173], v[198:201], v[40:43]
	v_mfma_f32_16x16x32_bf16 v[32:35], v[178:181], v[198:201], v[32:35]
	v_mfma_f32_16x16x32_bf16 v[24:27], v[170:173], v[206:209], v[24:27]
	v_mfma_f32_16x16x32_bf16 v[16:19], v[178:181], v[206:209], v[16:19]
	v_mfma_f32_16x16x32_bf16 v[8:11], v[170:173], v[214:217], v[8:11]
	v_mfma_f32_16x16x32_bf16 v[0:3], v[178:181], v[214:217], v[0:3]
	v_mfma_f32_16x16x32_bf16 v[56:59], v[174:177], v[190:193], v[56:59]
	v_mfma_f32_16x16x32_bf16 v[48:51], v[182:185], v[190:193], v[48:51]
	v_mfma_f32_16x16x32_bf16 v[40:43], v[174:177], v[202:205], v[40:43]
	v_mfma_f32_16x16x32_bf16 v[32:35], v[182:185], v[202:205], v[32:35]
	v_mfma_f32_16x16x32_bf16 v[24:27], v[174:177], v[210:213], v[24:27]
	v_mfma_f32_16x16x32_bf16 v[16:19], v[182:185], v[210:213], v[16:19]
	v_mfma_f32_16x16x32_bf16 v[8:11], v[174:177], v[218:221], v[8:11]
	v_mfma_f32_16x16x32_bf16 v[0:3], v[182:185], v[218:221], v[0:3]
	s_barrier
	s_add_i32 s68, 0, 0x18000
	v_add_u32_e32 v153, s68, v147
	s_add_i32 s69, 0, 0x1c000
	ds_read_b128 v[154:157], v153
	ds_read_b128 v[158:161], v153 offset:1024
	ds_read_b128 v[162:165], v153 offset:2048
	ds_read_b128 v[166:169], v153 offset:3072
	v_add_u32_e32 v153, s69, v147
	ds_read_b128 v[170:173], v153
	ds_read_b128 v[174:177], v153 offset:1024
	ds_read_b128 v[178:181], v153 offset:2048
	ds_read_b128 v[182:185], v153 offset:3072
	s_add_u32 s42, s42, 0x40000
	s_addc_u32 s43, s43, 0
	s_mov_b32 m0, s53
	ds_read_b128 v[186:189], v152 offset:32768
	ds_read_b128 v[190:193], v152 offset:33792
	ds_read_b128 v[198:201], v152 offset:34816
	ds_read_b128 v[202:205], v152 offset:35840
	ds_read_b128 v[206:209], v152 offset:36864
	ds_read_b128 v[210:213], v152 offset:37888
	ds_read_b128 v[214:217], v152 offset:38912
	ds_read_b128 v[218:221], v152 offset:39936
	global_load_lds_dwordx4 v134, s[42:43]
	s_mov_b32 m0, s54
	s_nop 0
	global_load_lds_dwordx4 v130, s[42:43]
	s_waitcnt vmcnt(8)
	s_waitcnt lgkmcnt(0)
	s_barrier
; #define PG8_STAGE(bufoff, gbase, voff) do { _Pragma("unroll") for (int _i = 0; _i < 2; ++_i) \
;         __builtin_amdgcn_global_load_lds((const unsigned*)((const char*)(gbase) + (voff)[_i]), (PG8_LAS unsigned*)(lds + (bufoff) + ldsw + _i * 8192), 16, 0, 0); } while (0)
; #define PG8_LDA(dst, b, h) do { _Pragma("unroll") for (int m = 0; m < 4; ++m) _Pragma("unroll") for (int k = 0; k < 2; ++k) dst[m][k] = *(const PG8_LAS bf16x8*)(lds + PG8_SA(b, h) + aoff + m * 2048 + k * 1024); } while (0)
; #define PG8_MMA(ai, bj, At, Bt) do { __builtin_amdgcn_s_setprio(1); _Pragma("unroll") for (int m = 0; m < 4; ++m) _Pragma("unroll") for (int n = 0; n < 2; ++n) _Pragma("unroll") for (int k = 0; k < 2; ++k) \
;         acc[ai][bj][m][n] = __builtin_amdgcn_mfma_f32_16x16x32_bf16(Bt[n][k], At[m][k], acc[ai][bj][m][n], 0, 0, 0); __builtin_amdgcn_s_setprio(0); } while (0)
; #define PG8_WAIT_V(n) asm volatile("s_waitcnt vmcnt(" #n ")" ::: "memory")
; #define PG8_WAIT_L(n) asm volatile("s_waitcnt lgkmcnt(" #n ")" ::: "memory")
; #define PG8_BAR __builtin_amdgcn_s_barrier()
; #define PG8_SCHED __builtin_amdgcn_sched_barrier(0)
; template <class Epi, class Sched, bool ALIGN_EPI = false, bool SP2 = false>
; __device__ __forceinline__ void gemm_phase(PG8_LAS unsigned char* lds, const Gemm g, const Sched& S, const Epi& E) {
;     ...
;             PG8_WAIT_V(8); PG8_WAIT_L(0); PG8_BAR; PG8_MMA(0, 0, At, B0); PG8_MMA(0, 1, At, B1); PG8_BAR; PG8_SCHED;
;             PG8_LDA(At, 1, 1); PG8_STAGE(PG8_SB(1, 0), b3, voffB); PG8_STAGE(PG8_SB(1, 1), b3 + hstep, voffB); PG8_STAGE(PG8_SA(1, 0), a3, voffA);
;             PG8_WAIT_V(8); PG8_WAIT_L(0); PG8_BAR; PG8_MMA(1, 0, At, B0); PG8_MMA(1, 1, At, B1); PG8_BAR; PG8_SCHED;
;     ...
;         if constexpr (ALIGN_EPI) { if (wr == 0) PG8_BAR; }
	v_mfma_f32_16x16x32_bf16 v[124:127], v[154:157], v[186:189], v[124:127]
	v_mfma_f32_16x16x32_bf16 v[116:119], v[162:165], v[186:189], v[116:119]
	v_mfma_f32_16x16x32_bf16 v[108:111], v[154:157], v[198:201], v[108:111]
	v_mfma_f32_16x16x32_bf16 v[100:103], v[162:165], v[198:201], v[100:103]
	v_mfma_f32_16x16x32_bf16 v[92:95], v[154:157], v[206:209], v[92:95]
	v_mfma_f32_16x16x32_bf16 v[84:87], v[162:165], v[206:209], v[84:87]
	v_mfma_f32_16x16x32_bf16 v[76:79], v[154:157], v[214:217], v[76:79]
	v_mfma_f32_16x16x32_bf16 v[68:71], v[162:165], v[214:217], v[68:71]
	v_mfma_f32_16x16x32_bf16 v[124:127], v[158:161], v[190:193], v[124:127]
	v_mfma_f32_16x16x32_bf16 v[116:119], v[166:169], v[190:193], v[116:119]
	v_mfma_f32_16x16x32_bf16 v[108:111], v[158:161], v[202:205], v[108:111]
	v_mfma_f32_16x16x32_bf16 v[100:103], v[166:169], v[202:205], v[100:103]
	v_mfma_f32_16x16x32_bf16 v[92:95], v[158:161], v[210:213], v[92:95]
	v_mfma_f32_16x16x32_bf16 v[84:87], v[166:169], v[210:213], v[84:87]
	v_mfma_f32_16x16x32_bf16 v[76:79], v[158:161], v[218:221], v[76:79]
	v_mfma_f32_16x16x32_bf16 v[68:71], v[166:169], v[218:221], v[68:71]
	v_mfma_f32_16x16x32_bf16 v[120:123], v[170:173], v[186:189], v[120:123]
	v_mfma_f32_16x16x32_bf16 v[112:115], v[178:181], v[186:189], v[112:115]
	v_mfma_f32_16x16x32_bf16 v[104:107], v[170:173], v[198:201], v[104:107]
	v_mfma_f32_16x16x32_bf16 v[96:99], v[178:181], v[198:201], v[96:99]
	v_mfma_f32_16x16x32_bf16 v[88:91], v[170:173], v[206:209], v[88:91]
	v_mfma_f32_16x16x32_bf16 v[80:83], v[178:181], v[206:209], v[80:83]
	v_mfma_f32_16x16x32_bf16 v[72:75], v[170:173], v[214:217], v[72:75]
	v_mfma_f32_16x16x32_bf16 v[64:67], v[178:181], v[214:217], v[64:67]
	v_mfma_f32_16x16x32_bf16 v[120:123], v[174:177], v[190:193], v[120:123]
	v_mfma_f32_16x16x32_bf16 v[112:115], v[182:185], v[190:193], v[112:115]
	v_mfma_f32_16x16x32_bf16 v[104:107], v[174:177], v[202:205], v[104:107]
	v_mfma_f32_16x16x32_bf16 v[96:99], v[182:185], v[202:205], v[96:99]
	v_mfma_f32_16x16x32_bf16 v[88:91], v[174:177], v[210:213], v[88:91]
	v_mfma_f32_16x16x32_bf16 v[80:83], v[182:185], v[210:213], v[80:83]
	v_mfma_f32_16x16x32_bf16 v[72:75], v[174:177], v[218:221], v[72:75]
	v_mfma_f32_16x16x32_bf16 v[64:67], v[182:185], v[218:221], v[64:67]
	s_barrier
	s_add_i32 s42, s68, s50
	s_mov_b32 m0, s42
	ds_read_b128 v[186:189], v152 offset:49152
	ds_read_b128 v[190:193], v152 offset:50176
	ds_read_b128 v[198:201], v152 offset:51200
	ds_read_b128 v[202:205], v152 offset:52224
	ds_read_b128 v[206:209], v152 offset:53248
	ds_read_b128 v[210:213], v152 offset:54272
	ds_read_b128 v[214:217], v152 offset:55296
	ds_read_b128 v[218:221], v152 offset:56320
	global_load_lds_dwordx4 v132, s[98:99]
	s_add_i32 m0, s42, 0x2000
	s_add_u32 s38, s38, 0x40080
	s_addc_u32 s39, s39, 0
	s_add_i32 s42, s69, s50
	global_load_lds_dwordx4 v128, s[98:99]
	s_mov_b32 m0, s42
	s_nop 0
	global_load_lds_dwordx4 v132, s[38:39]
	s_add_i32 m0, s42, 0x2000
	s_nop 0
	global_load_lds_dwordx4 v128, s[38:39]
	s_mov_b32 m0, s56
	s_nop 0
	global_load_lds_dwordx4 v134, s[100:101]
	s_mov_b32 m0, s57
	s_nop 0
	global_load_lds_dwordx4 v130, s[100:101]
	s_nop 0
	s_waitcnt vmcnt(8)
	s_waitcnt lgkmcnt(0)
	s_barrier
	v_mfma_f32_16x16x32_bf16 v[60:63], v[154:157], v[186:189], v[60:63]
	v_mfma_f32_16x16x32_bf16 v[52:55], v[162:165], v[186:189], v[52:55]
	v_mfma_f32_16x16x32_bf16 v[44:47], v[154:157], v[198:201], v[44:47]
	v_mfma_f32_16x16x32_bf16 v[36:39], v[162:165], v[198:201], v[36:39]
	v_mfma_f32_16x16x32_bf16 v[28:31], v[154:157], v[206:209], v[28:31]
	v_mfma_f32_16x16x32_bf16 v[20:23], v[162:165], v[206:209], v[20:23]
	v_mfma_f32_16x16x32_bf16 v[12:15], v[154:157], v[214:217], v[12:15]
	v_mfma_f32_16x16x32_bf16 v[4:7], v[162:165], v[214:217], v[4:7]
	v_mfma_f32_16x16x32_bf16 v[60:63], v[158:161], v[190:193], v[60:63]
	v_mfma_f32_16x16x32_bf16 v[52:55], v[166:169], v[190:193], v[52:55]
	v_mfma_f32_16x16x32_bf16 v[44:47], v[158:161], v[202:205], v[44:47]
	v_mfma_f32_16x16x32_bf16 v[36:39], v[166:169], v[202:205], v[36:39]
	v_mfma_f32_16x16x32_bf16 v[28:31], v[158:161], v[210:213], v[28:31]
	v_mfma_f32_16x16x32_bf16 v[20:23], v[166:169], v[210:213], v[20:23]
	v_mfma_f32_16x16x32_bf16 v[12:15], v[158:161], v[218:221], v[12:15]
	v_mfma_f32_16x16x32_bf16 v[4:7], v[166:169], v[218:221], v[4:7]
	v_mfma_f32_16x16x32_bf16 v[56:59], v[170:173], v[186:189], v[56:59]
	v_mfma_f32_16x16x32_bf16 v[48:51], v[178:181], v[186:189], v[48:51]
	v_mfma_f32_16x16x32_bf16 v[40:43], v[170:173], v[198:201], v[40:43]
	v_mfma_f32_16x16x32_bf16 v[32:35], v[178:181], v[198:201], v[32:35]
	v_mfma_f32_16x16x32_bf16 v[24:27], v[170:173], v[206:209], v[24:27]
	v_mfma_f32_16x16x32_bf16 v[16:19], v[178:181], v[206:209], v[16:19]
	v_mfma_f32_16x16x32_bf16 v[8:11], v[170:173], v[214:217], v[8:11]
	v_mfma_f32_16x16x32_bf16 v[0:3], v[178:181], v[214:217], v[0:3]
	v_mfma_f32_16x16x32_bf16 v[56:59], v[174:177], v[190:193], v[56:59]
	v_mfma_f32_16x16x32_bf16 v[48:51], v[182:185], v[190:193], v[48:51]
	v_mfma_f32_16x16x32_bf16 v[40:43], v[174:177], v[202:205], v[40:43]
	v_mfma_f32_16x16x32_bf16 v[32:35], v[182:185], v[202:205], v[32:35]
	v_mfma_f32_16x16x32_bf16 v[24:27], v[174:177], v[210:213], v[24:27]
	v_mfma_f32_16x16x32_bf16 v[16:19], v[182:185], v[210:213], v[16:19]
	v_mfma_f32_16x16x32_bf16 v[8:11], v[174:177], v[218:221], v[8:11]
	v_mfma_f32_16x16x32_bf16 v[0:3], v[182:185], v[218:221], v[0:3]
	s_barrier
	s_add_i32 s67, s67, 2
	s_add_u32 s20, s20, 0x100
	s_addc_u32 s21, s21, 0
	s_add_u32 s65, s65, 0x100
	s_addc_u32 s66, s66, 0
	s_cmp_gt_u32 s67, 13
	s_cbranch_scc0 .LBB0_1740
	s_and_b64 vcc, exec, s[10:11]
	s_cbranch_vccz .LBB0_1743
	s_barrier

; #define PG8_STAGE(bufoff, gbase, voff) do { _Pragma("unroll") for (int _i = 0; _i < 2; ++_i) \
;         __builtin_amdgcn_global_load_lds((const unsigned*)((const char*)(gbase) + (voff)[_i]), (PG8_LAS unsigned*)(lds + (bufoff) + ldsw + _i * 8192), 16, 0, 0); } while (0)
; #define PG8_LDA(dst, b, h) do { _Pragma("unroll") for (int m = 0; m < 4; ++m) _Pragma("unroll") for (int k = 0; k < 2; ++k) dst[m][k] = *(const PG8_LAS bf16x8*)(lds + PG8_SA(b, h) + aoff + m * 2048 + k * 1024); } while (0)
; #define PG8_LDB(dst, b, h) do { _Pragma("unroll") for (int n = 0; n < 2; ++n) _Pragma("unroll") for (int k = 0; k < 2; ++k) dst[n][k] = *(const PG8_LAS bf16x8*)(lds + PG8_SB(b, h) + boff + n * 2048 + k * 1024); } while (0)
; #define PG8_WAIT_V(n) asm volatile("s_waitcnt vmcnt(" #n ")" ::: "memory")
; #define PG8_WAIT_L(n) asm volatile("s_waitcnt lgkmcnt(" #n ")" ::: "memory")
; #define PG8_BAR __builtin_amdgcn_s_barrier()
; #define PG8_SCHED __builtin_amdgcn_sched_barrier(0)
; template <class Epi, class Sched, bool ALIGN_EPI = false, bool SP2 = false>
; __device__ __forceinline__ void gemm_phase(PG8_LAS unsigned char* lds, const Gemm g, const Sched& S, const Epi& E) {
;     ...
;         const bool has_next = S.next(ui + 1, nxt);
;         const char* nA = has_next ? (const char*)g.A + (size_t)nxt.pm * tstep : cA; const char* nB = has_next ? (const char*)g.Bt + (size_t)nxt.pn * tstep : cB;
;         for (int t = 0; t < nt; t += 2) {
;             const bool last = (t == nt - 2);
;             const char* a1 = cA + (size_t)(t + 1) * kstep;
;             const char* a2 = last ? nA : cA + (size_t)(t + 2) * kstep; const char* b2 = last ? nB : cB + (size_t)(t + 2) * kstep;
;             const char* a3 = a2 + kstep; const char* b3 = b2 + kstep;
;             if (last && has_next) S.a_ready(nxt);
;             if constexpr (SP2) {
;             PG8_LDB(B0, 0, 0); PG8_LDB(B1, 0, 1); PG8_SCHED; PG8_LDA(At, 0, 0); PG8_STAGE(PG8_SA(1, 1), a1 + hstep, voffA);
;             PG8_WAIT_V(8); PG8_WAIT_L(0); PG8_BAR; PG8_MMA(0, 0, At, B0); PG8_MMA(0, 1, At, B1); PG8_BAR; PG8_SCHED;
;             PG8_LDA(At, 0, 1); PG8_STAGE(PG8_SB(0, 0), b2, voffB); PG8_STAGE(PG8_SB(0, 1), b2 + hstep, voffB); PG8_STAGE(PG8_SA(0, 0), a2, voffA);
;             PG8_WAIT_V(8); PG8_WAIT_L(0); PG8_BAR; PG8_MMA(1, 0, At, B0); PG8_MMA(1, 1, At, B1); PG8_BAR; PG8_SCHED;
.LBB0_1824:
	s_add_u32 s20, s20, 0xb0080
	s_addc_u32 s21, s21, 0
	s_add_u32 s68, s34, 0x100
	s_addc_u32 s69, s35, 0
	s_mov_b32 s70, -2
	s_waitcnt lgkmcnt(0)
	ds_read_b128 v[96:99], v222
	ds_read_b128 v[108:111], v222 offset:1024
	ds_read_b128 v[120:123], v222 offset:2048
	ds_read_b128 v[128:131], v222 offset:3072
	ds_read_b128 v[144:147], v223
	ds_read_b128 v[148:151], v223 offset:1024
	ds_read_b128 v[152:155], v223 offset:2048
	ds_read_b128 v[156:159], v223 offset:3072
	s_add_u32 s34, s20, 0xfff50080
	s_addc_u32 s35, s21, -1
	s_cmp_eq_u32 s70, 40
	s_cselect_b32 s47, s1, s35
	s_cselect_b32 s46, s0, s34
	s_cselect_b32 s35, s45, s69
	s_cselect_b32 s34, s44, s68
	s_add_i32 m0, s49, 0xc000
	ds_read_b128 v[160:163], v224
	ds_read_b128 v[164:167], v224 offset:1024
	ds_read_b128 v[168:171], v224 offset:2048
	ds_read_b128 v[172:175], v224 offset:3072
	ds_read_b128 v[176:179], v224 offset:4096
	ds_read_b128 v[180:183], v224 offset:5120
	ds_read_b128 v[202:205], v224 offset:6144
	ds_read_b128 v[206:209], v224 offset:7168
	global_load_lds_dwordx4 v192, s[20:21]
	s_add_i32 m0, s49, 0xe000
	s_nop 0
	global_load_lds_dwordx4 v194, s[20:21]
	s_nop 0
	s_waitcnt vmcnt(8)
	s_waitcnt lgkmcnt(0)
	s_barrier
	v_mfma_f32_16x16x32_bf16 v[140:143], v[96:99], v[160:163], 0
	v_mfma_f32_16x16x32_bf16 v[136:139], v[120:123], v[160:163], 0
	v_mfma_f32_16x16x32_bf16 v[116:119], v[96:99], v[168:171], 0
	v_mfma_f32_16x16x32_bf16 v[112:115], v[120:123], v[168:171], 0
	v_mfma_f32_16x16x32_bf16 v[92:95], v[96:99], v[176:179], 0
	v_mfma_f32_16x16x32_bf16 v[88:91], v[120:123], v[176:179], 0
	v_mfma_f32_16x16x32_bf16 v[76:79], v[96:99], v[202:205], 0
	v_mfma_f32_16x16x32_bf16 v[72:75], v[120:123], v[202:205], 0
	v_mfma_f32_16x16x32_bf16 v[140:143], v[108:111], v[164:167], v[140:143]
	v_mfma_f32_16x16x32_bf16 v[136:139], v[128:131], v[164:167], v[136:139]
	v_mfma_f32_16x16x32_bf16 v[116:119], v[108:111], v[172:175], v[116:119]
	v_mfma_f32_16x16x32_bf16 v[112:115], v[128:131], v[172:175], v[112:115]
	v_mfma_f32_16x16x32_bf16 v[92:95], v[108:111], v[180:183], v[92:95]
	v_mfma_f32_16x16x32_bf16 v[88:91], v[128:131], v[180:183], v[88:91]
	v_mfma_f32_16x16x32_bf16 v[76:79], v[108:111], v[206:209], v[76:79]
	v_mfma_f32_16x16x32_bf16 v[72:75], v[128:131], v[206:209], v[72:75]
	v_mfma_f32_16x16x32_bf16 v[132:135], v[144:147], v[160:163], 0
	v_mfma_f32_16x16x32_bf16 v[124:127], v[152:155], v[160:163], 0
	v_mfma_f32_16x16x32_bf16 v[104:107], v[144:147], v[168:171], 0
	v_mfma_f32_16x16x32_bf16 v[100:103], v[152:155], v[168:171], 0
	v_mfma_f32_16x16x32_bf16 v[84:87], v[144:147], v[176:179], 0
	v_mfma_f32_16x16x32_bf16 v[80:83], v[152:155], v[176:179], 0
	v_mfma_f32_16x16x32_bf16 v[68:71], v[144:147], v[202:205], 0
	v_mfma_f32_16x16x32_bf16 v[64:67], v[152:155], v[202:205], 0
	v_mfma_f32_16x16x32_bf16 v[132:135], v[148:151], v[164:167], v[132:135]
	v_mfma_f32_16x16x32_bf16 v[124:127], v[156:159], v[164:167], v[124:127]
	v_mfma_f32_16x16x32_bf16 v[104:107], v[148:151], v[172:175], v[104:107]
	v_mfma_f32_16x16x32_bf16 v[100:103], v[156:159], v[172:175], v[100:103]
	v_mfma_f32_16x16x32_bf16 v[84:87], v[148:151], v[180:183], v[84:87]
	v_mfma_f32_16x16x32_bf16 v[80:83], v[156:159], v[180:183], v[80:83]
	v_mfma_f32_16x16x32_bf16 v[68:71], v[148:151], v[206:209], v[68:71]
	v_mfma_f32_16x16x32_bf16 v[64:67], v[156:159], v[206:209], v[64:67]
	s_barrier
	s_add_i32 s71, s62, s48
	s_add_u32 s98, s34, s12
	s_addc_u32 s99, s35, s13
	s_add_u32 s100, s46, s12
	s_addc_u32 s101, s47, s13
	s_mov_b32 m0, s71
	ds_read_b128 v[160:163], v224 offset:16384
	ds_read_b128 v[164:167], v224 offset:17408
	ds_read_b128 v[168:171], v224 offset:18432
	ds_read_b128 v[172:175], v224 offset:19456
	ds_read_b128 v[176:179], v224 offset:20480
	ds_read_b128 v[180:183], v224 offset:21504
	ds_read_b128 v[202:205], v224 offset:22528
	ds_read_b128 v[206:209], v224 offset:23552
	global_load_lds_dwordx4 v186, s[34:35]
	s_add_i32 m0, s71, 0x2000
	s_add_u32 s72, s34, 0xb0000
	s_addc_u32 s73, s35, 0
	s_add_i32 s71, s63, s48
	global_load_lds_dwordx4 v190, s[34:35]
	s_mov_b32 m0, s71
	s_nop 0
	global_load_lds_dwordx4 v186, s[72:73]
	s_add_i32 m0, s71, 0x2000
	s_nop 0
	global_load_lds_dwordx4 v190, s[72:73]
	s_mov_b32 m0, s49
	s_nop 0
	global_load_lds_dwordx4 v184, s[46:47]
	s_mov_b32 m0, s50
	s_nop 0
	global_load_lds_dwordx4 v188, s[46:47]
	s_nop 0
	s_waitcnt vmcnt(8)
	s_waitcnt lgkmcnt(0)
	s_barrier
	v_mfma_f32_16x16x32_bf16 v[60:63], v[96:99], v[160:163], 0
	v_mfma_f32_16x16x32_bf16 v[56:59], v[120:123], v[160:163], 0
	v_mfma_f32_16x16x32_bf16 v[44:47], v[96:99], v[168:171], 0
	v_mfma_f32_16x16x32_bf16 v[40:43], v[120:123], v[168:171], 0
	v_mfma_f32_16x16x32_bf16 v[28:31], v[96:99], v[176:179], 0
	v_mfma_f32_16x16x32_bf16 v[24:27], v[120:123], v[176:179], 0
	v_mfma_f32_16x16x32_bf16 v[12:15], v[96:99], v[202:205], 0
	v_mfma_f32_16x16x32_bf16 v[8:11], v[120:123], v[202:205], 0
	v_mfma_f32_16x16x32_bf16 v[60:63], v[108:111], v[164:167], v[60:63]
	v_mfma_f32_16x16x32_bf16 v[56:59], v[128:131], v[164:167], v[56:59]
	v_mfma_f32_16x16x32_bf16 v[44:47], v[108:111], v[172:175], v[44:47]
	v_mfma_f32_16x16x32_bf16 v[40:43], v[128:131], v[172:175], v[40:43]
	v_mfma_f32_16x16x32_bf16 v[28:31], v[108:111], v[180:183], v[28:31]
	v_mfma_f32_16x16x32_bf16 v[24:27], v[128:131], v[180:183], v[24:27]
	v_mfma_f32_16x16x32_bf16 v[12:15], v[108:111], v[206:209], v[12:15]
	v_mfma_f32_16x16x32_bf16 v[8:11], v[128:131], v[206:209], v[8:11]
	v_mfma_f32_16x16x32_bf16 v[52:55], v[144:147], v[160:163], 0
	v_mfma_f32_16x16x32_bf16 v[48:51], v[152:155], v[160:163], 0
	v_mfma_f32_16x16x32_bf16 v[36:39], v[144:147], v[168:171], 0
	v_mfma_f32_16x16x32_bf16 v[32:35], v[152:155], v[168:171], 0
	v_mfma_f32_16x16x32_bf16 v[20:23], v[144:147], v[176:179], 0
	v_mfma_f32_16x16x32_bf16 v[16:19], v[152:155], v[176:179], 0
	v_mfma_f32_16x16x32_bf16 v[4:7], v[144:147], v[202:205], 0
	v_mfma_f32_16x16x32_bf16 v[0:3], v[152:155], v[202:205], 0
	v_mfma_f32_16x16x32_bf16 v[52:55], v[148:151], v[164:167], v[52:55]
	v_mfma_f32_16x16x32_bf16 v[48:51], v[156:159], v[164:167], v[48:51]
	v_mfma_f32_16x16x32_bf16 v[36:39], v[148:151], v[172:175], v[36:39]
	v_mfma_f32_16x16x32_bf16 v[32:35], v[156:159], v[172:175], v[32:35]
	v_mfma_f32_16x16x32_bf16 v[20:23], v[148:151], v[180:183], v[20:23]
	v_mfma_f32_16x16x32_bf16 v[16:19], v[156:159], v[180:183], v[16:19]
	v_mfma_f32_16x16x32_bf16 v[4:7], v[148:151], v[206:209], v[4:7]
	v_mfma_f32_16x16x32_bf16 v[0:3], v[156:159], v[206:209], v[0:3]
	s_barrier
; #define PG8_STAGE(bufoff, gbase, voff) do { _Pragma("unroll") for (int _i = 0; _i < 2; ++_i) \
;         __builtin_amdgcn_global_load_lds((const unsigned*)((const char*)(gbase) + (voff)[_i]), (PG8_LAS unsigned*)(lds + (bufoff) + ldsw + _i * 8192), 16, 0, 0); } while (0)
; #define PG8_LDA(dst, b, h) do { _Pragma("unroll") for (int m = 0; m < 4; ++m) _Pragma("unroll") for (int k = 0; k < 2; ++k) dst[m][k] = *(const PG8_LAS bf16x8*)(lds + PG8_SA(b, h) + aoff + m * 2048 + k * 1024); } while (0)
; #define PG8_LDB(dst, b, h) do { _Pragma("unroll") for (int n = 0; n < 2; ++n) _Pragma("unroll") for (int k = 0; k < 2; ++k) dst[n][k] = *(const PG8_LAS bf16x8*)(lds + PG8_SB(b, h) + boff + n * 2048 + k * 1024); } while (0)
; #define PG8_MMA(ai, bj, At, Bt) do { __builtin_amdgcn_s_setprio(1); _Pragma("unroll") for (int m = 0; m < 4; ++m) _Pragma("unroll") for (int n = 0; n < 2; ++n) _Pragma("unroll") for (int k = 0; k < 2; ++k) \
;         acc[ai][bj][m][n] = __builtin_amdgcn_mfma_f32_16x16x32_bf16(Bt[n][k], At[m][k], acc[ai][bj][m][n], 0, 0, 0); __builtin_amdgcn_s_setprio(0); } while (0)
; #define PG8_WAIT_V(n) asm volatile("s_waitcnt vmcnt(" #n ")" ::: "memory")
; #define PG8_WAIT_L(n) asm volatile("s_waitcnt lgkmcnt(" #n ")" ::: "memory")
; #define PG8_BAR __builtin_amdgcn_s_barrier()
; template <class Epi, class Sched, bool ALIGN_EPI = false, bool SP2 = false>
; __device__ __forceinline__ void gemm_phase(PG8_LAS unsigned char* lds, const Gemm g, const Sched& S, const Epi& E) {
;     ...
;         for (int t = 0; t < nt; t += 2) {
;             const bool last = (t == nt - 2);
;             const char* a1 = cA + (size_t)(t + 1) * kstep;
;             const char* a2 = last ? nA : cA + (size_t)(t + 2) * kstep; const char* b2 = last ? nB : cB + (size_t)(t + 2) * kstep;
;             const char* a3 = a2 + kstep; const char* b3 = b2 + kstep;
;     ...
;             PG8_LDB(B0, 1, 0); PG8_LDB(B1, 1, 1); PG8_SCHED; PG8_LDA(At, 1, 0); PG8_STAGE(PG8_SA(0, 1), a2 + hstep, voffA);
;             PG8_WAIT_V(8); PG8_WAIT_L(0); PG8_BAR; PG8_MMA(0, 0, At, B0); PG8_MMA(0, 1, At, B1); PG8_BAR; PG8_SCHED;
;             PG8_LDA(At, 1, 1); PG8_STAGE(PG8_SB(1, 0), b3, voffB); PG8_STAGE(PG8_SB(1, 1), b3 + hstep, voffB); PG8_STAGE(PG8_SA(1, 0), a3, voffA);
;             PG8_WAIT_V(8); PG8_WAIT_L(0); PG8_BAR; PG8_MMA(1, 0, At, B0); PG8_MMA(1, 1, At, B1); PG8_BAR; PG8_SCHED;
	s_add_i32 s71, 0, 0x18000
	s_add_i32 s72, 0, 0x1c000
	v_add_u32_e32 v128, s71, v197
	v_add_u32_e32 v156, s72, v197
	ds_read_b128 v[96:99], v128
	ds_read_b128 v[108:111], v128 offset:1024
	ds_read_b128 v[120:123], v128 offset:2048
	ds_read_b128 v[128:131], v128 offset:3072
	ds_read_b128 v[144:147], v156
	ds_read_b128 v[148:151], v156 offset:1024
	ds_read_b128 v[152:155], v156 offset:2048
	ds_read_b128 v[156:159], v156 offset:3072
	s_add_u32 s46, s46, 0xb0000
	s_addc_u32 s47, s47, 0
	s_mov_b32 m0, s51
	ds_read_b128 v[160:163], v224 offset:32768
	ds_read_b128 v[164:167], v224 offset:33792
	ds_read_b128 v[168:171], v224 offset:34816
	ds_read_b128 v[172:175], v224 offset:35840
	ds_read_b128 v[176:179], v224 offset:36864
	ds_read_b128 v[180:183], v224 offset:37888
	ds_read_b128 v[202:205], v224 offset:38912
	ds_read_b128 v[206:209], v224 offset:39936
	global_load_lds_dwordx4 v184, s[46:47]
	s_mov_b32 m0, s52
	s_nop 0
	global_load_lds_dwordx4 v188, s[46:47]
	s_waitcnt vmcnt(8)
	s_waitcnt lgkmcnt(0)
	s_barrier
	v_mfma_f32_16x16x32_bf16 v[140:143], v[96:99], v[160:163], v[140:143]
	v_mfma_f32_16x16x32_bf16 v[136:139], v[120:123], v[160:163], v[136:139]
	v_mfma_f32_16x16x32_bf16 v[116:119], v[96:99], v[168:171], v[116:119]
	v_mfma_f32_16x16x32_bf16 v[112:115], v[120:123], v[168:171], v[112:115]
	v_mfma_f32_16x16x32_bf16 v[92:95], v[96:99], v[176:179], v[92:95]
	v_mfma_f32_16x16x32_bf16 v[88:91], v[120:123], v[176:179], v[88:91]
	v_mfma_f32_16x16x32_bf16 v[76:79], v[96:99], v[202:205], v[76:79]
	v_mfma_f32_16x16x32_bf16 v[72:75], v[120:123], v[202:205], v[72:75]
	v_mfma_f32_16x16x32_bf16 v[140:143], v[108:111], v[164:167], v[140:143]
	v_mfma_f32_16x16x32_bf16 v[136:139], v[128:131], v[164:167], v[136:139]
	v_mfma_f32_16x16x32_bf16 v[116:119], v[108:111], v[172:175], v[116:119]
	v_mfma_f32_16x16x32_bf16 v[112:115], v[128:131], v[172:175], v[112:115]
	v_mfma_f32_16x16x32_bf16 v[92:95], v[108:111], v[180:183], v[92:95]
	v_mfma_f32_16x16x32_bf16 v[88:91], v[128:131], v[180:183], v[88:91]
	v_mfma_f32_16x16x32_bf16 v[76:79], v[108:111], v[206:209], v[76:79]
	v_mfma_f32_16x16x32_bf16 v[72:75], v[128:131], v[206:209], v[72:75]
	v_mfma_f32_16x16x32_bf16 v[132:135], v[144:147], v[160:163], v[132:135]
	v_mfma_f32_16x16x32_bf16 v[124:127], v[152:155], v[160:163], v[124:127]
	v_mfma_f32_16x16x32_bf16 v[104:107], v[144:147], v[168:171], v[104:107]
	v_mfma_f32_16x16x32_bf16 v[100:103], v[152:155], v[168:171], v[100:103]
	v_mfma_f32_16x16x32_bf16 v[84:87], v[144:147], v[176:179], v[84:87]
	v_mfma_f32_16x16x32_bf16 v[80:83], v[152:155], v[176:179], v[80:83]
	v_mfma_f32_16x16x32_bf16 v[68:71], v[144:147], v[202:205], v[68:71]
	v_mfma_f32_16x16x32_bf16 v[64:67], v[152:155], v[202:205], v[64:67]
	v_mfma_f32_16x16x32_bf16 v[132:135], v[148:151], v[164:167], v[132:135]
	v_mfma_f32_16x16x32_bf16 v[124:127], v[156:159], v[164:167], v[124:127]
	v_mfma_f32_16x16x32_bf16 v[104:107], v[148:151], v[172:175], v[104:107]
	v_mfma_f32_16x16x32_bf16 v[100:103], v[156:159], v[172:175], v[100:103]
	v_mfma_f32_16x16x32_bf16 v[84:87], v[148:151], v[180:183], v[84:87]
	v_mfma_f32_16x16x32_bf16 v[80:83], v[156:159], v[180:183], v[80:83]
	v_mfma_f32_16x16x32_bf16 v[68:71], v[148:151], v[206:209], v[68:71]
	v_mfma_f32_16x16x32_bf16 v[64:67], v[156:159], v[206:209], v[64:67]
	s_barrier
	s_add_i32 s46, s71, s48
	s_mov_b32 m0, s46
	ds_read_b128 v[160:163], v224 offset:49152
	ds_read_b128 v[164:167], v224 offset:50176
	ds_read_b128 v[168:171], v224 offset:51200
	ds_read_b128 v[172:175], v224 offset:52224
	ds_read_b128 v[176:179], v224 offset:53248
	ds_read_b128 v[180:183], v224 offset:54272
	ds_read_b128 v[202:205], v224 offset:55296
	ds_read_b128 v[206:209], v224 offset:56320
	global_load_lds_dwordx4 v186, s[98:99]
	s_add_i32 m0, s46, 0x2000
	s_add_u32 s34, s34, 0xb0080
	s_addc_u32 s35, s35, 0
	s_add_i32 s46, s72, s48
	global_load_lds_dwordx4 v190, s[98:99]
	s_mov_b32 m0, s46
	s_nop 0
	global_load_lds_dwordx4 v186, s[34:35]
	s_add_i32 m0, s46, 0x2000
	s_nop 0
	global_load_lds_dwordx4 v190, s[34:35]
	s_mov_b32 m0, s57
	s_nop 0
	global_load_lds_dwordx4 v184, s[100:101]
	s_mov_b32 m0, s58
	s_nop 0
	global_load_lds_dwordx4 v188, s[100:101]
	s_nop 0
	s_waitcnt vmcnt(8)
	s_waitcnt lgkmcnt(0)
	s_barrier
	v_mfma_f32_16x16x32_bf16 v[60:63], v[96:99], v[160:163], v[60:63]
	v_mfma_f32_16x16x32_bf16 v[56:59], v[120:123], v[160:163], v[56:59]
	v_mfma_f32_16x16x32_bf16 v[44:47], v[96:99], v[168:171], v[44:47]
	v_mfma_f32_16x16x32_bf16 v[40:43], v[120:123], v[168:171], v[40:43]
	v_mfma_f32_16x16x32_bf16 v[28:31], v[96:99], v[176:179], v[28:31]
	v_mfma_f32_16x16x32_bf16 v[24:27], v[120:123], v[176:179], v[24:27]
	v_mfma_f32_16x16x32_bf16 v[12:15], v[96:99], v[202:205], v[12:15]
	v_mfma_f32_16x16x32_bf16 v[8:11], v[120:123], v[202:205], v[8:11]
	v_mfma_f32_16x16x32_bf16 v[60:63], v[108:111], v[164:167], v[60:63]
	v_mfma_f32_16x16x32_bf16 v[56:59], v[128:131], v[164:167], v[56:59]
	v_mfma_f32_16x16x32_bf16 v[44:47], v[108:111], v[172:175], v[44:47]
	v_mfma_f32_16x16x32_bf16 v[40:43], v[128:131], v[172:175], v[40:43]
	v_mfma_f32_16x16x32_bf16 v[28:31], v[108:111], v[180:183], v[28:31]
	v_mfma_f32_16x16x32_bf16 v[24:27], v[128:131], v[180:183], v[24:27]
	v_mfma_f32_16x16x32_bf16 v[12:15], v[108:111], v[206:209], v[12:15]
	v_mfma_f32_16x16x32_bf16 v[8:11], v[128:131], v[206:209], v[8:11]
	v_mfma_f32_16x16x32_bf16 v[52:55], v[144:147], v[160:163], v[52:55]
	v_mfma_f32_16x16x32_bf16 v[48:51], v[152:155], v[160:163], v[48:51]
	v_mfma_f32_16x16x32_bf16 v[36:39], v[144:147], v[168:171], v[36:39]
	v_mfma_f32_16x16x32_bf16 v[32:35], v[152:155], v[168:171], v[32:35]
	v_mfma_f32_16x16x32_bf16 v[20:23], v[144:147], v[176:179], v[20:23]
	v_mfma_f32_16x16x32_bf16 v[16:19], v[152:155], v[176:179], v[16:19]
	v_mfma_f32_16x16x32_bf16 v[4:7], v[144:147], v[202:205], v[4:7]
	v_mfma_f32_16x16x32_bf16 v[0:3], v[152:155], v[202:205], v[0:3]
	v_mfma_f32_16x16x32_bf16 v[52:55], v[148:151], v[164:167], v[52:55]
	v_mfma_f32_16x16x32_bf16 v[48:51], v[156:159], v[164:167], v[48:51]
	v_mfma_f32_16x16x32_bf16 v[36:39], v[148:151], v[172:175], v[36:39]
	v_mfma_f32_16x16x32_bf16 v[32:35], v[156:159], v[172:175], v[32:35]
	v_mfma_f32_16x16x32_bf16 v[20:23], v[148:151], v[180:183], v[20:23]
	v_mfma_f32_16x16x32_bf16 v[16:19], v[156:159], v[180:183], v[16:19]
	v_mfma_f32_16x16x32_bf16 v[4:7], v[148:151], v[206:209], v[4:7]
	v_mfma_f32_16x16x32_bf16 v[0:3], v[156:159], v[206:209], v[0:3]
	s_barrier
	s_add_i32 s70, s70, 2
	s_add_u32 s20, s20, 0x100
	s_addc_u32 s21, s21, 0
	s_add_u32 s68, s68, 0x100
	s_addc_u32 s69, s69, 0
	s_cmp_gt_u32 s70, 41
; #define PG8_STAGE(bufoff, gbase, voff) do { _Pragma("unroll") for (int _i = 0; _i < 2; ++_i) \
;         __builtin_amdgcn_global_load_lds((const unsigned*)((const char*)(gbase) + (voff)[_i]), (PG8_LAS unsigned*)(lds + (bufoff) + ldsw + _i * 8192), 16, 0, 0); } while (0)
; #define PG8_LDA(dst, b, h) do { _Pragma("unroll") for (int m = 0; m < 4; ++m) _Pragma("unroll") for (int k = 0; k < 2; ++k) dst[m][k] = *(const PG8_LAS bf16x8*)(lds + PG8_SA(b, h) + aoff + m * 2048 + k * 1024); } while (0)
; #define PG8_LDB(dst, b, h) do { _Pragma("unroll") for (int n = 0; n < 2; ++n) _Pragma("unroll") for (int k = 0; k < 2; ++k) dst[n][k] = *(const PG8_LAS bf16x8*)(lds + PG8_SB(b, h) + boff + n * 2048 + k * 1024); } while (0)
; #define PG8_MMA(ai, bj, At, Bt) do { __builtin_amdgcn_s_setprio(1); _Pragma("unroll") for (int m = 0; m < 4; ++m) _Pragma("unroll") for (int n = 0; n < 2; ++n) _Pragma("unroll") for (int k = 0; k < 2; ++k) \
;         acc[ai][bj][m][n] = __builtin_amdgcn_mfma_f32_16x16x32_bf16(Bt[n][k], At[m][k], acc[ai][bj][m][n], 0, 0, 0); __builtin_amdgcn_s_setprio(0); } while (0)
; #define PG8_WAIT_V(n) asm volatile("s_waitcnt vmcnt(" #n ")" ::: "memory")
; #define PG8_WAIT_L(n) asm volatile("s_waitcnt lgkmcnt(" #n ")" ::: "memory")
; #define PG8_BAR __builtin_amdgcn_s_barrier()
; #define PG8_SCHED __builtin_amdgcn_sched_barrier(0)
; template <class Epi, class Sched, bool ALIGN_EPI = false, bool SP2 = false>
; __device__ __forceinline__ void gemm_phase(PG8_LAS unsigned char* lds, const Gemm g, const Sched& S, const Epi& E) {
;     ...
;             PG8_LDB(B0, 0, 0); PG8_LDB(B1, 0, 1); PG8_SCHED; PG8_LDA(At, 0, 0); PG8_STAGE(PG8_SA(1, 1), a1 + hstep, voffA);
;             PG8_WAIT_V(8); PG8_WAIT_L(0); PG8_BAR; PG8_MMA(0, 0, At, B0); PG8_MMA(0, 1, At, B1); PG8_BAR; PG8_SCHED;
;             PG8_LDA(At, 0, 1); PG8_STAGE(PG8_SB(0, 0), b2, voffB); PG8_STAGE(PG8_SB(0, 1), b2 + hstep, voffB); PG8_STAGE(PG8_SA(0, 0), a2, voffA);
;             PG8_WAIT_V(8); PG8_WAIT_L(0); PG8_BAR; PG8_MMA(1, 0, At, B0); PG8_MMA(1, 1, At, B1); PG8_BAR; PG8_SCHED;
.LBB0_1825:
	ds_read_b128 v[96:99], v222
	ds_read_b128 v[108:111], v222 offset:1024
	ds_read_b128 v[120:123], v222 offset:2048
	ds_read_b128 v[128:131], v222 offset:3072
	ds_read_b128 v[144:147], v223
	ds_read_b128 v[148:151], v223 offset:1024
	ds_read_b128 v[152:155], v223 offset:2048
	ds_read_b128 v[156:159], v223 offset:3072
	s_add_u32 s34, s20, 0xfff50080
	s_addc_u32 s35, s21, -1
	s_cmp_eq_u32 s70, 40
	s_cselect_b32 s47, s1, s35
	s_cselect_b32 s46, s0, s34
	s_cselect_b32 s35, s45, s69
	s_cselect_b32 s34, s44, s68
	s_add_i32 m0, s49, 0xc000
	ds_read_b128 v[160:163], v224
	ds_read_b128 v[164:167], v224 offset:1024
	ds_read_b128 v[168:171], v224 offset:2048
	ds_read_b128 v[172:175], v224 offset:3072
	ds_read_b128 v[176:179], v224 offset:4096
	ds_read_b128 v[180:183], v224 offset:5120
	ds_read_b128 v[202:205], v224 offset:6144
	ds_read_b128 v[206:209], v224 offset:7168
	global_load_lds_dwordx4 v192, s[20:21]
	s_add_i32 m0, s49, 0xe000
	s_nop 0
	global_load_lds_dwordx4 v194, s[20:21]
	s_nop 0
	s_waitcnt vmcnt(8)
	s_waitcnt lgkmcnt(0)
	s_barrier
	v_mfma_f32_16x16x32_bf16 v[140:143], v[96:99], v[160:163], v[140:143]
	v_mfma_f32_16x16x32_bf16 v[136:139], v[120:123], v[160:163], v[136:139]
	v_mfma_f32_16x16x32_bf16 v[116:119], v[96:99], v[168:171], v[116:119]
	v_mfma_f32_16x16x32_bf16 v[112:115], v[120:123], v[168:171], v[112:115]
	v_mfma_f32_16x16x32_bf16 v[92:95], v[96:99], v[176:179], v[92:95]
	v_mfma_f32_16x16x32_bf16 v[88:91], v[120:123], v[176:179], v[88:91]
	v_mfma_f32_16x16x32_bf16 v[76:79], v[96:99], v[202:205], v[76:79]
	v_mfma_f32_16x16x32_bf16 v[72:75], v[120:123], v[202:205], v[72:75]
	v_mfma_f32_16x16x32_bf16 v[140:143], v[108:111], v[164:167], v[140:143]
	v_mfma_f32_16x16x32_bf16 v[136:139], v[128:131], v[164:167], v[136:139]
	v_mfma_f32_16x16x32_bf16 v[116:119], v[108:111], v[172:175], v[116:119]
	v_mfma_f32_16x16x32_bf16 v[112:115], v[128:131], v[172:175], v[112:115]
	v_mfma_f32_16x16x32_bf16 v[92:95], v[108:111], v[180:183], v[92:95]
	v_mfma_f32_16x16x32_bf16 v[88:91], v[128:131], v[180:183], v[88:91]
	v_mfma_f32_16x16x32_bf16 v[76:79], v[108:111], v[206:209], v[76:79]
	v_mfma_f32_16x16x32_bf16 v[72:75], v[128:131], v[206:209], v[72:75]
	v_mfma_f32_16x16x32_bf16 v[132:135], v[144:147], v[160:163], v[132:135]
	v_mfma_f32_16x16x32_bf16 v[124:127], v[152:155], v[160:163], v[124:127]
	v_mfma_f32_16x16x32_bf16 v[104:107], v[144:147], v[168:171], v[104:107]
	v_mfma_f32_16x16x32_bf16 v[100:103], v[152:155], v[168:171], v[100:103]
	v_mfma_f32_16x16x32_bf16 v[84:87], v[144:147], v[176:179], v[84:87]
	v_mfma_f32_16x16x32_bf16 v[80:83], v[152:155], v[176:179], v[80:83]
	v_mfma_f32_16x16x32_bf16 v[68:71], v[144:147], v[202:205], v[68:71]
	v_mfma_f32_16x16x32_bf16 v[64:67], v[152:155], v[202:205], v[64:67]
	v_mfma_f32_16x16x32_bf16 v[132:135], v[148:151], v[164:167], v[132:135]
	v_mfma_f32_16x16x32_bf16 v[124:127], v[156:159], v[164:167], v[124:127]
	v_mfma_f32_16x16x32_bf16 v[104:107], v[148:151], v[172:175], v[104:107]
	v_mfma_f32_16x16x32_bf16 v[100:103], v[156:159], v[172:175], v[100:103]
	v_mfma_f32_16x16x32_bf16 v[84:87], v[148:151], v[180:183], v[84:87]
	v_mfma_f32_16x16x32_bf16 v[80:83], v[156:159], v[180:183], v[80:83]
	v_mfma_f32_16x16x32_bf16 v[68:71], v[148:151], v[206:209], v[68:71]
	v_mfma_f32_16x16x32_bf16 v[64:67], v[156:159], v[206:209], v[64:67]
	s_barrier
	s_add_i32 s71, s62, s48
	s_add_u32 s98, s34, s12
	s_addc_u32 s99, s35, s13
	s_add_u32 s100, s46, s12
	s_addc_u32 s101, s47, s13
	s_mov_b32 m0, s71
	ds_read_b128 v[160:163], v224 offset:16384
	ds_read_b128 v[164:167], v224 offset:17408
	ds_read_b128 v[168:171], v224 offset:18432
	ds_read_b128 v[172:175], v224 offset:19456
	ds_read_b128 v[176:179], v224 offset:20480
	ds_read_b128 v[180:183], v224 offset:21504
	ds_read_b128 v[202:205], v224 offset:22528
	ds_read_b128 v[206:209], v224 offset:23552
	global_load_lds_dwordx4 v186, s[34:35]
	s_add_i32 m0, s71, 0x2000
	s_add_u32 s72, s34, 0xb0000
	s_addc_u32 s73, s35, 0
	s_add_i32 s71, s63, s48
	global_load_lds_dwordx4 v190, s[34:35]
	s_mov_b32 m0, s71
	s_nop 0
	global_load_lds_dwordx4 v186, s[72:73]
	s_add_i32 m0, s71, 0x2000
	s_nop 0
	global_load_lds_dwordx4 v190, s[72:73]
	s_mov_b32 m0, s49
	s_nop 0
	global_load_lds_dwordx4 v184, s[46:47]
	s_mov_b32 m0, s50
	s_nop 0
	global_load_lds_dwordx4 v188, s[46:47]
	s_nop 0
	s_waitcnt vmcnt(8)
	s_waitcnt lgkmcnt(0)
	s_barrier
	v_mfma_f32_16x16x32_bf16 v[60:63], v[96:99], v[160:163], v[60:63]
	v_mfma_f32_16x16x32_bf16 v[56:59], v[120:123], v[160:163], v[56:59]
	v_mfma_f32_16x16x32_bf16 v[44:47], v[96:99], v[168:171], v[44:47]
	v_mfma_f32_16x16x32_bf16 v[40:43], v[120:123], v[168:171], v[40:43]
	v_mfma_f32_16x16x32_bf16 v[28:31], v[96:99], v[176:179], v[28:31]
	v_mfma_f32_16x16x32_bf16 v[24:27], v[120:123], v[176:179], v[24:27]
	v_mfma_f32_16x16x32_bf16 v[12:15], v[96:99], v[202:205], v[12:15]
	v_mfma_f32_16x16x32_bf16 v[8:11], v[120:123], v[202:205], v[8:11]
	v_mfma_f32_16x16x32_bf16 v[60:63], v[108:111], v[164:167], v[60:63]
	v_mfma_f32_16x16x32_bf16 v[56:59], v[128:131], v[164:167], v[56:59]
	v_mfma_f32_16x16x32_bf16 v[44:47], v[108:111], v[172:175], v[44:47]
	v_mfma_f32_16x16x32_bf16 v[40:43], v[128:131], v[172:175], v[40:43]
	v_mfma_f32_16x16x32_bf16 v[28:31], v[108:111], v[180:183], v[28:31]
	v_mfma_f32_16x16x32_bf16 v[24:27], v[128:131], v[180:183], v[24:27]
	v_mfma_f32_16x16x32_bf16 v[12:15], v[108:111], v[206:209], v[12:15]
	v_mfma_f32_16x16x32_bf16 v[8:11], v[128:131], v[206:209], v[8:11]
	v_mfma_f32_16x16x32_bf16 v[52:55], v[144:147], v[160:163], v[52:55]
	v_mfma_f32_16x16x32_bf16 v[48:51], v[152:155], v[160:163], v[48:51]
	v_mfma_f32_16x16x32_bf16 v[36:39], v[144:147], v[168:171], v[36:39]
	v_mfma_f32_16x16x32_bf16 v[32:35], v[152:155], v[168:171], v[32:35]
	v_mfma_f32_16x16x32_bf16 v[20:23], v[144:147], v[176:179], v[20:23]
	v_mfma_f32_16x16x32_bf16 v[16:19], v[152:155], v[176:179], v[16:19]
	v_mfma_f32_16x16x32_bf16 v[4:7], v[144:147], v[202:205], v[4:7]
	v_mfma_f32_16x16x32_bf16 v[0:3], v[152:155], v[202:205], v[0:3]
	v_mfma_f32_16x16x32_bf16 v[52:55], v[148:151], v[164:167], v[52:55]
	v_mfma_f32_16x16x32_bf16 v[48:51], v[156:159], v[164:167], v[48:51]
	v_mfma_f32_16x16x32_bf16 v[36:39], v[148:151], v[172:175], v[36:39]
	v_mfma_f32_16x16x32_bf16 v[32:35], v[156:159], v[172:175], v[32:35]
	v_mfma_f32_16x16x32_bf16 v[20:23], v[148:151], v[180:183], v[20:23]
	v_mfma_f32_16x16x32_bf16 v[16:19], v[156:159], v[180:183], v[16:19]
	v_mfma_f32_16x16x32_bf16 v[4:7], v[148:151], v[206:209], v[4:7]
	v_mfma_f32_16x16x32_bf16 v[0:3], v[156:159], v[206:209], v[0:3]
	s_barrier
; #define PG8_STAGE(bufoff, gbase, voff) do { _Pragma("unroll") for (int _i = 0; _i < 2; ++_i) \
;         __builtin_amdgcn_global_load_lds((const unsigned*)((const char*)(gbase) + (voff)[_i]), (PG8_LAS unsigned*)(lds + (bufoff) + ldsw + _i * 8192), 16, 0, 0); } while (0)
; #define PG8_LDA(dst, b, h) do { _Pragma("unroll") for (int m = 0; m < 4; ++m) _Pragma("unroll") for (int k = 0; k < 2; ++k) dst[m][k] = *(const PG8_LAS bf16x8*)(lds + PG8_SA(b, h) + aoff + m * 2048 + k * 1024); } while (0)
; #define PG8_LDB(dst, b, h) do { _Pragma("unroll") for (int n = 0; n < 2; ++n) _Pragma("unroll") for (int k = 0; k < 2; ++k) dst[n][k] = *(const PG8_LAS bf16x8*)(lds + PG8_SB(b, h) + boff + n * 2048 + k * 1024); } while (0)
; #define PG8_MMA(ai, bj, At, Bt) do { __builtin_amdgcn_s_setprio(1); _Pragma("unroll") for (int m = 0; m < 4; ++m) _Pragma("unroll") for (int n = 0; n < 2; ++n) _Pragma("unroll") for (int k = 0; k < 2; ++k) \
;         acc[ai][bj][m][n] = __builtin_amdgcn_mfma_f32_16x16x32_bf16(Bt[n][k], At[m][k], acc[ai][bj][m][n], 0, 0, 0); __builtin_amdgcn_s_setprio(0); } while (0)
; #define PG8_WAIT_V(n) asm volatile("s_waitcnt vmcnt(" #n ")" ::: "memory")
; #define PG8_WAIT_L(n) asm volatile("s_waitcnt lgkmcnt(" #n ")" ::: "memory")
; #define PG8_BAR __builtin_amdgcn_s_barrier()
; #define PG8_SCHED __builtin_amdgcn_sched_barrier(0)
; template <class Epi, class Sched, bool ALIGN_EPI = false, bool SP2 = false>
; __device__ __forceinline__ void gemm_phase(PG8_LAS unsigned char* lds, const Gemm g, const Sched& S, const Epi& E) {
;     ...
;             PG8_LDB(B0, 1, 0); PG8_LDB(B1, 1, 1); PG8_SCHED; PG8_LDA(At, 1, 0); PG8_STAGE(PG8_SA(0, 1), a2 + hstep, voffA);
;             PG8_WAIT_V(8); PG8_WAIT_L(0); PG8_BAR; PG8_MMA(0, 0, At, B0); PG8_MMA(0, 1, At, B1); PG8_BAR; PG8_SCHED;
;             PG8_LDA(At, 1, 1); PG8_STAGE(PG8_SB(1, 0), b3, voffB); PG8_STAGE(PG8_SB(1, 1), b3 + hstep, voffB); PG8_STAGE(PG8_SA(1, 0), a3, voffA);
;             PG8_WAIT_V(8); PG8_WAIT_L(0); PG8_BAR; PG8_MMA(1, 0, At, B0); PG8_MMA(1, 1, At, B1); PG8_BAR; PG8_SCHED;
;     ...
;         if constexpr (ALIGN_EPI) { if (wr == 0) PG8_BAR; }
	s_add_i32 s71, 0, 0x18000
	s_add_i32 s72, 0, 0x1c000
	v_add_u32_e32 v128, s71, v197
	v_add_u32_e32 v156, s72, v197
	ds_read_b128 v[96:99], v128
	ds_read_b128 v[108:111], v128 offset:1024
	ds_read_b128 v[120:123], v128 offset:2048
	ds_read_b128 v[128:131], v128 offset:3072
	ds_read_b128 v[144:147], v156
	ds_read_b128 v[148:151], v156 offset:1024
	ds_read_b128 v[152:155], v156 offset:2048
	ds_read_b128 v[156:159], v156 offset:3072
	s_add_u32 s46, s46, 0xb0000
	s_addc_u32 s47, s47, 0
	s_mov_b32 m0, s51
	ds_read_b128 v[160:163], v224 offset:32768
	ds_read_b128 v[164:167], v224 offset:33792
	ds_read_b128 v[168:171], v224 offset:34816
	ds_read_b128 v[172:175], v224 offset:35840
	ds_read_b128 v[176:179], v224 offset:36864
	ds_read_b128 v[180:183], v224 offset:37888
	ds_read_b128 v[202:205], v224 offset:38912
	ds_read_b128 v[206:209], v224 offset:39936
	global_load_lds_dwordx4 v184, s[46:47]
	s_mov_b32 m0, s52
	s_nop 0
	global_load_lds_dwordx4 v188, s[46:47]
	s_waitcnt vmcnt(8)
	s_waitcnt lgkmcnt(0)
	s_barrier
	v_mfma_f32_16x16x32_bf16 v[140:143], v[96:99], v[160:163], v[140:143]
	v_mfma_f32_16x16x32_bf16 v[136:139], v[120:123], v[160:163], v[136:139]
	v_mfma_f32_16x16x32_bf16 v[116:119], v[96:99], v[168:171], v[116:119]
	v_mfma_f32_16x16x32_bf16 v[112:115], v[120:123], v[168:171], v[112:115]
	v_mfma_f32_16x16x32_bf16 v[92:95], v[96:99], v[176:179], v[92:95]
	v_mfma_f32_16x16x32_bf16 v[88:91], v[120:123], v[176:179], v[88:91]
	v_mfma_f32_16x16x32_bf16 v[76:79], v[96:99], v[202:205], v[76:79]
	v_mfma_f32_16x16x32_bf16 v[72:75], v[120:123], v[202:205], v[72:75]
	v_mfma_f32_16x16x32_bf16 v[140:143], v[108:111], v[164:167], v[140:143]
	v_mfma_f32_16x16x32_bf16 v[136:139], v[128:131], v[164:167], v[136:139]
	v_mfma_f32_16x16x32_bf16 v[116:119], v[108:111], v[172:175], v[116:119]
	v_mfma_f32_16x16x32_bf16 v[112:115], v[128:131], v[172:175], v[112:115]
	v_mfma_f32_16x16x32_bf16 v[92:95], v[108:111], v[180:183], v[92:95]
	v_mfma_f32_16x16x32_bf16 v[88:91], v[128:131], v[180:183], v[88:91]
	v_mfma_f32_16x16x32_bf16 v[76:79], v[108:111], v[206:209], v[76:79]
	v_mfma_f32_16x16x32_bf16 v[72:75], v[128:131], v[206:209], v[72:75]
	v_mfma_f32_16x16x32_bf16 v[132:135], v[144:147], v[160:163], v[132:135]
	v_mfma_f32_16x16x32_bf16 v[124:127], v[152:155], v[160:163], v[124:127]
	v_mfma_f32_16x16x32_bf16 v[104:107], v[144:147], v[168:171], v[104:107]
	v_mfma_f32_16x16x32_bf16 v[100:103], v[152:155], v[168:171], v[100:103]
	v_mfma_f32_16x16x32_bf16 v[84:87], v[144:147], v[176:179], v[84:87]
	v_mfma_f32_16x16x32_bf16 v[80:83], v[152:155], v[176:179], v[80:83]
	v_mfma_f32_16x16x32_bf16 v[68:71], v[144:147], v[202:205], v[68:71]
	v_mfma_f32_16x16x32_bf16 v[64:67], v[152:155], v[202:205], v[64:67]
	v_mfma_f32_16x16x32_bf16 v[132:135], v[148:151], v[164:167], v[132:135]
	v_mfma_f32_16x16x32_bf16 v[124:127], v[156:159], v[164:167], v[124:127]
	v_mfma_f32_16x16x32_bf16 v[104:107], v[148:151], v[172:175], v[104:107]
	v_mfma_f32_16x16x32_bf16 v[100:103], v[156:159], v[172:175], v[100:103]
	v_mfma_f32_16x16x32_bf16 v[84:87], v[148:151], v[180:183], v[84:87]
	v_mfma_f32_16x16x32_bf16 v[80:83], v[156:159], v[180:183], v[80:83]
	v_mfma_f32_16x16x32_bf16 v[68:71], v[148:151], v[206:209], v[68:71]
	v_mfma_f32_16x16x32_bf16 v[64:67], v[156:159], v[206:209], v[64:67]
	s_barrier
	s_add_i32 s46, s71, s48
	s_mov_b32 m0, s46
	ds_read_b128 v[160:163], v224 offset:49152
	ds_read_b128 v[164:167], v224 offset:50176
	ds_read_b128 v[168:171], v224 offset:51200
	ds_read_b128 v[172:175], v224 offset:52224
	ds_read_b128 v[176:179], v224 offset:53248
	ds_read_b128 v[180:183], v224 offset:54272
	ds_read_b128 v[202:205], v224 offset:55296
	ds_read_b128 v[206:209], v224 offset:56320
	global_load_lds_dwordx4 v186, s[98:99]
	s_add_i32 m0, s46, 0x2000
	s_add_u32 s34, s34, 0xb0080
	s_addc_u32 s35, s35, 0
	s_add_i32 s46, s72, s48
	global_load_lds_dwordx4 v190, s[98:99]
	s_mov_b32 m0, s46
	s_nop 0
	global_load_lds_dwordx4 v186, s[34:35]
	s_add_i32 m0, s46, 0x2000
	s_nop 0
	global_load_lds_dwordx4 v190, s[34:35]
	s_mov_b32 m0, s57
	s_nop 0
	global_load_lds_dwordx4 v184, s[100:101]
	s_mov_b32 m0, s58
	s_nop 0
	global_load_lds_dwordx4 v188, s[100:101]
	s_nop 0
	s_waitcnt vmcnt(8)
	s_waitcnt lgkmcnt(0)
	s_barrier
	v_mfma_f32_16x16x32_bf16 v[60:63], v[96:99], v[160:163], v[60:63]
	v_mfma_f32_16x16x32_bf16 v[56:59], v[120:123], v[160:163], v[56:59]
	v_mfma_f32_16x16x32_bf16 v[44:47], v[96:99], v[168:171], v[44:47]
	v_mfma_f32_16x16x32_bf16 v[40:43], v[120:123], v[168:171], v[40:43]
	v_mfma_f32_16x16x32_bf16 v[28:31], v[96:99], v[176:179], v[28:31]
	v_mfma_f32_16x16x32_bf16 v[24:27], v[120:123], v[176:179], v[24:27]
	v_mfma_f32_16x16x32_bf16 v[12:15], v[96:99], v[202:205], v[12:15]
	v_mfma_f32_16x16x32_bf16 v[8:11], v[120:123], v[202:205], v[8:11]
	v_mfma_f32_16x16x32_bf16 v[60:63], v[108:111], v[164:167], v[60:63]
	v_mfma_f32_16x16x32_bf16 v[56:59], v[128:131], v[164:167], v[56:59]
	v_mfma_f32_16x16x32_bf16 v[44:47], v[108:111], v[172:175], v[44:47]
	v_mfma_f32_16x16x32_bf16 v[40:43], v[128:131], v[172:175], v[40:43]
	v_mfma_f32_16x16x32_bf16 v[28:31], v[108:111], v[180:183], v[28:31]
	v_mfma_f32_16x16x32_bf16 v[24:27], v[128:131], v[180:183], v[24:27]
	v_mfma_f32_16x16x32_bf16 v[12:15], v[108:111], v[206:209], v[12:15]
	v_mfma_f32_16x16x32_bf16 v[8:11], v[128:131], v[206:209], v[8:11]
	v_mfma_f32_16x16x32_bf16 v[52:55], v[144:147], v[160:163], v[52:55]
	v_mfma_f32_16x16x32_bf16 v[48:51], v[152:155], v[160:163], v[48:51]
	v_mfma_f32_16x16x32_bf16 v[36:39], v[144:147], v[168:171], v[36:39]
	v_mfma_f32_16x16x32_bf16 v[32:35], v[152:155], v[168:171], v[32:35]
	v_mfma_f32_16x16x32_bf16 v[20:23], v[144:147], v[176:179], v[20:23]
	v_mfma_f32_16x16x32_bf16 v[16:19], v[152:155], v[176:179], v[16:19]
	v_mfma_f32_16x16x32_bf16 v[4:7], v[144:147], v[202:205], v[4:7]
	v_mfma_f32_16x16x32_bf16 v[0:3], v[152:155], v[202:205], v[0:3]
	v_mfma_f32_16x16x32_bf16 v[52:55], v[148:151], v[164:167], v[52:55]
	v_mfma_f32_16x16x32_bf16 v[48:51], v[156:159], v[164:167], v[48:51]
	v_mfma_f32_16x16x32_bf16 v[36:39], v[148:151], v[172:175], v[36:39]
	v_mfma_f32_16x16x32_bf16 v[32:35], v[156:159], v[172:175], v[32:35]
	v_mfma_f32_16x16x32_bf16 v[20:23], v[148:151], v[180:183], v[20:23]
	v_mfma_f32_16x16x32_bf16 v[16:19], v[156:159], v[180:183], v[16:19]
	v_mfma_f32_16x16x32_bf16 v[4:7], v[148:151], v[206:209], v[4:7]
	v_mfma_f32_16x16x32_bf16 v[0:3], v[156:159], v[206:209], v[0:3]
	s_barrier
	s_add_i32 s70, s70, 2
	s_add_u32 s20, s20, 0x100
	s_addc_u32 s21, s21, 0
	s_add_u32 s68, s68, 0x100
	s_addc_u32 s69, s69, 0
	s_cmp_gt_u32 s70, 41
	s_cbranch_scc0 .LBB0_1825
	s_and_b64 vcc, exec, s[14:15]
	s_cbranch_vccz .LBB0_1828
	s_barrier
